# 48 provably redundant lgkmcnt(0) waits removed (straight-line, prior lgkmcnt(0) with no LGKM op between) on top of v42
# baseline (speedup 1.0000x reference)
; #define LAS __attribute__((address_space(3)))
; __device__ __forceinline__ void tr_item(const float* W, int ldw, int c0, bf16* WT, int ldk, int r0, int nblk, int item, LAS float* scr, int lane) {
;     const int kb = item / nblk, nb = item % nblk, k0 = 64 * kb, n0 = 32 * nb;
; #pragma unroll 8
;     for (int i = 0; i < 32; ++i) { const int kk = 2 * i + (lane >> 5); scr[kk * 33 + (lane & 31)] = W[(size_t)(k0 + kk) * ldw + c0 + n0 + (lane & 31)]; }
.LBB0_37:
	s_lshl_b32 s34, s20, 1
	s_lshl_b32 s35, s21, 1
	v_or_b32_e32 v0, s35, v38
	s_add_i32 s36, s34, 4
	s_add_i32 s37, s35, 4
	v_mov_b32_e32 v47, v1
	s_add_i32 s39, s35, 8
	v_lshlrev_b64 v[60:61], 12, v[0:1]
	v_or_b32_e32 v46, s36, v7
	v_or_b32_e32 v0, s37, v38
	v_mov_b32_e32 v45, v1
	v_or_b32_e32 v44, s34, v7
	s_add_i32 s41, s35, 12
	v_lshlrev_b64 v[46:47], 12, v[46:47]
	v_lshlrev_b64 v[62:63], 12, v[0:1]
	v_or_b32_e32 v0, s39, v38
	s_add_i32 s38, s34, 8
	s_add_i32 s40, s34, 12
	s_add_i32 s43, s35, 16
	v_lshlrev_b64 v[44:45], 12, v[44:45]
	v_lshl_add_u64 v[60:61], v[36:37], 0, v[60:61]
	v_lshl_add_u64 v[46:47], v[36:37], 0, v[46:47]
	v_lshlrev_b64 v[64:65], 12, v[0:1]
	v_or_b32_e32 v0, s41, v38
	v_mov_b32_e32 v49, v1
	v_mov_b32_e32 v51, v1
	s_add_i32 s45, s35, 20
	v_or_b32_e32 v48, s38, v7
	v_or_b32_e32 v50, s40, v7
	v_lshl_add_u64 v[44:45], v[36:37], 0, v[44:45]
	v_lshl_add_u64 v[62:63], v[36:37], 0, v[62:63]
	global_load_dword v35, v[60:61], off
	global_load_dword v76, v[44:45], off
	global_load_dword v77, v[62:63], off
	global_load_dword v78, v[46:47], off
	v_lshlrev_b64 v[46:47], 12, v[0:1]
	v_or_b32_e32 v0, s43, v38
	s_add_i32 s42, s34, 16
	s_add_i32 s44, s34, 20
	s_add_i32 s47, s35, 24
	v_lshlrev_b64 v[48:49], 12, v[48:49]
	v_lshlrev_b64 v[50:51], 12, v[50:51]
	v_lshl_add_u64 v[44:45], v[36:37], 0, v[64:65]
	v_lshl_add_u64 v[46:47], v[36:37], 0, v[46:47]
	v_lshlrev_b64 v[60:61], 12, v[0:1]
	v_or_b32_e32 v0, s45, v38
	v_mov_b32_e32 v53, v1
	v_mov_b32_e32 v55, v1
	s_add_i32 s46, s34, 24
	s_add_i32 s48, s34, 28
	s_add_i32 s49, s35, 28
	v_or_b32_e32 v52, s42, v7
	v_or_b32_e32 v54, s44, v7
	v_lshl_add_u64 v[48:49], v[36:37], 0, v[48:49]
	v_lshl_add_u64 v[50:51], v[36:37], 0, v[50:51]
	global_load_dword v79, v[44:45], off
	global_load_dword v80, v[48:49], off
	global_load_dword v81, v[46:47], off
	global_load_dword v82, v[50:51], off
	v_lshlrev_b64 v[46:47], 12, v[0:1]
	v_or_b32_e32 v0, s47, v38
	v_mov_b32_e32 v57, v1
	v_mov_b32_e32 v59, v1
	v_or_b32_e32 v56, s46, v7
	v_or_b32_e32 v58, s48, v7
	v_lshlrev_b64 v[52:53], 12, v[52:53]
	v_lshlrev_b64 v[54:55], 12, v[54:55]
	v_lshl_add_u64 v[44:45], v[36:37], 0, v[60:61]
	v_lshl_add_u64 v[46:47], v[36:37], 0, v[46:47]
	v_lshlrev_b64 v[48:49], 12, v[0:1]
	v_or_b32_e32 v0, s49, v38
	v_lshlrev_b64 v[56:57], 12, v[56:57]
	v_lshlrev_b64 v[58:59], 12, v[58:59]
	v_lshl_add_u64 v[52:53], v[36:37], 0, v[52:53]
	v_lshl_add_u64 v[54:55], v[36:37], 0, v[54:55]
	global_load_dword v83, v[44:45], off
	global_load_dword v84, v[52:53], off
	global_load_dword v85, v[46:47], off
	global_load_dword v86, v[54:55], off
	v_lshl_add_u64 v[44:45], v[36:37], 0, v[48:49]
	v_lshlrev_b64 v[46:47], 12, v[0:1]
	v_lshl_add_u64 v[56:57], v[36:37], 0, v[56:57]
	v_lshl_add_u64 v[58:59], v[36:37], 0, v[58:59]
	v_lshl_add_u64 v[46:47], v[36:37], 0, v[46:47]
	global_load_dword v0, v[44:45], off
	global_load_dword v87, v[56:57], off
	global_load_dword v88, v[46:47], off
	global_load_dword v89, v[58:59], off
	v_or_b32_e32 v46, s34, v3
	v_or_b32_e32 v44, s35, v2
	s_add_i32 s21, s21, 16
	s_add_i32 s20, s20, 16
	s_add_i32 s31, s31, -16
	v_mad_u64_u32 v[44:45], s[10:11], v44, s27, v[6:7]
	v_mad_u64_u32 v[46:47], s[10:11], v46, s27, v[6:7]
	v_or_b32_e32 v45, s36, v3
	v_or_b32_e32 v47, s37, v2
	v_or_b32_e32 v54, s38, v3
	v_or_b32_e32 v52, s39, v2
	v_or_b32_e32 v58, s40, v3
	v_or_b32_e32 v56, s41, v2
	v_or_b32_e32 v62, s42, v3
	v_or_b32_e32 v60, s43, v2
	v_or_b32_e32 v66, s44, v3
	v_or_b32_e32 v64, s45, v2
	v_or_b32_e32 v70, s46, v3
	v_or_b32_e32 v68, s47, v2
	v_or_b32_e32 v74, s48, v3
	v_or_b32_e32 v72, s49, v2
	s_cmp_lg_u32 s31, 0
	v_mad_u64_u32 v[48:49], s[10:11], v47, s27, v[6:7]
	v_mad_u64_u32 v[50:51], s[10:11], v45, s27, v[6:7]
	v_mad_u64_u32 v[52:53], s[10:11], v52, s27, v[6:7]
	v_mad_u64_u32 v[54:55], s[10:11], v54, s27, v[6:7]
	v_mad_u64_u32 v[56:57], s[10:11], v56, s27, v[6:7]
	v_mad_u64_u32 v[58:59], s[10:11], v58, s27, v[6:7]
	v_mad_u64_u32 v[60:61], s[10:11], v60, s27, v[6:7]
	v_mad_u64_u32 v[62:63], s[10:11], v62, s27, v[6:7]
	v_mad_u64_u32 v[64:65], s[10:11], v64, s27, v[6:7]
	v_mad_u64_u32 v[66:67], s[10:11], v66, s27, v[6:7]
	v_mad_u64_u32 v[68:69], s[10:11], v68, s27, v[6:7]
	v_mad_u64_u32 v[70:71], s[10:11], v70, s27, v[6:7]
	v_mad_u64_u32 v[72:73], s[10:11], v72, s27, v[6:7]
	v_mad_u64_u32 v[74:75], s[10:11], v74, s27, v[6:7]
	s_waitcnt vmcnt(15)
	ds_write_b32 v44, v35
	s_waitcnt vmcnt(14)
	ds_write_b32 v46, v76
	s_waitcnt vmcnt(13)
	ds_write_b32 v48, v77
	s_waitcnt vmcnt(12)
	ds_write_b32 v50, v78
	s_waitcnt vmcnt(11)
	ds_write_b32 v52, v79
	s_waitcnt vmcnt(10)
	ds_write_b32 v54, v80
	s_waitcnt vmcnt(9)
	ds_write_b32 v56, v81
	s_waitcnt vmcnt(8)
	ds_write_b32 v58, v82
	s_waitcnt vmcnt(7)
	ds_write_b32 v60, v83
	s_waitcnt vmcnt(6)
	ds_write_b32 v62, v84
	s_waitcnt vmcnt(5)
	ds_write_b32 v64, v85
	s_waitcnt vmcnt(4)
	ds_write_b32 v66, v86
	s_waitcnt vmcnt(3)
	ds_write_b32 v68, v0
	s_waitcnt vmcnt(2)
	ds_write_b32 v70, v87
	s_waitcnt vmcnt(1)
	ds_write_b32 v72, v88
	s_waitcnt vmcnt(0)
	ds_write_b32 v74, v89
	s_cbranch_scc1 .LBB0_37
; #define LAS __attribute__((address_space(3)))
; __device__ __forceinline__ unsigned pk2(float lo, float hi) { return f2bf(lo) | (f2bf(hi) << 16); }
; __device__ __forceinline__ void tr_item(const float* W, int ldw, int c0, bf16* WT, int ldk, int r0, int nblk, int item, LAS float* scr, int lane) {
;     ...
;     asm volatile("s_waitcnt lgkmcnt(0)" ::: "memory");
;     const int c = lane & 7;
; #pragma unroll
;     for (int j = 0; j < 4; ++j) { const int n = (lane >> 3) + 8 * j; const LAS float* s = scr + (8 * c) * 33 + n;
;         v4u o; o.x = pk2(s[0 * 33], s[1 * 33]); o.y = pk2(s[2 * 33], s[3 * 33]); o.z = pk2(s[4 * 33], s[5 * 33]); o.w = pk2(s[6 * 33], s[7 * 33]);
;         *(v4u*)(WT + (size_t)(r0 + n0 + n) * ldk + k0 + 8 * c) = o; }
;     asm volatile("s_waitcnt lgkmcnt(0)" ::: "memory");
; }
	s_waitcnt lgkmcnt(0)
	ds_read2_b32 v[36:37], v40 offset1:8
	ds_read2_b32 v[50:51], v40 offset0:33 offset1:41
	ds_read2_b32 v[52:53], v40 offset0:66 offset1:74
	ds_read2_b32 v[54:55], v40 offset0:99 offset1:107
	ds_read2_b32 v[56:57], v40 offset0:132 offset1:140
	s_mov_b32 s85, 0xffff0000
	s_waitcnt lgkmcnt(4)
	v_bfe_u32 v0, v36, 16, 1
	v_add3_u32 v0, v36, v0, s80
	s_waitcnt lgkmcnt(3)
	v_bfe_u32 v7, v50, 16, 1
	v_lshrrev_b32_e32 v0, 16, v0
	v_add3_u32 v7, v50, v7, s80
	ds_read2_b32 v[58:59], v40 offset0:165 offset1:173
	v_and_or_b32 v44, v7, s85, v0
	s_waitcnt lgkmcnt(3)
	v_bfe_u32 v0, v52, 16, 1
	v_add3_u32 v0, v52, v0, s80
	s_waitcnt lgkmcnt(2)
	v_bfe_u32 v7, v54, 16, 1
	ds_read2_b32 v[60:61], v40 offset0:198 offset1:206
	v_lshrrev_b32_e32 v0, 16, v0
	v_add3_u32 v7, v54, v7, s80
	ds_read2_b32 v[62:63], v40 offset0:231 offset1:239
	v_and_or_b32 v45, v7, s85, v0
	s_waitcnt lgkmcnt(3)
	v_bfe_u32 v0, v56, 16, 1
	v_add3_u32 v0, v56, v0, s80
	s_waitcnt lgkmcnt(2)
	v_bfe_u32 v7, v58, 16, 1
	v_lshrrev_b32_e32 v0, 16, v0
	v_add3_u32 v7, v58, v7, s80
	v_and_or_b32 v46, v7, s85, v0
	s_waitcnt lgkmcnt(1)
	v_bfe_u32 v0, v60, 16, 1
	v_add3_u32 v0, v60, v0, s80
	s_waitcnt lgkmcnt(0)
	v_bfe_u32 v7, v62, 16, 1
	v_lshrrev_b32_e32 v0, 16, v0
	v_add3_u32 v7, v62, v7, s80
	s_lshl_b32 s88, s4, 1
	v_and_or_b32 v47, v7, s85, v0
	v_or_b32_e32 v0, s1, v39
	v_lshl_add_u64 v[48:49], v[10:11], 0, s[88:89]
	v_lshlrev_b32_e32 v0, 13, v0
	v_lshl_add_u64 v[64:65], v[48:49], 0, v[0:1]
	v_bfe_u32 v0, v37, 16, 1
	v_add3_u32 v0, v37, v0, s80
	v_bfe_u32 v7, v51, 16, 1
	v_lshrrev_b32_e32 v0, 16, v0
	v_add3_u32 v7, v51, v7, s80
	global_store_dwordx4 v[64:65], v[44:47], off
	ds_read2_b32 v[36:37], v40 offset0:16 offset1:24
	s_mov_b64 s[20:21], 0
	v_and_or_b32 v44, v7, s85, v0
	v_bfe_u32 v0, v53, 16, 1
	v_add3_u32 v0, v53, v0, s80
	v_bfe_u32 v7, v55, 16, 1
	v_lshrrev_b32_e32 v0, 16, v0
	v_add3_u32 v7, v55, v7, s80
	v_and_or_b32 v45, v7, s85, v0
	v_bfe_u32 v0, v57, 16, 1
	v_add3_u32 v0, v57, v0, s80
	v_bfe_u32 v7, v59, 16, 1
	v_lshrrev_b32_e32 v0, 16, v0
	v_add3_u32 v7, v59, v7, s80
	v_and_or_b32 v46, v7, s85, v0
	v_bfe_u32 v0, v61, 16, 1
	v_add3_u32 v0, v61, v0, s80
	v_bfe_u32 v7, v63, 16, 1
	v_lshrrev_b32_e32 v0, 16, v0
	v_add3_u32 v7, v63, v7, s80
	v_and_or_b32 v47, v7, s85, v0
	v_or_b32_e32 v0, s1, v41
	v_lshlrev_b32_e32 v0, 13, v0
	v_lshl_add_u64 v[50:51], v[48:49], 0, v[0:1]
	global_store_dwordx4 v[50:51], v[44:47], off
	ds_read2_b32 v[50:51], v40 offset0:49 offset1:57
	ds_read2_b32 v[52:53], v40 offset0:82 offset1:90
	ds_read2_b32 v[54:55], v40 offset0:115 offset1:123
	s_waitcnt lgkmcnt(3)
	v_bfe_u32 v0, v36, 16, 1
	v_add3_u32 v0, v36, v0, s80
	s_waitcnt lgkmcnt(2)
	v_bfe_u32 v7, v50, 16, 1
	ds_read2_b32 v[56:57], v40 offset0:148 offset1:156
	v_lshrrev_b32_e32 v0, 16, v0
	v_add3_u32 v7, v50, v7, s80
	ds_read2_b32 v[58:59], v40 offset0:181 offset1:189
	v_and_or_b32 v44, v7, s85, v0
	s_waitcnt lgkmcnt(3)
	v_bfe_u32 v0, v52, 16, 1
	v_add3_u32 v0, v52, v0, s80
	s_waitcnt lgkmcnt(2)
	v_bfe_u32 v7, v54, 16, 1
	ds_read2_b32 v[60:61], v40 offset0:214 offset1:222
	v_lshrrev_b32_e32 v0, 16, v0
	v_add3_u32 v7, v54, v7, s80
	ds_read2_b32 v[62:63], v40 offset0:247 offset1:255
	v_and_or_b32 v45, v7, s85, v0
	s_waitcnt lgkmcnt(3)
	v_bfe_u32 v0, v56, 16, 1
	v_add3_u32 v0, v56, v0, s80
	s_waitcnt lgkmcnt(2)
	v_bfe_u32 v7, v58, 16, 1
	v_lshrrev_b32_e32 v0, 16, v0
	v_add3_u32 v7, v58, v7, s80
	v_and_or_b32 v46, v7, s85, v0
	s_waitcnt lgkmcnt(1)
	v_bfe_u32 v0, v60, 16, 1
	v_add3_u32 v0, v60, v0, s80
	s_waitcnt lgkmcnt(0)
	v_bfe_u32 v7, v62, 16, 1
	v_lshrrev_b32_e32 v0, 16, v0
	v_add3_u32 v7, v62, v7, s80
	v_and_or_b32 v47, v7, s85, v0
	v_or_b32_e32 v0, s1, v42
	v_lshlrev_b32_e32 v0, 13, v0
	v_lshl_add_u64 v[64:65], v[48:49], 0, v[0:1]
	v_bfe_u32 v0, v37, 16, 1
	v_add3_u32 v0, v37, v0, s80
	v_bfe_u32 v7, v51, 16, 1
	v_lshrrev_b32_e32 v0, 16, v0
	v_add3_u32 v7, v51, v7, s80
	global_store_dwordx4 v[64:65], v[44:47], off
	v_readlane_b32 s81, v254, 55
	s_nop 0
	v_and_or_b32 v44, v7, s85, v0
	v_bfe_u32 v0, v53, 16, 1
	v_add3_u32 v0, v53, v0, s80
	v_bfe_u32 v7, v55, 16, 1
	v_lshrrev_b32_e32 v0, 16, v0
	v_add3_u32 v7, v55, v7, s80
	v_and_or_b32 v45, v7, s85, v0
	v_bfe_u32 v0, v57, 16, 1
	v_add3_u32 v0, v57, v0, s80
	v_bfe_u32 v7, v59, 16, 1
	v_lshrrev_b32_e32 v0, 16, v0
	v_add3_u32 v7, v59, v7, s80
	v_and_or_b32 v46, v7, s85, v0
	v_bfe_u32 v0, v61, 16, 1
	v_add3_u32 v0, v61, v0, s80
	v_bfe_u32 v7, v63, 16, 1
	v_lshrrev_b32_e32 v0, 16, v0
	v_add3_u32 v7, v63, v7, s80
	v_and_or_b32 v47, v7, s85, v0
	v_or_b32_e32 v0, s1, v43
	v_lshlrev_b32_e32 v0, 13, v0
	v_lshl_add_u64 v[36:37], v[48:49], 0, v[0:1]
	global_store_dwordx4 v[36:37], v[44:47], off
.LBB0_39:
	s_and_b64 vcc, exec, s[20:21]
	s_cbranch_vccz .LBB0_43
	s_add_i32 s1, s8, 0xfffff010
	s_lshr_b32 s4, s1, 1
	s_lshl_b32 s1, s1, 5
	s_and_b32 s1, s1, 0xfe0
	s_and_b32 s4, s4, 0x7fc0
	s_lshl_b32 s88, s1, 2
	s_mov_b32 s20, 1
	v_lshl_add_u64 v[36:37], v[12:13], 0, s[88:89]
	v_or_b32_e32 v7, s4, v3
	v_or_b32_e32 v38, s4, v2
	s_mov_b32 s21, 0
	s_mov_b32 s31, 32
; #define LAS __attribute__((address_space(3)))
; __device__ __forceinline__ void tr_item(const float* W, int ldw, int c0, bf16* WT, int ldk, int r0, int nblk, int item, LAS float* scr, int lane) {
;     const int kb = item / nblk, nb = item % nblk, k0 = 64 * kb, n0 = 32 * nb;
; #pragma unroll 8
;     for (int i = 0; i < 32; ++i) { const int kk = 2 * i + (lane >> 5); scr[kk * 33 + (lane & 31)] = W[(size_t)(k0 + kk) * ldw + c0 + n0 + (lane & 31)]; }
.LBB0_41:
	s_lshl_b32 s34, s20, 1
	s_lshl_b32 s35, s21, 1
	v_or_b32_e32 v0, s35, v38
	s_add_i32 s36, s34, 4
	s_add_i32 s37, s35, 4
	v_mov_b32_e32 v47, v1
	s_add_i32 s39, s35, 8
	v_lshlrev_b64 v[60:61], 14, v[0:1]
	v_or_b32_e32 v46, s36, v7
	v_or_b32_e32 v0, s37, v38
	v_mov_b32_e32 v45, v1
	v_or_b32_e32 v44, s34, v7
	s_add_i32 s41, s35, 12
	v_lshlrev_b64 v[46:47], 14, v[46:47]
	v_lshlrev_b64 v[62:63], 14, v[0:1]
	v_or_b32_e32 v0, s39, v38
	s_add_i32 s38, s34, 8
	s_add_i32 s40, s34, 12
	s_add_i32 s43, s35, 16
	v_lshlrev_b64 v[44:45], 14, v[44:45]
	v_lshl_add_u64 v[60:61], v[36:37], 0, v[60:61]
	v_lshl_add_u64 v[46:47], v[36:37], 0, v[46:47]
	v_lshlrev_b64 v[64:65], 14, v[0:1]
	v_or_b32_e32 v0, s41, v38
	v_mov_b32_e32 v49, v1
	v_mov_b32_e32 v51, v1
	s_add_i32 s45, s35, 20
	v_or_b32_e32 v48, s38, v7
	v_or_b32_e32 v50, s40, v7
	v_lshl_add_u64 v[44:45], v[36:37], 0, v[44:45]
	v_lshl_add_u64 v[62:63], v[36:37], 0, v[62:63]
	global_load_dword v35, v[60:61], off
	global_load_dword v76, v[44:45], off
	global_load_dword v77, v[62:63], off
	global_load_dword v78, v[46:47], off
	v_lshlrev_b64 v[46:47], 14, v[0:1]
	v_or_b32_e32 v0, s43, v38
	s_add_i32 s42, s34, 16
	s_add_i32 s44, s34, 20
	s_add_i32 s47, s35, 24
	v_lshlrev_b64 v[48:49], 14, v[48:49]
	v_lshlrev_b64 v[50:51], 14, v[50:51]
	v_lshl_add_u64 v[44:45], v[36:37], 0, v[64:65]
	v_lshl_add_u64 v[46:47], v[36:37], 0, v[46:47]
	v_lshlrev_b64 v[60:61], 14, v[0:1]
	v_or_b32_e32 v0, s45, v38
	v_mov_b32_e32 v53, v1
	v_mov_b32_e32 v55, v1
	s_add_i32 s46, s34, 24
	s_add_i32 s48, s34, 28
	s_add_i32 s49, s35, 28
	v_or_b32_e32 v52, s42, v7
	v_or_b32_e32 v54, s44, v7
	v_lshl_add_u64 v[48:49], v[36:37], 0, v[48:49]
	v_lshl_add_u64 v[50:51], v[36:37], 0, v[50:51]
	global_load_dword v79, v[44:45], off
	global_load_dword v80, v[48:49], off
	global_load_dword v81, v[46:47], off
	global_load_dword v82, v[50:51], off
	v_lshlrev_b64 v[46:47], 14, v[0:1]
	v_or_b32_e32 v0, s47, v38
	v_mov_b32_e32 v57, v1
	v_mov_b32_e32 v59, v1
	v_or_b32_e32 v56, s46, v7
	v_or_b32_e32 v58, s48, v7
	v_lshlrev_b64 v[52:53], 14, v[52:53]
	v_lshlrev_b64 v[54:55], 14, v[54:55]
	v_lshl_add_u64 v[44:45], v[36:37], 0, v[60:61]
	v_lshl_add_u64 v[46:47], v[36:37], 0, v[46:47]
	v_lshlrev_b64 v[48:49], 14, v[0:1]
	v_or_b32_e32 v0, s49, v38
	v_lshlrev_b64 v[56:57], 14, v[56:57]
	v_lshlrev_b64 v[58:59], 14, v[58:59]
	v_lshl_add_u64 v[52:53], v[36:37], 0, v[52:53]
	v_lshl_add_u64 v[54:55], v[36:37], 0, v[54:55]
	global_load_dword v83, v[44:45], off
	global_load_dword v84, v[52:53], off
	global_load_dword v85, v[46:47], off
	global_load_dword v86, v[54:55], off
	v_lshl_add_u64 v[44:45], v[36:37], 0, v[48:49]
	v_lshlrev_b64 v[46:47], 14, v[0:1]
	v_lshl_add_u64 v[56:57], v[36:37], 0, v[56:57]
	v_lshl_add_u64 v[58:59], v[36:37], 0, v[58:59]
	v_lshl_add_u64 v[46:47], v[36:37], 0, v[46:47]
	global_load_dword v0, v[44:45], off
	global_load_dword v87, v[56:57], off
	global_load_dword v88, v[46:47], off
	global_load_dword v89, v[58:59], off
	v_or_b32_e32 v46, s34, v3
	v_or_b32_e32 v44, s35, v2
	s_add_i32 s21, s21, 16
	s_add_i32 s20, s20, 16
	s_add_i32 s31, s31, -16
	v_mad_u64_u32 v[44:45], s[10:11], v44, s27, v[6:7]
	v_mad_u64_u32 v[46:47], s[10:11], v46, s27, v[6:7]
	v_or_b32_e32 v45, s36, v3
	v_or_b32_e32 v47, s37, v2
	v_or_b32_e32 v54, s38, v3
	v_or_b32_e32 v52, s39, v2
	v_or_b32_e32 v58, s40, v3
	v_or_b32_e32 v56, s41, v2
	v_or_b32_e32 v62, s42, v3
	v_or_b32_e32 v60, s43, v2
	v_or_b32_e32 v66, s44, v3
	v_or_b32_e32 v64, s45, v2
	v_or_b32_e32 v70, s46, v3
	v_or_b32_e32 v68, s47, v2
	v_or_b32_e32 v74, s48, v3
	v_or_b32_e32 v72, s49, v2
	s_cmp_lg_u32 s31, 0
	v_mad_u64_u32 v[48:49], s[10:11], v47, s27, v[6:7]
	v_mad_u64_u32 v[50:51], s[10:11], v45, s27, v[6:7]
	v_mad_u64_u32 v[52:53], s[10:11], v52, s27, v[6:7]
	v_mad_u64_u32 v[54:55], s[10:11], v54, s27, v[6:7]
	v_mad_u64_u32 v[56:57], s[10:11], v56, s27, v[6:7]
	v_mad_u64_u32 v[58:59], s[10:11], v58, s27, v[6:7]
	v_mad_u64_u32 v[60:61], s[10:11], v60, s27, v[6:7]
	v_mad_u64_u32 v[62:63], s[10:11], v62, s27, v[6:7]
	v_mad_u64_u32 v[64:65], s[10:11], v64, s27, v[6:7]
	v_mad_u64_u32 v[66:67], s[10:11], v66, s27, v[6:7]
	v_mad_u64_u32 v[68:69], s[10:11], v68, s27, v[6:7]
	v_mad_u64_u32 v[70:71], s[10:11], v70, s27, v[6:7]
	v_mad_u64_u32 v[72:73], s[10:11], v72, s27, v[6:7]
	v_mad_u64_u32 v[74:75], s[10:11], v74, s27, v[6:7]
	s_waitcnt vmcnt(15)
	ds_write_b32 v44, v35
	s_waitcnt vmcnt(14)
	ds_write_b32 v46, v76
	s_waitcnt vmcnt(13)
	ds_write_b32 v48, v77
	s_waitcnt vmcnt(12)
	ds_write_b32 v50, v78
	s_waitcnt vmcnt(11)
	ds_write_b32 v52, v79
	s_waitcnt vmcnt(10)
	ds_write_b32 v54, v80
	s_waitcnt vmcnt(9)
	ds_write_b32 v56, v81
	s_waitcnt vmcnt(8)
	ds_write_b32 v58, v82
	s_waitcnt vmcnt(7)
	ds_write_b32 v60, v83
	s_waitcnt vmcnt(6)
	ds_write_b32 v62, v84
	s_waitcnt vmcnt(5)
	ds_write_b32 v64, v85
	s_waitcnt vmcnt(4)
	ds_write_b32 v66, v86
	s_waitcnt vmcnt(3)
	ds_write_b32 v68, v0
	s_waitcnt vmcnt(2)
	ds_write_b32 v70, v87
	s_waitcnt vmcnt(1)
	ds_write_b32 v72, v88
	s_waitcnt vmcnt(0)
	ds_write_b32 v74, v89
	s_cbranch_scc1 .LBB0_41
; #define LAS __attribute__((address_space(3)))
; __device__ __forceinline__ unsigned pk2(float lo, float hi) { return f2bf(lo) | (f2bf(hi) << 16); }
; __device__ __forceinline__ void tr_item(const float* W, int ldw, int c0, bf16* WT, int ldk, int r0, int nblk, int item, LAS float* scr, int lane) {
;     ...
;     asm volatile("s_waitcnt lgkmcnt(0)" ::: "memory");
;     const int c = lane & 7;
; #pragma unroll
;     for (int j = 0; j < 4; ++j) { const int n = (lane >> 3) + 8 * j; const LAS float* s = scr + (8 * c) * 33 + n;
;         v4u o; o.x = pk2(s[0 * 33], s[1 * 33]); o.y = pk2(s[2 * 33], s[3 * 33]); o.z = pk2(s[4 * 33], s[5 * 33]); o.w = pk2(s[6 * 33], s[7 * 33]);
;         *(v4u*)(WT + (size_t)(r0 + n0 + n) * ldk + k0 + 8 * c) = o; }
;     asm volatile("s_waitcnt lgkmcnt(0)" ::: "memory");
; }
	s_waitcnt lgkmcnt(0)
	ds_read2_b32 v[36:37], v40 offset1:8
	ds_read2_b32 v[50:51], v40 offset0:33 offset1:41
	ds_read2_b32 v[52:53], v40 offset0:66 offset1:74
	ds_read2_b32 v[54:55], v40 offset0:99 offset1:107
	ds_read2_b32 v[56:57], v40 offset0:132 offset1:140
	s_mov_b32 s85, 0xffff0000
	s_waitcnt lgkmcnt(4)
	v_bfe_u32 v0, v36, 16, 1
	v_add3_u32 v0, v36, v0, s80
	s_waitcnt lgkmcnt(3)
	v_bfe_u32 v7, v50, 16, 1
	v_lshrrev_b32_e32 v0, 16, v0
	v_add3_u32 v7, v50, v7, s80
	ds_read2_b32 v[58:59], v40 offset0:165 offset1:173
	v_and_or_b32 v44, v7, s85, v0
	s_waitcnt lgkmcnt(3)
	v_bfe_u32 v0, v52, 16, 1
	v_add3_u32 v0, v52, v0, s80
	s_waitcnt lgkmcnt(2)
	v_bfe_u32 v7, v54, 16, 1
	ds_read2_b32 v[60:61], v40 offset0:198 offset1:206
	v_lshrrev_b32_e32 v0, 16, v0
	v_add3_u32 v7, v54, v7, s80
	ds_read2_b32 v[62:63], v40 offset0:231 offset1:239
	v_and_or_b32 v45, v7, s85, v0
	s_waitcnt lgkmcnt(3)
	v_bfe_u32 v0, v56, 16, 1
	v_add3_u32 v0, v56, v0, s80
	s_waitcnt lgkmcnt(2)
	v_bfe_u32 v7, v58, 16, 1
	v_lshrrev_b32_e32 v0, 16, v0
	v_add3_u32 v7, v58, v7, s80
	v_and_or_b32 v46, v7, s85, v0
	s_waitcnt lgkmcnt(1)
	v_bfe_u32 v0, v60, 16, 1
	v_add3_u32 v0, v60, v0, s80
	s_waitcnt lgkmcnt(0)
	v_bfe_u32 v7, v62, 16, 1
	v_lshrrev_b32_e32 v0, 16, v0
	v_add3_u32 v7, v62, v7, s80
	s_lshl_b32 s88, s4, 1
	v_and_or_b32 v47, v7, s85, v0
	v_or_b32_e32 v0, s1, v39
	v_lshl_add_u64 v[48:49], v[14:15], 0, s[88:89]
	v_lshlrev_b32_e32 v0, 11, v0
	v_lshl_add_u64 v[64:65], v[48:49], 0, v[0:1]
	v_bfe_u32 v0, v37, 16, 1
	v_add3_u32 v0, v37, v0, s80
	v_bfe_u32 v7, v51, 16, 1
	v_lshrrev_b32_e32 v0, 16, v0
	v_add3_u32 v7, v51, v7, s80
	global_store_dwordx4 v[64:65], v[44:47], off
	ds_read2_b32 v[36:37], v40 offset0:16 offset1:24
	v_readlane_b32 s81, v254, 55
	v_and_or_b32 v44, v7, s85, v0
	v_bfe_u32 v0, v53, 16, 1
	v_add3_u32 v0, v53, v0, s80
	v_bfe_u32 v7, v55, 16, 1
	v_lshrrev_b32_e32 v0, 16, v0
	v_add3_u32 v7, v55, v7, s80
	v_and_or_b32 v45, v7, s85, v0
	v_bfe_u32 v0, v57, 16, 1
	v_add3_u32 v0, v57, v0, s80
	v_bfe_u32 v7, v59, 16, 1
	v_lshrrev_b32_e32 v0, 16, v0
	v_add3_u32 v7, v59, v7, s80
	v_and_or_b32 v46, v7, s85, v0
	v_bfe_u32 v0, v61, 16, 1
	v_add3_u32 v0, v61, v0, s80
	v_bfe_u32 v7, v63, 16, 1
	v_lshrrev_b32_e32 v0, 16, v0
	v_add3_u32 v7, v63, v7, s80
	v_and_or_b32 v47, v7, s85, v0
	v_or_b32_e32 v0, s1, v41
	v_lshlrev_b32_e32 v0, 11, v0
	v_lshl_add_u64 v[50:51], v[48:49], 0, v[0:1]
	global_store_dwordx4 v[50:51], v[44:47], off
	ds_read2_b32 v[50:51], v40 offset0:49 offset1:57
	ds_read2_b32 v[52:53], v40 offset0:82 offset1:90
	ds_read2_b32 v[54:55], v40 offset0:115 offset1:123
	s_waitcnt lgkmcnt(3)
	v_bfe_u32 v0, v36, 16, 1
	v_add3_u32 v0, v36, v0, s80
	s_waitcnt lgkmcnt(2)
	v_bfe_u32 v7, v50, 16, 1
	ds_read2_b32 v[56:57], v40 offset0:148 offset1:156
	v_lshrrev_b32_e32 v0, 16, v0
	v_add3_u32 v7, v50, v7, s80
	ds_read2_b32 v[58:59], v40 offset0:181 offset1:189
	v_and_or_b32 v44, v7, s85, v0
	s_waitcnt lgkmcnt(3)
	v_bfe_u32 v0, v52, 16, 1
	v_add3_u32 v0, v52, v0, s80
	s_waitcnt lgkmcnt(2)
	v_bfe_u32 v7, v54, 16, 1
	ds_read2_b32 v[60:61], v40 offset0:214 offset1:222
	v_lshrrev_b32_e32 v0, 16, v0
	v_add3_u32 v7, v54, v7, s80
	ds_read2_b32 v[62:63], v40 offset0:247 offset1:255
	v_and_or_b32 v45, v7, s85, v0
	s_waitcnt lgkmcnt(3)
	v_bfe_u32 v0, v56, 16, 1
	v_add3_u32 v0, v56, v0, s80
	s_waitcnt lgkmcnt(2)
	v_bfe_u32 v7, v58, 16, 1
	v_lshrrev_b32_e32 v0, 16, v0
	v_add3_u32 v7, v58, v7, s80
	v_and_or_b32 v46, v7, s85, v0
	s_waitcnt lgkmcnt(1)
	v_bfe_u32 v0, v60, 16, 1
	v_add3_u32 v0, v60, v0, s80
	s_waitcnt lgkmcnt(0)
	v_bfe_u32 v7, v62, 16, 1
	v_lshrrev_b32_e32 v0, 16, v0
	v_add3_u32 v7, v62, v7, s80
	v_and_or_b32 v47, v7, s85, v0
	v_or_b32_e32 v0, s1, v42
	v_lshlrev_b32_e32 v0, 11, v0
	v_lshl_add_u64 v[64:65], v[48:49], 0, v[0:1]
	v_bfe_u32 v0, v37, 16, 1
	v_add3_u32 v0, v37, v0, s80
	v_bfe_u32 v7, v51, 16, 1
	v_lshrrev_b32_e32 v0, 16, v0
	v_add3_u32 v7, v51, v7, s80
	global_store_dwordx4 v[64:65], v[44:47], off
	s_nop 1
	v_and_or_b32 v44, v7, s85, v0
	v_bfe_u32 v0, v53, 16, 1
	v_add3_u32 v0, v53, v0, s80
	v_bfe_u32 v7, v55, 16, 1
	v_lshrrev_b32_e32 v0, 16, v0
	v_add3_u32 v7, v55, v7, s80
	v_and_or_b32 v45, v7, s85, v0
	v_bfe_u32 v0, v57, 16, 1
	v_add3_u32 v0, v57, v0, s80
	v_bfe_u32 v7, v59, 16, 1
	v_lshrrev_b32_e32 v0, 16, v0
	v_add3_u32 v7, v59, v7, s80
	v_and_or_b32 v46, v7, s85, v0
	v_bfe_u32 v0, v61, 16, 1
	v_add3_u32 v0, v61, v0, s80
	v_bfe_u32 v7, v63, 16, 1
	v_lshrrev_b32_e32 v0, 16, v0
	v_add3_u32 v7, v63, v7, s80
	v_and_or_b32 v47, v7, s85, v0
	v_or_b32_e32 v0, s1, v43
	v_lshlrev_b32_e32 v0, 11, v0
	v_lshl_add_u64 v[36:37], v[48:49], 0, v[0:1]
	global_store_dwordx4 v[36:37], v[44:47], off
.LBB0_43:
	s_mov_b64 s[20:21], 0

; #define LAS __attribute__((address_space(3)))
; __device__ __forceinline__ void tr_item(const float* W, int ldw, int c0, bf16* WT, int ldk, int r0, int nblk, int item, LAS float* scr, int lane) {
;     const int kb = item / nblk, nb = item % nblk, k0 = 64 * kb, n0 = 32 * nb;
; #pragma unroll 8
;     for (int i = 0; i < 32; ++i) { const int kk = 2 * i + (lane >> 5); scr[kk * 33 + (lane & 31)] = W[(size_t)(k0 + kk) * ldw + c0 + n0 + (lane & 31)]; }
.LBB0_46:
	s_lshl_b32 s34, s20, 1
	s_lshl_b32 s35, s21, 1
	v_or_b32_e32 v0, s35, v38
	s_add_i32 s36, s34, 4
	s_add_i32 s37, s35, 4
	v_mov_b32_e32 v47, v1
	s_add_i32 s39, s35, 8
	v_lshlrev_b64 v[60:61], 12, v[0:1]
	v_or_b32_e32 v46, s36, v7
	v_or_b32_e32 v0, s37, v38
	v_mov_b32_e32 v45, v1
	v_or_b32_e32 v44, s34, v7
	s_add_i32 s41, s35, 12
	v_lshlrev_b64 v[46:47], 12, v[46:47]
	v_lshlrev_b64 v[62:63], 12, v[0:1]
	v_or_b32_e32 v0, s39, v38
	s_add_i32 s38, s34, 8
	s_add_i32 s40, s34, 12
	s_add_i32 s43, s35, 16
	v_lshlrev_b64 v[44:45], 12, v[44:45]
	v_lshl_add_u64 v[60:61], v[36:37], 0, v[60:61]
	v_lshl_add_u64 v[46:47], v[36:37], 0, v[46:47]
	v_lshlrev_b64 v[64:65], 12, v[0:1]
	v_or_b32_e32 v0, s41, v38
	v_mov_b32_e32 v49, v1
	v_mov_b32_e32 v51, v1
	s_add_i32 s45, s35, 20
	v_or_b32_e32 v48, s38, v7
	v_or_b32_e32 v50, s40, v7
	v_lshl_add_u64 v[44:45], v[36:37], 0, v[44:45]
	v_lshl_add_u64 v[62:63], v[36:37], 0, v[62:63]
	global_load_dword v35, v[60:61], off
	global_load_dword v76, v[44:45], off
	global_load_dword v77, v[62:63], off
	global_load_dword v78, v[46:47], off
	v_lshlrev_b64 v[46:47], 12, v[0:1]
	v_or_b32_e32 v0, s43, v38
	s_add_i32 s42, s34, 16
	s_add_i32 s44, s34, 20
	s_add_i32 s47, s35, 24
	v_lshlrev_b64 v[48:49], 12, v[48:49]
	v_lshlrev_b64 v[50:51], 12, v[50:51]
	v_lshl_add_u64 v[44:45], v[36:37], 0, v[64:65]
	v_lshl_add_u64 v[46:47], v[36:37], 0, v[46:47]
	v_lshlrev_b64 v[60:61], 12, v[0:1]
	v_or_b32_e32 v0, s45, v38
	v_mov_b32_e32 v53, v1
	v_mov_b32_e32 v55, v1
	s_add_i32 s46, s34, 24
	s_add_i32 s48, s34, 28
	s_add_i32 s49, s35, 28
	v_or_b32_e32 v52, s42, v7
	v_or_b32_e32 v54, s44, v7
	v_lshl_add_u64 v[48:49], v[36:37], 0, v[48:49]
	v_lshl_add_u64 v[50:51], v[36:37], 0, v[50:51]
	global_load_dword v79, v[44:45], off
	global_load_dword v80, v[48:49], off
	global_load_dword v81, v[46:47], off
	global_load_dword v82, v[50:51], off
	v_lshlrev_b64 v[46:47], 12, v[0:1]
	v_or_b32_e32 v0, s47, v38
	v_mov_b32_e32 v57, v1
	v_mov_b32_e32 v59, v1
	v_or_b32_e32 v56, s46, v7
	v_or_b32_e32 v58, s48, v7
	v_lshlrev_b64 v[52:53], 12, v[52:53]
	v_lshlrev_b64 v[54:55], 12, v[54:55]
	v_lshl_add_u64 v[44:45], v[36:37], 0, v[60:61]
	v_lshl_add_u64 v[46:47], v[36:37], 0, v[46:47]
	v_lshlrev_b64 v[48:49], 12, v[0:1]
	v_or_b32_e32 v0, s49, v38
	v_lshlrev_b64 v[56:57], 12, v[56:57]
	v_lshlrev_b64 v[58:59], 12, v[58:59]
	v_lshl_add_u64 v[52:53], v[36:37], 0, v[52:53]
	v_lshl_add_u64 v[54:55], v[36:37], 0, v[54:55]
	global_load_dword v83, v[44:45], off
	global_load_dword v84, v[52:53], off
	global_load_dword v85, v[46:47], off
	global_load_dword v86, v[54:55], off
	v_lshl_add_u64 v[44:45], v[36:37], 0, v[48:49]
	v_lshlrev_b64 v[46:47], 12, v[0:1]
	v_lshl_add_u64 v[56:57], v[36:37], 0, v[56:57]
	v_lshl_add_u64 v[58:59], v[36:37], 0, v[58:59]
	v_lshl_add_u64 v[46:47], v[36:37], 0, v[46:47]
	global_load_dword v0, v[44:45], off
	global_load_dword v87, v[56:57], off
	global_load_dword v88, v[46:47], off
	global_load_dword v89, v[58:59], off
	v_or_b32_e32 v46, s34, v3
	v_or_b32_e32 v44, s35, v2
	s_add_i32 s21, s21, 16
	s_add_i32 s20, s20, 16
	s_add_i32 s31, s31, -16
	v_mad_u64_u32 v[44:45], s[10:11], v44, s27, v[6:7]
	v_mad_u64_u32 v[46:47], s[10:11], v46, s27, v[6:7]
	v_or_b32_e32 v45, s36, v3
	v_or_b32_e32 v47, s37, v2
	v_or_b32_e32 v54, s38, v3
	v_or_b32_e32 v52, s39, v2
	v_or_b32_e32 v58, s40, v3
	v_or_b32_e32 v56, s41, v2
	v_or_b32_e32 v62, s42, v3
	v_or_b32_e32 v60, s43, v2
	v_or_b32_e32 v66, s44, v3
	v_or_b32_e32 v64, s45, v2
	v_or_b32_e32 v70, s46, v3
	v_or_b32_e32 v68, s47, v2
	v_or_b32_e32 v74, s48, v3
	v_or_b32_e32 v72, s49, v2
	s_cmp_lg_u32 s31, 0
	v_mad_u64_u32 v[48:49], s[10:11], v47, s27, v[6:7]
	v_mad_u64_u32 v[50:51], s[10:11], v45, s27, v[6:7]
	v_mad_u64_u32 v[52:53], s[10:11], v52, s27, v[6:7]
	v_mad_u64_u32 v[54:55], s[10:11], v54, s27, v[6:7]
	v_mad_u64_u32 v[56:57], s[10:11], v56, s27, v[6:7]
	v_mad_u64_u32 v[58:59], s[10:11], v58, s27, v[6:7]
	v_mad_u64_u32 v[60:61], s[10:11], v60, s27, v[6:7]
	v_mad_u64_u32 v[62:63], s[10:11], v62, s27, v[6:7]
	v_mad_u64_u32 v[64:65], s[10:11], v64, s27, v[6:7]
	v_mad_u64_u32 v[66:67], s[10:11], v66, s27, v[6:7]
	v_mad_u64_u32 v[68:69], s[10:11], v68, s27, v[6:7]
	v_mad_u64_u32 v[70:71], s[10:11], v70, s27, v[6:7]
	v_mad_u64_u32 v[72:73], s[10:11], v72, s27, v[6:7]
	v_mad_u64_u32 v[74:75], s[10:11], v74, s27, v[6:7]
	s_waitcnt vmcnt(15)
	ds_write_b32 v44, v35
	s_waitcnt vmcnt(14)
	ds_write_b32 v46, v76
	s_waitcnt vmcnt(13)
	ds_write_b32 v48, v77
	s_waitcnt vmcnt(12)
	ds_write_b32 v50, v78
	s_waitcnt vmcnt(11)
	ds_write_b32 v52, v79
	s_waitcnt vmcnt(10)
	ds_write_b32 v54, v80
	s_waitcnt vmcnt(9)
	ds_write_b32 v56, v81
	s_waitcnt vmcnt(8)
	ds_write_b32 v58, v82
	s_waitcnt vmcnt(7)
	ds_write_b32 v60, v83
	s_waitcnt vmcnt(6)
	ds_write_b32 v62, v84
	s_waitcnt vmcnt(5)
	ds_write_b32 v64, v85
	s_waitcnt vmcnt(4)
	ds_write_b32 v66, v86
	s_waitcnt vmcnt(3)
	ds_write_b32 v68, v0
	s_waitcnt vmcnt(2)
	ds_write_b32 v70, v87
	s_waitcnt vmcnt(1)
	ds_write_b32 v72, v88
	s_waitcnt vmcnt(0)
	ds_write_b32 v74, v89
	s_cbranch_scc1 .LBB0_46
; #define LAS __attribute__((address_space(3)))
; __device__ __forceinline__ unsigned pk2(float lo, float hi) { return f2bf(lo) | (f2bf(hi) << 16); }
; __device__ __forceinline__ void tr_item(const float* W, int ldw, int c0, bf16* WT, int ldk, int r0, int nblk, int item, LAS float* scr, int lane) {
;     ...
;     asm volatile("s_waitcnt lgkmcnt(0)" ::: "memory");
;     const int c = lane & 7;
; #pragma unroll
;     for (int j = 0; j < 4; ++j) { const int n = (lane >> 3) + 8 * j; const LAS float* s = scr + (8 * c) * 33 + n;
;         v4u o; o.x = pk2(s[0 * 33], s[1 * 33]); o.y = pk2(s[2 * 33], s[3 * 33]); o.z = pk2(s[4 * 33], s[5 * 33]); o.w = pk2(s[6 * 33], s[7 * 33]);
;         *(v4u*)(WT + (size_t)(r0 + n0 + n) * ldk + k0 + 8 * c) = o; }
;     asm volatile("s_waitcnt lgkmcnt(0)" ::: "memory");
; }
	s_waitcnt lgkmcnt(0)
	ds_read2_b32 v[36:37], v40 offset1:8
	ds_read2_b32 v[50:51], v40 offset0:33 offset1:41
	ds_read2_b32 v[52:53], v40 offset0:66 offset1:74
	ds_read2_b32 v[54:55], v40 offset0:99 offset1:107
	ds_read2_b32 v[56:57], v40 offset0:132 offset1:140
	s_mov_b32 s85, 0xffff0000
	s_waitcnt lgkmcnt(4)
	v_bfe_u32 v0, v36, 16, 1
	v_add3_u32 v0, v36, v0, s80
	s_waitcnt lgkmcnt(3)
	v_bfe_u32 v7, v50, 16, 1
	v_lshrrev_b32_e32 v0, 16, v0
	v_add3_u32 v7, v50, v7, s80
	ds_read2_b32 v[58:59], v40 offset0:165 offset1:173
	v_and_or_b32 v44, v7, s85, v0
	s_waitcnt lgkmcnt(3)
	v_bfe_u32 v0, v52, 16, 1
	v_add3_u32 v0, v52, v0, s80
	s_waitcnt lgkmcnt(2)
	v_bfe_u32 v7, v54, 16, 1
	ds_read2_b32 v[60:61], v40 offset0:198 offset1:206
	v_lshrrev_b32_e32 v0, 16, v0
	v_add3_u32 v7, v54, v7, s80
	ds_read2_b32 v[62:63], v40 offset0:231 offset1:239
	v_and_or_b32 v45, v7, s85, v0
	s_waitcnt lgkmcnt(3)
	v_bfe_u32 v0, v56, 16, 1
	v_add3_u32 v0, v56, v0, s80
	s_waitcnt lgkmcnt(2)
	v_bfe_u32 v7, v58, 16, 1
	v_lshrrev_b32_e32 v0, 16, v0
	v_add3_u32 v7, v58, v7, s80
	v_and_or_b32 v46, v7, s85, v0
	s_waitcnt lgkmcnt(1)
	v_bfe_u32 v0, v60, 16, 1
	v_add3_u32 v0, v60, v0, s80
	s_waitcnt lgkmcnt(0)
	v_bfe_u32 v7, v62, 16, 1
	v_lshrrev_b32_e32 v0, 16, v0
	v_add3_u32 v7, v62, v7, s80
	s_lshl_b32 s88, s4, 1
	v_and_or_b32 v47, v7, s85, v0
	v_or_b32_e32 v0, s1, v39
	v_lshl_add_u64 v[48:49], v[18:19], 0, s[88:89]
	v_lshlrev_b32_e32 v0, 11, v0
	v_lshl_add_u64 v[64:65], v[48:49], 0, v[0:1]
	v_bfe_u32 v0, v37, 16, 1
	v_add3_u32 v0, v37, v0, s80
	v_bfe_u32 v7, v51, 16, 1
	v_lshrrev_b32_e32 v0, 16, v0
	v_add3_u32 v7, v51, v7, s80
	global_store_dwordx4 v[64:65], v[44:47], off
	ds_read2_b32 v[36:37], v40 offset0:16 offset1:24
	v_readlane_b32 s81, v254, 55
	v_and_or_b32 v44, v7, s85, v0
	v_bfe_u32 v0, v53, 16, 1
	v_add3_u32 v0, v53, v0, s80
	v_bfe_u32 v7, v55, 16, 1
	v_lshrrev_b32_e32 v0, 16, v0
	v_add3_u32 v7, v55, v7, s80
	v_and_or_b32 v45, v7, s85, v0
	v_bfe_u32 v0, v57, 16, 1
	v_add3_u32 v0, v57, v0, s80
	v_bfe_u32 v7, v59, 16, 1
	v_lshrrev_b32_e32 v0, 16, v0
	v_add3_u32 v7, v59, v7, s80
	v_and_or_b32 v46, v7, s85, v0
	v_bfe_u32 v0, v61, 16, 1
	v_add3_u32 v0, v61, v0, s80
	v_bfe_u32 v7, v63, 16, 1
	v_lshrrev_b32_e32 v0, 16, v0
	v_add3_u32 v7, v63, v7, s80
	v_and_or_b32 v47, v7, s85, v0
	v_or_b32_e32 v0, s1, v41
	v_lshlrev_b32_e32 v0, 11, v0
	v_lshl_add_u64 v[50:51], v[48:49], 0, v[0:1]
	global_store_dwordx4 v[50:51], v[44:47], off
	ds_read2_b32 v[50:51], v40 offset0:49 offset1:57
	ds_read2_b32 v[52:53], v40 offset0:82 offset1:90
	ds_read2_b32 v[54:55], v40 offset0:115 offset1:123
	s_waitcnt lgkmcnt(3)
	v_bfe_u32 v0, v36, 16, 1
	v_add3_u32 v0, v36, v0, s80
	s_waitcnt lgkmcnt(2)
	v_bfe_u32 v7, v50, 16, 1
	ds_read2_b32 v[56:57], v40 offset0:148 offset1:156
	v_lshrrev_b32_e32 v0, 16, v0
	v_add3_u32 v7, v50, v7, s80
	ds_read2_b32 v[58:59], v40 offset0:181 offset1:189
	v_and_or_b32 v44, v7, s85, v0
	s_waitcnt lgkmcnt(3)
	v_bfe_u32 v0, v52, 16, 1
	v_add3_u32 v0, v52, v0, s80
	s_waitcnt lgkmcnt(2)
	v_bfe_u32 v7, v54, 16, 1
	ds_read2_b32 v[60:61], v40 offset0:214 offset1:222
	v_lshrrev_b32_e32 v0, 16, v0
	v_add3_u32 v7, v54, v7, s80
	ds_read2_b32 v[62:63], v40 offset0:247 offset1:255
	v_and_or_b32 v45, v7, s85, v0
	s_waitcnt lgkmcnt(3)
	v_bfe_u32 v0, v56, 16, 1
	v_add3_u32 v0, v56, v0, s80
	s_waitcnt lgkmcnt(2)
	v_bfe_u32 v7, v58, 16, 1
	v_lshrrev_b32_e32 v0, 16, v0
	v_add3_u32 v7, v58, v7, s80
	v_and_or_b32 v46, v7, s85, v0
	s_waitcnt lgkmcnt(1)
	v_bfe_u32 v0, v60, 16, 1
	v_add3_u32 v0, v60, v0, s80
	s_waitcnt lgkmcnt(0)
	v_bfe_u32 v7, v62, 16, 1
	v_lshrrev_b32_e32 v0, 16, v0
	v_add3_u32 v7, v62, v7, s80
	v_and_or_b32 v47, v7, s85, v0
	v_or_b32_e32 v0, s1, v42
	v_lshlrev_b32_e32 v0, 11, v0
	v_lshl_add_u64 v[64:65], v[48:49], 0, v[0:1]
	v_bfe_u32 v0, v37, 16, 1
	v_add3_u32 v0, v37, v0, s80
	v_bfe_u32 v7, v51, 16, 1
	v_lshrrev_b32_e32 v0, 16, v0
	v_add3_u32 v7, v51, v7, s80
	global_store_dwordx4 v[64:65], v[44:47], off
	s_nop 1
	v_and_or_b32 v44, v7, s85, v0
	v_bfe_u32 v0, v53, 16, 1
	v_add3_u32 v0, v53, v0, s80
	v_bfe_u32 v7, v55, 16, 1
	v_lshrrev_b32_e32 v0, 16, v0
	v_add3_u32 v7, v55, v7, s80
	v_and_or_b32 v45, v7, s85, v0
	v_bfe_u32 v0, v57, 16, 1
	v_add3_u32 v0, v57, v0, s80
	v_bfe_u32 v7, v59, 16, 1
	v_lshrrev_b32_e32 v0, 16, v0
	v_add3_u32 v7, v59, v7, s80
	v_and_or_b32 v46, v7, s85, v0
	v_bfe_u32 v0, v61, 16, 1
	v_add3_u32 v0, v61, v0, s80
	v_bfe_u32 v7, v63, 16, 1
	v_lshrrev_b32_e32 v0, 16, v0
	v_add3_u32 v7, v63, v7, s80
	v_and_or_b32 v47, v7, s85, v0
	v_or_b32_e32 v0, s1, v43
	v_lshlrev_b32_e32 v0, 11, v0
	v_lshl_add_u64 v[36:37], v[48:49], 0, v[0:1]
	global_store_dwordx4 v[36:37], v[44:47], off
.LBB0_48:
	s_mov_b64 s[20:21], 0

; __device__ __forceinline__ void tr_item(const float* W, int ldw, int c0, bf16* WT, int ldk, int r0, int nblk, int item, LAS float* scr, int lane) {
;     const int kb = item / nblk, nb = item % nblk, k0 = 64 * kb, n0 = 32 * nb;
; #pragma unroll 8
;     for (int i = 0; i < 32; ++i) { const int kk = 2 * i + (lane >> 5); scr[kk * 33 + (lane & 31)] = W[(size_t)(k0 + kk) * ldw + c0 + n0 + (lane & 31)]; }
.LBB0_51:
	s_lshl_b32 s34, s20, 1
	s_lshl_b32 s35, s21, 1
	v_or_b32_e32 v0, s35, v38
	s_add_i32 s36, s34, 4
	s_add_i32 s37, s35, 4
	v_mov_b32_e32 v47, v1
	s_add_i32 s39, s35, 8
	v_lshlrev_b64 v[60:61], 12, v[0:1]
	v_or_b32_e32 v46, s36, v7
	v_or_b32_e32 v0, s37, v38
	v_mov_b32_e32 v45, v1
	v_or_b32_e32 v44, s34, v7
	s_add_i32 s41, s35, 12
	v_lshlrev_b64 v[46:47], 12, v[46:47]
	v_lshlrev_b64 v[62:63], 12, v[0:1]
	v_or_b32_e32 v0, s39, v38
	s_add_i32 s38, s34, 8
	s_add_i32 s40, s34, 12
	s_add_i32 s43, s35, 16
	v_lshlrev_b64 v[44:45], 12, v[44:45]
	v_lshl_add_u64 v[60:61], v[36:37], 0, v[60:61]
	v_lshl_add_u64 v[46:47], v[36:37], 0, v[46:47]
	v_lshlrev_b64 v[64:65], 12, v[0:1]
	v_or_b32_e32 v0, s41, v38
	v_mov_b32_e32 v49, v1
	v_mov_b32_e32 v51, v1
	s_add_i32 s45, s35, 20
	v_or_b32_e32 v48, s38, v7
	v_or_b32_e32 v50, s40, v7
	v_lshl_add_u64 v[44:45], v[36:37], 0, v[44:45]
	v_lshl_add_u64 v[62:63], v[36:37], 0, v[62:63]
	global_load_dword v35, v[60:61], off
	global_load_dword v76, v[44:45], off
	global_load_dword v77, v[62:63], off
	global_load_dword v78, v[46:47], off
	v_lshlrev_b64 v[46:47], 12, v[0:1]
	v_or_b32_e32 v0, s43, v38
	s_add_i32 s42, s34, 16
	s_add_i32 s44, s34, 20
	s_add_i32 s47, s35, 24
	v_lshlrev_b64 v[48:49], 12, v[48:49]
	v_lshlrev_b64 v[50:51], 12, v[50:51]
	v_lshl_add_u64 v[44:45], v[36:37], 0, v[64:65]
	v_lshl_add_u64 v[46:47], v[36:37], 0, v[46:47]
	v_lshlrev_b64 v[60:61], 12, v[0:1]
	v_or_b32_e32 v0, s45, v38
	v_mov_b32_e32 v53, v1
	v_mov_b32_e32 v55, v1
	s_add_i32 s46, s34, 24
	s_add_i32 s48, s34, 28
	s_add_i32 s49, s35, 28
	v_or_b32_e32 v52, s42, v7
	v_or_b32_e32 v54, s44, v7
	v_lshl_add_u64 v[48:49], v[36:37], 0, v[48:49]
	v_lshl_add_u64 v[50:51], v[36:37], 0, v[50:51]
	global_load_dword v79, v[44:45], off
	global_load_dword v80, v[48:49], off
	global_load_dword v81, v[46:47], off
	global_load_dword v82, v[50:51], off
	v_lshlrev_b64 v[46:47], 12, v[0:1]
	v_or_b32_e32 v0, s47, v38
	v_mov_b32_e32 v57, v1
	v_mov_b32_e32 v59, v1
	v_or_b32_e32 v56, s46, v7
	v_or_b32_e32 v58, s48, v7
	v_lshlrev_b64 v[52:53], 12, v[52:53]
	v_lshlrev_b64 v[54:55], 12, v[54:55]
	v_lshl_add_u64 v[44:45], v[36:37], 0, v[60:61]
	v_lshl_add_u64 v[46:47], v[36:37], 0, v[46:47]
	v_lshlrev_b64 v[48:49], 12, v[0:1]
	v_or_b32_e32 v0, s49, v38
	v_lshlrev_b64 v[56:57], 12, v[56:57]
	v_lshlrev_b64 v[58:59], 12, v[58:59]
	v_lshl_add_u64 v[52:53], v[36:37], 0, v[52:53]
	v_lshl_add_u64 v[54:55], v[36:37], 0, v[54:55]
	global_load_dword v83, v[44:45], off
	global_load_dword v84, v[52:53], off
	global_load_dword v85, v[46:47], off
	global_load_dword v86, v[54:55], off
	v_lshl_add_u64 v[44:45], v[36:37], 0, v[48:49]
	v_lshlrev_b64 v[46:47], 12, v[0:1]
	v_lshl_add_u64 v[56:57], v[36:37], 0, v[56:57]
	v_lshl_add_u64 v[58:59], v[36:37], 0, v[58:59]
	v_lshl_add_u64 v[46:47], v[36:37], 0, v[46:47]
	global_load_dword v0, v[44:45], off
	global_load_dword v87, v[56:57], off
	global_load_dword v88, v[46:47], off
	global_load_dword v89, v[58:59], off
	v_or_b32_e32 v46, s34, v3
	v_or_b32_e32 v44, s35, v2
	s_add_i32 s21, s21, 16
	s_add_i32 s20, s20, 16
	s_add_i32 s31, s31, -16
	v_mad_u64_u32 v[44:45], s[10:11], v44, s27, v[6:7]
	v_mad_u64_u32 v[46:47], s[10:11], v46, s27, v[6:7]
	v_or_b32_e32 v45, s36, v3
	v_or_b32_e32 v47, s37, v2
	v_or_b32_e32 v54, s38, v3
	v_or_b32_e32 v52, s39, v2
	v_or_b32_e32 v58, s40, v3
	v_or_b32_e32 v56, s41, v2
	v_or_b32_e32 v62, s42, v3
	v_or_b32_e32 v60, s43, v2
	v_or_b32_e32 v66, s44, v3
	v_or_b32_e32 v64, s45, v2
	v_or_b32_e32 v70, s46, v3
	v_or_b32_e32 v68, s47, v2
	v_or_b32_e32 v74, s48, v3
	v_or_b32_e32 v72, s49, v2
	s_cmp_lg_u32 s31, 0
	v_mad_u64_u32 v[48:49], s[10:11], v47, s27, v[6:7]
	v_mad_u64_u32 v[50:51], s[10:11], v45, s27, v[6:7]
	v_mad_u64_u32 v[52:53], s[10:11], v52, s27, v[6:7]
	v_mad_u64_u32 v[54:55], s[10:11], v54, s27, v[6:7]
	v_mad_u64_u32 v[56:57], s[10:11], v56, s27, v[6:7]
	v_mad_u64_u32 v[58:59], s[10:11], v58, s27, v[6:7]
	v_mad_u64_u32 v[60:61], s[10:11], v60, s27, v[6:7]
	v_mad_u64_u32 v[62:63], s[10:11], v62, s27, v[6:7]
	v_mad_u64_u32 v[64:65], s[10:11], v64, s27, v[6:7]
	v_mad_u64_u32 v[66:67], s[10:11], v66, s27, v[6:7]
	v_mad_u64_u32 v[68:69], s[10:11], v68, s27, v[6:7]
	v_mad_u64_u32 v[70:71], s[10:11], v70, s27, v[6:7]
	v_mad_u64_u32 v[72:73], s[10:11], v72, s27, v[6:7]
	v_mad_u64_u32 v[74:75], s[10:11], v74, s27, v[6:7]
	s_waitcnt vmcnt(15)
	ds_write_b32 v44, v35
	s_waitcnt vmcnt(14)
	ds_write_b32 v46, v76
	s_waitcnt vmcnt(13)
	ds_write_b32 v48, v77
	s_waitcnt vmcnt(12)
	ds_write_b32 v50, v78
	s_waitcnt vmcnt(11)
	ds_write_b32 v52, v79
	s_waitcnt vmcnt(10)
	ds_write_b32 v54, v80
	s_waitcnt vmcnt(9)
	ds_write_b32 v56, v81
	s_waitcnt vmcnt(8)
	ds_write_b32 v58, v82
	s_waitcnt vmcnt(7)
	ds_write_b32 v60, v83
	s_waitcnt vmcnt(6)
	ds_write_b32 v62, v84
	s_waitcnt vmcnt(5)
	ds_write_b32 v64, v85
	s_waitcnt vmcnt(4)
	ds_write_b32 v66, v86
	s_waitcnt vmcnt(3)
	ds_write_b32 v68, v0
	s_waitcnt vmcnt(2)
	ds_write_b32 v70, v87
	s_waitcnt vmcnt(1)
	ds_write_b32 v72, v88
	s_waitcnt vmcnt(0)
	ds_write_b32 v74, v89
	s_cbranch_scc1 .LBB0_51
; #define LAS __attribute__((address_space(3)))
; __device__ __forceinline__ unsigned pk2(float lo, float hi) { return f2bf(lo) | (f2bf(hi) << 16); }
; __device__ __forceinline__ void tr_item(const float* W, int ldw, int c0, bf16* WT, int ldk, int r0, int nblk, int item, LAS float* scr, int lane) {
;     ...
;     asm volatile("s_waitcnt lgkmcnt(0)" ::: "memory");
;     const int c = lane & 7;
; #pragma unroll
;     for (int j = 0; j < 4; ++j) { const int n = (lane >> 3) + 8 * j; const LAS float* s = scr + (8 * c) * 33 + n;
;         v4u o; o.x = pk2(s[0 * 33], s[1 * 33]); o.y = pk2(s[2 * 33], s[3 * 33]); o.z = pk2(s[4 * 33], s[5 * 33]); o.w = pk2(s[6 * 33], s[7 * 33]);
;         *(v4u*)(WT + (size_t)(r0 + n0 + n) * ldk + k0 + 8 * c) = o; }
;     asm volatile("s_waitcnt lgkmcnt(0)" ::: "memory");
; __device__ __forceinline__ void phase_convert_weights(const Ctx& C0, const Params& p, int l) {
;     ...
;         if (r < I_B) { const int n = r / 256, s = r % 256; tr_item(w_br + (size_t)n * 512 * 1024, 1024, 0, W + WO_B + (size_t)n * 1024 * 512, 512, 0, 32, s, scr, C.lane); continue; } r -= I_B;
	s_waitcnt lgkmcnt(0)
	s_lshl_b64 s[10:11], s[88:89], 20
	v_readlane_b32 s13, v251, 39
	ds_read2_b32 v[36:37], v40 offset1:8
	s_add_u32 s10, s13, s10
	v_readlane_b32 s13, v251, 40
	ds_read2_b32 v[50:51], v40 offset0:33 offset1:41
	s_addc_u32 s11, s13, s11
	s_lshl_b32 s4, s4, 1
	s_add_u32 s10, s10, s4
	ds_read2_b32 v[52:53], v40 offset0:66 offset1:74
	s_addc_u32 s11, s11, 0
	v_lshlrev_b32_e32 v0, 1, v8
	ds_read2_b32 v[54:55], v40 offset0:99 offset1:107
	v_lshl_add_u64 v[48:49], s[10:11], 0, v[0:1]
	s_waitcnt lgkmcnt(3)
	v_bfe_u32 v0, v36, 16, 1
	v_add3_u32 v0, v36, v0, s80
	s_waitcnt lgkmcnt(2)
	v_bfe_u32 v7, v50, 16, 1
	ds_read2_b32 v[56:57], v40 offset0:132 offset1:140
	v_lshrrev_b32_e32 v0, 16, v0
	v_add3_u32 v7, v50, v7, s80
	s_mov_b32 s85, 0xffff0000
	ds_read2_b32 v[58:59], v40 offset0:165 offset1:173
	v_and_or_b32 v44, v7, s85, v0
	s_waitcnt lgkmcnt(3)
	v_bfe_u32 v0, v52, 16, 1
	v_add3_u32 v0, v52, v0, s80
	s_waitcnt lgkmcnt(2)
	v_bfe_u32 v7, v54, 16, 1
	ds_read2_b32 v[60:61], v40 offset0:198 offset1:206
	v_lshrrev_b32_e32 v0, 16, v0
	v_add3_u32 v7, v54, v7, s80
	ds_read2_b32 v[62:63], v40 offset0:231 offset1:239
	v_and_or_b32 v45, v7, s85, v0
	s_waitcnt lgkmcnt(3)
	v_bfe_u32 v0, v56, 16, 1
	v_add3_u32 v0, v56, v0, s80
	s_waitcnt lgkmcnt(2)
	v_bfe_u32 v7, v58, 16, 1
	v_lshrrev_b32_e32 v0, 16, v0
	v_add3_u32 v7, v58, v7, s80
	v_and_or_b32 v46, v7, s85, v0
	s_waitcnt lgkmcnt(1)
	v_bfe_u32 v0, v60, 16, 1
	v_add3_u32 v0, v60, v0, s80
	s_waitcnt lgkmcnt(0)
	v_bfe_u32 v7, v62, 16, 1
	v_lshrrev_b32_e32 v0, 16, v0
	v_add3_u32 v7, v62, v7, s80
	v_and_or_b32 v47, v7, s85, v0
	v_or_b32_e32 v0, s1, v39
	v_lshlrev_b32_e32 v0, 10, v0
	v_lshl_add_u64 v[64:65], v[48:49], 0, v[0:1]
	v_bfe_u32 v0, v37, 16, 1
	v_add3_u32 v0, v37, v0, s80
	v_bfe_u32 v7, v51, 16, 1
	v_lshrrev_b32_e32 v0, 16, v0
	v_add3_u32 v7, v51, v7, s80
	global_store_dwordx4 v[64:65], v[44:47], off
	ds_read2_b32 v[36:37], v40 offset0:16 offset1:24
	v_readlane_b32 s81, v254, 55
	v_and_or_b32 v44, v7, s85, v0
	v_bfe_u32 v0, v53, 16, 1
	v_add3_u32 v0, v53, v0, s80
	v_bfe_u32 v7, v55, 16, 1
	v_lshrrev_b32_e32 v0, 16, v0
	v_add3_u32 v7, v55, v7, s80
	v_and_or_b32 v45, v7, s85, v0
	v_bfe_u32 v0, v57, 16, 1
	v_add3_u32 v0, v57, v0, s80
	v_bfe_u32 v7, v59, 16, 1
	v_lshrrev_b32_e32 v0, 16, v0
	v_add3_u32 v7, v59, v7, s80
	v_and_or_b32 v46, v7, s85, v0
	v_bfe_u32 v0, v61, 16, 1
	v_add3_u32 v0, v61, v0, s80
	v_bfe_u32 v7, v63, 16, 1
	v_lshrrev_b32_e32 v0, 16, v0
	v_add3_u32 v7, v63, v7, s80
	v_and_or_b32 v47, v7, s85, v0
	v_or_b32_e32 v0, s1, v41
	v_lshlrev_b32_e32 v0, 10, v0
	v_lshl_add_u64 v[50:51], v[48:49], 0, v[0:1]
	global_store_dwordx4 v[50:51], v[44:47], off
	ds_read2_b32 v[50:51], v40 offset0:49 offset1:57
	ds_read2_b32 v[52:53], v40 offset0:82 offset1:90
	ds_read2_b32 v[54:55], v40 offset0:115 offset1:123
	s_waitcnt lgkmcnt(3)
	v_bfe_u32 v0, v36, 16, 1
	v_add3_u32 v0, v36, v0, s80
	s_waitcnt lgkmcnt(2)
	v_bfe_u32 v7, v50, 16, 1
	ds_read2_b32 v[56:57], v40 offset0:148 offset1:156
	v_lshrrev_b32_e32 v0, 16, v0
	v_add3_u32 v7, v50, v7, s80
	ds_read2_b32 v[58:59], v40 offset0:181 offset1:189
	v_and_or_b32 v44, v7, s85, v0
	s_waitcnt lgkmcnt(3)
	v_bfe_u32 v0, v52, 16, 1
	v_add3_u32 v0, v52, v0, s80
	s_waitcnt lgkmcnt(2)
	v_bfe_u32 v7, v54, 16, 1
	ds_read2_b32 v[60:61], v40 offset0:214 offset1:222
	v_lshrrev_b32_e32 v0, 16, v0
	v_add3_u32 v7, v54, v7, s80
	ds_read2_b32 v[62:63], v40 offset0:247 offset1:255
	v_and_or_b32 v45, v7, s85, v0
	s_waitcnt lgkmcnt(3)
	v_bfe_u32 v0, v56, 16, 1
	v_add3_u32 v0, v56, v0, s80
	s_waitcnt lgkmcnt(2)
	v_bfe_u32 v7, v58, 16, 1
	v_lshrrev_b32_e32 v0, 16, v0
	v_add3_u32 v7, v58, v7, s80
	v_and_or_b32 v46, v7, s85, v0
	s_waitcnt lgkmcnt(1)
	v_bfe_u32 v0, v60, 16, 1
	v_add3_u32 v0, v60, v0, s80
	s_waitcnt lgkmcnt(0)
	v_bfe_u32 v7, v62, 16, 1
	v_lshrrev_b32_e32 v0, 16, v0
	v_add3_u32 v7, v62, v7, s80
	v_and_or_b32 v47, v7, s85, v0
	v_or_b32_e32 v0, s1, v42
	v_lshlrev_b32_e32 v0, 10, v0
	v_lshl_add_u64 v[64:65], v[48:49], 0, v[0:1]
	v_bfe_u32 v0, v37, 16, 1
	v_add3_u32 v0, v37, v0, s80
	v_bfe_u32 v7, v51, 16, 1
	v_lshrrev_b32_e32 v0, 16, v0
	v_add3_u32 v7, v51, v7, s80
	global_store_dwordx4 v[64:65], v[44:47], off
	s_nop 1
	v_and_or_b32 v44, v7, s85, v0
	v_bfe_u32 v0, v53, 16, 1
	v_add3_u32 v0, v53, v0, s80
	v_bfe_u32 v7, v55, 16, 1
	v_lshrrev_b32_e32 v0, 16, v0
	v_add3_u32 v7, v55, v7, s80
	v_and_or_b32 v45, v7, s85, v0
	v_bfe_u32 v0, v57, 16, 1
	v_add3_u32 v0, v57, v0, s80
	v_bfe_u32 v7, v59, 16, 1
	v_lshrrev_b32_e32 v0, 16, v0
	v_add3_u32 v7, v59, v7, s80
	v_and_or_b32 v46, v7, s85, v0
	v_bfe_u32 v0, v61, 16, 1
	v_add3_u32 v0, v61, v0, s80
	v_bfe_u32 v7, v63, 16, 1
	v_lshrrev_b32_e32 v0, 16, v0
	v_add3_u32 v7, v63, v7, s80
	v_and_or_b32 v47, v7, s85, v0
	v_or_b32_e32 v0, s1, v43
	v_lshlrev_b32_e32 v0, 10, v0
	v_lshl_add_u64 v[36:37], v[48:49], 0, v[0:1]
	global_store_dwordx4 v[36:37], v[44:47], off
.LBB0_53:
	s_mov_b64 s[20:21], 0

; __device__ __forceinline__ void tr_item(const float* W, int ldw, int c0, bf16* WT, int ldk, int r0, int nblk, int item, LAS float* scr, int lane) {
;     const int kb = item / nblk, nb = item % nblk, k0 = 64 * kb, n0 = 32 * nb;
; #pragma unroll 8
;     for (int i = 0; i < 32; ++i) { const int kk = 2 * i + (lane >> 5); scr[kk * 33 + (lane & 31)] = W[(size_t)(k0 + kk) * ldw + c0 + n0 + (lane & 31)]; }
.LBB0_56:
	s_lshl_b32 s35, s21, 1
	s_lshl_b32 s36, s31, 1
	v_or_b32_e32 v0, s36, v38
	s_add_i32 s37, s35, 4
	s_add_i32 s38, s36, 4
	v_mov_b32_e32 v47, v1
	s_add_i32 s40, s36, 8
	v_lshlrev_b64 v[60:61], 12, v[0:1]
	v_or_b32_e32 v46, s37, v7
	v_or_b32_e32 v0, s38, v38
	v_mov_b32_e32 v45, v1
	v_or_b32_e32 v44, s35, v7
	s_add_i32 s42, s36, 12
	v_lshlrev_b64 v[46:47], 12, v[46:47]
	v_lshlrev_b64 v[62:63], 12, v[0:1]
	v_or_b32_e32 v0, s40, v38
	s_add_i32 s39, s35, 8
	s_add_i32 s41, s35, 12
	s_add_i32 s44, s36, 16
	v_lshlrev_b64 v[44:45], 12, v[44:45]
	v_lshl_add_u64 v[60:61], v[36:37], 0, v[60:61]
	v_lshl_add_u64 v[46:47], v[36:37], 0, v[46:47]
	v_lshlrev_b64 v[64:65], 12, v[0:1]
	v_or_b32_e32 v0, s42, v38
	v_mov_b32_e32 v49, v1
	v_mov_b32_e32 v51, v1
	s_add_i32 s46, s36, 20
	v_or_b32_e32 v48, s39, v7
	v_or_b32_e32 v50, s41, v7
	v_lshl_add_u64 v[44:45], v[36:37], 0, v[44:45]
	v_lshl_add_u64 v[62:63], v[36:37], 0, v[62:63]
	global_load_dword v35, v[60:61], off
	global_load_dword v76, v[44:45], off
	global_load_dword v77, v[62:63], off
	global_load_dword v78, v[46:47], off
	v_lshlrev_b64 v[46:47], 12, v[0:1]
	v_or_b32_e32 v0, s44, v38
	s_add_i32 s43, s35, 16
	s_add_i32 s45, s35, 20
	s_add_i32 s48, s36, 24
	v_lshlrev_b64 v[48:49], 12, v[48:49]
	v_lshlrev_b64 v[50:51], 12, v[50:51]
	v_lshl_add_u64 v[44:45], v[36:37], 0, v[64:65]
	v_lshl_add_u64 v[46:47], v[36:37], 0, v[46:47]
	v_lshlrev_b64 v[60:61], 12, v[0:1]
	v_or_b32_e32 v0, s46, v38
	v_mov_b32_e32 v53, v1
	v_mov_b32_e32 v55, v1
	s_add_i32 s47, s35, 24
	s_add_i32 s49, s35, 28
	s_add_i32 s50, s36, 28
	v_or_b32_e32 v52, s43, v7
	v_or_b32_e32 v54, s45, v7
	v_lshl_add_u64 v[48:49], v[36:37], 0, v[48:49]
	v_lshl_add_u64 v[50:51], v[36:37], 0, v[50:51]
	global_load_dword v79, v[44:45], off
	global_load_dword v80, v[48:49], off
	global_load_dword v81, v[46:47], off
	global_load_dword v82, v[50:51], off
	v_lshlrev_b64 v[46:47], 12, v[0:1]
	v_or_b32_e32 v0, s48, v38
	v_mov_b32_e32 v57, v1
	v_mov_b32_e32 v59, v1
	v_or_b32_e32 v56, s47, v7
	v_or_b32_e32 v58, s49, v7
	v_lshlrev_b64 v[52:53], 12, v[52:53]
	v_lshlrev_b64 v[54:55], 12, v[54:55]
	v_lshl_add_u64 v[44:45], v[36:37], 0, v[60:61]
	v_lshl_add_u64 v[46:47], v[36:37], 0, v[46:47]
	v_lshlrev_b64 v[48:49], 12, v[0:1]
	v_or_b32_e32 v0, s50, v38
	v_lshlrev_b64 v[56:57], 12, v[56:57]
	v_lshlrev_b64 v[58:59], 12, v[58:59]
	v_lshl_add_u64 v[52:53], v[36:37], 0, v[52:53]
	v_lshl_add_u64 v[54:55], v[36:37], 0, v[54:55]
	global_load_dword v83, v[44:45], off
	global_load_dword v84, v[52:53], off
	global_load_dword v85, v[46:47], off
	global_load_dword v86, v[54:55], off
	v_lshl_add_u64 v[44:45], v[36:37], 0, v[48:49]
	v_lshlrev_b64 v[46:47], 12, v[0:1]
	v_lshl_add_u64 v[56:57], v[36:37], 0, v[56:57]
	v_lshl_add_u64 v[58:59], v[36:37], 0, v[58:59]
	v_lshl_add_u64 v[46:47], v[36:37], 0, v[46:47]
	global_load_dword v0, v[44:45], off
	global_load_dword v87, v[56:57], off
	global_load_dword v88, v[46:47], off
	global_load_dword v89, v[58:59], off
	v_or_b32_e32 v46, s35, v3
	v_or_b32_e32 v44, s36, v2
	s_add_i32 s31, s31, 16
	s_add_i32 s21, s21, 16
	s_add_i32 s34, s34, -16
	v_mad_u64_u32 v[44:45], s[10:11], v44, s27, v[6:7]
	v_mad_u64_u32 v[46:47], s[10:11], v46, s27, v[6:7]
	v_or_b32_e32 v45, s37, v3
	v_or_b32_e32 v47, s38, v2
	v_or_b32_e32 v54, s39, v3
	v_or_b32_e32 v52, s40, v2
	v_or_b32_e32 v58, s41, v3
	v_or_b32_e32 v56, s42, v2
	v_or_b32_e32 v62, s43, v3
	v_or_b32_e32 v60, s44, v2
	v_or_b32_e32 v66, s45, v3
	v_or_b32_e32 v64, s46, v2
	v_or_b32_e32 v70, s47, v3
	v_or_b32_e32 v68, s48, v2
	v_or_b32_e32 v74, s49, v3
	v_or_b32_e32 v72, s50, v2
	s_cmp_lg_u32 s34, 0
	v_mad_u64_u32 v[48:49], s[10:11], v47, s27, v[6:7]
	v_mad_u64_u32 v[50:51], s[10:11], v45, s27, v[6:7]
	v_mad_u64_u32 v[52:53], s[10:11], v52, s27, v[6:7]
	v_mad_u64_u32 v[54:55], s[10:11], v54, s27, v[6:7]
	v_mad_u64_u32 v[56:57], s[10:11], v56, s27, v[6:7]
	v_mad_u64_u32 v[58:59], s[10:11], v58, s27, v[6:7]
	v_mad_u64_u32 v[60:61], s[10:11], v60, s27, v[6:7]
	v_mad_u64_u32 v[62:63], s[10:11], v62, s27, v[6:7]
	v_mad_u64_u32 v[64:65], s[10:11], v64, s27, v[6:7]
	v_mad_u64_u32 v[66:67], s[10:11], v66, s27, v[6:7]
	v_mad_u64_u32 v[68:69], s[10:11], v68, s27, v[6:7]
	v_mad_u64_u32 v[70:71], s[10:11], v70, s27, v[6:7]
	v_mad_u64_u32 v[72:73], s[10:11], v72, s27, v[6:7]
	v_mad_u64_u32 v[74:75], s[10:11], v74, s27, v[6:7]
	s_waitcnt vmcnt(15)
	ds_write_b32 v44, v35
	s_waitcnt vmcnt(14)
	ds_write_b32 v46, v76
	s_waitcnt vmcnt(13)
	ds_write_b32 v48, v77
	s_waitcnt vmcnt(12)
	ds_write_b32 v50, v78
	s_waitcnt vmcnt(11)
	ds_write_b32 v52, v79
	s_waitcnt vmcnt(10)
	ds_write_b32 v54, v80
	s_waitcnt vmcnt(9)
	ds_write_b32 v56, v81
	s_waitcnt vmcnt(8)
	ds_write_b32 v58, v82
	s_waitcnt vmcnt(7)
	ds_write_b32 v60, v83
	s_waitcnt vmcnt(6)
	ds_write_b32 v62, v84
	s_waitcnt vmcnt(5)
	ds_write_b32 v64, v85
	s_waitcnt vmcnt(4)
	ds_write_b32 v66, v86
	s_waitcnt vmcnt(3)
	ds_write_b32 v68, v0
	s_waitcnt vmcnt(2)
	ds_write_b32 v70, v87
	s_waitcnt vmcnt(1)
	ds_write_b32 v72, v88
	s_waitcnt vmcnt(0)
	ds_write_b32 v74, v89
	s_cbranch_scc1 .LBB0_56
; #define LAS __attribute__((address_space(3)))
; __device__ __forceinline__ unsigned pk2(float lo, float hi) { return f2bf(lo) | (f2bf(hi) << 16); }
; __device__ __forceinline__ void tr_item(const float* W, int ldw, int c0, bf16* WT, int ldk, int r0, int nblk, int item, LAS float* scr, int lane) {
;     ...
;     asm volatile("s_waitcnt lgkmcnt(0)" ::: "memory");
;     const int c = lane & 7;
; #pragma unroll
;     for (int j = 0; j < 4; ++j) { const int n = (lane >> 3) + 8 * j; const LAS float* s = scr + (8 * c) * 33 + n;
;         v4u o; o.x = pk2(s[0 * 33], s[1 * 33]); o.y = pk2(s[2 * 33], s[3 * 33]); o.z = pk2(s[4 * 33], s[5 * 33]); o.w = pk2(s[6 * 33], s[7 * 33]);
;         *(v4u*)(WT + (size_t)(r0 + n0 + n) * ldk + k0 + 8 * c) = o; }
;     asm volatile("s_waitcnt lgkmcnt(0)" ::: "memory");
; __device__ __forceinline__ void phase_convert_weights(const Ctx& C0, const Params& p, int l) {
;     ...
;         if (r < I_KV) { const int job = r >> 2, sub = r & 3, h = job >> 1, part = job & 1;
;             tr_item(w_kvup, 1024, h * 128 + part * 64, W + (part ? WO_V : WO_K), 256, h * 64, 2, sub, scr, C.lane); continue; } r -= I_KV;
	s_cmp_eq_u32 s20, 0
	s_mov_b32 s10, 0xae0000
	s_cselect_b32 s10, s10, 0xb20000
	v_readlane_b32 s20, v252, 44
	s_waitcnt lgkmcnt(0)
	v_readlane_b32 s21, v252, 45
	s_add_u32 s10, s20, s10
	ds_read2_b32 v[36:37], v40 offset1:8
	s_addc_u32 s11, s21, 0
	s_lshl_b32 s1, s1, 6
	ds_read2_b32 v[50:51], v40 offset0:33 offset1:41
	s_add_i32 s1, s1, s0
	s_lshl_b32 s4, s4, 1
	s_add_u32 s10, s10, s4
	ds_read2_b32 v[52:53], v40 offset0:66 offset1:74
	s_addc_u32 s11, s11, 0
	v_lshlrev_b32_e32 v0, 1, v8
	ds_read2_b32 v[54:55], v40 offset0:99 offset1:107
	v_lshl_add_u64 v[48:49], s[10:11], 0, v[0:1]
	s_waitcnt lgkmcnt(3)
	v_bfe_u32 v0, v36, 16, 1
	v_add3_u32 v0, v36, v0, s80
	s_waitcnt lgkmcnt(2)
	v_bfe_u32 v7, v50, 16, 1
	ds_read2_b32 v[56:57], v40 offset0:132 offset1:140
	v_lshrrev_b32_e32 v0, 16, v0
	v_add3_u32 v7, v50, v7, s80
	s_mov_b32 s85, 0xffff0000
	ds_read2_b32 v[58:59], v40 offset0:165 offset1:173
	v_and_or_b32 v44, v7, s85, v0
	s_waitcnt lgkmcnt(3)
	v_bfe_u32 v0, v52, 16, 1
	v_add3_u32 v0, v52, v0, s80
	s_waitcnt lgkmcnt(2)
	v_bfe_u32 v7, v54, 16, 1
	ds_read2_b32 v[60:61], v40 offset0:198 offset1:206
	v_lshrrev_b32_e32 v0, 16, v0
	v_add3_u32 v7, v54, v7, s80
	ds_read2_b32 v[62:63], v40 offset0:231 offset1:239
	v_and_or_b32 v45, v7, s85, v0
	s_waitcnt lgkmcnt(3)
	v_bfe_u32 v0, v56, 16, 1
	v_add3_u32 v0, v56, v0, s80
	s_waitcnt lgkmcnt(2)
	v_bfe_u32 v7, v58, 16, 1
	v_lshrrev_b32_e32 v0, 16, v0
	v_add3_u32 v7, v58, v7, s80
	v_and_or_b32 v46, v7, s85, v0
	s_waitcnt lgkmcnt(1)
	v_bfe_u32 v0, v60, 16, 1
	v_add3_u32 v0, v60, v0, s80
	s_waitcnt lgkmcnt(0)
	v_bfe_u32 v7, v62, 16, 1
	v_lshrrev_b32_e32 v0, 16, v0
	v_add3_u32 v7, v62, v7, s80
	v_or_b32_e32 v64, s1, v39
	v_and_or_b32 v47, v7, s85, v0
	v_ashrrev_i32_e32 v65, 31, v64
	v_bfe_u32 v0, v37, 16, 1
	v_lshlrev_b64 v[64:65], 9, v[64:65]
	v_add3_u32 v0, v37, v0, s80
	v_bfe_u32 v7, v51, 16, 1
	v_lshl_add_u64 v[64:65], v[48:49], 0, v[64:65]
	v_lshrrev_b32_e32 v0, 16, v0
	v_add3_u32 v7, v51, v7, s80
	global_store_dwordx4 v[64:65], v[44:47], off
	v_or_b32_e32 v36, s1, v41
	v_ashrrev_i32_e32 v37, 31, v36
	v_and_or_b32 v44, v7, s85, v0
	v_bfe_u32 v0, v53, 16, 1
	v_add3_u32 v0, v53, v0, s80
	v_bfe_u32 v7, v55, 16, 1
	v_lshrrev_b32_e32 v0, 16, v0
	v_add3_u32 v7, v55, v7, s80
	v_and_or_b32 v45, v7, s85, v0
	v_bfe_u32 v0, v57, 16, 1
	v_add3_u32 v0, v57, v0, s80
	v_bfe_u32 v7, v59, 16, 1
	v_lshrrev_b32_e32 v0, 16, v0
	v_add3_u32 v7, v59, v7, s80
	v_and_or_b32 v46, v7, s85, v0
	v_bfe_u32 v0, v61, 16, 1
	v_add3_u32 v0, v61, v0, s80
	v_bfe_u32 v7, v63, 16, 1
	v_lshrrev_b32_e32 v0, 16, v0
	v_add3_u32 v7, v63, v7, s80
	v_lshlrev_b64 v[36:37], 9, v[36:37]
	v_and_or_b32 v47, v7, s85, v0
	ds_read2_b32 v[50:51], v40 offset0:16 offset1:24
	v_lshl_add_u64 v[36:37], v[48:49], 0, v[36:37]
	global_store_dwordx4 v[36:37], v[44:47], off
	ds_read2_b32 v[36:37], v40 offset0:49 offset1:57
	ds_read2_b32 v[52:53], v40 offset0:82 offset1:90
	ds_read2_b32 v[54:55], v40 offset0:115 offset1:123
	s_waitcnt lgkmcnt(3)
	v_bfe_u32 v0, v50, 16, 1
	v_add3_u32 v0, v50, v0, s80
	s_waitcnt lgkmcnt(2)
	v_bfe_u32 v7, v36, 16, 1
	ds_read2_b32 v[56:57], v40 offset0:148 offset1:156
	v_lshrrev_b32_e32 v0, 16, v0
	v_add3_u32 v7, v36, v7, s80
	ds_read2_b32 v[58:59], v40 offset0:181 offset1:189
	v_and_or_b32 v44, v7, s85, v0
	s_waitcnt lgkmcnt(3)
	v_bfe_u32 v0, v52, 16, 1
	v_add3_u32 v0, v52, v0, s80
	s_waitcnt lgkmcnt(2)
	v_bfe_u32 v7, v54, 16, 1
	ds_read2_b32 v[60:61], v40 offset0:214 offset1:222
	v_lshrrev_b32_e32 v0, 16, v0
	v_add3_u32 v7, v54, v7, s80
	ds_read2_b32 v[62:63], v40 offset0:247 offset1:255
	v_and_or_b32 v45, v7, s85, v0
	s_waitcnt lgkmcnt(3)
	v_bfe_u32 v0, v56, 16, 1
	v_add3_u32 v0, v56, v0, s80
	s_waitcnt lgkmcnt(2)
	v_bfe_u32 v7, v58, 16, 1
	v_lshrrev_b32_e32 v0, 16, v0
	v_add3_u32 v7, v58, v7, s80
	v_and_or_b32 v46, v7, s85, v0
	s_waitcnt lgkmcnt(1)
	v_bfe_u32 v0, v60, 16, 1
	v_add3_u32 v0, v60, v0, s80
	s_waitcnt lgkmcnt(0)
	v_bfe_u32 v7, v62, 16, 1
	v_lshrrev_b32_e32 v0, 16, v0
	v_add3_u32 v7, v62, v7, s80
	v_or_b32_e32 v64, s1, v42
	v_and_or_b32 v47, v7, s85, v0
	v_ashrrev_i32_e32 v65, 31, v64
	v_bfe_u32 v0, v51, 16, 1
	v_lshlrev_b64 v[64:65], 9, v[64:65]
	v_add3_u32 v0, v51, v0, s80
	v_bfe_u32 v7, v37, 16, 1
	v_lshl_add_u64 v[64:65], v[48:49], 0, v[64:65]
	v_lshrrev_b32_e32 v0, 16, v0
	v_add3_u32 v7, v37, v7, s80
	global_store_dwordx4 v[64:65], v[44:47], off
	v_or_b32_e32 v36, s1, v43
	v_ashrrev_i32_e32 v37, 31, v36
	v_and_or_b32 v44, v7, s85, v0
	v_bfe_u32 v0, v53, 16, 1
	v_add3_u32 v0, v53, v0, s80
	v_bfe_u32 v7, v55, 16, 1
	v_lshrrev_b32_e32 v0, 16, v0
	v_add3_u32 v7, v55, v7, s80
	v_and_or_b32 v45, v7, s85, v0
	v_bfe_u32 v0, v57, 16, 1
	v_add3_u32 v0, v57, v0, s80
	v_bfe_u32 v7, v59, 16, 1
	v_lshrrev_b32_e32 v0, 16, v0
	v_add3_u32 v7, v59, v7, s80
	v_and_or_b32 v46, v7, s85, v0
	v_bfe_u32 v0, v61, 16, 1
	v_add3_u32 v0, v61, v0, s80
	v_bfe_u32 v7, v63, 16, 1
	v_lshrrev_b32_e32 v0, 16, v0
	v_add3_u32 v7, v63, v7, s80
	v_lshlrev_b64 v[36:37], 9, v[36:37]
	v_and_or_b32 v47, v7, s85, v0
	v_lshl_add_u64 v[36:37], v[48:49], 0, v[36:37]
	global_store_dwordx4 v[36:37], v[44:47], off
	v_readlane_b32 s81, v254, 55

; __device__ __forceinline__ void tr_item(const float* W, int ldw, int c0, bf16* WT, int ldk, int r0, int nblk, int item, LAS float* scr, int lane) {
;     const int kb = item / nblk, nb = item % nblk, k0 = 64 * kb, n0 = 32 * nb;
; #pragma unroll 8
;     for (int i = 0; i < 32; ++i) { const int kk = 2 * i + (lane >> 5); scr[kk * 33 + (lane & 31)] = W[(size_t)(k0 + kk) * ldw + c0 + n0 + (lane & 31)]; }
.LBB0_61:
	s_lshl_b32 s34, s20, 1
	s_lshl_b32 s35, s21, 1
	v_or_b32_e32 v35, s34, v7
	v_or_b32_e32 v38, s35, v0
	s_add_i32 s36, s34, 4
	s_add_i32 s37, s35, 4
	s_add_i32 s38, s34, 8
	s_add_i32 s39, s35, 8
	s_add_i32 s40, s34, 12
	s_add_i32 s41, s35, 12
	s_add_i32 s42, s34, 16
	s_add_i32 s43, s35, 16
	s_add_i32 s44, s34, 20
	s_add_i32 s45, s35, 20
	s_add_i32 s46, s34, 24
	s_add_i32 s47, s35, 24
	s_add_i32 s48, s34, 28
	s_add_i32 s49, s35, 28
	v_mad_u64_u32 v[44:45], s[10:11], v38, s82, v[36:37]
	v_mad_u64_u32 v[46:47], s[10:11], v35, s82, v[36:37]
	v_or_b32_e32 v35, s36, v7
	v_or_b32_e32 v38, s37, v0
	v_or_b32_e32 v54, s38, v7
	v_or_b32_e32 v52, s39, v0
	v_or_b32_e32 v58, s40, v7
	v_or_b32_e32 v56, s41, v0
	v_or_b32_e32 v62, s42, v7
	v_or_b32_e32 v60, s43, v0
	v_or_b32_e32 v66, s44, v7
	v_or_b32_e32 v64, s45, v0
	v_or_b32_e32 v70, s46, v7
	v_or_b32_e32 v68, s47, v0
	v_or_b32_e32 v74, s48, v7
	v_or_b32_e32 v72, s49, v0
	v_mad_u64_u32 v[48:49], s[10:11], v38, s82, v[36:37]
	v_mad_u64_u32 v[50:51], s[10:11], v35, s82, v[36:37]
	v_mad_u64_u32 v[52:53], s[10:11], v52, s82, v[36:37]
	v_mad_u64_u32 v[54:55], s[10:11], v54, s82, v[36:37]
	v_mad_u64_u32 v[56:57], s[10:11], v56, s82, v[36:37]
	v_mad_u64_u32 v[58:59], s[10:11], v58, s82, v[36:37]
	v_mad_u64_u32 v[60:61], s[10:11], v60, s82, v[36:37]
	v_mad_u64_u32 v[62:63], s[10:11], v62, s82, v[36:37]
	v_mad_u64_u32 v[64:65], s[10:11], v64, s82, v[36:37]
	v_mad_u64_u32 v[66:67], s[10:11], v66, s82, v[36:37]
	v_mad_u64_u32 v[68:69], s[10:11], v68, s82, v[36:37]
	v_mad_u64_u32 v[70:71], s[10:11], v70, s82, v[36:37]
	v_mad_u64_u32 v[72:73], s[10:11], v72, s82, v[36:37]
	v_mad_u64_u32 v[74:75], s[10:11], v74, s82, v[36:37]
	global_load_dword v35, v[44:45], off
	global_load_dword v38, v[46:47], off
	global_load_dword v76, v[48:49], off
	global_load_dword v77, v[50:51], off
	global_load_dword v78, v[52:53], off
	global_load_dword v79, v[54:55], off
	global_load_dword v80, v[56:57], off
	global_load_dword v81, v[58:59], off
	global_load_dword v82, v[60:61], off
	global_load_dword v83, v[62:63], off
	global_load_dword v84, v[64:65], off
	global_load_dword v85, v[66:67], off
	global_load_dword v86, v[68:69], off
	global_load_dword v87, v[70:71], off
	global_load_dword v88, v[72:73], off
	global_load_dword v89, v[74:75], off
	v_or_b32_e32 v46, s34, v3
	v_or_b32_e32 v44, s35, v2
	s_add_i32 s21, s21, 16
	s_add_i32 s20, s20, 16
	s_add_i32 s31, s31, -16
	v_mad_u64_u32 v[44:45], s[10:11], v44, s27, v[6:7]
	v_mad_u64_u32 v[46:47], s[10:11], v46, s27, v[6:7]
	v_or_b32_e32 v45, s36, v3
	v_or_b32_e32 v47, s37, v2
	v_or_b32_e32 v54, s38, v3
	v_or_b32_e32 v52, s39, v2
	v_or_b32_e32 v58, s40, v3
	v_or_b32_e32 v56, s41, v2
	v_or_b32_e32 v62, s42, v3
	v_or_b32_e32 v60, s43, v2
	v_or_b32_e32 v66, s44, v3
	v_or_b32_e32 v64, s45, v2
	v_or_b32_e32 v70, s46, v3
	v_or_b32_e32 v68, s47, v2
	v_or_b32_e32 v74, s48, v3
	v_or_b32_e32 v72, s49, v2
	s_cmp_lg_u32 s31, 0
	v_mad_u64_u32 v[48:49], s[10:11], v47, s27, v[6:7]
	v_mad_u64_u32 v[50:51], s[10:11], v45, s27, v[6:7]
	v_mad_u64_u32 v[52:53], s[10:11], v52, s27, v[6:7]
	v_mad_u64_u32 v[54:55], s[10:11], v54, s27, v[6:7]
	v_mad_u64_u32 v[56:57], s[10:11], v56, s27, v[6:7]
	v_mad_u64_u32 v[58:59], s[10:11], v58, s27, v[6:7]
	v_mad_u64_u32 v[60:61], s[10:11], v60, s27, v[6:7]
	v_mad_u64_u32 v[62:63], s[10:11], v62, s27, v[6:7]
	v_mad_u64_u32 v[64:65], s[10:11], v64, s27, v[6:7]
	v_mad_u64_u32 v[66:67], s[10:11], v66, s27, v[6:7]
	v_mad_u64_u32 v[68:69], s[10:11], v68, s27, v[6:7]
	v_mad_u64_u32 v[70:71], s[10:11], v70, s27, v[6:7]
	v_mad_u64_u32 v[72:73], s[10:11], v72, s27, v[6:7]
	v_mad_u64_u32 v[74:75], s[10:11], v74, s27, v[6:7]
	s_waitcnt vmcnt(15)
	ds_write_b32 v44, v35
	s_waitcnt vmcnt(14)
	ds_write_b32 v46, v38
	s_waitcnt vmcnt(13)
	ds_write_b32 v48, v76
	s_waitcnt vmcnt(12)
	ds_write_b32 v50, v77
	s_waitcnt vmcnt(11)
	ds_write_b32 v52, v78
	s_waitcnt vmcnt(10)
	ds_write_b32 v54, v79
	s_waitcnt vmcnt(9)
	ds_write_b32 v56, v80
	s_waitcnt vmcnt(8)
	ds_write_b32 v58, v81
	s_waitcnt vmcnt(7)
	ds_write_b32 v60, v82
	s_waitcnt vmcnt(6)
	ds_write_b32 v62, v83
	s_waitcnt vmcnt(5)
	ds_write_b32 v64, v84
	s_waitcnt vmcnt(4)
	ds_write_b32 v66, v85
	s_waitcnt vmcnt(3)
	ds_write_b32 v68, v86
	s_waitcnt vmcnt(2)
	ds_write_b32 v70, v87
	s_waitcnt vmcnt(1)
	ds_write_b32 v72, v88
	s_waitcnt vmcnt(0)
	ds_write_b32 v74, v89
	s_cbranch_scc1 .LBB0_61
; #define LAS __attribute__((address_space(3)))
; __device__ __forceinline__ unsigned pk2(float lo, float hi) { return f2bf(lo) | (f2bf(hi) << 16); }
; __device__ __forceinline__ void tr_item(const float* W, int ldw, int c0, bf16* WT, int ldk, int r0, int nblk, int item, LAS float* scr, int lane) {
;     ...
;     asm volatile("s_waitcnt lgkmcnt(0)" ::: "memory");
;     const int c = lane & 7;
; #pragma unroll
;     for (int j = 0; j < 4; ++j) { const int n = (lane >> 3) + 8 * j; const LAS float* s = scr + (8 * c) * 33 + n;
;         v4u o; o.x = pk2(s[0 * 33], s[1 * 33]); o.y = pk2(s[2 * 33], s[3 * 33]); o.z = pk2(s[4 * 33], s[5 * 33]); o.w = pk2(s[6 * 33], s[7 * 33]);
;         *(v4u*)(WT + (size_t)(r0 + n0 + n) * ldk + k0 + 8 * c) = o; }
;     asm volatile("s_waitcnt lgkmcnt(0)" ::: "memory");
; __device__ __forceinline__ void phase_convert_weights(const Ctx& C0, const Params& p, int l) {
;     ...
;         if (r < I_Q) { tr_item(w_qup, 768, 0, W + WO_Q, 256, 0, 24, r, scr, C.lane); continue; } r -= I_Q;
	s_waitcnt lgkmcnt(0)
	ds_read2_b32 v[36:37], v40 offset1:8
	ds_read2_b32 v[50:51], v40 offset0:33 offset1:41
	ds_read2_b32 v[52:53], v40 offset0:66 offset1:74
	ds_read2_b32 v[54:55], v40 offset0:99 offset1:107
	ds_read2_b32 v[56:57], v40 offset0:132 offset1:140
	s_mov_b32 s85, 0xffff0000
	s_waitcnt lgkmcnt(4)
	v_bfe_u32 v0, v36, 16, 1
	v_add3_u32 v0, v36, v0, s80
	s_waitcnt lgkmcnt(3)
	v_bfe_u32 v7, v50, 16, 1
	v_lshrrev_b32_e32 v0, 16, v0
	v_add3_u32 v7, v50, v7, s80
	ds_read2_b32 v[58:59], v40 offset0:165 offset1:173
	v_and_or_b32 v44, v7, s85, v0
	s_waitcnt lgkmcnt(3)
	v_bfe_u32 v0, v52, 16, 1
	v_add3_u32 v0, v52, v0, s80
	s_waitcnt lgkmcnt(2)
	v_bfe_u32 v7, v54, 16, 1
	ds_read2_b32 v[60:61], v40 offset0:198 offset1:206
	v_lshrrev_b32_e32 v0, 16, v0
	v_add3_u32 v7, v54, v7, s80
	ds_read2_b32 v[62:63], v40 offset0:231 offset1:239
	v_and_or_b32 v45, v7, s85, v0
	s_waitcnt lgkmcnt(3)
	v_bfe_u32 v0, v56, 16, 1
	v_add3_u32 v0, v56, v0, s80
	s_waitcnt lgkmcnt(2)
	v_bfe_u32 v7, v58, 16, 1
	v_lshrrev_b32_e32 v0, 16, v0
	v_add3_u32 v7, v58, v7, s80
	v_and_or_b32 v46, v7, s85, v0
	s_waitcnt lgkmcnt(1)
	v_bfe_u32 v0, v60, 16, 1
	v_add3_u32 v0, v60, v0, s80
	s_waitcnt lgkmcnt(0)
	v_bfe_u32 v7, v62, 16, 1
	v_lshrrev_b32_e32 v0, 16, v0
	v_add3_u32 v7, v62, v7, s80
	s_lshl_b32 s88, s4, 1
	v_and_or_b32 v47, v7, s85, v0
	v_or_b32_e32 v0, s1, v39
	v_lshl_add_u64 v[48:49], v[22:23], 0, s[88:89]
	v_lshlrev_b32_e32 v0, 9, v0
	v_lshl_add_u64 v[64:65], v[48:49], 0, v[0:1]
	v_bfe_u32 v0, v37, 16, 1
	v_add3_u32 v0, v37, v0, s80
	v_bfe_u32 v7, v51, 16, 1
	v_lshrrev_b32_e32 v0, 16, v0
	v_add3_u32 v7, v51, v7, s80
	global_store_dwordx4 v[64:65], v[44:47], off
	ds_read2_b32 v[36:37], v40 offset0:16 offset1:24
	v_readlane_b32 s81, v254, 55
	v_and_or_b32 v44, v7, s85, v0
	v_bfe_u32 v0, v53, 16, 1
	v_add3_u32 v0, v53, v0, s80
	v_bfe_u32 v7, v55, 16, 1
	v_lshrrev_b32_e32 v0, 16, v0
	v_add3_u32 v7, v55, v7, s80
	v_and_or_b32 v45, v7, s85, v0
	v_bfe_u32 v0, v57, 16, 1
	v_add3_u32 v0, v57, v0, s80
	v_bfe_u32 v7, v59, 16, 1
	v_lshrrev_b32_e32 v0, 16, v0
	v_add3_u32 v7, v59, v7, s80
	v_and_or_b32 v46, v7, s85, v0
	v_bfe_u32 v0, v61, 16, 1
	v_add3_u32 v0, v61, v0, s80
	v_bfe_u32 v7, v63, 16, 1
	v_lshrrev_b32_e32 v0, 16, v0
	v_add3_u32 v7, v63, v7, s80
	v_and_or_b32 v47, v7, s85, v0
	v_or_b32_e32 v0, s1, v41
	v_lshlrev_b32_e32 v0, 9, v0
	v_lshl_add_u64 v[50:51], v[48:49], 0, v[0:1]
	global_store_dwordx4 v[50:51], v[44:47], off
	ds_read2_b32 v[50:51], v40 offset0:49 offset1:57
	ds_read2_b32 v[52:53], v40 offset0:82 offset1:90
	ds_read2_b32 v[54:55], v40 offset0:115 offset1:123
	s_waitcnt lgkmcnt(3)
	v_bfe_u32 v0, v36, 16, 1
	v_add3_u32 v0, v36, v0, s80
	s_waitcnt lgkmcnt(2)
	v_bfe_u32 v7, v50, 16, 1
	ds_read2_b32 v[56:57], v40 offset0:148 offset1:156
	v_lshrrev_b32_e32 v0, 16, v0
	v_add3_u32 v7, v50, v7, s80
	ds_read2_b32 v[58:59], v40 offset0:181 offset1:189
	v_and_or_b32 v44, v7, s85, v0
	s_waitcnt lgkmcnt(3)
	v_bfe_u32 v0, v52, 16, 1
	v_add3_u32 v0, v52, v0, s80
	s_waitcnt lgkmcnt(2)
	v_bfe_u32 v7, v54, 16, 1
	ds_read2_b32 v[60:61], v40 offset0:214 offset1:222
	v_lshrrev_b32_e32 v0, 16, v0
	v_add3_u32 v7, v54, v7, s80
	ds_read2_b32 v[62:63], v40 offset0:247 offset1:255
	v_and_or_b32 v45, v7, s85, v0
	s_waitcnt lgkmcnt(3)
	v_bfe_u32 v0, v56, 16, 1
	v_add3_u32 v0, v56, v0, s80
	s_waitcnt lgkmcnt(2)
	v_bfe_u32 v7, v58, 16, 1
	v_lshrrev_b32_e32 v0, 16, v0
	v_add3_u32 v7, v58, v7, s80
	v_and_or_b32 v46, v7, s85, v0
	s_waitcnt lgkmcnt(1)
	v_bfe_u32 v0, v60, 16, 1
	v_add3_u32 v0, v60, v0, s80
	s_waitcnt lgkmcnt(0)
	v_bfe_u32 v7, v62, 16, 1
	v_lshrrev_b32_e32 v0, 16, v0
	v_add3_u32 v7, v62, v7, s80
	v_and_or_b32 v47, v7, s85, v0
	v_or_b32_e32 v0, s1, v42
	v_lshlrev_b32_e32 v0, 9, v0
	v_lshl_add_u64 v[64:65], v[48:49], 0, v[0:1]
	v_bfe_u32 v0, v37, 16, 1
	v_add3_u32 v0, v37, v0, s80
	v_bfe_u32 v7, v51, 16, 1
	v_lshrrev_b32_e32 v0, 16, v0
	v_add3_u32 v7, v51, v7, s80
	global_store_dwordx4 v[64:65], v[44:47], off
	s_nop 1
	v_and_or_b32 v44, v7, s85, v0
	v_bfe_u32 v0, v53, 16, 1
	v_add3_u32 v0, v53, v0, s80
	v_bfe_u32 v7, v55, 16, 1
	v_lshrrev_b32_e32 v0, 16, v0
	v_add3_u32 v7, v55, v7, s80
	v_and_or_b32 v45, v7, s85, v0
	v_bfe_u32 v0, v57, 16, 1
	v_add3_u32 v0, v57, v0, s80
	v_bfe_u32 v7, v59, 16, 1
	v_lshrrev_b32_e32 v0, 16, v0
	v_add3_u32 v7, v59, v7, s80
	v_and_or_b32 v46, v7, s85, v0
	v_bfe_u32 v0, v61, 16, 1
	v_add3_u32 v0, v61, v0, s80
	v_bfe_u32 v7, v63, 16, 1
	v_lshrrev_b32_e32 v0, 16, v0
	v_add3_u32 v7, v63, v7, s80
	v_and_or_b32 v47, v7, s85, v0
	v_or_b32_e32 v0, s1, v43
	v_lshlrev_b32_e32 v0, 9, v0
	v_lshl_add_u64 v[36:37], v[48:49], 0, v[0:1]
	global_store_dwordx4 v[36:37], v[44:47], off
.LBB0_63:
	s_mov_b64 s[20:21], 0

; __device__ __forceinline__ void tr_item(const float* W, int ldw, int c0, bf16* WT, int ldk, int r0, int nblk, int item, LAS float* scr, int lane) {
;     const int kb = item / nblk, nb = item % nblk, k0 = 64 * kb, n0 = 32 * nb;
; #pragma unroll 8
;     for (int i = 0; i < 32; ++i) { const int kk = 2 * i + (lane >> 5); scr[kk * 33 + (lane & 31)] = W[(size_t)(k0 + kk) * ldw + c0 + n0 + (lane & 31)]; }
.LBB0_66:
	s_lshl_b32 s34, s20, 1
	s_lshl_b32 s35, s21, 1
	v_or_b32_e32 v35, s34, v7
	v_or_b32_e32 v38, s35, v0
	s_add_i32 s36, s34, 4
	s_add_i32 s37, s35, 4
	s_add_i32 s38, s34, 8
	s_add_i32 s39, s35, 8
	s_add_i32 s40, s34, 12
	s_add_i32 s41, s35, 12
	s_add_i32 s42, s34, 16
	s_add_i32 s43, s35, 16
	s_add_i32 s44, s34, 20
	s_add_i32 s45, s35, 20
	s_add_i32 s46, s34, 24
	s_add_i32 s47, s35, 24
	s_add_i32 s48, s34, 28
	s_add_i32 s49, s35, 28
	v_mad_u64_u32 v[44:45], s[10:11], v38, s83, v[36:37]
	v_mad_u64_u32 v[46:47], s[10:11], v35, s83, v[36:37]
	v_or_b32_e32 v35, s36, v7
	v_or_b32_e32 v38, s37, v0
	v_or_b32_e32 v54, s38, v7
	v_or_b32_e32 v52, s39, v0
	v_or_b32_e32 v58, s40, v7
	v_or_b32_e32 v56, s41, v0
	v_or_b32_e32 v62, s42, v7
	v_or_b32_e32 v60, s43, v0
	v_or_b32_e32 v66, s44, v7
	v_or_b32_e32 v64, s45, v0
	v_or_b32_e32 v70, s46, v7
	v_or_b32_e32 v68, s47, v0
	v_or_b32_e32 v74, s48, v7
	v_or_b32_e32 v72, s49, v0
	v_mad_u64_u32 v[48:49], s[10:11], v38, s83, v[36:37]
	v_mad_u64_u32 v[50:51], s[10:11], v35, s83, v[36:37]
	v_mad_u64_u32 v[52:53], s[10:11], v52, s83, v[36:37]
	v_mad_u64_u32 v[54:55], s[10:11], v54, s83, v[36:37]
	v_mad_u64_u32 v[56:57], s[10:11], v56, s83, v[36:37]
	v_mad_u64_u32 v[58:59], s[10:11], v58, s83, v[36:37]
	v_mad_u64_u32 v[60:61], s[10:11], v60, s83, v[36:37]
	v_mad_u64_u32 v[62:63], s[10:11], v62, s83, v[36:37]
	v_mad_u64_u32 v[64:65], s[10:11], v64, s83, v[36:37]
	v_mad_u64_u32 v[66:67], s[10:11], v66, s83, v[36:37]
	v_mad_u64_u32 v[68:69], s[10:11], v68, s83, v[36:37]
	v_mad_u64_u32 v[70:71], s[10:11], v70, s83, v[36:37]
	v_mad_u64_u32 v[72:73], s[10:11], v72, s83, v[36:37]
	v_mad_u64_u32 v[74:75], s[10:11], v74, s83, v[36:37]
	global_load_dword v35, v[44:45], off
	global_load_dword v38, v[46:47], off
	global_load_dword v76, v[48:49], off
	global_load_dword v77, v[50:51], off
	global_load_dword v78, v[52:53], off
	global_load_dword v79, v[54:55], off
	global_load_dword v80, v[56:57], off
	global_load_dword v81, v[58:59], off
	global_load_dword v82, v[60:61], off
	global_load_dword v83, v[62:63], off
	global_load_dword v84, v[64:65], off
	global_load_dword v85, v[66:67], off
	global_load_dword v86, v[68:69], off
	global_load_dword v87, v[70:71], off
	global_load_dword v88, v[72:73], off
	global_load_dword v89, v[74:75], off
	v_or_b32_e32 v46, s34, v3
	v_or_b32_e32 v44, s35, v2
	s_add_i32 s21, s21, 16
	s_add_i32 s20, s20, 16
	s_add_i32 s31, s31, -16
	v_mad_u64_u32 v[44:45], s[10:11], v44, s27, v[6:7]
	v_mad_u64_u32 v[46:47], s[10:11], v46, s27, v[6:7]
	v_or_b32_e32 v45, s36, v3
	v_or_b32_e32 v47, s37, v2
	v_or_b32_e32 v54, s38, v3
	v_or_b32_e32 v52, s39, v2
	v_or_b32_e32 v58, s40, v3
	v_or_b32_e32 v56, s41, v2
	v_or_b32_e32 v62, s42, v3
	v_or_b32_e32 v60, s43, v2
	v_or_b32_e32 v66, s44, v3
	v_or_b32_e32 v64, s45, v2
	v_or_b32_e32 v70, s46, v3
	v_or_b32_e32 v68, s47, v2
	v_or_b32_e32 v74, s48, v3
	v_or_b32_e32 v72, s49, v2
	s_cmp_lg_u32 s31, 0
	v_mad_u64_u32 v[48:49], s[10:11], v47, s27, v[6:7]
	v_mad_u64_u32 v[50:51], s[10:11], v45, s27, v[6:7]
	v_mad_u64_u32 v[52:53], s[10:11], v52, s27, v[6:7]
	v_mad_u64_u32 v[54:55], s[10:11], v54, s27, v[6:7]
	v_mad_u64_u32 v[56:57], s[10:11], v56, s27, v[6:7]
	v_mad_u64_u32 v[58:59], s[10:11], v58, s27, v[6:7]
	v_mad_u64_u32 v[60:61], s[10:11], v60, s27, v[6:7]
	v_mad_u64_u32 v[62:63], s[10:11], v62, s27, v[6:7]
	v_mad_u64_u32 v[64:65], s[10:11], v64, s27, v[6:7]
	v_mad_u64_u32 v[66:67], s[10:11], v66, s27, v[6:7]
	v_mad_u64_u32 v[68:69], s[10:11], v68, s27, v[6:7]
	v_mad_u64_u32 v[70:71], s[10:11], v70, s27, v[6:7]
	v_mad_u64_u32 v[72:73], s[10:11], v72, s27, v[6:7]
	v_mad_u64_u32 v[74:75], s[10:11], v74, s27, v[6:7]
	s_waitcnt vmcnt(15)
	ds_write_b32 v44, v35
	s_waitcnt vmcnt(14)
	ds_write_b32 v46, v38
	s_waitcnt vmcnt(13)
	ds_write_b32 v48, v76
	s_waitcnt vmcnt(12)
	ds_write_b32 v50, v77
	s_waitcnt vmcnt(11)
	ds_write_b32 v52, v78
	s_waitcnt vmcnt(10)
	ds_write_b32 v54, v79
	s_waitcnt vmcnt(9)
	ds_write_b32 v56, v80
	s_waitcnt vmcnt(8)
	ds_write_b32 v58, v81
	s_waitcnt vmcnt(7)
	ds_write_b32 v60, v82
	s_waitcnt vmcnt(6)
	ds_write_b32 v62, v83
	s_waitcnt vmcnt(5)
	ds_write_b32 v64, v84
	s_waitcnt vmcnt(4)
	ds_write_b32 v66, v85
	s_waitcnt vmcnt(3)
	ds_write_b32 v68, v86
	s_waitcnt vmcnt(2)
	ds_write_b32 v70, v87
	s_waitcnt vmcnt(1)
	ds_write_b32 v72, v88
	s_waitcnt vmcnt(0)
	ds_write_b32 v74, v89
	s_cbranch_scc1 .LBB0_66
; #define LAS __attribute__((address_space(3)))
; __device__ __forceinline__ unsigned pk2(float lo, float hi) { return f2bf(lo) | (f2bf(hi) << 16); }
; __device__ __forceinline__ void tr_item(const float* W, int ldw, int c0, bf16* WT, int ldk, int r0, int nblk, int item, LAS float* scr, int lane) {
;     ...
;     asm volatile("s_waitcnt lgkmcnt(0)" ::: "memory");
;     const int c = lane & 7;
; #pragma unroll
;     for (int j = 0; j < 4; ++j) { const int n = (lane >> 3) + 8 * j; const LAS float* s = scr + (8 * c) * 33 + n;
;         v4u o; o.x = pk2(s[0 * 33], s[1 * 33]); o.y = pk2(s[2 * 33], s[3 * 33]); o.z = pk2(s[4 * 33], s[5 * 33]); o.w = pk2(s[6 * 33], s[7 * 33]);
;         *(v4u*)(WT + (size_t)(r0 + n0 + n) * ldk + k0 + 8 * c) = o; }
;     asm volatile("s_waitcnt lgkmcnt(0)" ::: "memory");
	s_waitcnt lgkmcnt(0)
	ds_read2_b32 v[36:37], v40 offset1:8
	ds_read2_b32 v[50:51], v40 offset0:33 offset1:41
	ds_read2_b32 v[52:53], v40 offset0:66 offset1:74
	ds_read2_b32 v[54:55], v40 offset0:99 offset1:107
	ds_read2_b32 v[56:57], v40 offset0:132 offset1:140
	s_waitcnt lgkmcnt(4)
	v_bfe_u32 v0, v36, 16, 1
	v_add3_u32 v0, v36, v0, s80
	s_waitcnt lgkmcnt(3)
	v_bfe_u32 v7, v50, 16, 1
	v_lshrrev_b32_e32 v0, 16, v0
	v_add3_u32 v7, v50, v7, s80
	s_mov_b32 s85, 0xffff0000
	ds_read2_b32 v[58:59], v40 offset0:165 offset1:173
	v_and_or_b32 v44, v7, s85, v0
	s_waitcnt lgkmcnt(3)
	v_bfe_u32 v0, v52, 16, 1
	v_add3_u32 v0, v52, v0, s80
	s_waitcnt lgkmcnt(2)
	v_bfe_u32 v7, v54, 16, 1
	ds_read2_b32 v[60:61], v40 offset0:198 offset1:206
	v_lshrrev_b32_e32 v0, 16, v0
	v_add3_u32 v7, v54, v7, s80
	ds_read2_b32 v[62:63], v40 offset0:231 offset1:239
	v_and_or_b32 v45, v7, s85, v0
	s_waitcnt lgkmcnt(3)
	v_bfe_u32 v0, v56, 16, 1
	v_add3_u32 v0, v56, v0, s80
	s_waitcnt lgkmcnt(2)
	v_bfe_u32 v7, v58, 16, 1
	v_lshrrev_b32_e32 v0, 16, v0
	v_add3_u32 v7, v58, v7, s80
	v_and_or_b32 v46, v7, s85, v0
	s_waitcnt lgkmcnt(1)
	v_bfe_u32 v0, v60, 16, 1
	v_add3_u32 v0, v60, v0, s80
	s_waitcnt lgkmcnt(0)
	v_bfe_u32 v7, v62, 16, 1
	s_and_b32 s4, 0xffff, s4
	s_and_b32 s1, 0xffff, s1
	v_lshrrev_b32_e32 v0, 16, v0
	v_add3_u32 v7, v62, v7, s80
	s_lshl_b32 s88, s1, 1
	v_and_or_b32 v47, v7, s85, v0
	v_or_b32_e32 v0, s4, v39
	v_lshl_add_u64 v[48:49], v[28:29], 0, s[88:89]
	v_lshlrev_b32_e32 v0, 11, v0
	v_lshl_add_u64 v[64:65], v[48:49], 0, v[0:1]
	v_bfe_u32 v0, v37, 16, 1
	v_add3_u32 v0, v37, v0, s80
	v_bfe_u32 v7, v51, 16, 1
	v_lshrrev_b32_e32 v0, 16, v0
	v_add3_u32 v7, v51, v7, s80
	global_store_dwordx4 v[64:65], v[44:47], off
	ds_read2_b32 v[36:37], v40 offset0:16 offset1:24
	v_readlane_b32 s81, v254, 55
	v_and_or_b32 v44, v7, s85, v0
	v_bfe_u32 v0, v53, 16, 1
	v_add3_u32 v0, v53, v0, s80
	v_bfe_u32 v7, v55, 16, 1
	v_lshrrev_b32_e32 v0, 16, v0
	v_add3_u32 v7, v55, v7, s80
	v_and_or_b32 v45, v7, s85, v0
	v_bfe_u32 v0, v57, 16, 1
	v_add3_u32 v0, v57, v0, s80
	v_bfe_u32 v7, v59, 16, 1
	v_lshrrev_b32_e32 v0, 16, v0
	v_add3_u32 v7, v59, v7, s80
	v_and_or_b32 v46, v7, s85, v0
	v_bfe_u32 v0, v61, 16, 1
	v_add3_u32 v0, v61, v0, s80
	v_bfe_u32 v7, v63, 16, 1
	v_lshrrev_b32_e32 v0, 16, v0
	v_add3_u32 v7, v63, v7, s80
	v_and_or_b32 v47, v7, s85, v0
	v_or_b32_e32 v0, s4, v41
	v_lshlrev_b32_e32 v0, 11, v0
	v_lshl_add_u64 v[50:51], v[48:49], 0, v[0:1]
	global_store_dwordx4 v[50:51], v[44:47], off
	ds_read2_b32 v[50:51], v40 offset0:49 offset1:57
	ds_read2_b32 v[52:53], v40 offset0:82 offset1:90
	ds_read2_b32 v[54:55], v40 offset0:115 offset1:123
	s_waitcnt lgkmcnt(3)
	v_bfe_u32 v0, v36, 16, 1
	v_add3_u32 v0, v36, v0, s80
	s_waitcnt lgkmcnt(2)
	v_bfe_u32 v7, v50, 16, 1
	ds_read2_b32 v[56:57], v40 offset0:148 offset1:156
	v_lshrrev_b32_e32 v0, 16, v0
	v_add3_u32 v7, v50, v7, s80
	ds_read2_b32 v[58:59], v40 offset0:181 offset1:189
	v_and_or_b32 v44, v7, s85, v0
	s_waitcnt lgkmcnt(3)
	v_bfe_u32 v0, v52, 16, 1
	v_add3_u32 v0, v52, v0, s80
	s_waitcnt lgkmcnt(2)
	v_bfe_u32 v7, v54, 16, 1
	ds_read2_b32 v[60:61], v40 offset0:214 offset1:222
	v_lshrrev_b32_e32 v0, 16, v0
	v_add3_u32 v7, v54, v7, s80
	ds_read2_b32 v[62:63], v40 offset0:247 offset1:255
	v_and_or_b32 v45, v7, s85, v0
	s_waitcnt lgkmcnt(3)
	v_bfe_u32 v0, v56, 16, 1
	v_add3_u32 v0, v56, v0, s80
	s_waitcnt lgkmcnt(2)
	v_bfe_u32 v7, v58, 16, 1
	v_lshrrev_b32_e32 v0, 16, v0
	v_add3_u32 v7, v58, v7, s80
	v_and_or_b32 v46, v7, s85, v0
	s_waitcnt lgkmcnt(1)
	v_bfe_u32 v0, v60, 16, 1
	v_add3_u32 v0, v60, v0, s80
	s_waitcnt lgkmcnt(0)
	v_bfe_u32 v7, v62, 16, 1
	v_lshrrev_b32_e32 v0, 16, v0
	v_add3_u32 v7, v62, v7, s80
	v_and_or_b32 v47, v7, s85, v0
	v_or_b32_e32 v0, s4, v42
	v_lshlrev_b32_e32 v0, 11, v0
	v_lshl_add_u64 v[64:65], v[48:49], 0, v[0:1]
	v_bfe_u32 v0, v37, 16, 1
	v_add3_u32 v0, v37, v0, s80
	v_bfe_u32 v7, v51, 16, 1
	v_lshrrev_b32_e32 v0, 16, v0
	v_add3_u32 v7, v51, v7, s80
	global_store_dwordx4 v[64:65], v[44:47], off
	s_nop 1
	v_and_or_b32 v44, v7, s85, v0
	v_bfe_u32 v0, v53, 16, 1
	v_add3_u32 v0, v53, v0, s80
	v_bfe_u32 v7, v55, 16, 1
	v_lshrrev_b32_e32 v0, 16, v0
	v_add3_u32 v7, v55, v7, s80
	v_and_or_b32 v45, v7, s85, v0
	v_bfe_u32 v0, v57, 16, 1
	v_add3_u32 v0, v57, v0, s80
	v_bfe_u32 v7, v59, 16, 1
	v_lshrrev_b32_e32 v0, 16, v0
	v_add3_u32 v7, v59, v7, s80
	v_and_or_b32 v46, v7, s85, v0
	v_bfe_u32 v0, v61, 16, 1
	v_add3_u32 v0, v61, v0, s80
	v_bfe_u32 v7, v63, 16, 1
	v_lshrrev_b32_e32 v0, 16, v0
	v_add3_u32 v7, v63, v7, s80
	v_and_or_b32 v47, v7, s85, v0
	v_or_b32_e32 v0, s4, v43
	v_lshlrev_b32_e32 v0, 11, v0
	v_lshl_add_u64 v[36:37], v[48:49], 0, v[0:1]
	global_store_dwordx4 v[36:37], v[44:47], off
.LBB0_68:
	s_cbranch_execnz .LBB0_28
	s_branch .LBB0_70

; __device__ __forceinline__ void tr_item(const float* W, int ldw, int c0, bf16* WT, int ldk, int r0, int nblk, int item, LAS float* scr, int lane) {
;     const int kb = item / nblk, nb = item % nblk, k0 = 64 * kb, n0 = 32 * nb;
; #pragma unroll 8
;     for (int i = 0; i < 32; ++i) { const int kk = 2 * i + (lane >> 5); scr[kk * 33 + (lane & 31)] = W[(size_t)(k0 + kk) * ldw + c0 + n0 + (lane & 31)]; }
.LBB0_71:
	s_lshl_b32 s31, s1, 1
	s_lshl_b32 s34, s4, 1
	v_or_b32_e32 v35, s31, v7
	v_or_b32_e32 v38, s34, v0
	s_add_i32 s35, s31, 4
	s_add_i32 s37, s34, 4
	s_add_i32 s38, s31, 8
	s_add_i32 s39, s34, 8
	s_add_i32 s40, s31, 12
	s_add_i32 s41, s34, 12
	s_add_i32 s42, s31, 16
	s_add_i32 s43, s34, 16
	s_add_i32 s44, s31, 20
	s_add_i32 s45, s34, 20
	s_add_i32 s46, s31, 24
	s_add_i32 s47, s34, 24
	s_add_i32 s48, s31, 28
	s_add_i32 s49, s34, 28
	v_mad_i64_i32 v[44:45], s[10:11], v38, s83, v[36:37]
	v_mad_i64_i32 v[46:47], s[10:11], v35, s83, v[36:37]
	v_or_b32_e32 v35, s35, v7
	v_or_b32_e32 v38, s37, v0
	v_or_b32_e32 v54, s38, v7
	v_or_b32_e32 v52, s39, v0
	v_or_b32_e32 v58, s40, v7
	v_or_b32_e32 v56, s41, v0
	v_or_b32_e32 v62, s42, v7
	v_or_b32_e32 v60, s43, v0
	v_or_b32_e32 v66, s44, v7
	v_or_b32_e32 v64, s45, v0
	v_or_b32_e32 v70, s46, v7
	v_or_b32_e32 v68, s47, v0
	v_or_b32_e32 v74, s48, v7
	v_or_b32_e32 v72, s49, v0
	v_mad_i64_i32 v[48:49], s[10:11], v38, s83, v[36:37]
	v_mad_i64_i32 v[50:51], s[10:11], v35, s83, v[36:37]
	v_mad_i64_i32 v[52:53], s[10:11], v52, s83, v[36:37]
	v_mad_i64_i32 v[54:55], s[10:11], v54, s83, v[36:37]
	v_mad_i64_i32 v[56:57], s[10:11], v56, s83, v[36:37]
	v_mad_i64_i32 v[58:59], s[10:11], v58, s83, v[36:37]
	v_mad_i64_i32 v[60:61], s[10:11], v60, s83, v[36:37]
	v_mad_i64_i32 v[62:63], s[10:11], v62, s83, v[36:37]
	v_mad_i64_i32 v[64:65], s[10:11], v64, s83, v[36:37]
	v_mad_i64_i32 v[66:67], s[10:11], v66, s83, v[36:37]
	v_mad_i64_i32 v[68:69], s[10:11], v68, s83, v[36:37]
	v_mad_i64_i32 v[70:71], s[10:11], v70, s83, v[36:37]
	v_mad_i64_i32 v[72:73], s[10:11], v72, s83, v[36:37]
	v_mad_i64_i32 v[74:75], s[10:11], v74, s83, v[36:37]
	global_load_dword v35, v[44:45], off
	global_load_dword v38, v[46:47], off
	global_load_dword v76, v[48:49], off
	global_load_dword v77, v[50:51], off
	global_load_dword v78, v[52:53], off
	global_load_dword v79, v[54:55], off
	global_load_dword v80, v[56:57], off
	global_load_dword v81, v[58:59], off
	global_load_dword v82, v[60:61], off
	global_load_dword v83, v[62:63], off
	global_load_dword v84, v[64:65], off
	global_load_dword v85, v[66:67], off
	global_load_dword v86, v[68:69], off
	global_load_dword v87, v[70:71], off
	global_load_dword v88, v[72:73], off
	global_load_dword v89, v[74:75], off
	v_or_b32_e32 v46, s31, v3
	v_or_b32_e32 v44, s34, v2
	s_add_i32 s4, s4, 16
	s_add_i32 s1, s1, 16
	s_add_i32 s21, s21, -16
	v_mad_u64_u32 v[44:45], s[10:11], v44, s27, v[6:7]
	v_mad_u64_u32 v[46:47], s[10:11], v46, s27, v[6:7]
	v_or_b32_e32 v45, s35, v3
	v_or_b32_e32 v47, s37, v2
	v_or_b32_e32 v54, s38, v3
	v_or_b32_e32 v52, s39, v2
	v_or_b32_e32 v58, s40, v3
	v_or_b32_e32 v56, s41, v2
	v_or_b32_e32 v62, s42, v3
	v_or_b32_e32 v60, s43, v2
	v_or_b32_e32 v66, s44, v3
	v_or_b32_e32 v64, s45, v2
	v_or_b32_e32 v70, s46, v3
	v_or_b32_e32 v68, s47, v2
	v_or_b32_e32 v74, s48, v3
	v_or_b32_e32 v72, s49, v2
	s_cmp_lg_u32 s21, 0
	v_mad_u64_u32 v[48:49], s[10:11], v47, s27, v[6:7]
	v_mad_u64_u32 v[50:51], s[10:11], v45, s27, v[6:7]
	v_mad_u64_u32 v[52:53], s[10:11], v52, s27, v[6:7]
	v_mad_u64_u32 v[54:55], s[10:11], v54, s27, v[6:7]
	v_mad_u64_u32 v[56:57], s[10:11], v56, s27, v[6:7]
	v_mad_u64_u32 v[58:59], s[10:11], v58, s27, v[6:7]
	v_mad_u64_u32 v[60:61], s[10:11], v60, s27, v[6:7]
	v_mad_u64_u32 v[62:63], s[10:11], v62, s27, v[6:7]
	v_mad_u64_u32 v[64:65], s[10:11], v64, s27, v[6:7]
	v_mad_u64_u32 v[66:67], s[10:11], v66, s27, v[6:7]
	v_mad_u64_u32 v[68:69], s[10:11], v68, s27, v[6:7]
	v_mad_u64_u32 v[70:71], s[10:11], v70, s27, v[6:7]
	v_mad_u64_u32 v[72:73], s[10:11], v72, s27, v[6:7]
	v_mad_u64_u32 v[74:75], s[10:11], v74, s27, v[6:7]
	s_waitcnt vmcnt(15)
	ds_write_b32 v44, v35
	s_waitcnt vmcnt(14)
	ds_write_b32 v46, v38
	s_waitcnt vmcnt(13)
	ds_write_b32 v48, v76
	s_waitcnt vmcnt(12)
	ds_write_b32 v50, v77
	s_waitcnt vmcnt(11)
	ds_write_b32 v52, v78
	s_waitcnt vmcnt(10)
	ds_write_b32 v54, v79
	s_waitcnt vmcnt(9)
	ds_write_b32 v56, v80
	s_waitcnt vmcnt(8)
	ds_write_b32 v58, v81
	s_waitcnt vmcnt(7)
	ds_write_b32 v60, v82
	s_waitcnt vmcnt(6)
	ds_write_b32 v62, v83
	s_waitcnt vmcnt(5)
	ds_write_b32 v64, v84
	s_waitcnt vmcnt(4)
	ds_write_b32 v66, v85
	s_waitcnt vmcnt(3)
	ds_write_b32 v68, v86
	s_waitcnt vmcnt(2)
	ds_write_b32 v70, v87
	s_waitcnt vmcnt(1)
	ds_write_b32 v72, v88
	s_waitcnt vmcnt(0)
	ds_write_b32 v74, v89
	s_cbranch_scc1 .LBB0_71
; #define LAS __attribute__((address_space(3)))
; __device__ __forceinline__ unsigned pk2(float lo, float hi) { return f2bf(lo) | (f2bf(hi) << 16); }
; __device__ __forceinline__ void tr_item(const float* W, int ldw, int c0, bf16* WT, int ldk, int r0, int nblk, int item, LAS float* scr, int lane) {
;     ...
;     asm volatile("s_waitcnt lgkmcnt(0)" ::: "memory");
;     const int c = lane & 7;
; #pragma unroll
;     for (int j = 0; j < 4; ++j) { const int n = (lane >> 3) + 8 * j; const LAS float* s = scr + (8 * c) * 33 + n;
;         v4u o; o.x = pk2(s[0 * 33], s[1 * 33]); o.y = pk2(s[2 * 33], s[3 * 33]); o.z = pk2(s[4 * 33], s[5 * 33]); o.w = pk2(s[6 * 33], s[7 * 33]);
;         *(v4u*)(WT + (size_t)(r0 + n0 + n) * ldk + k0 + 8 * c) = o; }
;     asm volatile("s_waitcnt lgkmcnt(0)" ::: "memory");
	s_waitcnt lgkmcnt(0)
	ds_read2_b32 v[36:37], v40 offset1:8
	ds_read2_b32 v[50:51], v40 offset0:33 offset1:41
	ds_read2_b32 v[52:53], v40 offset0:66 offset1:74
	ds_read2_b32 v[54:55], v40 offset0:99 offset1:107
	ds_read2_b32 v[56:57], v40 offset0:132 offset1:140
	ds_read2_b32 v[58:59], v40 offset0:165 offset1:173
	s_waitcnt lgkmcnt(5)
	v_bfe_u32 v0, v36, 16, 1
	v_add3_u32 v0, v36, v0, s80
	s_waitcnt lgkmcnt(4)
	v_bfe_u32 v7, v50, 16, 1
	v_lshrrev_b32_e32 v0, 16, v0
	v_add3_u32 v7, v50, v7, s80
	v_and_or_b32 v44, v7, s85, v0
	s_waitcnt lgkmcnt(3)
	v_bfe_u32 v0, v52, 16, 1
	v_add3_u32 v0, v52, v0, s80
	s_waitcnt lgkmcnt(2)
	v_bfe_u32 v7, v54, 16, 1
	ds_read2_b32 v[60:61], v40 offset0:198 offset1:206
	v_lshrrev_b32_e32 v0, 16, v0
	v_add3_u32 v7, v54, v7, s80
	ds_read2_b32 v[62:63], v40 offset0:231 offset1:239
	v_and_or_b32 v45, v7, s85, v0
	s_waitcnt lgkmcnt(3)
	v_bfe_u32 v0, v56, 16, 1
	v_add3_u32 v0, v56, v0, s80
	s_waitcnt lgkmcnt(2)
	v_bfe_u32 v7, v58, 16, 1
	v_lshrrev_b32_e32 v0, 16, v0
	v_add3_u32 v7, v58, v7, s80
	v_and_or_b32 v46, v7, s85, v0
	s_waitcnt lgkmcnt(1)
	v_bfe_u32 v0, v60, 16, 1
	v_add3_u32 v0, v60, v0, s80
	s_waitcnt lgkmcnt(0)
	v_bfe_u32 v7, v62, 16, 1
	v_lshrrev_b32_e32 v0, 16, v0
	v_add3_u32 v7, v62, v7, s80
	v_or_b32_e32 v64, s20, v39
	s_ashr_i32 s37, s36, 31
	v_and_or_b32 v47, v7, s85, v0
	v_ashrrev_i32_e32 v65, 31, v64
	v_bfe_u32 v0, v37, 16, 1
	v_lshl_add_u64 v[48:49], s[36:37], 1, v[30:31]
	v_lshlrev_b64 v[64:65], 11, v[64:65]
	v_add3_u32 v0, v37, v0, s80
	v_bfe_u32 v7, v51, 16, 1
	v_lshl_add_u64 v[64:65], v[48:49], 0, v[64:65]
	v_lshrrev_b32_e32 v0, 16, v0
	v_add3_u32 v7, v51, v7, s80
	global_store_dwordx4 v[64:65], v[44:47], off
	v_or_b32_e32 v36, s20, v41
	v_ashrrev_i32_e32 v37, 31, v36
	v_and_or_b32 v44, v7, s85, v0
	v_bfe_u32 v0, v53, 16, 1
	v_add3_u32 v0, v53, v0, s80
	v_bfe_u32 v7, v55, 16, 1
	v_lshrrev_b32_e32 v0, 16, v0
	v_add3_u32 v7, v55, v7, s80
	v_and_or_b32 v45, v7, s85, v0
	v_bfe_u32 v0, v57, 16, 1
	v_add3_u32 v0, v57, v0, s80
	v_bfe_u32 v7, v59, 16, 1
	v_lshrrev_b32_e32 v0, 16, v0
	v_add3_u32 v7, v59, v7, s80
	v_and_or_b32 v46, v7, s85, v0
	v_bfe_u32 v0, v61, 16, 1
	v_add3_u32 v0, v61, v0, s80
	v_bfe_u32 v7, v63, 16, 1
	v_lshrrev_b32_e32 v0, 16, v0
	v_add3_u32 v7, v63, v7, s80
	v_lshlrev_b64 v[36:37], 11, v[36:37]
	v_and_or_b32 v47, v7, s85, v0
	ds_read2_b32 v[50:51], v40 offset0:16 offset1:24
	v_lshl_add_u64 v[36:37], v[48:49], 0, v[36:37]
	global_store_dwordx4 v[36:37], v[44:47], off
	ds_read2_b32 v[36:37], v40 offset0:49 offset1:57
	ds_read2_b32 v[52:53], v40 offset0:82 offset1:90
	ds_read2_b32 v[54:55], v40 offset0:115 offset1:123
	s_waitcnt lgkmcnt(3)
	v_bfe_u32 v0, v50, 16, 1
	v_add3_u32 v0, v50, v0, s80
	s_waitcnt lgkmcnt(2)
	v_bfe_u32 v7, v36, 16, 1
	ds_read2_b32 v[56:57], v40 offset0:148 offset1:156
	v_lshrrev_b32_e32 v0, 16, v0
	v_add3_u32 v7, v36, v7, s80
	ds_read2_b32 v[58:59], v40 offset0:181 offset1:189
	v_and_or_b32 v44, v7, s85, v0
	s_waitcnt lgkmcnt(3)
	v_bfe_u32 v0, v52, 16, 1
	v_add3_u32 v0, v52, v0, s80
	s_waitcnt lgkmcnt(2)
	v_bfe_u32 v7, v54, 16, 1
	ds_read2_b32 v[60:61], v40 offset0:214 offset1:222
	v_lshrrev_b32_e32 v0, 16, v0
	v_add3_u32 v7, v54, v7, s80
	ds_read2_b32 v[62:63], v40 offset0:247 offset1:255
	v_and_or_b32 v45, v7, s85, v0
	s_waitcnt lgkmcnt(3)
	v_bfe_u32 v0, v56, 16, 1
	v_add3_u32 v0, v56, v0, s80
	s_waitcnt lgkmcnt(2)
	v_bfe_u32 v7, v58, 16, 1
	v_lshrrev_b32_e32 v0, 16, v0
	v_add3_u32 v7, v58, v7, s80
	v_and_or_b32 v46, v7, s85, v0
	s_waitcnt lgkmcnt(1)
	v_bfe_u32 v0, v60, 16, 1
	v_add3_u32 v0, v60, v0, s80
	s_waitcnt lgkmcnt(0)
	v_bfe_u32 v7, v62, 16, 1
	v_lshrrev_b32_e32 v0, 16, v0
	v_add3_u32 v7, v62, v7, s80
	v_or_b32_e32 v64, s20, v42
	v_and_or_b32 v47, v7, s85, v0
	v_ashrrev_i32_e32 v65, 31, v64
	v_bfe_u32 v0, v51, 16, 1
	v_lshlrev_b64 v[64:65], 11, v[64:65]
	v_add3_u32 v0, v51, v0, s80
	v_bfe_u32 v7, v37, 16, 1
	v_lshl_add_u64 v[64:65], v[48:49], 0, v[64:65]
	v_lshrrev_b32_e32 v0, 16, v0
	v_add3_u32 v7, v37, v7, s80
	global_store_dwordx4 v[64:65], v[44:47], off
	v_or_b32_e32 v36, s20, v43
	v_ashrrev_i32_e32 v37, 31, v36
	v_and_or_b32 v44, v7, s85, v0
	v_bfe_u32 v0, v53, 16, 1
	v_add3_u32 v0, v53, v0, s80
	v_bfe_u32 v7, v55, 16, 1
	v_lshrrev_b32_e32 v0, 16, v0
	v_add3_u32 v7, v55, v7, s80
	v_and_or_b32 v45, v7, s85, v0
	v_bfe_u32 v0, v57, 16, 1
	v_add3_u32 v0, v57, v0, s80
	v_bfe_u32 v7, v59, 16, 1
	v_lshrrev_b32_e32 v0, 16, v0
	v_add3_u32 v7, v59, v7, s80
	v_and_or_b32 v46, v7, s85, v0
	v_bfe_u32 v0, v61, 16, 1
	v_add3_u32 v0, v61, v0, s80
	v_bfe_u32 v7, v63, 16, 1
	v_lshrrev_b32_e32 v0, 16, v0
	v_add3_u32 v7, v63, v7, s80
	v_lshlrev_b64 v[36:37], 11, v[36:37]
	v_and_or_b32 v47, v7, s85, v0
	v_lshl_add_u64 v[36:37], v[48:49], 0, v[36:37]
	global_store_dwordx4 v[36:37], v[44:47], off
	s_branch .LBB0_28

; #define PG8_STAGE(bufoff, gbase, voff) do { _Pragma("unroll") for (int _i = 0; _i < 2; ++_i) \
;         __builtin_amdgcn_global_load_lds((const unsigned*)((const char*)(gbase) + (voff)[_i]), (PG8_LAS unsigned*)(lds + (bufoff) + ldsw + _i * 8192), 16, 0, 0); } while (0)
; #define PG8_LDA(dst, b, h) do { _Pragma("unroll") for (int m = 0; m < 4; ++m) _Pragma("unroll") for (int k = 0; k < 2; ++k) dst[m][k] = *(const PG8_LAS bf16x8*)(lds + PG8_SA(b, h) + aoff + m * 2048 + k * 1024); } while (0)
; #define PG8_LDB(dst, b, h) do { _Pragma("unroll") for (int n = 0; n < 2; ++n) _Pragma("unroll") for (int k = 0; k < 2; ++k) dst[n][k] = *(const PG8_LAS bf16x8*)(lds + PG8_SB(b, h) + boff + n * 2048 + k * 1024); } while (0)
; #define PG8_MMA(ai, bj, At, Bt) do { __builtin_amdgcn_s_setprio(1); _Pragma("unroll") for (int m = 0; m < 4; ++m) _Pragma("unroll") for (int n = 0; n < 2; ++n) _Pragma("unroll") for (int k = 0; k < 2; ++k) \
;         acc[ai][bj][m][n] = __builtin_amdgcn_mfma_f32_16x16x32_bf16(Bt[n][k], At[m][k], acc[ai][bj][m][n], 0, 0, 0); __builtin_amdgcn_s_setprio(0); } while (0)
; #define PG8_WAIT_V(n) asm volatile("s_waitcnt vmcnt(" #n ")" ::: "memory")
; #define PG8_WAIT_L(n) asm volatile("s_waitcnt lgkmcnt(" #n ")" ::: "memory")
; #define PG8_BAR __builtin_amdgcn_s_barrier()
; #define PG8_SCHED __builtin_amdgcn_sched_barrier(0)
; template <class Epi, class Sched, bool ALIGN_EPI = false, bool SP2 = false>
; __device__ __forceinline__ void gemm_phase(PG8_LAS unsigned char* lds, const Gemm g, const Sched& S, const Epi& E) {
;     ...
;             PG8_LDB(B0, 0, 0); PG8_LDB(B1, 0, 1); PG8_SCHED; PG8_LDA(At, 0, 0); PG8_STAGE(PG8_SA(1, 1), a1 + hstepA, voffA);
;             PG8_WAIT_V(8); PG8_WAIT_L(0); PG8_BAR; PG8_MMA(0, 0, At, B0); PG8_MMA(0, 1, At, B1); PG8_BAR; PG8_SCHED;
;             PG8_LDA(At, 0, 1); PG8_STAGE(PG8_SB(0, 0), b2, voffB); PG8_STAGE(PG8_SB(0, 1), b2 + hstepB, voffB); PG8_STAGE(PG8_SA(0, 0), a2, voffA);
;             PG8_WAIT_V(8); PG8_WAIT_L(0); PG8_BAR; PG8_MMA(1, 0, At, B0); PG8_MMA(1, 1, At, B1); PG8_BAR; PG8_SCHED;
.Lgk_146:
	ds_read_b128 v[164:167], v130
	ds_read_b128 v[168:171], v130 offset:1024
	ds_read_b128 v[186:189], v130 offset:2048
	ds_read_b128 v[190:193], v130 offset:3072
	v_add_u32_e32 v130, s81, v161
	ds_read_b128 v[198:201], v130
	ds_read_b128 v[202:205], v130 offset:1024
	ds_read_b128 v[206:209], v130 offset:2048
	ds_read_b128 v[210:213], v130 offset:3072
	v_lshl_add_u64 v[172:173], s[46:47], 0, v[156:157]
	s_add_i32 m0, s9, 0xc000
	ds_read_b128 v[214:217], v163
	ds_read_b128 v[218:221], v163 offset:1024
	ds_read_b128 v[222:225], v163 offset:2048
	ds_read_b128 v[226:229], v163 offset:3072
	ds_read_b128 v[230:233], v163 offset:4096
	ds_read_b128 v[234:237], v163 offset:5120
	ds_read_b128 v[238:241], v163 offset:6144
	ds_read_b128 v[242:245], v163 offset:7168
	global_load_lds_dwordx4 v[172:173], off
	v_lshl_add_u64 v[172:173], s[46:47], 0, v[158:159]
	s_add_i32 m0, s9, 0xe000
	s_nop 0
	global_load_lds_dwordx4 v[172:173], off
	s_waitcnt vmcnt(8)
	s_waitcnt lgkmcnt(0)
	s_barrier
	v_mfma_f32_16x16x32_bf16 v[126:129], v[164:167], v[214:217], v[126:129]
	v_mfma_f32_16x16x32_bf16 v[122:125], v[186:189], v[214:217], v[122:125]
	v_mfma_f32_16x16x32_bf16 v[118:121], v[164:167], v[222:225], v[118:121]
	v_mfma_f32_16x16x32_bf16 v[114:117], v[186:189], v[222:225], v[114:117]
	v_mfma_f32_16x16x32_bf16 v[102:105], v[164:167], v[230:233], v[102:105]
	v_mfma_f32_16x16x32_bf16 v[98:101], v[186:189], v[230:233], v[98:101]
	v_mfma_f32_16x16x32_bf16 v[86:89], v[164:167], v[238:241], v[86:89]
	v_mfma_f32_16x16x32_bf16 v[82:85], v[186:189], v[238:241], v[82:85]
	v_mfma_f32_16x16x32_bf16 v[126:129], v[168:171], v[218:221], v[126:129]
	v_mfma_f32_16x16x32_bf16 v[122:125], v[190:193], v[218:221], v[122:125]
	v_mfma_f32_16x16x32_bf16 v[118:121], v[168:171], v[226:229], v[118:121]
	v_mfma_f32_16x16x32_bf16 v[114:117], v[190:193], v[226:229], v[114:117]
	v_mfma_f32_16x16x32_bf16 v[102:105], v[168:171], v[234:237], v[102:105]
	v_mfma_f32_16x16x32_bf16 v[98:101], v[190:193], v[234:237], v[98:101]
	v_mfma_f32_16x16x32_bf16 v[86:89], v[168:171], v[242:245], v[86:89]
	v_mfma_f32_16x16x32_bf16 v[82:85], v[190:193], v[242:245], v[82:85]
	v_mfma_f32_16x16x32_bf16 v[110:113], v[198:201], v[214:217], v[110:113]
	v_mfma_f32_16x16x32_bf16 v[106:109], v[206:209], v[214:217], v[106:109]
	v_mfma_f32_16x16x32_bf16 v[94:97], v[198:201], v[222:225], v[94:97]
	v_mfma_f32_16x16x32_bf16 v[90:93], v[206:209], v[222:225], v[90:93]
	v_mfma_f32_16x16x32_bf16 v[78:81], v[198:201], v[230:233], v[78:81]
	v_mfma_f32_16x16x32_bf16 v[74:77], v[206:209], v[230:233], v[74:77]
	v_mfma_f32_16x16x32_bf16 v[70:73], v[198:201], v[238:241], v[70:73]
	v_mfma_f32_16x16x32_bf16 v[66:69], v[206:209], v[238:241], v[66:69]
	v_mfma_f32_16x16x32_bf16 v[110:113], v[202:205], v[218:221], v[110:113]
	v_mfma_f32_16x16x32_bf16 v[106:109], v[210:213], v[218:221], v[106:109]
	v_mfma_f32_16x16x32_bf16 v[94:97], v[202:205], v[226:229], v[94:97]
	v_mfma_f32_16x16x32_bf16 v[90:93], v[210:213], v[226:229], v[90:93]
	v_mfma_f32_16x16x32_bf16 v[78:81], v[202:205], v[234:237], v[78:81]
	v_mfma_f32_16x16x32_bf16 v[74:77], v[210:213], v[234:237], v[74:77]
	v_mfma_f32_16x16x32_bf16 v[70:73], v[202:205], v[242:245], v[70:73]
	v_mfma_f32_16x16x32_bf16 v[66:69], v[210:213], v[242:245], v[66:69]
	s_barrier
	s_add_i32 s10, s69, s8
	v_lshl_add_u64 v[172:173], s[48:49], 0, v[0:1]
	s_mov_b32 m0, s10
	ds_read_b128 v[214:217], v163 offset:16384
	ds_read_b128 v[218:221], v163 offset:17408
	ds_read_b128 v[222:225], v163 offset:18432
	ds_read_b128 v[226:229], v163 offset:19456
	ds_read_b128 v[230:233], v163 offset:20480
	ds_read_b128 v[234:237], v163 offset:21504
	ds_read_b128 v[238:241], v163 offset:22528
	ds_read_b128 v[242:245], v163 offset:23552
	global_load_lds_dwordx4 v[172:173], off
	s_add_i32 m0, s10, 0x2000
	s_add_u32 s10, s48, 0x40000
	v_lshl_add_u64 v[246:247], s[48:49], 0, v[150:151]
	s_addc_u32 s11, s49, 0
	s_add_i32 s69, s81, s8
	global_load_lds_dwordx4 v[246:247], off
	v_lshl_add_u64 v[248:249], s[10:11], 0, v[0:1]
	s_mov_b32 m0, s69
	v_lshl_add_u64 v[130:131], s[50:51], 0, v[152:153]
	global_load_lds_dwordx4 v[248:249], off
	v_lshl_add_u64 v[248:249], s[10:11], 0, v[150:151]
	s_add_i32 m0, s69, 0x2000
	s_nop 0
	global_load_lds_dwordx4 v[248:249], off
	v_lshl_add_u64 v[248:249], s[50:51], 0, v[154:155]
	s_mov_b32 m0, s9
	s_nop 0
	global_load_lds_dwordx4 v[248:249], off
	s_mov_b32 m0, s30
	s_nop 0
	global_load_lds_dwordx4 v[130:131], off
	s_waitcnt vmcnt(8)
	s_waitcnt lgkmcnt(0)
	s_barrier
	v_mfma_f32_16x16x32_bf16 v[62:65], v[164:167], v[214:217], v[62:65]
	v_mfma_f32_16x16x32_bf16 v[58:61], v[186:189], v[214:217], v[58:61]
	v_mfma_f32_16x16x32_bf16 v[54:57], v[164:167], v[222:225], v[54:57]
	v_mfma_f32_16x16x32_bf16 v[50:53], v[186:189], v[222:225], v[50:53]
	v_mfma_f32_16x16x32_bf16 v[38:41], v[164:167], v[230:233], v[38:41]
	v_mfma_f32_16x16x32_bf16 v[34:37], v[186:189], v[230:233], v[34:37]
	v_mfma_f32_16x16x32_bf16 v[22:25], v[164:167], v[238:241], v[22:25]
	v_mfma_f32_16x16x32_bf16 v[18:21], v[186:189], v[238:241], v[18:21]
	v_mfma_f32_16x16x32_bf16 v[62:65], v[168:171], v[218:221], v[62:65]
	v_mfma_f32_16x16x32_bf16 v[58:61], v[190:193], v[218:221], v[58:61]
	v_mfma_f32_16x16x32_bf16 v[54:57], v[168:171], v[226:229], v[54:57]
	v_mfma_f32_16x16x32_bf16 v[50:53], v[190:193], v[226:229], v[50:53]
	v_mfma_f32_16x16x32_bf16 v[38:41], v[168:171], v[234:237], v[38:41]
	v_mfma_f32_16x16x32_bf16 v[34:37], v[190:193], v[234:237], v[34:37]
	v_mfma_f32_16x16x32_bf16 v[22:25], v[168:171], v[242:245], v[22:25]
	v_mfma_f32_16x16x32_bf16 v[18:21], v[190:193], v[242:245], v[18:21]
	v_mfma_f32_16x16x32_bf16 v[46:49], v[198:201], v[214:217], v[46:49]
	v_mfma_f32_16x16x32_bf16 v[42:45], v[206:209], v[214:217], v[42:45]
	v_mfma_f32_16x16x32_bf16 v[30:33], v[198:201], v[222:225], v[30:33]
	v_mfma_f32_16x16x32_bf16 v[26:29], v[206:209], v[222:225], v[26:29]
	v_mfma_f32_16x16x32_bf16 v[14:17], v[198:201], v[230:233], v[14:17]
	v_mfma_f32_16x16x32_bf16 v[10:13], v[206:209], v[230:233], v[10:13]
	v_mfma_f32_16x16x32_bf16 v[6:9], v[198:201], v[238:241], v[6:9]
	v_mfma_f32_16x16x32_bf16 v[2:5], v[206:209], v[238:241], v[2:5]
	v_mfma_f32_16x16x32_bf16 v[46:49], v[202:205], v[218:221], v[46:49]
	v_mfma_f32_16x16x32_bf16 v[42:45], v[210:213], v[218:221], v[42:45]
	v_mfma_f32_16x16x32_bf16 v[30:33], v[202:205], v[226:229], v[30:33]
	v_mfma_f32_16x16x32_bf16 v[26:29], v[210:213], v[226:229], v[26:29]
	v_mfma_f32_16x16x32_bf16 v[14:17], v[202:205], v[234:237], v[14:17]
	v_mfma_f32_16x16x32_bf16 v[10:13], v[210:213], v[234:237], v[10:13]
	v_mfma_f32_16x16x32_bf16 v[6:9], v[202:205], v[242:245], v[6:9]
	v_mfma_f32_16x16x32_bf16 v[2:5], v[210:213], v[242:245], v[2:5]
	s_barrier
; #define PG8_STAGE(bufoff, gbase, voff) do { _Pragma("unroll") for (int _i = 0; _i < 2; ++_i) \
;         __builtin_amdgcn_global_load_lds((const unsigned*)((const char*)(gbase) + (voff)[_i]), (PG8_LAS unsigned*)(lds + (bufoff) + ldsw + _i * 8192), 16, 0, 0); } while (0)
; #define PG8_LDA(dst, b, h) do { _Pragma("unroll") for (int m = 0; m < 4; ++m) _Pragma("unroll") for (int k = 0; k < 2; ++k) dst[m][k] = *(const PG8_LAS bf16x8*)(lds + PG8_SA(b, h) + aoff + m * 2048 + k * 1024); } while (0)
; #define PG8_LDB(dst, b, h) do { _Pragma("unroll") for (int n = 0; n < 2; ++n) _Pragma("unroll") for (int k = 0; k < 2; ++k) dst[n][k] = *(const PG8_LAS bf16x8*)(lds + PG8_SB(b, h) + boff + n * 2048 + k * 1024); } while (0)
; #define PG8_MMA(ai, bj, At, Bt) do { __builtin_amdgcn_s_setprio(1); _Pragma("unroll") for (int m = 0; m < 4; ++m) _Pragma("unroll") for (int n = 0; n < 2; ++n) _Pragma("unroll") for (int k = 0; k < 2; ++k) \
;         acc[ai][bj][m][n] = __builtin_amdgcn_mfma_f32_16x16x32_bf16(Bt[n][k], At[m][k], acc[ai][bj][m][n], 0, 0, 0); __builtin_amdgcn_s_setprio(0); } while (0)
; #define PG8_WAIT_V(n) asm volatile("s_waitcnt vmcnt(" #n ")" ::: "memory")
; #define PG8_WAIT_L(n) asm volatile("s_waitcnt lgkmcnt(" #n ")" ::: "memory")
; #define PG8_BAR __builtin_amdgcn_s_barrier()
; #define PG8_SCHED __builtin_amdgcn_sched_barrier(0)
; template <class Epi, class Sched, bool ALIGN_EPI = false, bool SP2 = false>
; __device__ __forceinline__ void gemm_phase(PG8_LAS unsigned char* lds, const Gemm g, const Sched& S, const Epi& E) {
;     ...
;             PG8_LDB(B0, 1, 0); PG8_LDB(B1, 1, 1); PG8_SCHED; PG8_LDA(At, 1, 0); PG8_STAGE(PG8_SA(0, 1), a2 + hstepA, voffA);
;             PG8_WAIT_V(8); PG8_WAIT_L(0); PG8_BAR; PG8_MMA(0, 0, At, B0); PG8_MMA(0, 1, At, B1); PG8_BAR; PG8_SCHED;
	s_add_i32 s69, 0, 0x18000
	v_add_u32_e32 v132, s69, v161
	s_add_i32 s81, 0, 0x1c000
	ds_read_b128 v[164:167], v132
	ds_read_b128 v[168:171], v132 offset:1024
	ds_read_b128 v[186:189], v132 offset:2048
	ds_read_b128 v[190:193], v132 offset:3072
	v_add_u32_e32 v132, s81, v161
	ds_read_b128 v[198:201], v132
	ds_read_b128 v[202:205], v132 offset:1024
	ds_read_b128 v[206:209], v132 offset:2048
	ds_read_b128 v[210:213], v132 offset:3072
	s_add_u32 s10, s50, 0x40000
	s_addc_u32 s11, s51, 0
	s_mov_b32 m0, s31
	v_lshl_add_u64 v[132:133], s[10:11], 0, v[154:155]
	ds_read_b128 v[214:217], v163 offset:32768
	ds_read_b128 v[218:221], v163 offset:33792
	ds_read_b128 v[222:225], v163 offset:34816
	ds_read_b128 v[226:229], v163 offset:35840
	ds_read_b128 v[230:233], v163 offset:36864
	ds_read_b128 v[234:237], v163 offset:37888
	ds_read_b128 v[238:241], v163 offset:38912
	ds_read_b128 v[242:245], v163 offset:39936
	global_load_lds_dwordx4 v[132:133], off
	v_lshl_add_u64 v[132:133], s[10:11], 0, v[152:153]
	s_mov_b32 m0, s34
	s_nop 0
	global_load_lds_dwordx4 v[132:133], off
	s_waitcnt vmcnt(8)
	s_waitcnt lgkmcnt(0)
	s_barrier
	v_mfma_f32_16x16x32_bf16 v[126:129], v[164:167], v[214:217], v[126:129]
	v_mfma_f32_16x16x32_bf16 v[122:125], v[186:189], v[214:217], v[122:125]
	v_mfma_f32_16x16x32_bf16 v[118:121], v[164:167], v[222:225], v[118:121]
	v_mfma_f32_16x16x32_bf16 v[114:117], v[186:189], v[222:225], v[114:117]
	v_mfma_f32_16x16x32_bf16 v[102:105], v[164:167], v[230:233], v[102:105]
	v_mfma_f32_16x16x32_bf16 v[98:101], v[186:189], v[230:233], v[98:101]
	v_mfma_f32_16x16x32_bf16 v[86:89], v[164:167], v[238:241], v[86:89]
	v_mfma_f32_16x16x32_bf16 v[82:85], v[186:189], v[238:241], v[82:85]
	v_mfma_f32_16x16x32_bf16 v[126:129], v[168:171], v[218:221], v[126:129]
	v_mfma_f32_16x16x32_bf16 v[122:125], v[190:193], v[218:221], v[122:125]
	v_mfma_f32_16x16x32_bf16 v[118:121], v[168:171], v[226:229], v[118:121]
	v_mfma_f32_16x16x32_bf16 v[114:117], v[190:193], v[226:229], v[114:117]
	v_mfma_f32_16x16x32_bf16 v[102:105], v[168:171], v[234:237], v[102:105]
	v_mfma_f32_16x16x32_bf16 v[98:101], v[190:193], v[234:237], v[98:101]
	v_mfma_f32_16x16x32_bf16 v[86:89], v[168:171], v[242:245], v[86:89]
	v_mfma_f32_16x16x32_bf16 v[82:85], v[190:193], v[242:245], v[82:85]
	v_mfma_f32_16x16x32_bf16 v[110:113], v[198:201], v[214:217], v[110:113]
	v_mfma_f32_16x16x32_bf16 v[106:109], v[206:209], v[214:217], v[106:109]
	v_mfma_f32_16x16x32_bf16 v[94:97], v[198:201], v[222:225], v[94:97]
	v_mfma_f32_16x16x32_bf16 v[90:93], v[206:209], v[222:225], v[90:93]
	v_mfma_f32_16x16x32_bf16 v[78:81], v[198:201], v[230:233], v[78:81]
	v_mfma_f32_16x16x32_bf16 v[74:77], v[206:209], v[230:233], v[74:77]
	v_mfma_f32_16x16x32_bf16 v[70:73], v[198:201], v[238:241], v[70:73]
	v_mfma_f32_16x16x32_bf16 v[66:69], v[206:209], v[238:241], v[66:69]
	v_mfma_f32_16x16x32_bf16 v[110:113], v[202:205], v[218:221], v[110:113]
	v_mfma_f32_16x16x32_bf16 v[106:109], v[210:213], v[218:221], v[106:109]
	v_mfma_f32_16x16x32_bf16 v[94:97], v[202:205], v[226:229], v[94:97]
	v_mfma_f32_16x16x32_bf16 v[90:93], v[210:213], v[226:229], v[90:93]
	v_mfma_f32_16x16x32_bf16 v[78:81], v[202:205], v[234:237], v[78:81]
	v_mfma_f32_16x16x32_bf16 v[74:77], v[210:213], v[234:237], v[74:77]
	v_mfma_f32_16x16x32_bf16 v[70:73], v[202:205], v[242:245], v[70:73]
	v_mfma_f32_16x16x32_bf16 v[66:69], v[210:213], v[242:245], v[66:69]
	s_barrier
; #define PG8_STAGE(bufoff, gbase, voff) do { _Pragma("unroll") for (int _i = 0; _i < 2; ++_i) \
;         __builtin_amdgcn_global_load_lds((const unsigned*)((const char*)(gbase) + (voff)[_i]), (PG8_LAS unsigned*)(lds + (bufoff) + ldsw + _i * 8192), 16, 0, 0); } while (0)
; #define PG8_LDA(dst, b, h) do { _Pragma("unroll") for (int m = 0; m < 4; ++m) _Pragma("unroll") for (int k = 0; k < 2; ++k) dst[m][k] = *(const PG8_LAS bf16x8*)(lds + PG8_SA(b, h) + aoff + m * 2048 + k * 1024); } while (0)
; #define PG8_MMA(ai, bj, At, Bt) do { __builtin_amdgcn_s_setprio(1); _Pragma("unroll") for (int m = 0; m < 4; ++m) _Pragma("unroll") for (int n = 0; n < 2; ++n) _Pragma("unroll") for (int k = 0; k < 2; ++k) \
;         acc[ai][bj][m][n] = __builtin_amdgcn_mfma_f32_16x16x32_bf16(Bt[n][k], At[m][k], acc[ai][bj][m][n], 0, 0, 0); __builtin_amdgcn_s_setprio(0); } while (0)
; #define PG8_WAIT_V(n) asm volatile("s_waitcnt vmcnt(" #n ")" ::: "memory")
; #define PG8_WAIT_L(n) asm volatile("s_waitcnt lgkmcnt(" #n ")" ::: "memory")
; #define PG8_BAR __builtin_amdgcn_s_barrier()
; #define PG8_SCHED __builtin_amdgcn_sched_barrier(0)
; template <class Epi, class Sched, bool ALIGN_EPI = false, bool SP2 = false>
; __device__ __forceinline__ void gemm_phase(PG8_LAS unsigned char* lds, const Gemm g, const Sched& S, const Epi& E) {
;     ...
;             const bool last = (t == nt - 2);
;             const char* a1 = cA + (size_t)(t + 1) * kstep;
;             const char* a2 = last ? nA : cA + (size_t)(t + 2) * kstep; const char* b2 = last ? nB : cB + (size_t)(t + 2) * kstep;
;             const char* a3 = a2 + kstep; const char* b3 = b2 + kstep;
;             if (last && has_next) S.a_ready(nxt);
;     ...
;             PG8_LDA(At, 1, 1); PG8_STAGE(PG8_SB(1, 0), b3, voffB); PG8_STAGE(PG8_SB(1, 1), b3 + hstepB, voffB); PG8_STAGE(PG8_SA(1, 0), a3, voffA);
;             PG8_WAIT_V(8); PG8_WAIT_L(0); PG8_BAR; PG8_MMA(1, 0, At, B0); PG8_MMA(1, 1, At, B1); PG8_BAR; PG8_SCHED;
	s_add_i32 s10, s69, s8
	v_lshl_add_u64 v[132:133], v[172:173], 0, s[2:3]
	s_mov_b32 m0, s10
	ds_read_b128 v[214:217], v163 offset:49152
	ds_read_b128 v[218:221], v163 offset:50176
	ds_read_b128 v[222:225], v163 offset:51200
	ds_read_b128 v[226:229], v163 offset:52224
	ds_read_b128 v[230:233], v163 offset:53248
	ds_read_b128 v[234:237], v163 offset:54272
	ds_read_b128 v[238:241], v163 offset:55296
	ds_read_b128 v[242:245], v163 offset:56320
	global_load_lds_dwordx4 v[132:133], off
	s_add_i32 m0, s10, 0x2000
	s_add_u32 s10, s48, 0x40080
	v_lshl_add_u64 v[132:133], v[246:247], 0, s[2:3]
	s_addc_u32 s11, s49, 0
	s_add_i32 s48, s81, s8
	global_load_lds_dwordx4 v[132:133], off
	v_lshl_add_u64 v[132:133], s[10:11], 0, v[0:1]
	s_mov_b32 m0, s48
	v_lshl_add_u64 v[130:131], v[130:131], 0, s[2:3]
	global_load_lds_dwordx4 v[132:133], off
	v_lshl_add_u64 v[132:133], s[10:11], 0, v[150:151]
	s_add_i32 m0, s48, 0x2000
	s_nop 0
	global_load_lds_dwordx4 v[132:133], off
	v_lshl_add_u64 v[132:133], v[248:249], 0, s[2:3]
	s_mov_b32 m0, s35
	s_nop 0
	global_load_lds_dwordx4 v[132:133], off
	s_mov_b32 m0, s52
	s_nop 0
	global_load_lds_dwordx4 v[130:131], off
	s_waitcnt vmcnt(8)
	s_waitcnt lgkmcnt(0)
	s_barrier
	v_mfma_f32_16x16x32_bf16 v[62:65], v[164:167], v[214:217], v[62:65]
	v_mfma_f32_16x16x32_bf16 v[58:61], v[186:189], v[214:217], v[58:61]
	s_add_i32 s68, s68, 2
	v_mfma_f32_16x16x32_bf16 v[54:57], v[164:167], v[222:225], v[54:57]
	s_add_u32 s46, s46, 0x100
	v_mfma_f32_16x16x32_bf16 v[50:53], v[186:189], v[222:225], v[50:53]
	s_addc_u32 s47, s47, 0
	v_mfma_f32_16x16x32_bf16 v[38:41], v[164:167], v[230:233], v[38:41]
	s_add_u32 s62, s62, 0x100
	v_mfma_f32_16x16x32_bf16 v[34:37], v[186:189], v[230:233], v[34:37]
	s_addc_u32 s63, s63, 0
	v_mfma_f32_16x16x32_bf16 v[22:25], v[164:167], v[238:241], v[22:25]
	s_add_u32 s10, s46, 0xfffc0080
	v_mfma_f32_16x16x32_bf16 v[18:21], v[186:189], v[238:241], v[18:21]
	s_addc_u32 s11, s47, -1
	v_mfma_f32_16x16x32_bf16 v[62:65], v[168:171], v[218:221], v[62:65]
	s_add_i32 s69, 0, 0x10000
	v_mfma_f32_16x16x32_bf16 v[58:61], v[190:193], v[218:221], v[58:61]
	s_cmp_eq_u32 s68, 12
	v_mfma_f32_16x16x32_bf16 v[54:57], v[168:171], v[226:229], v[54:57]
	s_cselect_b32 s51, s41, s11
	v_mfma_f32_16x16x32_bf16 v[50:53], v[190:193], v[226:229], v[50:53]
	s_cselect_b32 s50, s57, s10
	v_mfma_f32_16x16x32_bf16 v[38:41], v[168:171], v[234:237], v[38:41]
	v_add_u32_e32 v130, s69, v161
	v_mfma_f32_16x16x32_bf16 v[34:37], v[190:193], v[234:237], v[34:37]
	s_cselect_b32 s49, s4, s63
	v_mfma_f32_16x16x32_bf16 v[22:25], v[168:171], v[242:245], v[22:25]
	s_cselect_b32 s48, s39, s62
	v_mfma_f32_16x16x32_bf16 v[18:21], v[190:193], v[242:245], v[18:21]
	s_add_i32 s81, 0, 0x14000
	v_mfma_f32_16x16x32_bf16 v[46:49], v[198:201], v[214:217], v[46:49]
	s_cmp_gt_u32 s68, 13
	v_mfma_f32_16x16x32_bf16 v[42:45], v[206:209], v[214:217], v[42:45]
	v_mfma_f32_16x16x32_bf16 v[30:33], v[198:201], v[222:225], v[30:33]
	v_mfma_f32_16x16x32_bf16 v[26:29], v[206:209], v[222:225], v[26:29]
	v_mfma_f32_16x16x32_bf16 v[14:17], v[198:201], v[230:233], v[14:17]
	v_mfma_f32_16x16x32_bf16 v[10:13], v[206:209], v[230:233], v[10:13]
	v_mfma_f32_16x16x32_bf16 v[6:9], v[198:201], v[238:241], v[6:9]
	v_mfma_f32_16x16x32_bf16 v[2:5], v[206:209], v[238:241], v[2:5]
	v_mfma_f32_16x16x32_bf16 v[46:49], v[202:205], v[218:221], v[46:49]
	v_mfma_f32_16x16x32_bf16 v[42:45], v[210:213], v[218:221], v[42:45]
	v_mfma_f32_16x16x32_bf16 v[30:33], v[202:205], v[226:229], v[30:33]
	v_mfma_f32_16x16x32_bf16 v[26:29], v[210:213], v[226:229], v[26:29]
	v_mfma_f32_16x16x32_bf16 v[14:17], v[202:205], v[234:237], v[14:17]
	v_mfma_f32_16x16x32_bf16 v[10:13], v[210:213], v[234:237], v[10:13]
	v_mfma_f32_16x16x32_bf16 v[6:9], v[202:205], v[242:245], v[6:9]
	v_mfma_f32_16x16x32_bf16 v[2:5], v[210:213], v[242:245], v[2:5]
	s_barrier
	s_cbranch_scc0 .Lgk_146
	s_and_b64 vcc, exec, s[20:21]
	s_cbranch_vccz .LBB0_149
	s_barrier

; #define PG8_STAGE(bufoff, gbase, voff) do { _Pragma("unroll") for (int _i = 0; _i < 2; ++_i) \
;         __builtin_amdgcn_global_load_lds((const unsigned*)((const char*)(gbase) + (voff)[_i]), (PG8_LAS unsigned*)(lds + (bufoff) + ldsw + _i * 8192), 16, 0, 0); } while (0)
; #define PG8_LDA(dst, b, h) do { _Pragma("unroll") for (int m = 0; m < 4; ++m) _Pragma("unroll") for (int k = 0; k < 2; ++k) dst[m][k] = *(const PG8_LAS bf16x8*)(lds + PG8_SA(b, h) + aoff + m * 2048 + k * 1024); } while (0)
; #define PG8_LDB(dst, b, h) do { _Pragma("unroll") for (int n = 0; n < 2; ++n) _Pragma("unroll") for (int k = 0; k < 2; ++k) dst[n][k] = *(const PG8_LAS bf16x8*)(lds + PG8_SB(b, h) + boff + n * 2048 + k * 1024); } while (0)
; #define PG8_MMA(ai, bj, At, Bt) do { __builtin_amdgcn_s_setprio(1); _Pragma("unroll") for (int m = 0; m < 4; ++m) _Pragma("unroll") for (int n = 0; n < 2; ++n) _Pragma("unroll") for (int k = 0; k < 2; ++k) \
;         acc[ai][bj][m][n] = __builtin_amdgcn_mfma_f32_16x16x32_bf16(Bt[n][k], At[m][k], acc[ai][bj][m][n], 0, 0, 0); __builtin_amdgcn_s_setprio(0); } while (0)
; #define PG8_WAIT_V(n) asm volatile("s_waitcnt vmcnt(" #n ")" ::: "memory")
; #define PG8_BAR __builtin_amdgcn_s_barrier()
; template <class Epi, class Sched, bool ALIGN_EPI = false, bool SP2 = false>
; __device__ __forceinline__ void gemm_phase(PG8_LAS unsigned char* lds, const Gemm g, const Sched& S, const Epi& E) {
;     ...
;         for (int t = 0; t < nt; t += 2) {
;             const bool last = (t == nt - 2);
;             const char* a1 = cA + (size_t)(t + 1) * kstep;
;             const char* a2 = last ? nA : cA + (size_t)(t + 2) * kstep; const char* b2 = last ? nB : cB + (size_t)(t + 2) * kstep;
;             const char* a3 = a2 + kstep; const char* b3 = b2 + kstep;
;             if (last && has_next) S.a_ready(nxt);
;             if constexpr (SP2) {
;             PG8_LDB(B0, 0, 0); PG8_LDB(B1, 0, 1); PG8_SCHED; PG8_LDA(At, 0, 0); PG8_STAGE(PG8_SA(1, 1), a1 + hstepA, voffA);
;             PG8_WAIT_V(8); PG8_WAIT_L(0); PG8_BAR; PG8_MMA(0, 0, At, B0); PG8_MMA(0, 1, At, B1); PG8_BAR; PG8_SCHED;
;             PG8_LDA(At, 0, 1); PG8_STAGE(PG8_SB(0, 0), b2, voffB); PG8_STAGE(PG8_SB(0, 1), b2 + hstepB, voffB); PG8_STAGE(PG8_SA(0, 0), a2, voffA);
;             PG8_WAIT_V(8); PG8_WAIT_L(0); PG8_BAR; PG8_MMA(1, 0, At, B0); PG8_MMA(1, 1, At, B1); PG8_BAR; PG8_SCHED;
.LBB0_168:
	s_add_u32 s10, s48, 0xfffc0080
	s_addc_u32 s11, s49, -1
	s_add_i32 s69, 0, 0x10000
	s_cmp_eq_u32 s68, 12
	s_cselect_b32 s53, s43, s11
	s_cselect_b32 s52, s57, s10
	v_add_u32_e32 v130, s69, v161
	s_cselect_b32 s51, s4, s63
	s_cselect_b32 s50, s41, s62
	s_add_i32 s81, 0, 0x14000
	ds_read_b128 v[164:167], v130
	ds_read_b128 v[168:171], v130 offset:1024
	ds_read_b128 v[186:189], v130 offset:2048
	ds_read_b128 v[190:193], v130 offset:3072
	v_add_u32_e32 v130, s81, v161
	ds_read_b128 v[198:201], v130
	ds_read_b128 v[202:205], v130 offset:1024
	ds_read_b128 v[206:209], v130 offset:2048
	ds_read_b128 v[210:213], v130 offset:3072
	v_lshl_add_u64 v[130:131], s[48:49], 0, v[156:157]
	s_add_i32 m0, s9, 0xc000
	ds_read_b128 v[214:217], v163
	ds_read_b128 v[218:221], v163 offset:1024
	ds_read_b128 v[222:225], v163 offset:2048
	ds_read_b128 v[226:229], v163 offset:3072
	ds_read_b128 v[230:233], v163 offset:4096
	ds_read_b128 v[234:237], v163 offset:5120
	ds_read_b128 v[238:241], v163 offset:6144
	ds_read_b128 v[242:245], v163 offset:7168
	global_load_lds_dwordx4 v[130:131], off
	v_lshl_add_u64 v[130:131], s[48:49], 0, v[158:159]
	s_add_i32 m0, s9, 0xe000
	s_nop 0
	global_load_lds_dwordx4 v[130:131], off
	s_waitcnt vmcnt(8)
	s_waitcnt lgkmcnt(0)
	s_barrier
	v_mfma_f32_16x16x32_bf16 v[126:129], v[164:167], v[214:217], v[126:129]
	v_mfma_f32_16x16x32_bf16 v[122:125], v[186:189], v[214:217], v[122:125]
	v_mfma_f32_16x16x32_bf16 v[118:121], v[164:167], v[222:225], v[118:121]
	v_mfma_f32_16x16x32_bf16 v[114:117], v[186:189], v[222:225], v[114:117]
	v_mfma_f32_16x16x32_bf16 v[102:105], v[164:167], v[230:233], v[102:105]
	v_mfma_f32_16x16x32_bf16 v[98:101], v[186:189], v[230:233], v[98:101]
	v_mfma_f32_16x16x32_bf16 v[86:89], v[164:167], v[238:241], v[86:89]
	v_mfma_f32_16x16x32_bf16 v[82:85], v[186:189], v[238:241], v[82:85]
	v_mfma_f32_16x16x32_bf16 v[126:129], v[168:171], v[218:221], v[126:129]
	v_mfma_f32_16x16x32_bf16 v[122:125], v[190:193], v[218:221], v[122:125]
	v_mfma_f32_16x16x32_bf16 v[118:121], v[168:171], v[226:229], v[118:121]
	v_mfma_f32_16x16x32_bf16 v[114:117], v[190:193], v[226:229], v[114:117]
	v_mfma_f32_16x16x32_bf16 v[102:105], v[168:171], v[234:237], v[102:105]
	v_mfma_f32_16x16x32_bf16 v[98:101], v[190:193], v[234:237], v[98:101]
	v_mfma_f32_16x16x32_bf16 v[86:89], v[168:171], v[242:245], v[86:89]
	v_mfma_f32_16x16x32_bf16 v[82:85], v[190:193], v[242:245], v[82:85]
	v_mfma_f32_16x16x32_bf16 v[110:113], v[198:201], v[214:217], v[110:113]
	v_mfma_f32_16x16x32_bf16 v[106:109], v[206:209], v[214:217], v[106:109]
	v_mfma_f32_16x16x32_bf16 v[94:97], v[198:201], v[222:225], v[94:97]
	v_mfma_f32_16x16x32_bf16 v[90:93], v[206:209], v[222:225], v[90:93]
	v_mfma_f32_16x16x32_bf16 v[78:81], v[198:201], v[230:233], v[78:81]
	v_mfma_f32_16x16x32_bf16 v[74:77], v[206:209], v[230:233], v[74:77]
	v_mfma_f32_16x16x32_bf16 v[70:73], v[198:201], v[238:241], v[70:73]
	v_mfma_f32_16x16x32_bf16 v[66:69], v[206:209], v[238:241], v[66:69]
	v_mfma_f32_16x16x32_bf16 v[110:113], v[202:205], v[218:221], v[110:113]
	v_mfma_f32_16x16x32_bf16 v[106:109], v[210:213], v[218:221], v[106:109]
	v_mfma_f32_16x16x32_bf16 v[94:97], v[202:205], v[226:229], v[94:97]
	v_mfma_f32_16x16x32_bf16 v[90:93], v[210:213], v[226:229], v[90:93]
	v_mfma_f32_16x16x32_bf16 v[78:81], v[202:205], v[234:237], v[78:81]
	v_mfma_f32_16x16x32_bf16 v[74:77], v[210:213], v[234:237], v[74:77]
	v_mfma_f32_16x16x32_bf16 v[70:73], v[202:205], v[242:245], v[70:73]
	v_mfma_f32_16x16x32_bf16 v[66:69], v[210:213], v[242:245], v[66:69]
	s_barrier
	s_add_i32 s10, s69, s8
	v_lshl_add_u64 v[130:131], s[50:51], 0, v[0:1]
	s_mov_b32 m0, s10
	ds_read_b128 v[214:217], v163 offset:16384
	ds_read_b128 v[218:221], v163 offset:17408
	ds_read_b128 v[222:225], v163 offset:18432
	ds_read_b128 v[226:229], v163 offset:19456
	ds_read_b128 v[230:233], v163 offset:20480
	ds_read_b128 v[234:237], v163 offset:21504
	ds_read_b128 v[238:241], v163 offset:22528
	ds_read_b128 v[242:245], v163 offset:23552
	global_load_lds_dwordx4 v[130:131], off
	s_add_i32 m0, s10, 0x2000
	s_add_u32 s10, s50, 0x40000
	v_lshl_add_u64 v[132:133], s[50:51], 0, v[154:155]
	s_addc_u32 s11, s51, 0
	s_add_i32 s69, s81, s8
	global_load_lds_dwordx4 v[132:133], off
	v_lshl_add_u64 v[172:173], s[10:11], 0, v[0:1]
	s_mov_b32 m0, s69
	v_lshl_add_u64 v[246:247], s[52:53], 0, v[152:153]
	global_load_lds_dwordx4 v[172:173], off
	v_lshl_add_u64 v[172:173], s[10:11], 0, v[154:155]
	s_add_i32 m0, s69, 0x2000
	s_nop 0
	global_load_lds_dwordx4 v[172:173], off
	v_lshl_add_u64 v[172:173], s[52:53], 0, v[150:151]
	s_mov_b32 m0, s9
	s_nop 0
	global_load_lds_dwordx4 v[172:173], off
	s_mov_b32 m0, s30
	s_nop 0
	global_load_lds_dwordx4 v[246:247], off
	s_waitcnt vmcnt(8)
	s_waitcnt lgkmcnt(0)
	s_barrier
; #define PG8_STAGE(bufoff, gbase, voff) do { _Pragma("unroll") for (int _i = 0; _i < 2; ++_i) \
;         __builtin_amdgcn_global_load_lds((const unsigned*)((const char*)(gbase) + (voff)[_i]), (PG8_LAS unsigned*)(lds + (bufoff) + ldsw + _i * 8192), 16, 0, 0); } while (0)
; #define PG8_LDA(dst, b, h) do { _Pragma("unroll") for (int m = 0; m < 4; ++m) _Pragma("unroll") for (int k = 0; k < 2; ++k) dst[m][k] = *(const PG8_LAS bf16x8*)(lds + PG8_SA(b, h) + aoff + m * 2048 + k * 1024); } while (0)
; #define PG8_LDB(dst, b, h) do { _Pragma("unroll") for (int n = 0; n < 2; ++n) _Pragma("unroll") for (int k = 0; k < 2; ++k) dst[n][k] = *(const PG8_LAS bf16x8*)(lds + PG8_SB(b, h) + boff + n * 2048 + k * 1024); } while (0)
; #define PG8_MMA(ai, bj, At, Bt) do { __builtin_amdgcn_s_setprio(1); _Pragma("unroll") for (int m = 0; m < 4; ++m) _Pragma("unroll") for (int n = 0; n < 2; ++n) _Pragma("unroll") for (int k = 0; k < 2; ++k) \
;         acc[ai][bj][m][n] = __builtin_amdgcn_mfma_f32_16x16x32_bf16(Bt[n][k], At[m][k], acc[ai][bj][m][n], 0, 0, 0); __builtin_amdgcn_s_setprio(0); } while (0)
; #define PG8_WAIT_V(n) asm volatile("s_waitcnt vmcnt(" #n ")" ::: "memory")
; #define PG8_WAIT_L(n) asm volatile("s_waitcnt lgkmcnt(" #n ")" ::: "memory")
; #define PG8_BAR __builtin_amdgcn_s_barrier()
; #define PG8_SCHED __builtin_amdgcn_sched_barrier(0)
; template <class Epi, class Sched, bool ALIGN_EPI = false, bool SP2 = false>
; __device__ __forceinline__ void gemm_phase(PG8_LAS unsigned char* lds, const Gemm g, const Sched& S, const Epi& E) {
;     ...
;             PG8_WAIT_V(8); PG8_WAIT_L(0); PG8_BAR; PG8_MMA(1, 0, At, B0); PG8_MMA(1, 1, At, B1); PG8_BAR; PG8_SCHED;
;             PG8_LDB(B0, 1, 0); PG8_LDB(B1, 1, 1); PG8_SCHED; PG8_LDA(At, 1, 0); PG8_STAGE(PG8_SA(0, 1), a2 + hstepA, voffA);
;             PG8_WAIT_V(8); PG8_WAIT_L(0); PG8_BAR; PG8_MMA(0, 0, At, B0); PG8_MMA(0, 1, At, B1); PG8_BAR; PG8_SCHED;
	v_mfma_f32_16x16x32_bf16 v[62:65], v[164:167], v[214:217], v[62:65]
	v_mfma_f32_16x16x32_bf16 v[58:61], v[186:189], v[214:217], v[58:61]
	v_mfma_f32_16x16x32_bf16 v[54:57], v[164:167], v[222:225], v[54:57]
	v_mfma_f32_16x16x32_bf16 v[50:53], v[186:189], v[222:225], v[50:53]
	v_mfma_f32_16x16x32_bf16 v[38:41], v[164:167], v[230:233], v[38:41]
	v_mfma_f32_16x16x32_bf16 v[34:37], v[186:189], v[230:233], v[34:37]
	v_mfma_f32_16x16x32_bf16 v[22:25], v[164:167], v[238:241], v[22:25]
	v_mfma_f32_16x16x32_bf16 v[18:21], v[186:189], v[238:241], v[18:21]
	v_mfma_f32_16x16x32_bf16 v[62:65], v[168:171], v[218:221], v[62:65]
	v_mfma_f32_16x16x32_bf16 v[58:61], v[190:193], v[218:221], v[58:61]
	v_mfma_f32_16x16x32_bf16 v[54:57], v[168:171], v[226:229], v[54:57]
	v_mfma_f32_16x16x32_bf16 v[50:53], v[190:193], v[226:229], v[50:53]
	v_mfma_f32_16x16x32_bf16 v[38:41], v[168:171], v[234:237], v[38:41]
	v_mfma_f32_16x16x32_bf16 v[34:37], v[190:193], v[234:237], v[34:37]
	v_mfma_f32_16x16x32_bf16 v[22:25], v[168:171], v[242:245], v[22:25]
	v_mfma_f32_16x16x32_bf16 v[18:21], v[190:193], v[242:245], v[18:21]
	v_mfma_f32_16x16x32_bf16 v[46:49], v[198:201], v[214:217], v[46:49]
	v_mfma_f32_16x16x32_bf16 v[42:45], v[206:209], v[214:217], v[42:45]
	v_mfma_f32_16x16x32_bf16 v[30:33], v[198:201], v[222:225], v[30:33]
	v_mfma_f32_16x16x32_bf16 v[26:29], v[206:209], v[222:225], v[26:29]
	v_mfma_f32_16x16x32_bf16 v[14:17], v[198:201], v[230:233], v[14:17]
	v_mfma_f32_16x16x32_bf16 v[10:13], v[206:209], v[230:233], v[10:13]
	v_mfma_f32_16x16x32_bf16 v[6:9], v[198:201], v[238:241], v[6:9]
	v_mfma_f32_16x16x32_bf16 v[2:5], v[206:209], v[238:241], v[2:5]
	v_mfma_f32_16x16x32_bf16 v[46:49], v[202:205], v[218:221], v[46:49]
	v_mfma_f32_16x16x32_bf16 v[42:45], v[210:213], v[218:221], v[42:45]
	v_mfma_f32_16x16x32_bf16 v[30:33], v[202:205], v[226:229], v[30:33]
	v_mfma_f32_16x16x32_bf16 v[26:29], v[210:213], v[226:229], v[26:29]
	v_mfma_f32_16x16x32_bf16 v[14:17], v[202:205], v[234:237], v[14:17]
	v_mfma_f32_16x16x32_bf16 v[10:13], v[210:213], v[234:237], v[10:13]
	v_mfma_f32_16x16x32_bf16 v[6:9], v[202:205], v[242:245], v[6:9]
	v_mfma_f32_16x16x32_bf16 v[2:5], v[210:213], v[242:245], v[2:5]
	s_barrier
	s_add_i32 s69, 0, 0x18000
	s_add_i32 s81, 0, 0x1c000
	v_add_u32_e32 v190, s69, v161
	v_add_u32_e32 v210, s81, v161
	ds_read_b128 v[164:167], v190
	ds_read_b128 v[168:171], v190 offset:1024
	ds_read_b128 v[186:189], v190 offset:2048
	ds_read_b128 v[190:193], v190 offset:3072
	ds_read_b128 v[198:201], v210
	ds_read_b128 v[202:205], v210 offset:1024
	ds_read_b128 v[206:209], v210 offset:2048
	ds_read_b128 v[210:213], v210 offset:3072
	s_add_u32 s10, s52, 0x40000
	s_addc_u32 s11, s53, 0
	s_mov_b32 m0, s31
	v_lshl_add_u64 v[248:249], s[10:11], 0, v[150:151]
	ds_read_b128 v[214:217], v163 offset:32768
	ds_read_b128 v[218:221], v163 offset:33792
	ds_read_b128 v[222:225], v163 offset:34816
	ds_read_b128 v[226:229], v163 offset:35840
	ds_read_b128 v[230:233], v163 offset:36864
	ds_read_b128 v[234:237], v163 offset:37888
	ds_read_b128 v[238:241], v163 offset:38912
	ds_read_b128 v[242:245], v163 offset:39936
	global_load_lds_dwordx4 v[248:249], off
	v_lshl_add_u64 v[248:249], s[10:11], 0, v[152:153]
	s_mov_b32 m0, s34
	s_nop 0
	global_load_lds_dwordx4 v[248:249], off
	s_waitcnt vmcnt(8)
	s_waitcnt lgkmcnt(0)
	s_barrier
	v_mfma_f32_16x16x32_bf16 v[126:129], v[164:167], v[214:217], v[126:129]
	v_mfma_f32_16x16x32_bf16 v[122:125], v[186:189], v[214:217], v[122:125]
	v_mfma_f32_16x16x32_bf16 v[118:121], v[164:167], v[222:225], v[118:121]
	v_mfma_f32_16x16x32_bf16 v[114:117], v[186:189], v[222:225], v[114:117]
	v_mfma_f32_16x16x32_bf16 v[102:105], v[164:167], v[230:233], v[102:105]
	v_mfma_f32_16x16x32_bf16 v[98:101], v[186:189], v[230:233], v[98:101]
	v_mfma_f32_16x16x32_bf16 v[86:89], v[164:167], v[238:241], v[86:89]
	v_mfma_f32_16x16x32_bf16 v[82:85], v[186:189], v[238:241], v[82:85]
	v_mfma_f32_16x16x32_bf16 v[126:129], v[168:171], v[218:221], v[126:129]
	v_mfma_f32_16x16x32_bf16 v[122:125], v[190:193], v[218:221], v[122:125]
	v_mfma_f32_16x16x32_bf16 v[118:121], v[168:171], v[226:229], v[118:121]
	v_mfma_f32_16x16x32_bf16 v[114:117], v[190:193], v[226:229], v[114:117]
	v_mfma_f32_16x16x32_bf16 v[102:105], v[168:171], v[234:237], v[102:105]
	v_mfma_f32_16x16x32_bf16 v[98:101], v[190:193], v[234:237], v[98:101]
	v_mfma_f32_16x16x32_bf16 v[86:89], v[168:171], v[242:245], v[86:89]
	v_mfma_f32_16x16x32_bf16 v[82:85], v[190:193], v[242:245], v[82:85]
	v_mfma_f32_16x16x32_bf16 v[110:113], v[198:201], v[214:217], v[110:113]
	v_mfma_f32_16x16x32_bf16 v[106:109], v[206:209], v[214:217], v[106:109]
	v_mfma_f32_16x16x32_bf16 v[94:97], v[198:201], v[222:225], v[94:97]
	v_mfma_f32_16x16x32_bf16 v[90:93], v[206:209], v[222:225], v[90:93]
	v_mfma_f32_16x16x32_bf16 v[78:81], v[198:201], v[230:233], v[78:81]
	v_mfma_f32_16x16x32_bf16 v[74:77], v[206:209], v[230:233], v[74:77]
	v_mfma_f32_16x16x32_bf16 v[70:73], v[198:201], v[238:241], v[70:73]
	v_mfma_f32_16x16x32_bf16 v[66:69], v[206:209], v[238:241], v[66:69]
	v_mfma_f32_16x16x32_bf16 v[110:113], v[202:205], v[218:221], v[110:113]
	v_mfma_f32_16x16x32_bf16 v[106:109], v[210:213], v[218:221], v[106:109]
	v_mfma_f32_16x16x32_bf16 v[94:97], v[202:205], v[226:229], v[94:97]
	v_mfma_f32_16x16x32_bf16 v[90:93], v[210:213], v[226:229], v[90:93]
	v_mfma_f32_16x16x32_bf16 v[78:81], v[202:205], v[234:237], v[78:81]
	v_mfma_f32_16x16x32_bf16 v[74:77], v[210:213], v[234:237], v[74:77]
	v_mfma_f32_16x16x32_bf16 v[70:73], v[202:205], v[242:245], v[70:73]
	v_mfma_f32_16x16x32_bf16 v[66:69], v[210:213], v[242:245], v[66:69]
	s_barrier
; #define PG8_STAGE(bufoff, gbase, voff) do { _Pragma("unroll") for (int _i = 0; _i < 2; ++_i) \
;         __builtin_amdgcn_global_load_lds((const unsigned*)((const char*)(gbase) + (voff)[_i]), (PG8_LAS unsigned*)(lds + (bufoff) + ldsw + _i * 8192), 16, 0, 0); } while (0)
; #define PG8_LDA(dst, b, h) do { _Pragma("unroll") for (int m = 0; m < 4; ++m) _Pragma("unroll") for (int k = 0; k < 2; ++k) dst[m][k] = *(const PG8_LAS bf16x8*)(lds + PG8_SA(b, h) + aoff + m * 2048 + k * 1024); } while (0)
; #define PG8_MMA(ai, bj, At, Bt) do { __builtin_amdgcn_s_setprio(1); _Pragma("unroll") for (int m = 0; m < 4; ++m) _Pragma("unroll") for (int n = 0; n < 2; ++n) _Pragma("unroll") for (int k = 0; k < 2; ++k) \
;         acc[ai][bj][m][n] = __builtin_amdgcn_mfma_f32_16x16x32_bf16(Bt[n][k], At[m][k], acc[ai][bj][m][n], 0, 0, 0); __builtin_amdgcn_s_setprio(0); } while (0)
; #define PG8_WAIT_V(n) asm volatile("s_waitcnt vmcnt(" #n ")" ::: "memory")
; #define PG8_WAIT_L(n) asm volatile("s_waitcnt lgkmcnt(" #n ")" ::: "memory")
; #define PG8_BAR __builtin_amdgcn_s_barrier()
; #define PG8_SCHED __builtin_amdgcn_sched_barrier(0)
; template <class Epi, class Sched, bool ALIGN_EPI = false, bool SP2 = false>
; __device__ __forceinline__ void gemm_phase(PG8_LAS unsigned char* lds, const Gemm g, const Sched& S, const Epi& E) {
;     ...
;             PG8_LDA(At, 1, 1); PG8_STAGE(PG8_SB(1, 0), b3, voffB); PG8_STAGE(PG8_SB(1, 1), b3 + hstepB, voffB); PG8_STAGE(PG8_SA(1, 0), a3, voffA);
;             PG8_WAIT_V(8); PG8_WAIT_L(0); PG8_BAR; PG8_MMA(1, 0, At, B0); PG8_MMA(1, 1, At, B1); PG8_BAR; PG8_SCHED;
	s_add_i32 s10, s69, s8
	v_lshl_add_u64 v[130:131], v[130:131], 0, s[2:3]
	s_mov_b32 m0, s10
	ds_read_b128 v[214:217], v163 offset:49152
	ds_read_b128 v[218:221], v163 offset:50176
	ds_read_b128 v[222:225], v163 offset:51200
	ds_read_b128 v[226:229], v163 offset:52224
	ds_read_b128 v[230:233], v163 offset:53248
	ds_read_b128 v[234:237], v163 offset:54272
	ds_read_b128 v[238:241], v163 offset:55296
	ds_read_b128 v[242:245], v163 offset:56320
	global_load_lds_dwordx4 v[130:131], off
	s_add_i32 m0, s10, 0x2000
	s_add_u32 s10, s50, 0x40080
	v_lshl_add_u64 v[130:131], v[132:133], 0, s[2:3]
	s_addc_u32 s11, s51, 0
	s_add_i32 s50, s81, s8
	global_load_lds_dwordx4 v[130:131], off
	v_lshl_add_u64 v[130:131], s[10:11], 0, v[0:1]
	s_mov_b32 m0, s50
	s_nop 0
	global_load_lds_dwordx4 v[130:131], off
	v_lshl_add_u64 v[130:131], s[10:11], 0, v[154:155]
	s_add_i32 m0, s50, 0x2000
	s_nop 0
	global_load_lds_dwordx4 v[130:131], off
	v_lshl_add_u64 v[130:131], v[172:173], 0, s[2:3]
	s_mov_b32 m0, s35
	s_nop 0
	global_load_lds_dwordx4 v[130:131], off
	v_lshl_add_u64 v[130:131], v[246:247], 0, s[2:3]
	s_mov_b32 m0, s39
	s_nop 0
	global_load_lds_dwordx4 v[130:131], off
	s_waitcnt vmcnt(8)
	s_waitcnt lgkmcnt(0)
	s_barrier
	v_mfma_f32_16x16x32_bf16 v[62:65], v[164:167], v[214:217], v[62:65]
	v_mfma_f32_16x16x32_bf16 v[58:61], v[186:189], v[214:217], v[58:61]
	v_mfma_f32_16x16x32_bf16 v[54:57], v[164:167], v[222:225], v[54:57]
	v_mfma_f32_16x16x32_bf16 v[50:53], v[186:189], v[222:225], v[50:53]
	v_mfma_f32_16x16x32_bf16 v[38:41], v[164:167], v[230:233], v[38:41]
	v_mfma_f32_16x16x32_bf16 v[34:37], v[186:189], v[230:233], v[34:37]
	v_mfma_f32_16x16x32_bf16 v[22:25], v[164:167], v[238:241], v[22:25]
	v_mfma_f32_16x16x32_bf16 v[18:21], v[186:189], v[238:241], v[18:21]
	v_mfma_f32_16x16x32_bf16 v[62:65], v[168:171], v[218:221], v[62:65]
	v_mfma_f32_16x16x32_bf16 v[58:61], v[190:193], v[218:221], v[58:61]
	v_mfma_f32_16x16x32_bf16 v[54:57], v[168:171], v[226:229], v[54:57]
	v_mfma_f32_16x16x32_bf16 v[50:53], v[190:193], v[226:229], v[50:53]
	v_mfma_f32_16x16x32_bf16 v[38:41], v[168:171], v[234:237], v[38:41]
	v_mfma_f32_16x16x32_bf16 v[34:37], v[190:193], v[234:237], v[34:37]
	v_mfma_f32_16x16x32_bf16 v[22:25], v[168:171], v[242:245], v[22:25]
	v_mfma_f32_16x16x32_bf16 v[18:21], v[190:193], v[242:245], v[18:21]
	v_mfma_f32_16x16x32_bf16 v[46:49], v[198:201], v[214:217], v[46:49]
	v_mfma_f32_16x16x32_bf16 v[42:45], v[206:209], v[214:217], v[42:45]
	v_mfma_f32_16x16x32_bf16 v[30:33], v[198:201], v[222:225], v[30:33]
	v_mfma_f32_16x16x32_bf16 v[26:29], v[206:209], v[222:225], v[26:29]
	v_mfma_f32_16x16x32_bf16 v[14:17], v[198:201], v[230:233], v[14:17]
	v_mfma_f32_16x16x32_bf16 v[10:13], v[206:209], v[230:233], v[10:13]
	v_mfma_f32_16x16x32_bf16 v[6:9], v[198:201], v[238:241], v[6:9]
	v_mfma_f32_16x16x32_bf16 v[2:5], v[206:209], v[238:241], v[2:5]
	v_mfma_f32_16x16x32_bf16 v[46:49], v[202:205], v[218:221], v[46:49]
	v_mfma_f32_16x16x32_bf16 v[42:45], v[210:213], v[218:221], v[42:45]
	v_mfma_f32_16x16x32_bf16 v[30:33], v[202:205], v[226:229], v[30:33]
	v_mfma_f32_16x16x32_bf16 v[26:29], v[210:213], v[226:229], v[26:29]
	v_mfma_f32_16x16x32_bf16 v[14:17], v[202:205], v[234:237], v[14:17]
	v_mfma_f32_16x16x32_bf16 v[10:13], v[210:213], v[234:237], v[10:13]
	v_mfma_f32_16x16x32_bf16 v[6:9], v[202:205], v[242:245], v[6:9]
	v_mfma_f32_16x16x32_bf16 v[2:5], v[210:213], v[242:245], v[2:5]
	s_barrier
	s_add_i32 s68, s68, 2
	s_add_u32 s48, s48, 0x100
	s_addc_u32 s49, s49, 0
	s_add_u32 s62, s62, 0x100
	s_addc_u32 s63, s63, 0
	s_cmp_gt_u32 s68, 13
	s_cbranch_scc0 .LBB0_168
	s_and_b64 vcc, exec, s[20:21]
	s_mov_b64 s[62:63], s[14:15]
	s_cbranch_vccz .LBB0_171
	s_barrier

; #define PG8_STAGE(bufoff, gbase, voff) do { _Pragma("unroll") for (int _i = 0; _i < 2; ++_i) \
;         __builtin_amdgcn_global_load_lds((const unsigned*)((const char*)(gbase) + (voff)[_i]), (PG8_LAS unsigned*)(lds + (bufoff) + ldsw + _i * 8192), 16, 0, 0); } while (0)
; #define PG8_LDA(dst, b, h) do { _Pragma("unroll") for (int m = 0; m < 4; ++m) _Pragma("unroll") for (int k = 0; k < 2; ++k) dst[m][k] = *(const PG8_LAS bf16x8*)(lds + PG8_SA(b, h) + aoff + m * 2048 + k * 1024); } while (0)
; #define PG8_LDB(dst, b, h) do { _Pragma("unroll") for (int n = 0; n < 2; ++n) _Pragma("unroll") for (int k = 0; k < 2; ++k) dst[n][k] = *(const PG8_LAS bf16x8*)(lds + PG8_SB(b, h) + boff + n * 2048 + k * 1024); } while (0)
; #define PG8_MMA(ai, bj, At, Bt) do { __builtin_amdgcn_s_setprio(1); _Pragma("unroll") for (int m = 0; m < 4; ++m) _Pragma("unroll") for (int n = 0; n < 2; ++n) _Pragma("unroll") for (int k = 0; k < 2; ++k) \
;         acc[ai][bj][m][n] = __builtin_amdgcn_mfma_f32_16x16x32_bf16(Bt[n][k], At[m][k], acc[ai][bj][m][n], 0, 0, 0); __builtin_amdgcn_s_setprio(0); } while (0)
; #define PG8_WAIT_V(n) asm volatile("s_waitcnt vmcnt(" #n ")" ::: "memory")
; #define PG8_BAR __builtin_amdgcn_s_barrier()
; template <class Epi, class Sched, bool ALIGN_EPI = false, bool SP2 = false>
; __device__ __forceinline__ void gemm_phase(PG8_LAS unsigned char* lds, const Gemm g, const Sched& S, const Epi& E) {
;     ...
;         for (int t = 0; t < nt; t += 2) {
;             const bool last = (t == nt - 2);
;             const char* a1 = cA + (size_t)(t + 1) * kstep;
;             const char* a2 = last ? nA : cA + (size_t)(t + 2) * kstep; const char* b2 = last ? nB : cB + (size_t)(t + 2) * kstep;
;             const char* a3 = a2 + kstep; const char* b3 = b2 + kstep;
;             if (last && has_next) S.a_ready(nxt);
;             if constexpr (SP2) {
;             PG8_LDB(B0, 0, 0); PG8_LDB(B1, 0, 1); PG8_SCHED; PG8_LDA(At, 0, 0); PG8_STAGE(PG8_SA(1, 1), a1 + hstepA, voffA);
;             PG8_WAIT_V(8); PG8_WAIT_L(0); PG8_BAR; PG8_MMA(0, 0, At, B0); PG8_MMA(0, 1, At, B1); PG8_BAR; PG8_SCHED;
;             PG8_LDA(At, 0, 1); PG8_STAGE(PG8_SB(0, 0), b2, voffB); PG8_STAGE(PG8_SB(0, 1), b2 + hstepB, voffB); PG8_STAGE(PG8_SA(0, 0), a2, voffA);
;             PG8_WAIT_V(8); PG8_WAIT_L(0); PG8_BAR; PG8_MMA(1, 0, At, B0); PG8_MMA(1, 1, At, B1); PG8_BAR; PG8_SCHED;
.LBB0_380:
	s_add_u32 s36, s50, s4
	s_addc_u32 s37, s51, 0
	s_add_u32 s54, s36, 0x100
	s_addc_u32 s55, s37, 0
	s_and_b64 s[10:11], s[52:53], exec
	s_cselect_b32 s57, s45, s55
	s_cselect_b32 s56, s44, s54
	s_add_u32 s4, s48, s4
	s_addc_u32 s10, s49, 0
	s_add_u32 s4, s4, 0x100
	s_addc_u32 s54, s10, 0
	s_add_i32 s81, 0, 0x10000
	s_and_b64 s[10:11], s[52:53], exec
	s_cselect_b32 s63, s43, s54
	s_cselect_b32 s62, s94, s4
	s_add_i32 s10, 0, 0x14000
	s_add_u32 s36, s36, 0x90080
	s_addc_u32 s37, s37, 0
	s_add_i32 s86, s81, s8
	s_add_i32 m0, s9, 0xc000
	s_add_i32 s13, s9, 0xe000
	s_add_i32 s12, s86, 0x2000
	v_add_u32_e32 v130, s81, v157
	s_add_u32 vcc_lo, s62, 0x10000
	ds_read_b128 v[160:163], v130
	ds_read_b128 v[164:167], v130 offset:1024
	ds_read_b128 v[168:171], v130 offset:2048
	ds_read_b128 v[186:189], v130 offset:3072
	v_add_u32_e32 v130, s10, v157
	s_addc_u32 vcc_hi, s63, 0
	s_add_i32 s93, s10, s8
	ds_read_b128 v[190:193], v130
	ds_read_b128 v[198:201], v130 offset:1024
	ds_read_b128 v[202:205], v130 offset:2048
	ds_read_b128 v[206:209], v130 offset:3072
	s_add_i32 s92, s93, 0x2000
	s_add_i32 s95, 0, 0x18000
	s_add_i32 s85, 0, 0x1c000
	s_add_u32 s54, s56, 0x90000
	s_addc_u32 s55, s57, 0
	s_add_i32 s4, s95, s8
	s_add_i32 s87, s4, 0x2000
	s_add_u32 s52, s62, 0x10080
	s_addc_u32 s53, s63, 0
	s_add_i32 s11, s85, s8
	s_add_i32 s10, s11, 0x2000
	v_lshl_add_u64 v[130:131], s[36:37], 0, v[154:155]
	ds_read_b128 v[210:213], v159
	ds_read_b128 v[214:217], v159 offset:1024
	ds_read_b128 v[218:221], v159 offset:2048
	ds_read_b128 v[222:225], v159 offset:3072
	ds_read_b128 v[226:229], v159 offset:4096
	ds_read_b128 v[230:233], v159 offset:5120
	ds_read_b128 v[234:237], v159 offset:6144
	ds_read_b128 v[238:241], v159 offset:7168
	global_load_lds_dwordx4 v[130:131], off
	v_lshl_add_u64 v[130:131], s[36:37], 0, v[152:153]
	s_mov_b32 m0, s13
	s_nop 0
	global_load_lds_dwordx4 v[130:131], off
	s_waitcnt vmcnt(8)
	s_waitcnt lgkmcnt(0)
	s_barrier
	v_mfma_f32_16x16x32_bf16 v[126:129], v[160:163], v[210:213], v[126:129]
	v_mfma_f32_16x16x32_bf16 v[122:125], v[168:171], v[210:213], v[122:125]
	v_mfma_f32_16x16x32_bf16 v[118:121], v[160:163], v[218:221], v[118:121]
	v_mfma_f32_16x16x32_bf16 v[114:117], v[168:171], v[218:221], v[114:117]
	v_mfma_f32_16x16x32_bf16 v[102:105], v[160:163], v[226:229], v[102:105]
	v_mfma_f32_16x16x32_bf16 v[98:101], v[168:171], v[226:229], v[98:101]
	v_mfma_f32_16x16x32_bf16 v[86:89], v[160:163], v[234:237], v[86:89]
	v_mfma_f32_16x16x32_bf16 v[82:85], v[168:171], v[234:237], v[82:85]
	v_mfma_f32_16x16x32_bf16 v[126:129], v[164:167], v[214:217], v[126:129]
	v_mfma_f32_16x16x32_bf16 v[122:125], v[186:189], v[214:217], v[122:125]
	v_mfma_f32_16x16x32_bf16 v[118:121], v[164:167], v[222:225], v[118:121]
	v_mfma_f32_16x16x32_bf16 v[114:117], v[186:189], v[222:225], v[114:117]
	v_mfma_f32_16x16x32_bf16 v[102:105], v[164:167], v[230:233], v[102:105]
	v_mfma_f32_16x16x32_bf16 v[98:101], v[186:189], v[230:233], v[98:101]
	v_mfma_f32_16x16x32_bf16 v[86:89], v[164:167], v[238:241], v[86:89]
	v_mfma_f32_16x16x32_bf16 v[82:85], v[186:189], v[238:241], v[82:85]
	v_mfma_f32_16x16x32_bf16 v[110:113], v[190:193], v[210:213], v[110:113]
	v_mfma_f32_16x16x32_bf16 v[106:109], v[202:205], v[210:213], v[106:109]
	v_mfma_f32_16x16x32_bf16 v[94:97], v[190:193], v[218:221], v[94:97]
	v_mfma_f32_16x16x32_bf16 v[90:93], v[202:205], v[218:221], v[90:93]
	v_mfma_f32_16x16x32_bf16 v[78:81], v[190:193], v[226:229], v[78:81]
	v_mfma_f32_16x16x32_bf16 v[74:77], v[202:205], v[226:229], v[74:77]
	v_mfma_f32_16x16x32_bf16 v[70:73], v[190:193], v[234:237], v[70:73]
	v_mfma_f32_16x16x32_bf16 v[66:69], v[202:205], v[234:237], v[66:69]
	v_mfma_f32_16x16x32_bf16 v[110:113], v[198:201], v[214:217], v[110:113]
	v_mfma_f32_16x16x32_bf16 v[106:109], v[206:209], v[214:217], v[106:109]
	v_mfma_f32_16x16x32_bf16 v[94:97], v[198:201], v[222:225], v[94:97]
	v_mfma_f32_16x16x32_bf16 v[90:93], v[206:209], v[222:225], v[90:93]
	v_mfma_f32_16x16x32_bf16 v[78:81], v[198:201], v[230:233], v[78:81]
	v_mfma_f32_16x16x32_bf16 v[74:77], v[206:209], v[230:233], v[74:77]
	v_mfma_f32_16x16x32_bf16 v[70:73], v[198:201], v[238:241], v[70:73]
	v_mfma_f32_16x16x32_bf16 v[66:69], v[206:209], v[238:241], v[66:69]
	s_barrier
	s_mov_b32 m0, s86
	v_lshl_add_u64 v[130:131], s[62:63], 0, v[0:1]
	ds_read_b128 v[210:213], v159 offset:16384
	ds_read_b128 v[214:217], v159 offset:17408
	ds_read_b128 v[218:221], v159 offset:18432
	ds_read_b128 v[222:225], v159 offset:19456
	ds_read_b128 v[226:229], v159 offset:20480
	ds_read_b128 v[230:233], v159 offset:21504
	ds_read_b128 v[234:237], v159 offset:22528
	ds_read_b128 v[238:241], v159 offset:23552
	global_load_lds_dwordx4 v[130:131], off
	v_lshl_add_u64 v[132:133], s[62:63], 0, v[150:151]
	s_mov_b32 m0, s12
	v_lshl_add_u64 v[172:173], vcc, 0, v[0:1]
	global_load_lds_dwordx4 v[132:133], off
	s_mov_b32 m0, s93
	v_lshl_add_u64 v[242:243], s[56:57], 0, v[152:153]
	global_load_lds_dwordx4 v[172:173], off
	v_lshl_add_u64 v[172:173], vcc, 0, v[150:151]
	s_mov_b32 m0, s92
	s_nop 0
	global_load_lds_dwordx4 v[172:173], off
	v_lshl_add_u64 v[172:173], s[56:57], 0, v[154:155]
	s_mov_b32 m0, s9
	s_nop 0
	global_load_lds_dwordx4 v[172:173], off
	s_mov_b32 m0, s30
	s_nop 0
	global_load_lds_dwordx4 v[242:243], off
	s_waitcnt vmcnt(8)
	s_waitcnt lgkmcnt(0)
	s_barrier
; #define PG8_STAGE(bufoff, gbase, voff) do { _Pragma("unroll") for (int _i = 0; _i < 2; ++_i) \
;         __builtin_amdgcn_global_load_lds((const unsigned*)((const char*)(gbase) + (voff)[_i]), (PG8_LAS unsigned*)(lds + (bufoff) + ldsw + _i * 8192), 16, 0, 0); } while (0)
; #define PG8_LDA(dst, b, h) do { _Pragma("unroll") for (int m = 0; m < 4; ++m) _Pragma("unroll") for (int k = 0; k < 2; ++k) dst[m][k] = *(const PG8_LAS bf16x8*)(lds + PG8_SA(b, h) + aoff + m * 2048 + k * 1024); } while (0)
; #define PG8_LDB(dst, b, h) do { _Pragma("unroll") for (int n = 0; n < 2; ++n) _Pragma("unroll") for (int k = 0; k < 2; ++k) dst[n][k] = *(const PG8_LAS bf16x8*)(lds + PG8_SB(b, h) + boff + n * 2048 + k * 1024); } while (0)
; #define PG8_MMA(ai, bj, At, Bt) do { __builtin_amdgcn_s_setprio(1); _Pragma("unroll") for (int m = 0; m < 4; ++m) _Pragma("unroll") for (int n = 0; n < 2; ++n) _Pragma("unroll") for (int k = 0; k < 2; ++k) \
;         acc[ai][bj][m][n] = __builtin_amdgcn_mfma_f32_16x16x32_bf16(Bt[n][k], At[m][k], acc[ai][bj][m][n], 0, 0, 0); __builtin_amdgcn_s_setprio(0); } while (0)
; #define PG8_WAIT_V(n) asm volatile("s_waitcnt vmcnt(" #n ")" ::: "memory")
; #define PG8_WAIT_L(n) asm volatile("s_waitcnt lgkmcnt(" #n ")" ::: "memory")
; #define PG8_BAR __builtin_amdgcn_s_barrier()
; #define PG8_SCHED __builtin_amdgcn_sched_barrier(0)
; template <class Epi, class Sched, bool ALIGN_EPI = false, bool SP2 = false>
; __device__ __forceinline__ void gemm_phase(PG8_LAS unsigned char* lds, const Gemm g, const Sched& S, const Epi& E) {
;     ...
;             PG8_WAIT_V(8); PG8_WAIT_L(0); PG8_BAR; PG8_MMA(1, 0, At, B0); PG8_MMA(1, 1, At, B1); PG8_BAR; PG8_SCHED;
;             PG8_LDB(B0, 1, 0); PG8_LDB(B1, 1, 1); PG8_SCHED; PG8_LDA(At, 1, 0); PG8_STAGE(PG8_SA(0, 1), a2 + hstepA, voffA);
;             PG8_WAIT_V(8); PG8_WAIT_L(0); PG8_BAR; PG8_MMA(0, 0, At, B0); PG8_MMA(0, 1, At, B1); PG8_BAR; PG8_SCHED;
	v_mfma_f32_16x16x32_bf16 v[62:65], v[160:163], v[210:213], v[62:65]
	v_mfma_f32_16x16x32_bf16 v[58:61], v[168:171], v[210:213], v[58:61]
	v_mfma_f32_16x16x32_bf16 v[54:57], v[160:163], v[218:221], v[54:57]
	v_mfma_f32_16x16x32_bf16 v[50:53], v[168:171], v[218:221], v[50:53]
	v_mfma_f32_16x16x32_bf16 v[38:41], v[160:163], v[226:229], v[38:41]
	v_mfma_f32_16x16x32_bf16 v[34:37], v[168:171], v[226:229], v[34:37]
	v_mfma_f32_16x16x32_bf16 v[22:25], v[160:163], v[234:237], v[22:25]
	v_mfma_f32_16x16x32_bf16 v[18:21], v[168:171], v[234:237], v[18:21]
	v_mfma_f32_16x16x32_bf16 v[62:65], v[164:167], v[214:217], v[62:65]
	v_mfma_f32_16x16x32_bf16 v[58:61], v[186:189], v[214:217], v[58:61]
	v_mfma_f32_16x16x32_bf16 v[54:57], v[164:167], v[222:225], v[54:57]
	v_mfma_f32_16x16x32_bf16 v[50:53], v[186:189], v[222:225], v[50:53]
	v_mfma_f32_16x16x32_bf16 v[38:41], v[164:167], v[230:233], v[38:41]
	v_mfma_f32_16x16x32_bf16 v[34:37], v[186:189], v[230:233], v[34:37]
	v_mfma_f32_16x16x32_bf16 v[22:25], v[164:167], v[238:241], v[22:25]
	v_mfma_f32_16x16x32_bf16 v[18:21], v[186:189], v[238:241], v[18:21]
	v_mfma_f32_16x16x32_bf16 v[46:49], v[190:193], v[210:213], v[46:49]
	v_mfma_f32_16x16x32_bf16 v[42:45], v[202:205], v[210:213], v[42:45]
	v_mfma_f32_16x16x32_bf16 v[30:33], v[190:193], v[218:221], v[30:33]
	v_mfma_f32_16x16x32_bf16 v[26:29], v[202:205], v[218:221], v[26:29]
	v_mfma_f32_16x16x32_bf16 v[14:17], v[190:193], v[226:229], v[14:17]
	v_mfma_f32_16x16x32_bf16 v[10:13], v[202:205], v[226:229], v[10:13]
	v_mfma_f32_16x16x32_bf16 v[6:9], v[190:193], v[234:237], v[6:9]
	v_mfma_f32_16x16x32_bf16 v[2:5], v[202:205], v[234:237], v[2:5]
	v_mfma_f32_16x16x32_bf16 v[46:49], v[198:201], v[214:217], v[46:49]
	v_mfma_f32_16x16x32_bf16 v[42:45], v[206:209], v[214:217], v[42:45]
	v_mfma_f32_16x16x32_bf16 v[30:33], v[198:201], v[222:225], v[30:33]
	v_mfma_f32_16x16x32_bf16 v[26:29], v[206:209], v[222:225], v[26:29]
	v_mfma_f32_16x16x32_bf16 v[14:17], v[198:201], v[230:233], v[14:17]
	v_mfma_f32_16x16x32_bf16 v[10:13], v[206:209], v[230:233], v[10:13]
	v_mfma_f32_16x16x32_bf16 v[6:9], v[198:201], v[238:241], v[6:9]
	v_mfma_f32_16x16x32_bf16 v[2:5], v[206:209], v[238:241], v[2:5]
	s_barrier
	v_add_u32_e32 v186, s95, v157
	v_add_u32_e32 v206, s85, v157
	ds_read_b128 v[160:163], v186
	ds_read_b128 v[164:167], v186 offset:1024
	ds_read_b128 v[168:171], v186 offset:2048
	ds_read_b128 v[186:189], v186 offset:3072
	ds_read_b128 v[190:193], v206
	ds_read_b128 v[198:201], v206 offset:1024
	ds_read_b128 v[202:205], v206 offset:2048
	ds_read_b128 v[206:209], v206 offset:3072
	s_mov_b32 m0, s31
	v_lshl_add_u64 v[244:245], s[54:55], 0, v[154:155]
	ds_read_b128 v[210:213], v159 offset:32768
	ds_read_b128 v[214:217], v159 offset:33792
	ds_read_b128 v[218:221], v159 offset:34816
	ds_read_b128 v[222:225], v159 offset:35840
	ds_read_b128 v[226:229], v159 offset:36864
	ds_read_b128 v[230:233], v159 offset:37888
	ds_read_b128 v[234:237], v159 offset:38912
	ds_read_b128 v[238:241], v159 offset:39936
	global_load_lds_dwordx4 v[244:245], off
	v_lshl_add_u64 v[244:245], s[54:55], 0, v[152:153]
	s_mov_b32 m0, s34
	s_nop 0
	global_load_lds_dwordx4 v[244:245], off
	s_waitcnt vmcnt(8)
	s_waitcnt lgkmcnt(0)
	s_barrier
	v_mfma_f32_16x16x32_bf16 v[126:129], v[160:163], v[210:213], v[126:129]
	v_mfma_f32_16x16x32_bf16 v[122:125], v[168:171], v[210:213], v[122:125]
	v_mfma_f32_16x16x32_bf16 v[118:121], v[160:163], v[218:221], v[118:121]
	v_mfma_f32_16x16x32_bf16 v[114:117], v[168:171], v[218:221], v[114:117]
	v_mfma_f32_16x16x32_bf16 v[102:105], v[160:163], v[226:229], v[102:105]
	v_mfma_f32_16x16x32_bf16 v[98:101], v[168:171], v[226:229], v[98:101]
	v_mfma_f32_16x16x32_bf16 v[86:89], v[160:163], v[234:237], v[86:89]
	v_mfma_f32_16x16x32_bf16 v[82:85], v[168:171], v[234:237], v[82:85]
	v_mfma_f32_16x16x32_bf16 v[126:129], v[164:167], v[214:217], v[126:129]
	v_mfma_f32_16x16x32_bf16 v[122:125], v[186:189], v[214:217], v[122:125]
	v_mfma_f32_16x16x32_bf16 v[118:121], v[164:167], v[222:225], v[118:121]
	v_mfma_f32_16x16x32_bf16 v[114:117], v[186:189], v[222:225], v[114:117]
	v_mfma_f32_16x16x32_bf16 v[102:105], v[164:167], v[230:233], v[102:105]
	v_mfma_f32_16x16x32_bf16 v[98:101], v[186:189], v[230:233], v[98:101]
	v_mfma_f32_16x16x32_bf16 v[86:89], v[164:167], v[238:241], v[86:89]
	v_mfma_f32_16x16x32_bf16 v[82:85], v[186:189], v[238:241], v[82:85]
	v_mfma_f32_16x16x32_bf16 v[110:113], v[190:193], v[210:213], v[110:113]
	v_mfma_f32_16x16x32_bf16 v[106:109], v[202:205], v[210:213], v[106:109]
	v_mfma_f32_16x16x32_bf16 v[94:97], v[190:193], v[218:221], v[94:97]
	v_mfma_f32_16x16x32_bf16 v[90:93], v[202:205], v[218:221], v[90:93]
	v_mfma_f32_16x16x32_bf16 v[78:81], v[190:193], v[226:229], v[78:81]
	v_mfma_f32_16x16x32_bf16 v[74:77], v[202:205], v[226:229], v[74:77]
	v_mfma_f32_16x16x32_bf16 v[70:73], v[190:193], v[234:237], v[70:73]
	v_mfma_f32_16x16x32_bf16 v[66:69], v[202:205], v[234:237], v[66:69]
	v_mfma_f32_16x16x32_bf16 v[110:113], v[198:201], v[214:217], v[110:113]
	v_mfma_f32_16x16x32_bf16 v[106:109], v[206:209], v[214:217], v[106:109]
	v_mfma_f32_16x16x32_bf16 v[94:97], v[198:201], v[222:225], v[94:97]
	v_mfma_f32_16x16x32_bf16 v[90:93], v[206:209], v[222:225], v[90:93]
	v_mfma_f32_16x16x32_bf16 v[78:81], v[198:201], v[230:233], v[78:81]
	v_mfma_f32_16x16x32_bf16 v[74:77], v[206:209], v[230:233], v[74:77]
	v_mfma_f32_16x16x32_bf16 v[70:73], v[198:201], v[238:241], v[70:73]
	v_mfma_f32_16x16x32_bf16 v[66:69], v[206:209], v[238:241], v[66:69]
	s_barrier
; #define PG8_STAGE(bufoff, gbase, voff) do { _Pragma("unroll") for (int _i = 0; _i < 2; ++_i) \
;         __builtin_amdgcn_global_load_lds((const unsigned*)((const char*)(gbase) + (voff)[_i]), (PG8_LAS unsigned*)(lds + (bufoff) + ldsw + _i * 8192), 16, 0, 0); } while (0)
; #define PG8_LDA(dst, b, h) do { _Pragma("unroll") for (int m = 0; m < 4; ++m) _Pragma("unroll") for (int k = 0; k < 2; ++k) dst[m][k] = *(const PG8_LAS bf16x8*)(lds + PG8_SA(b, h) + aoff + m * 2048 + k * 1024); } while (0)
; #define PG8_MMA(ai, bj, At, Bt) do { __builtin_amdgcn_s_setprio(1); _Pragma("unroll") for (int m = 0; m < 4; ++m) _Pragma("unroll") for (int n = 0; n < 2; ++n) _Pragma("unroll") for (int k = 0; k < 2; ++k) \
;         acc[ai][bj][m][n] = __builtin_amdgcn_mfma_f32_16x16x32_bf16(Bt[n][k], At[m][k], acc[ai][bj][m][n], 0, 0, 0); __builtin_amdgcn_s_setprio(0); } while (0)
; #define PG8_WAIT_V(n) asm volatile("s_waitcnt vmcnt(" #n ")" ::: "memory")
; #define PG8_WAIT_L(n) asm volatile("s_waitcnt lgkmcnt(" #n ")" ::: "memory")
; #define PG8_BAR __builtin_amdgcn_s_barrier()
; #define PG8_SCHED __builtin_amdgcn_sched_barrier(0)
; template <class Epi, class Sched, bool ALIGN_EPI = false, bool SP2 = false>
; __device__ __forceinline__ void gemm_phase(PG8_LAS unsigned char* lds, const Gemm g, const Sched& S, const Epi& E) {
;     ...
;             PG8_LDA(At, 1, 1); PG8_STAGE(PG8_SB(1, 0), b3, voffB); PG8_STAGE(PG8_SB(1, 1), b3 + hstepB, voffB); PG8_STAGE(PG8_SA(1, 0), a3, voffA);
;             PG8_WAIT_V(8); PG8_WAIT_L(0); PG8_BAR; PG8_MMA(1, 0, At, B0); PG8_MMA(1, 1, At, B1); PG8_BAR; PG8_SCHED;
	s_mov_b32 m0, s4
	v_lshl_add_u64 v[130:131], v[130:131], 0, s[2:3]
	ds_read_b128 v[210:213], v159 offset:49152
	ds_read_b128 v[214:217], v159 offset:50176
	ds_read_b128 v[218:221], v159 offset:51200
	ds_read_b128 v[222:225], v159 offset:52224
	ds_read_b128 v[226:229], v159 offset:53248
	ds_read_b128 v[230:233], v159 offset:54272
	ds_read_b128 v[234:237], v159 offset:55296
	ds_read_b128 v[238:241], v159 offset:56320
	global_load_lds_dwordx4 v[130:131], off
	v_lshl_add_u64 v[130:131], v[132:133], 0, s[2:3]
	s_mov_b32 m0, s87
	s_nop 0
	global_load_lds_dwordx4 v[130:131], off
	v_lshl_add_u64 v[130:131], s[52:53], 0, v[0:1]
	s_mov_b32 m0, s11
	s_nop 0
	global_load_lds_dwordx4 v[130:131], off
	v_lshl_add_u64 v[130:131], s[52:53], 0, v[150:151]
	s_mov_b32 m0, s10
	s_nop 0
	global_load_lds_dwordx4 v[130:131], off
	v_lshl_add_u64 v[130:131], v[172:173], 0, s[2:3]
	s_mov_b32 m0, s35
	s_nop 0
	global_load_lds_dwordx4 v[130:131], off
	v_lshl_add_u64 v[130:131], v[242:243], 0, s[2:3]
	s_mov_b32 m0, s68
	s_nop 0
	global_load_lds_dwordx4 v[130:131], off
	s_waitcnt vmcnt(8)
	s_waitcnt lgkmcnt(0)
	s_barrier
	v_mfma_f32_16x16x32_bf16 v[62:65], v[160:163], v[210:213], v[62:65]
	v_mfma_f32_16x16x32_bf16 v[58:61], v[168:171], v[210:213], v[58:61]
	v_mfma_f32_16x16x32_bf16 v[54:57], v[160:163], v[218:221], v[54:57]
	v_mfma_f32_16x16x32_bf16 v[50:53], v[168:171], v[218:221], v[50:53]
	v_mfma_f32_16x16x32_bf16 v[38:41], v[160:163], v[226:229], v[38:41]
	v_mfma_f32_16x16x32_bf16 v[34:37], v[168:171], v[226:229], v[34:37]
	v_mfma_f32_16x16x32_bf16 v[22:25], v[160:163], v[234:237], v[22:25]
	v_mfma_f32_16x16x32_bf16 v[18:21], v[168:171], v[234:237], v[18:21]
	v_mfma_f32_16x16x32_bf16 v[62:65], v[164:167], v[214:217], v[62:65]
	v_mfma_f32_16x16x32_bf16 v[58:61], v[186:189], v[214:217], v[58:61]
	v_mfma_f32_16x16x32_bf16 v[54:57], v[164:167], v[222:225], v[54:57]
	v_mfma_f32_16x16x32_bf16 v[50:53], v[186:189], v[222:225], v[50:53]
	v_mfma_f32_16x16x32_bf16 v[38:41], v[164:167], v[230:233], v[38:41]
	v_mfma_f32_16x16x32_bf16 v[34:37], v[186:189], v[230:233], v[34:37]
	v_mfma_f32_16x16x32_bf16 v[22:25], v[164:167], v[238:241], v[22:25]
	v_mfma_f32_16x16x32_bf16 v[18:21], v[186:189], v[238:241], v[18:21]
	v_mfma_f32_16x16x32_bf16 v[46:49], v[190:193], v[210:213], v[46:49]
	v_mfma_f32_16x16x32_bf16 v[42:45], v[202:205], v[210:213], v[42:45]
	v_mfma_f32_16x16x32_bf16 v[30:33], v[190:193], v[218:221], v[30:33]
	v_mfma_f32_16x16x32_bf16 v[26:29], v[202:205], v[218:221], v[26:29]
	v_mfma_f32_16x16x32_bf16 v[14:17], v[190:193], v[226:229], v[14:17]
	v_mfma_f32_16x16x32_bf16 v[10:13], v[202:205], v[226:229], v[10:13]
	v_mfma_f32_16x16x32_bf16 v[6:9], v[190:193], v[234:237], v[6:9]
	v_mfma_f32_16x16x32_bf16 v[2:5], v[202:205], v[234:237], v[2:5]
	v_mfma_f32_16x16x32_bf16 v[46:49], v[198:201], v[214:217], v[46:49]
	v_mfma_f32_16x16x32_bf16 v[42:45], v[206:209], v[214:217], v[42:45]
	v_mfma_f32_16x16x32_bf16 v[30:33], v[198:201], v[222:225], v[30:33]
	v_mfma_f32_16x16x32_bf16 v[26:29], v[206:209], v[222:225], v[26:29]
	v_mfma_f32_16x16x32_bf16 v[14:17], v[198:201], v[230:233], v[14:17]
	v_mfma_f32_16x16x32_bf16 v[10:13], v[206:209], v[230:233], v[10:13]
	v_mfma_f32_16x16x32_bf16 v[6:9], v[198:201], v[238:241], v[6:9]
	v_mfma_f32_16x16x32_bf16 v[2:5], v[206:209], v[238:241], v[2:5]
	s_barrier
	s_movk_i32 s4, 0x100
	s_andn2_b64 vcc, exec, s[0:1]
	s_mov_b64 s[52:53], -1
	s_mov_b64 s[0:1], 0
	s_cbranch_vccz .LBB0_380
	s_and_b64 vcc, exec, s[40:41]
	s_cbranch_vccz .LBB0_383
	s_barrier

; #define PG8_STAGE(bufoff, gbase, voff) do { _Pragma("unroll") for (int _i = 0; _i < 2; ++_i) \
;         __builtin_amdgcn_global_load_lds((const unsigned*)((const char*)(gbase) + (voff)[_i]), (PG8_LAS unsigned*)(lds + (bufoff) + ldsw + _i * 8192), 16, 0, 0); } while (0)
; #define PG8_LDA(dst, b, h) do { _Pragma("unroll") for (int m = 0; m < 4; ++m) _Pragma("unroll") for (int k = 0; k < 2; ++k) dst[m][k] = *(const PG8_LAS bf16x8*)(lds + PG8_SA(b, h) + aoff + m * 2048 + k * 1024); } while (0)
; #define PG8_LDB(dst, b, h) do { _Pragma("unroll") for (int n = 0; n < 2; ++n) _Pragma("unroll") for (int k = 0; k < 2; ++k) dst[n][k] = *(const PG8_LAS bf16x8*)(lds + PG8_SB(b, h) + boff + n * 2048 + k * 1024); } while (0)
; #define PG8_MMA(ai, bj, At, Bt) do { __builtin_amdgcn_s_setprio(1); _Pragma("unroll") for (int m = 0; m < 4; ++m) _Pragma("unroll") for (int n = 0; n < 2; ++n) _Pragma("unroll") for (int k = 0; k < 2; ++k) \
;         acc[ai][bj][m][n] = __builtin_amdgcn_mfma_f32_16x16x32_bf16(Bt[n][k], At[m][k], acc[ai][bj][m][n], 0, 0, 0); __builtin_amdgcn_s_setprio(0); } while (0)
; #define PG8_WAIT_V(n) asm volatile("s_waitcnt vmcnt(" #n ")" ::: "memory")
; #define PG8_BAR __builtin_amdgcn_s_barrier()
; template <class Epi, class Sched, bool ALIGN_EPI = false, bool SP2 = false>
; __device__ __forceinline__ void gemm_phase(PG8_LAS unsigned char* lds, const Gemm g, const Sched& S, const Epi& E) {
;     ...
;         for (int t = 0; t < nt; t += 2) {
;             const bool last = (t == nt - 2);
;             const char* a1 = cA + (size_t)(t + 1) * kstep;
;             const char* a2 = last ? nA : cA + (size_t)(t + 2) * kstep; const char* b2 = last ? nB : cB + (size_t)(t + 2) * kstep;
;             const char* a3 = a2 + kstep; const char* b3 = b2 + kstep;
;             if (last && has_next) S.a_ready(nxt);
;             if constexpr (SP2) {
;             PG8_LDB(B0, 0, 0); PG8_LDB(B1, 0, 1); PG8_SCHED; PG8_LDA(At, 0, 0); PG8_STAGE(PG8_SA(1, 1), a1 + hstepA, voffA);
;             PG8_WAIT_V(8); PG8_WAIT_L(0); PG8_BAR; PG8_MMA(0, 0, At, B0); PG8_MMA(0, 1, At, B1); PG8_BAR; PG8_SCHED;
;             PG8_LDA(At, 0, 1); PG8_STAGE(PG8_SB(0, 0), b2, voffB); PG8_STAGE(PG8_SB(0, 1), b2 + hstepB, voffB); PG8_STAGE(PG8_SA(0, 0), a2, voffA);
;             PG8_WAIT_V(8); PG8_WAIT_L(0); PG8_BAR; PG8_MMA(1, 0, At, B0); PG8_MMA(1, 1, At, B1); PG8_BAR; PG8_SCHED;
.LBB0_402:
	s_add_u32 s12, s52, s4
	s_addc_u32 s13, s53, 0
	s_add_u32 s36, s12, 0x100
	s_addc_u32 s37, s13, 0
	s_and_b64 s[10:11], s[54:55], exec
	s_cselect_b32 s63, s47, s37
	s_cselect_b32 s62, s46, s36
	s_add_u32 s4, s50, s4
	s_addc_u32 s10, s51, 0
	s_add_u32 s4, s4, 0x100
	s_addc_u32 s36, s10, 0
	s_add_i32 s86, 0, 0x10000
	s_and_b64 s[10:11], s[54:55], exec
	s_cselect_b32 vcc_hi, s45, s36
	s_cselect_b32 vcc_lo, s38, s4
	s_add_i32 s10, 0, 0x14000
	s_add_u32 s68, s12, 0x90080
	s_addc_u32 s69, s13, 0
	s_add_i32 s12, s86, s8
	s_add_i32 m0, s9, 0xc000
	s_add_i32 s13, s9, 0xe000
	s_add_i32 s81, s12, 0x2000
	v_add_u32_e32 v130, s86, v157
	s_add_u32 s36, vcc_lo, 0x10000
	ds_read_b128 v[160:163], v130
	ds_read_b128 v[164:167], v130 offset:1024
	ds_read_b128 v[168:171], v130 offset:2048
	ds_read_b128 v[186:189], v130 offset:3072
	v_add_u32_e32 v130, s10, v157
	s_addc_u32 s37, vcc_hi, 0
	s_add_i32 s93, s10, s8
	ds_read_b128 v[190:193], v130
	ds_read_b128 v[198:201], v130 offset:1024
	ds_read_b128 v[202:205], v130 offset:2048
	ds_read_b128 v[206:209], v130 offset:3072
	s_add_i32 s92, s93, 0x2000
	s_add_i32 s87, 0, 0x18000
	s_add_i32 s85, 0, 0x1c000
	s_add_u32 s56, s62, 0x90000
	s_addc_u32 s57, s63, 0
	s_add_i32 s39, s87, s8
	s_add_i32 s4, s39, 0x2000
	s_add_u32 s54, vcc_lo, 0x10080
	s_addc_u32 s55, vcc_hi, 0
	s_add_i32 s11, s85, s8
	s_add_i32 s10, s11, 0x2000
	v_lshl_add_u64 v[130:131], s[68:69], 0, v[154:155]
	ds_read_b128 v[210:213], v159
	ds_read_b128 v[214:217], v159 offset:1024
	ds_read_b128 v[218:221], v159 offset:2048
	ds_read_b128 v[222:225], v159 offset:3072
	ds_read_b128 v[226:229], v159 offset:4096
	ds_read_b128 v[230:233], v159 offset:5120
	ds_read_b128 v[234:237], v159 offset:6144
	ds_read_b128 v[238:241], v159 offset:7168
	global_load_lds_dwordx4 v[130:131], off
	v_lshl_add_u64 v[130:131], s[68:69], 0, v[152:153]
	s_mov_b32 m0, s13
	s_nop 0
	global_load_lds_dwordx4 v[130:131], off
	s_waitcnt vmcnt(8)
	s_waitcnt lgkmcnt(0)
	s_barrier
	v_mfma_f32_16x16x32_bf16 v[126:129], v[160:163], v[210:213], v[126:129]
	v_mfma_f32_16x16x32_bf16 v[122:125], v[168:171], v[210:213], v[122:125]
	v_mfma_f32_16x16x32_bf16 v[118:121], v[160:163], v[218:221], v[118:121]
	v_mfma_f32_16x16x32_bf16 v[114:117], v[168:171], v[218:221], v[114:117]
	v_mfma_f32_16x16x32_bf16 v[102:105], v[160:163], v[226:229], v[102:105]
	v_mfma_f32_16x16x32_bf16 v[98:101], v[168:171], v[226:229], v[98:101]
	v_mfma_f32_16x16x32_bf16 v[86:89], v[160:163], v[234:237], v[86:89]
	v_mfma_f32_16x16x32_bf16 v[82:85], v[168:171], v[234:237], v[82:85]
	v_mfma_f32_16x16x32_bf16 v[126:129], v[164:167], v[214:217], v[126:129]
	v_mfma_f32_16x16x32_bf16 v[122:125], v[186:189], v[214:217], v[122:125]
	v_mfma_f32_16x16x32_bf16 v[118:121], v[164:167], v[222:225], v[118:121]
	v_mfma_f32_16x16x32_bf16 v[114:117], v[186:189], v[222:225], v[114:117]
	v_mfma_f32_16x16x32_bf16 v[102:105], v[164:167], v[230:233], v[102:105]
	v_mfma_f32_16x16x32_bf16 v[98:101], v[186:189], v[230:233], v[98:101]
	v_mfma_f32_16x16x32_bf16 v[86:89], v[164:167], v[238:241], v[86:89]
	v_mfma_f32_16x16x32_bf16 v[82:85], v[186:189], v[238:241], v[82:85]
	v_mfma_f32_16x16x32_bf16 v[110:113], v[190:193], v[210:213], v[110:113]
	v_mfma_f32_16x16x32_bf16 v[106:109], v[202:205], v[210:213], v[106:109]
	v_mfma_f32_16x16x32_bf16 v[94:97], v[190:193], v[218:221], v[94:97]
	v_mfma_f32_16x16x32_bf16 v[90:93], v[202:205], v[218:221], v[90:93]
	v_mfma_f32_16x16x32_bf16 v[78:81], v[190:193], v[226:229], v[78:81]
	v_mfma_f32_16x16x32_bf16 v[74:77], v[202:205], v[226:229], v[74:77]
	v_mfma_f32_16x16x32_bf16 v[70:73], v[190:193], v[234:237], v[70:73]
	v_mfma_f32_16x16x32_bf16 v[66:69], v[202:205], v[234:237], v[66:69]
	v_mfma_f32_16x16x32_bf16 v[110:113], v[198:201], v[214:217], v[110:113]
	v_mfma_f32_16x16x32_bf16 v[106:109], v[206:209], v[214:217], v[106:109]
	v_mfma_f32_16x16x32_bf16 v[94:97], v[198:201], v[222:225], v[94:97]
	v_mfma_f32_16x16x32_bf16 v[90:93], v[206:209], v[222:225], v[90:93]
	v_mfma_f32_16x16x32_bf16 v[78:81], v[198:201], v[230:233], v[78:81]
	v_mfma_f32_16x16x32_bf16 v[74:77], v[206:209], v[230:233], v[74:77]
	v_mfma_f32_16x16x32_bf16 v[70:73], v[198:201], v[238:241], v[70:73]
	v_mfma_f32_16x16x32_bf16 v[66:69], v[206:209], v[238:241], v[66:69]
	s_barrier
	s_mov_b32 m0, s12
	v_lshl_add_u64 v[130:131], vcc, 0, v[0:1]
	ds_read_b128 v[210:213], v159 offset:16384
	ds_read_b128 v[214:217], v159 offset:17408
	ds_read_b128 v[218:221], v159 offset:18432
	ds_read_b128 v[222:225], v159 offset:19456
	ds_read_b128 v[226:229], v159 offset:20480
	ds_read_b128 v[230:233], v159 offset:21504
	ds_read_b128 v[234:237], v159 offset:22528
	ds_read_b128 v[238:241], v159 offset:23552
	global_load_lds_dwordx4 v[130:131], off
	v_lshl_add_u64 v[132:133], vcc, 0, v[150:151]
	s_mov_b32 m0, s81
	v_lshl_add_u64 v[172:173], s[36:37], 0, v[0:1]
	global_load_lds_dwordx4 v[132:133], off
	s_mov_b32 m0, s93
	v_lshl_add_u64 v[242:243], s[62:63], 0, v[152:153]
	global_load_lds_dwordx4 v[172:173], off
	v_lshl_add_u64 v[172:173], s[36:37], 0, v[150:151]
	s_mov_b32 m0, s92
	s_nop 0
	global_load_lds_dwordx4 v[172:173], off
	v_lshl_add_u64 v[172:173], s[62:63], 0, v[154:155]
	s_mov_b32 m0, s9
	s_nop 0
	global_load_lds_dwordx4 v[172:173], off
	s_mov_b32 m0, s30
	s_nop 0
	global_load_lds_dwordx4 v[242:243], off
	s_waitcnt vmcnt(8)
	s_waitcnt lgkmcnt(0)
	s_barrier
; #define PG8_STAGE(bufoff, gbase, voff) do { _Pragma("unroll") for (int _i = 0; _i < 2; ++_i) \
;         __builtin_amdgcn_global_load_lds((const unsigned*)((const char*)(gbase) + (voff)[_i]), (PG8_LAS unsigned*)(lds + (bufoff) + ldsw + _i * 8192), 16, 0, 0); } while (0)
; #define PG8_LDA(dst, b, h) do { _Pragma("unroll") for (int m = 0; m < 4; ++m) _Pragma("unroll") for (int k = 0; k < 2; ++k) dst[m][k] = *(const PG8_LAS bf16x8*)(lds + PG8_SA(b, h) + aoff + m * 2048 + k * 1024); } while (0)
; #define PG8_LDB(dst, b, h) do { _Pragma("unroll") for (int n = 0; n < 2; ++n) _Pragma("unroll") for (int k = 0; k < 2; ++k) dst[n][k] = *(const PG8_LAS bf16x8*)(lds + PG8_SB(b, h) + boff + n * 2048 + k * 1024); } while (0)
; #define PG8_MMA(ai, bj, At, Bt) do { __builtin_amdgcn_s_setprio(1); _Pragma("unroll") for (int m = 0; m < 4; ++m) _Pragma("unroll") for (int n = 0; n < 2; ++n) _Pragma("unroll") for (int k = 0; k < 2; ++k) \
;         acc[ai][bj][m][n] = __builtin_amdgcn_mfma_f32_16x16x32_bf16(Bt[n][k], At[m][k], acc[ai][bj][m][n], 0, 0, 0); __builtin_amdgcn_s_setprio(0); } while (0)
; #define PG8_WAIT_V(n) asm volatile("s_waitcnt vmcnt(" #n ")" ::: "memory")
; #define PG8_WAIT_L(n) asm volatile("s_waitcnt lgkmcnt(" #n ")" ::: "memory")
; #define PG8_BAR __builtin_amdgcn_s_barrier()
; #define PG8_SCHED __builtin_amdgcn_sched_barrier(0)
; template <class Epi, class Sched, bool ALIGN_EPI = false, bool SP2 = false>
; __device__ __forceinline__ void gemm_phase(PG8_LAS unsigned char* lds, const Gemm g, const Sched& S, const Epi& E) {
;     ...
;             PG8_WAIT_V(8); PG8_WAIT_L(0); PG8_BAR; PG8_MMA(1, 0, At, B0); PG8_MMA(1, 1, At, B1); PG8_BAR; PG8_SCHED;
;             PG8_LDB(B0, 1, 0); PG8_LDB(B1, 1, 1); PG8_SCHED; PG8_LDA(At, 1, 0); PG8_STAGE(PG8_SA(0, 1), a2 + hstepA, voffA);
;             PG8_WAIT_V(8); PG8_WAIT_L(0); PG8_BAR; PG8_MMA(0, 0, At, B0); PG8_MMA(0, 1, At, B1); PG8_BAR; PG8_SCHED;
	v_mfma_f32_16x16x32_bf16 v[62:65], v[160:163], v[210:213], v[62:65]
	v_mfma_f32_16x16x32_bf16 v[58:61], v[168:171], v[210:213], v[58:61]
	v_mfma_f32_16x16x32_bf16 v[54:57], v[160:163], v[218:221], v[54:57]
	v_mfma_f32_16x16x32_bf16 v[50:53], v[168:171], v[218:221], v[50:53]
	v_mfma_f32_16x16x32_bf16 v[38:41], v[160:163], v[226:229], v[38:41]
	v_mfma_f32_16x16x32_bf16 v[34:37], v[168:171], v[226:229], v[34:37]
	v_mfma_f32_16x16x32_bf16 v[22:25], v[160:163], v[234:237], v[22:25]
	v_mfma_f32_16x16x32_bf16 v[18:21], v[168:171], v[234:237], v[18:21]
	v_mfma_f32_16x16x32_bf16 v[62:65], v[164:167], v[214:217], v[62:65]
	v_mfma_f32_16x16x32_bf16 v[58:61], v[186:189], v[214:217], v[58:61]
	v_mfma_f32_16x16x32_bf16 v[54:57], v[164:167], v[222:225], v[54:57]
	v_mfma_f32_16x16x32_bf16 v[50:53], v[186:189], v[222:225], v[50:53]
	v_mfma_f32_16x16x32_bf16 v[38:41], v[164:167], v[230:233], v[38:41]
	v_mfma_f32_16x16x32_bf16 v[34:37], v[186:189], v[230:233], v[34:37]
	v_mfma_f32_16x16x32_bf16 v[22:25], v[164:167], v[238:241], v[22:25]
	v_mfma_f32_16x16x32_bf16 v[18:21], v[186:189], v[238:241], v[18:21]
	v_mfma_f32_16x16x32_bf16 v[46:49], v[190:193], v[210:213], v[46:49]
	v_mfma_f32_16x16x32_bf16 v[42:45], v[202:205], v[210:213], v[42:45]
	v_mfma_f32_16x16x32_bf16 v[30:33], v[190:193], v[218:221], v[30:33]
	v_mfma_f32_16x16x32_bf16 v[26:29], v[202:205], v[218:221], v[26:29]
	v_mfma_f32_16x16x32_bf16 v[14:17], v[190:193], v[226:229], v[14:17]
	v_mfma_f32_16x16x32_bf16 v[10:13], v[202:205], v[226:229], v[10:13]
	v_mfma_f32_16x16x32_bf16 v[6:9], v[190:193], v[234:237], v[6:9]
	v_mfma_f32_16x16x32_bf16 v[2:5], v[202:205], v[234:237], v[2:5]
	v_mfma_f32_16x16x32_bf16 v[46:49], v[198:201], v[214:217], v[46:49]
	v_mfma_f32_16x16x32_bf16 v[42:45], v[206:209], v[214:217], v[42:45]
	v_mfma_f32_16x16x32_bf16 v[30:33], v[198:201], v[222:225], v[30:33]
	v_mfma_f32_16x16x32_bf16 v[26:29], v[206:209], v[222:225], v[26:29]
	v_mfma_f32_16x16x32_bf16 v[14:17], v[198:201], v[230:233], v[14:17]
	v_mfma_f32_16x16x32_bf16 v[10:13], v[206:209], v[230:233], v[10:13]
	v_mfma_f32_16x16x32_bf16 v[6:9], v[198:201], v[238:241], v[6:9]
	v_mfma_f32_16x16x32_bf16 v[2:5], v[206:209], v[238:241], v[2:5]
	s_barrier
	v_add_u32_e32 v186, s87, v157
	v_add_u32_e32 v206, s85, v157
	ds_read_b128 v[160:163], v186
	ds_read_b128 v[164:167], v186 offset:1024
	ds_read_b128 v[168:171], v186 offset:2048
	ds_read_b128 v[186:189], v186 offset:3072
	ds_read_b128 v[190:193], v206
	ds_read_b128 v[198:201], v206 offset:1024
	ds_read_b128 v[202:205], v206 offset:2048
	ds_read_b128 v[206:209], v206 offset:3072
	s_mov_b32 m0, s31
	v_lshl_add_u64 v[244:245], s[56:57], 0, v[154:155]
	ds_read_b128 v[210:213], v159 offset:32768
	ds_read_b128 v[214:217], v159 offset:33792
	ds_read_b128 v[218:221], v159 offset:34816
	ds_read_b128 v[222:225], v159 offset:35840
	ds_read_b128 v[226:229], v159 offset:36864
	ds_read_b128 v[230:233], v159 offset:37888
	ds_read_b128 v[234:237], v159 offset:38912
	ds_read_b128 v[238:241], v159 offset:39936
	global_load_lds_dwordx4 v[244:245], off
	v_lshl_add_u64 v[244:245], s[56:57], 0, v[152:153]
	s_mov_b32 m0, s34
	s_nop 0
	global_load_lds_dwordx4 v[244:245], off
	s_waitcnt vmcnt(8)
	s_waitcnt lgkmcnt(0)
	s_barrier
	v_mfma_f32_16x16x32_bf16 v[126:129], v[160:163], v[210:213], v[126:129]
	v_mfma_f32_16x16x32_bf16 v[122:125], v[168:171], v[210:213], v[122:125]
	v_mfma_f32_16x16x32_bf16 v[118:121], v[160:163], v[218:221], v[118:121]
	v_mfma_f32_16x16x32_bf16 v[114:117], v[168:171], v[218:221], v[114:117]
	v_mfma_f32_16x16x32_bf16 v[102:105], v[160:163], v[226:229], v[102:105]
	v_mfma_f32_16x16x32_bf16 v[98:101], v[168:171], v[226:229], v[98:101]
	v_mfma_f32_16x16x32_bf16 v[86:89], v[160:163], v[234:237], v[86:89]
	v_mfma_f32_16x16x32_bf16 v[82:85], v[168:171], v[234:237], v[82:85]
	v_mfma_f32_16x16x32_bf16 v[126:129], v[164:167], v[214:217], v[126:129]
	v_mfma_f32_16x16x32_bf16 v[122:125], v[186:189], v[214:217], v[122:125]
	v_mfma_f32_16x16x32_bf16 v[118:121], v[164:167], v[222:225], v[118:121]
	v_mfma_f32_16x16x32_bf16 v[114:117], v[186:189], v[222:225], v[114:117]
	v_mfma_f32_16x16x32_bf16 v[102:105], v[164:167], v[230:233], v[102:105]
	v_mfma_f32_16x16x32_bf16 v[98:101], v[186:189], v[230:233], v[98:101]
	v_mfma_f32_16x16x32_bf16 v[86:89], v[164:167], v[238:241], v[86:89]
	v_mfma_f32_16x16x32_bf16 v[82:85], v[186:189], v[238:241], v[82:85]
	v_mfma_f32_16x16x32_bf16 v[110:113], v[190:193], v[210:213], v[110:113]
	v_mfma_f32_16x16x32_bf16 v[106:109], v[202:205], v[210:213], v[106:109]
	v_mfma_f32_16x16x32_bf16 v[94:97], v[190:193], v[218:221], v[94:97]
	v_mfma_f32_16x16x32_bf16 v[90:93], v[202:205], v[218:221], v[90:93]
	v_mfma_f32_16x16x32_bf16 v[78:81], v[190:193], v[226:229], v[78:81]
	v_mfma_f32_16x16x32_bf16 v[74:77], v[202:205], v[226:229], v[74:77]
	v_mfma_f32_16x16x32_bf16 v[70:73], v[190:193], v[234:237], v[70:73]
	v_mfma_f32_16x16x32_bf16 v[66:69], v[202:205], v[234:237], v[66:69]
	v_mfma_f32_16x16x32_bf16 v[110:113], v[198:201], v[214:217], v[110:113]
	v_mfma_f32_16x16x32_bf16 v[106:109], v[206:209], v[214:217], v[106:109]
	v_mfma_f32_16x16x32_bf16 v[94:97], v[198:201], v[222:225], v[94:97]
	v_mfma_f32_16x16x32_bf16 v[90:93], v[206:209], v[222:225], v[90:93]
	v_mfma_f32_16x16x32_bf16 v[78:81], v[198:201], v[230:233], v[78:81]
	v_mfma_f32_16x16x32_bf16 v[74:77], v[206:209], v[230:233], v[74:77]
	v_mfma_f32_16x16x32_bf16 v[70:73], v[198:201], v[238:241], v[70:73]
	v_mfma_f32_16x16x32_bf16 v[66:69], v[206:209], v[238:241], v[66:69]
	s_barrier
; #define PG8_STAGE(bufoff, gbase, voff) do { _Pragma("unroll") for (int _i = 0; _i < 2; ++_i) \
;         __builtin_amdgcn_global_load_lds((const unsigned*)((const char*)(gbase) + (voff)[_i]), (PG8_LAS unsigned*)(lds + (bufoff) + ldsw + _i * 8192), 16, 0, 0); } while (0)
; #define PG8_LDA(dst, b, h) do { _Pragma("unroll") for (int m = 0; m < 4; ++m) _Pragma("unroll") for (int k = 0; k < 2; ++k) dst[m][k] = *(const PG8_LAS bf16x8*)(lds + PG8_SA(b, h) + aoff + m * 2048 + k * 1024); } while (0)
; #define PG8_MMA(ai, bj, At, Bt) do { __builtin_amdgcn_s_setprio(1); _Pragma("unroll") for (int m = 0; m < 4; ++m) _Pragma("unroll") for (int n = 0; n < 2; ++n) _Pragma("unroll") for (int k = 0; k < 2; ++k) \
;         acc[ai][bj][m][n] = __builtin_amdgcn_mfma_f32_16x16x32_bf16(Bt[n][k], At[m][k], acc[ai][bj][m][n], 0, 0, 0); __builtin_amdgcn_s_setprio(0); } while (0)
; #define PG8_WAIT_V(n) asm volatile("s_waitcnt vmcnt(" #n ")" ::: "memory")
; #define PG8_WAIT_L(n) asm volatile("s_waitcnt lgkmcnt(" #n ")" ::: "memory")
; #define PG8_BAR __builtin_amdgcn_s_barrier()
; #define PG8_SCHED __builtin_amdgcn_sched_barrier(0)
; template <class Epi, class Sched, bool ALIGN_EPI = false, bool SP2 = false>
; __device__ __forceinline__ void gemm_phase(PG8_LAS unsigned char* lds, const Gemm g, const Sched& S, const Epi& E) {
;     ...
;             PG8_LDA(At, 1, 1); PG8_STAGE(PG8_SB(1, 0), b3, voffB); PG8_STAGE(PG8_SB(1, 1), b3 + hstepB, voffB); PG8_STAGE(PG8_SA(1, 0), a3, voffA);
;             PG8_WAIT_V(8); PG8_WAIT_L(0); PG8_BAR; PG8_MMA(1, 0, At, B0); PG8_MMA(1, 1, At, B1); PG8_BAR; PG8_SCHED;
	s_mov_b32 m0, s39
	v_lshl_add_u64 v[130:131], v[130:131], 0, s[2:3]
	ds_read_b128 v[210:213], v159 offset:49152
	ds_read_b128 v[214:217], v159 offset:50176
	ds_read_b128 v[218:221], v159 offset:51200
	ds_read_b128 v[222:225], v159 offset:52224
	ds_read_b128 v[226:229], v159 offset:53248
	ds_read_b128 v[230:233], v159 offset:54272
	ds_read_b128 v[234:237], v159 offset:55296
	ds_read_b128 v[238:241], v159 offset:56320
	global_load_lds_dwordx4 v[130:131], off
	v_lshl_add_u64 v[130:131], v[132:133], 0, s[2:3]
	s_mov_b32 m0, s4
	s_nop 0
	global_load_lds_dwordx4 v[130:131], off
	v_lshl_add_u64 v[130:131], s[54:55], 0, v[0:1]
	s_mov_b32 m0, s11
	s_nop 0
	global_load_lds_dwordx4 v[130:131], off
	v_lshl_add_u64 v[130:131], s[54:55], 0, v[150:151]
	s_mov_b32 m0, s10
	s_nop 0
	global_load_lds_dwordx4 v[130:131], off
	v_lshl_add_u64 v[130:131], v[172:173], 0, s[2:3]
	s_mov_b32 m0, s35
	s_nop 0
	global_load_lds_dwordx4 v[130:131], off
	v_lshl_add_u64 v[130:131], v[242:243], 0, s[2:3]
	s_mov_b32 m0, s88
	s_nop 0
	global_load_lds_dwordx4 v[130:131], off
	s_waitcnt vmcnt(8)
	s_waitcnt lgkmcnt(0)
	s_barrier
	v_mfma_f32_16x16x32_bf16 v[62:65], v[160:163], v[210:213], v[62:65]
	v_mfma_f32_16x16x32_bf16 v[58:61], v[168:171], v[210:213], v[58:61]
	v_mfma_f32_16x16x32_bf16 v[54:57], v[160:163], v[218:221], v[54:57]
	v_mfma_f32_16x16x32_bf16 v[50:53], v[168:171], v[218:221], v[50:53]
	v_mfma_f32_16x16x32_bf16 v[38:41], v[160:163], v[226:229], v[38:41]
	v_mfma_f32_16x16x32_bf16 v[34:37], v[168:171], v[226:229], v[34:37]
	v_mfma_f32_16x16x32_bf16 v[22:25], v[160:163], v[234:237], v[22:25]
	v_mfma_f32_16x16x32_bf16 v[18:21], v[168:171], v[234:237], v[18:21]
	v_mfma_f32_16x16x32_bf16 v[62:65], v[164:167], v[214:217], v[62:65]
	v_mfma_f32_16x16x32_bf16 v[58:61], v[186:189], v[214:217], v[58:61]
	v_mfma_f32_16x16x32_bf16 v[54:57], v[164:167], v[222:225], v[54:57]
	v_mfma_f32_16x16x32_bf16 v[50:53], v[186:189], v[222:225], v[50:53]
	v_mfma_f32_16x16x32_bf16 v[38:41], v[164:167], v[230:233], v[38:41]
	v_mfma_f32_16x16x32_bf16 v[34:37], v[186:189], v[230:233], v[34:37]
	v_mfma_f32_16x16x32_bf16 v[22:25], v[164:167], v[238:241], v[22:25]
	v_mfma_f32_16x16x32_bf16 v[18:21], v[186:189], v[238:241], v[18:21]
	v_mfma_f32_16x16x32_bf16 v[46:49], v[190:193], v[210:213], v[46:49]
	v_mfma_f32_16x16x32_bf16 v[42:45], v[202:205], v[210:213], v[42:45]
	v_mfma_f32_16x16x32_bf16 v[30:33], v[190:193], v[218:221], v[30:33]
	v_mfma_f32_16x16x32_bf16 v[26:29], v[202:205], v[218:221], v[26:29]
	v_mfma_f32_16x16x32_bf16 v[14:17], v[190:193], v[226:229], v[14:17]
	v_mfma_f32_16x16x32_bf16 v[10:13], v[202:205], v[226:229], v[10:13]
	v_mfma_f32_16x16x32_bf16 v[6:9], v[190:193], v[234:237], v[6:9]
	v_mfma_f32_16x16x32_bf16 v[2:5], v[202:205], v[234:237], v[2:5]
	v_mfma_f32_16x16x32_bf16 v[46:49], v[198:201], v[214:217], v[46:49]
	v_mfma_f32_16x16x32_bf16 v[42:45], v[206:209], v[214:217], v[42:45]
	v_mfma_f32_16x16x32_bf16 v[30:33], v[198:201], v[222:225], v[30:33]
	v_mfma_f32_16x16x32_bf16 v[26:29], v[206:209], v[222:225], v[26:29]
	v_mfma_f32_16x16x32_bf16 v[14:17], v[198:201], v[230:233], v[14:17]
	v_mfma_f32_16x16x32_bf16 v[10:13], v[206:209], v[230:233], v[10:13]
	v_mfma_f32_16x16x32_bf16 v[6:9], v[198:201], v[238:241], v[6:9]
	v_mfma_f32_16x16x32_bf16 v[2:5], v[206:209], v[238:241], v[2:5]
	s_barrier
	s_movk_i32 s4, 0x100
	s_andn2_b64 vcc, exec, s[0:1]
	s_mov_b64 s[54:55], -1
	s_mov_b64 s[0:1], 0
	s_cbranch_vccz .LBB0_402
	s_and_b64 vcc, exec, s[42:43]
	s_cbranch_vccz .LBB0_405
	s_barrier

; #define PG8_STAGE(bufoff, gbase, voff) do { _Pragma("unroll") for (int _i = 0; _i < 2; ++_i) \
;         __builtin_amdgcn_global_load_lds((const unsigned*)((const char*)(gbase) + (voff)[_i]), (PG8_LAS unsigned*)(lds + (bufoff) + ldsw + _i * 8192), 16, 0, 0); } while (0)
; #define PG8_LDA(dst, b, h) do { _Pragma("unroll") for (int m = 0; m < 4; ++m) _Pragma("unroll") for (int k = 0; k < 2; ++k) dst[m][k] = *(const PG8_LAS bf16x8*)(lds + PG8_SA(b, h) + aoff + m * 2048 + k * 1024); } while (0)
; #define PG8_LDB(dst, b, h) do { _Pragma("unroll") for (int n = 0; n < 2; ++n) _Pragma("unroll") for (int k = 0; k < 2; ++k) dst[n][k] = *(const PG8_LAS bf16x8*)(lds + PG8_SB(b, h) + boff + n * 2048 + k * 1024); } while (0)
; #define PG8_MMA(ai, bj, At, Bt) do { __builtin_amdgcn_s_setprio(1); _Pragma("unroll") for (int m = 0; m < 4; ++m) _Pragma("unroll") for (int n = 0; n < 2; ++n) _Pragma("unroll") for (int k = 0; k < 2; ++k) \
;         acc[ai][bj][m][n] = __builtin_amdgcn_mfma_f32_16x16x32_bf16(Bt[n][k], At[m][k], acc[ai][bj][m][n], 0, 0, 0); __builtin_amdgcn_s_setprio(0); } while (0)
; #define PG8_WAIT_V(n) asm volatile("s_waitcnt vmcnt(" #n ")" ::: "memory")
; #define PG8_BAR __builtin_amdgcn_s_barrier()
; template <class Epi, class Sched, bool ALIGN_EPI = false, bool SP2 = false>
; __device__ __forceinline__ void gemm_phase(PG8_LAS unsigned char* lds, const Gemm g, const Sched& S, const Epi& E) {
;     ...
;         for (int t = 0; t < nt; t += 2) {
;             const bool last = (t == nt - 2);
;             const char* a1 = cA + (size_t)(t + 1) * kstep;
;             const char* a2 = last ? nA : cA + (size_t)(t + 2) * kstep; const char* b2 = last ? nB : cB + (size_t)(t + 2) * kstep;
;             const char* a3 = a2 + kstep; const char* b3 = b2 + kstep;
;             if (last && has_next) S.a_ready(nxt);
;             if constexpr (SP2) {
;             PG8_LDB(B0, 0, 0); PG8_LDB(B1, 0, 1); PG8_SCHED; PG8_LDA(At, 0, 0); PG8_STAGE(PG8_SA(1, 1), a1 + hstepA, voffA);
;             PG8_WAIT_V(8); PG8_WAIT_L(0); PG8_BAR; PG8_MMA(0, 0, At, B0); PG8_MMA(0, 1, At, B1); PG8_BAR; PG8_SCHED;
;             PG8_LDA(At, 0, 1); PG8_STAGE(PG8_SB(0, 0), b2, voffB); PG8_STAGE(PG8_SB(0, 1), b2 + hstepB, voffB); PG8_STAGE(PG8_SA(0, 0), a2, voffA);
;             PG8_WAIT_V(8); PG8_WAIT_L(0); PG8_BAR; PG8_MMA(1, 0, At, B0); PG8_MMA(1, 1, At, B1); PG8_BAR; PG8_SCHED;
.LBB0_424:
	s_add_u32 s12, s50, s36
	s_addc_u32 s13, s51, 0
	s_add_u32 s37, s12, 0x100
	s_addc_u32 s54, s13, 0
	s_and_b64 s[10:11], s[52:53], exec
	s_cselect_b32 s57, s43, s54
	s_cselect_b32 s56, s4, s37
	s_add_u32 s10, s48, s36
	s_addc_u32 s11, s49, 0
	s_add_u32 s36, s10, 0x100
	s_addc_u32 s37, s11, 0
	s_add_i32 s86, 0, 0x10000
	s_and_b64 s[10:11], s[52:53], exec
	s_cselect_b32 s63, s45, s37
	s_cselect_b32 s62, s44, s36
	s_add_i32 s10, 0, 0x14000
	s_add_u32 s68, s12, 0x10080
	s_addc_u32 s69, s13, 0
	s_add_i32 s12, s86, s8
	s_add_i32 m0, s9, 0xc000
	s_add_i32 s13, s9, 0xe000
	s_add_i32 s81, s12, 0x2000
	v_add_u32_e32 v130, s86, v157
	s_add_u32 s36, s62, 0x90000
	ds_read_b128 v[160:163], v130
	ds_read_b128 v[164:167], v130 offset:1024
	ds_read_b128 v[168:171], v130 offset:2048
	ds_read_b128 v[186:189], v130 offset:3072
	v_add_u32_e32 v130, s10, v157
	s_addc_u32 s37, s63, 0
	s_add_i32 s93, s10, s8
	ds_read_b128 v[190:193], v130
	ds_read_b128 v[198:201], v130 offset:1024
	ds_read_b128 v[202:205], v130 offset:2048
	ds_read_b128 v[206:209], v130 offset:3072
	s_add_i32 s92, s93, 0x2000
	s_add_i32 s87, 0, 0x18000
	s_add_i32 s85, 0, 0x1c000
	s_add_u32 s54, s56, 0x10000
	s_addc_u32 s55, s57, 0
	s_add_i32 vcc_hi, s87, s8
	s_add_i32 vcc_lo, vcc_hi, 0x2000
	s_add_u32 s52, s62, 0x90080
	s_addc_u32 s53, s63, 0
	s_add_i32 s11, s85, s8
	s_add_i32 s10, s11, 0x2000
	v_lshl_add_u64 v[130:131], s[68:69], 0, v[154:155]
	ds_read_b128 v[210:213], v159
	ds_read_b128 v[214:217], v159 offset:1024
	ds_read_b128 v[218:221], v159 offset:2048
	ds_read_b128 v[222:225], v159 offset:3072
	ds_read_b128 v[226:229], v159 offset:4096
	ds_read_b128 v[230:233], v159 offset:5120
	ds_read_b128 v[234:237], v159 offset:6144
	ds_read_b128 v[238:241], v159 offset:7168
	global_load_lds_dwordx4 v[130:131], off
	v_lshl_add_u64 v[130:131], s[68:69], 0, v[152:153]
	s_mov_b32 m0, s13
	s_nop 0
	global_load_lds_dwordx4 v[130:131], off
	s_waitcnt vmcnt(8)
	s_waitcnt lgkmcnt(0)
	s_barrier
	v_mfma_f32_16x16x32_bf16 v[126:129], v[160:163], v[210:213], v[126:129]
	v_mfma_f32_16x16x32_bf16 v[122:125], v[168:171], v[210:213], v[122:125]
	v_mfma_f32_16x16x32_bf16 v[118:121], v[160:163], v[218:221], v[118:121]
	v_mfma_f32_16x16x32_bf16 v[114:117], v[168:171], v[218:221], v[114:117]
	v_mfma_f32_16x16x32_bf16 v[102:105], v[160:163], v[226:229], v[102:105]
	v_mfma_f32_16x16x32_bf16 v[98:101], v[168:171], v[226:229], v[98:101]
	v_mfma_f32_16x16x32_bf16 v[86:89], v[160:163], v[234:237], v[86:89]
	v_mfma_f32_16x16x32_bf16 v[82:85], v[168:171], v[234:237], v[82:85]
	v_mfma_f32_16x16x32_bf16 v[126:129], v[164:167], v[214:217], v[126:129]
	v_mfma_f32_16x16x32_bf16 v[122:125], v[186:189], v[214:217], v[122:125]
	v_mfma_f32_16x16x32_bf16 v[118:121], v[164:167], v[222:225], v[118:121]
	v_mfma_f32_16x16x32_bf16 v[114:117], v[186:189], v[222:225], v[114:117]
	v_mfma_f32_16x16x32_bf16 v[102:105], v[164:167], v[230:233], v[102:105]
	v_mfma_f32_16x16x32_bf16 v[98:101], v[186:189], v[230:233], v[98:101]
	v_mfma_f32_16x16x32_bf16 v[86:89], v[164:167], v[238:241], v[86:89]
	v_mfma_f32_16x16x32_bf16 v[82:85], v[186:189], v[238:241], v[82:85]
	v_mfma_f32_16x16x32_bf16 v[110:113], v[190:193], v[210:213], v[110:113]
	v_mfma_f32_16x16x32_bf16 v[106:109], v[202:205], v[210:213], v[106:109]
	v_mfma_f32_16x16x32_bf16 v[94:97], v[190:193], v[218:221], v[94:97]
	v_mfma_f32_16x16x32_bf16 v[90:93], v[202:205], v[218:221], v[90:93]
	v_mfma_f32_16x16x32_bf16 v[78:81], v[190:193], v[226:229], v[78:81]
	v_mfma_f32_16x16x32_bf16 v[74:77], v[202:205], v[226:229], v[74:77]
	v_mfma_f32_16x16x32_bf16 v[70:73], v[190:193], v[234:237], v[70:73]
	v_mfma_f32_16x16x32_bf16 v[66:69], v[202:205], v[234:237], v[66:69]
	v_mfma_f32_16x16x32_bf16 v[110:113], v[198:201], v[214:217], v[110:113]
	v_mfma_f32_16x16x32_bf16 v[106:109], v[206:209], v[214:217], v[106:109]
	v_mfma_f32_16x16x32_bf16 v[94:97], v[198:201], v[222:225], v[94:97]
	v_mfma_f32_16x16x32_bf16 v[90:93], v[206:209], v[222:225], v[90:93]
	v_mfma_f32_16x16x32_bf16 v[78:81], v[198:201], v[230:233], v[78:81]
	v_mfma_f32_16x16x32_bf16 v[74:77], v[206:209], v[230:233], v[74:77]
	v_mfma_f32_16x16x32_bf16 v[70:73], v[198:201], v[238:241], v[70:73]
	v_mfma_f32_16x16x32_bf16 v[66:69], v[206:209], v[238:241], v[66:69]
	s_barrier
	s_mov_b32 m0, s12
	v_lshl_add_u64 v[130:131], s[62:63], 0, v[0:1]
	ds_read_b128 v[210:213], v159 offset:16384
	ds_read_b128 v[214:217], v159 offset:17408
	ds_read_b128 v[218:221], v159 offset:18432
	ds_read_b128 v[222:225], v159 offset:19456
	ds_read_b128 v[226:229], v159 offset:20480
	ds_read_b128 v[230:233], v159 offset:21504
	ds_read_b128 v[234:237], v159 offset:22528
	ds_read_b128 v[238:241], v159 offset:23552
	global_load_lds_dwordx4 v[130:131], off
	v_lshl_add_u64 v[132:133], s[62:63], 0, v[150:151]
	s_mov_b32 m0, s81
	v_lshl_add_u64 v[172:173], s[36:37], 0, v[0:1]
	global_load_lds_dwordx4 v[132:133], off
	s_mov_b32 m0, s93
	v_lshl_add_u64 v[242:243], s[56:57], 0, v[152:153]
	global_load_lds_dwordx4 v[172:173], off
	v_lshl_add_u64 v[172:173], s[36:37], 0, v[150:151]
	s_mov_b32 m0, s92
	s_nop 0
	global_load_lds_dwordx4 v[172:173], off
	v_lshl_add_u64 v[172:173], s[56:57], 0, v[154:155]
	s_mov_b32 m0, s9
	s_nop 0
	global_load_lds_dwordx4 v[172:173], off
	s_mov_b32 m0, s30
	s_nop 0
	global_load_lds_dwordx4 v[242:243], off
	s_waitcnt vmcnt(8)
	s_waitcnt lgkmcnt(0)
	s_barrier
; #define PG8_STAGE(bufoff, gbase, voff) do { _Pragma("unroll") for (int _i = 0; _i < 2; ++_i) \
;         __builtin_amdgcn_global_load_lds((const unsigned*)((const char*)(gbase) + (voff)[_i]), (PG8_LAS unsigned*)(lds + (bufoff) + ldsw + _i * 8192), 16, 0, 0); } while (0)
; #define PG8_LDA(dst, b, h) do { _Pragma("unroll") for (int m = 0; m < 4; ++m) _Pragma("unroll") for (int k = 0; k < 2; ++k) dst[m][k] = *(const PG8_LAS bf16x8*)(lds + PG8_SA(b, h) + aoff + m * 2048 + k * 1024); } while (0)
; #define PG8_LDB(dst, b, h) do { _Pragma("unroll") for (int n = 0; n < 2; ++n) _Pragma("unroll") for (int k = 0; k < 2; ++k) dst[n][k] = *(const PG8_LAS bf16x8*)(lds + PG8_SB(b, h) + boff + n * 2048 + k * 1024); } while (0)
; #define PG8_MMA(ai, bj, At, Bt) do { __builtin_amdgcn_s_setprio(1); _Pragma("unroll") for (int m = 0; m < 4; ++m) _Pragma("unroll") for (int n = 0; n < 2; ++n) _Pragma("unroll") for (int k = 0; k < 2; ++k) \
;         acc[ai][bj][m][n] = __builtin_amdgcn_mfma_f32_16x16x32_bf16(Bt[n][k], At[m][k], acc[ai][bj][m][n], 0, 0, 0); __builtin_amdgcn_s_setprio(0); } while (0)
; #define PG8_WAIT_V(n) asm volatile("s_waitcnt vmcnt(" #n ")" ::: "memory")
; #define PG8_WAIT_L(n) asm volatile("s_waitcnt lgkmcnt(" #n ")" ::: "memory")
; #define PG8_BAR __builtin_amdgcn_s_barrier()
; #define PG8_SCHED __builtin_amdgcn_sched_barrier(0)
; template <class Epi, class Sched, bool ALIGN_EPI = false, bool SP2 = false>
; __device__ __forceinline__ void gemm_phase(PG8_LAS unsigned char* lds, const Gemm g, const Sched& S, const Epi& E) {
;     ...
;             PG8_WAIT_V(8); PG8_WAIT_L(0); PG8_BAR; PG8_MMA(1, 0, At, B0); PG8_MMA(1, 1, At, B1); PG8_BAR; PG8_SCHED;
;             PG8_LDB(B0, 1, 0); PG8_LDB(B1, 1, 1); PG8_SCHED; PG8_LDA(At, 1, 0); PG8_STAGE(PG8_SA(0, 1), a2 + hstepA, voffA);
;             PG8_WAIT_V(8); PG8_WAIT_L(0); PG8_BAR; PG8_MMA(0, 0, At, B0); PG8_MMA(0, 1, At, B1); PG8_BAR; PG8_SCHED;
	v_mfma_f32_16x16x32_bf16 v[62:65], v[160:163], v[210:213], v[62:65]
	v_mfma_f32_16x16x32_bf16 v[58:61], v[168:171], v[210:213], v[58:61]
	v_mfma_f32_16x16x32_bf16 v[54:57], v[160:163], v[218:221], v[54:57]
	v_mfma_f32_16x16x32_bf16 v[50:53], v[168:171], v[218:221], v[50:53]
	v_mfma_f32_16x16x32_bf16 v[38:41], v[160:163], v[226:229], v[38:41]
	v_mfma_f32_16x16x32_bf16 v[34:37], v[168:171], v[226:229], v[34:37]
	v_mfma_f32_16x16x32_bf16 v[22:25], v[160:163], v[234:237], v[22:25]
	v_mfma_f32_16x16x32_bf16 v[18:21], v[168:171], v[234:237], v[18:21]
	v_mfma_f32_16x16x32_bf16 v[62:65], v[164:167], v[214:217], v[62:65]
	v_mfma_f32_16x16x32_bf16 v[58:61], v[186:189], v[214:217], v[58:61]
	v_mfma_f32_16x16x32_bf16 v[54:57], v[164:167], v[222:225], v[54:57]
	v_mfma_f32_16x16x32_bf16 v[50:53], v[186:189], v[222:225], v[50:53]
	v_mfma_f32_16x16x32_bf16 v[38:41], v[164:167], v[230:233], v[38:41]
	v_mfma_f32_16x16x32_bf16 v[34:37], v[186:189], v[230:233], v[34:37]
	v_mfma_f32_16x16x32_bf16 v[22:25], v[164:167], v[238:241], v[22:25]
	v_mfma_f32_16x16x32_bf16 v[18:21], v[186:189], v[238:241], v[18:21]
	v_mfma_f32_16x16x32_bf16 v[46:49], v[190:193], v[210:213], v[46:49]
	v_mfma_f32_16x16x32_bf16 v[42:45], v[202:205], v[210:213], v[42:45]
	v_mfma_f32_16x16x32_bf16 v[30:33], v[190:193], v[218:221], v[30:33]
	v_mfma_f32_16x16x32_bf16 v[26:29], v[202:205], v[218:221], v[26:29]
	v_mfma_f32_16x16x32_bf16 v[14:17], v[190:193], v[226:229], v[14:17]
	v_mfma_f32_16x16x32_bf16 v[10:13], v[202:205], v[226:229], v[10:13]
	v_mfma_f32_16x16x32_bf16 v[6:9], v[190:193], v[234:237], v[6:9]
	v_mfma_f32_16x16x32_bf16 v[2:5], v[202:205], v[234:237], v[2:5]
	v_mfma_f32_16x16x32_bf16 v[46:49], v[198:201], v[214:217], v[46:49]
	v_mfma_f32_16x16x32_bf16 v[42:45], v[206:209], v[214:217], v[42:45]
	v_mfma_f32_16x16x32_bf16 v[30:33], v[198:201], v[222:225], v[30:33]
	v_mfma_f32_16x16x32_bf16 v[26:29], v[206:209], v[222:225], v[26:29]
	v_mfma_f32_16x16x32_bf16 v[14:17], v[198:201], v[230:233], v[14:17]
	v_mfma_f32_16x16x32_bf16 v[10:13], v[206:209], v[230:233], v[10:13]
	v_mfma_f32_16x16x32_bf16 v[6:9], v[198:201], v[238:241], v[6:9]
	v_mfma_f32_16x16x32_bf16 v[2:5], v[206:209], v[238:241], v[2:5]
	s_barrier
	v_add_u32_e32 v186, s87, v157
	v_add_u32_e32 v206, s85, v157
	ds_read_b128 v[160:163], v186
	ds_read_b128 v[164:167], v186 offset:1024
	ds_read_b128 v[168:171], v186 offset:2048
	ds_read_b128 v[186:189], v186 offset:3072
	ds_read_b128 v[190:193], v206
	ds_read_b128 v[198:201], v206 offset:1024
	ds_read_b128 v[202:205], v206 offset:2048
	ds_read_b128 v[206:209], v206 offset:3072
	s_mov_b32 m0, s31
	v_lshl_add_u64 v[244:245], s[54:55], 0, v[154:155]
	ds_read_b128 v[210:213], v159 offset:32768
	ds_read_b128 v[214:217], v159 offset:33792
	ds_read_b128 v[218:221], v159 offset:34816
	ds_read_b128 v[222:225], v159 offset:35840
	ds_read_b128 v[226:229], v159 offset:36864
	ds_read_b128 v[230:233], v159 offset:37888
	ds_read_b128 v[234:237], v159 offset:38912
	ds_read_b128 v[238:241], v159 offset:39936
	global_load_lds_dwordx4 v[244:245], off
	v_lshl_add_u64 v[244:245], s[54:55], 0, v[152:153]
	s_mov_b32 m0, s34
	s_nop 0
	global_load_lds_dwordx4 v[244:245], off
	s_waitcnt vmcnt(8)
	s_waitcnt lgkmcnt(0)
	s_barrier
	v_mfma_f32_16x16x32_bf16 v[126:129], v[160:163], v[210:213], v[126:129]
	v_mfma_f32_16x16x32_bf16 v[122:125], v[168:171], v[210:213], v[122:125]
	v_mfma_f32_16x16x32_bf16 v[118:121], v[160:163], v[218:221], v[118:121]
	v_mfma_f32_16x16x32_bf16 v[114:117], v[168:171], v[218:221], v[114:117]
	v_mfma_f32_16x16x32_bf16 v[102:105], v[160:163], v[226:229], v[102:105]
	v_mfma_f32_16x16x32_bf16 v[98:101], v[168:171], v[226:229], v[98:101]
	v_mfma_f32_16x16x32_bf16 v[86:89], v[160:163], v[234:237], v[86:89]
	v_mfma_f32_16x16x32_bf16 v[82:85], v[168:171], v[234:237], v[82:85]
	v_mfma_f32_16x16x32_bf16 v[126:129], v[164:167], v[214:217], v[126:129]
	v_mfma_f32_16x16x32_bf16 v[122:125], v[186:189], v[214:217], v[122:125]
	v_mfma_f32_16x16x32_bf16 v[118:121], v[164:167], v[222:225], v[118:121]
	v_mfma_f32_16x16x32_bf16 v[114:117], v[186:189], v[222:225], v[114:117]
	v_mfma_f32_16x16x32_bf16 v[102:105], v[164:167], v[230:233], v[102:105]
	v_mfma_f32_16x16x32_bf16 v[98:101], v[186:189], v[230:233], v[98:101]
	v_mfma_f32_16x16x32_bf16 v[86:89], v[164:167], v[238:241], v[86:89]
	v_mfma_f32_16x16x32_bf16 v[82:85], v[186:189], v[238:241], v[82:85]
	v_mfma_f32_16x16x32_bf16 v[110:113], v[190:193], v[210:213], v[110:113]
	v_mfma_f32_16x16x32_bf16 v[106:109], v[202:205], v[210:213], v[106:109]
	v_mfma_f32_16x16x32_bf16 v[94:97], v[190:193], v[218:221], v[94:97]
	v_mfma_f32_16x16x32_bf16 v[90:93], v[202:205], v[218:221], v[90:93]
	v_mfma_f32_16x16x32_bf16 v[78:81], v[190:193], v[226:229], v[78:81]
	v_mfma_f32_16x16x32_bf16 v[74:77], v[202:205], v[226:229], v[74:77]
	v_mfma_f32_16x16x32_bf16 v[70:73], v[190:193], v[234:237], v[70:73]
	v_mfma_f32_16x16x32_bf16 v[66:69], v[202:205], v[234:237], v[66:69]
	v_mfma_f32_16x16x32_bf16 v[110:113], v[198:201], v[214:217], v[110:113]
	v_mfma_f32_16x16x32_bf16 v[106:109], v[206:209], v[214:217], v[106:109]
	v_mfma_f32_16x16x32_bf16 v[94:97], v[198:201], v[222:225], v[94:97]
	v_mfma_f32_16x16x32_bf16 v[90:93], v[206:209], v[222:225], v[90:93]
	v_mfma_f32_16x16x32_bf16 v[78:81], v[198:201], v[230:233], v[78:81]
	v_mfma_f32_16x16x32_bf16 v[74:77], v[206:209], v[230:233], v[74:77]
	v_mfma_f32_16x16x32_bf16 v[70:73], v[198:201], v[238:241], v[70:73]
	v_mfma_f32_16x16x32_bf16 v[66:69], v[206:209], v[238:241], v[66:69]
	s_barrier
; #define PG8_STAGE(bufoff, gbase, voff) do { _Pragma("unroll") for (int _i = 0; _i < 2; ++_i) \
;         __builtin_amdgcn_global_load_lds((const unsigned*)((const char*)(gbase) + (voff)[_i]), (PG8_LAS unsigned*)(lds + (bufoff) + ldsw + _i * 8192), 16, 0, 0); } while (0)
; #define PG8_LDA(dst, b, h) do { _Pragma("unroll") for (int m = 0; m < 4; ++m) _Pragma("unroll") for (int k = 0; k < 2; ++k) dst[m][k] = *(const PG8_LAS bf16x8*)(lds + PG8_SA(b, h) + aoff + m * 2048 + k * 1024); } while (0)
; #define PG8_MMA(ai, bj, At, Bt) do { __builtin_amdgcn_s_setprio(1); _Pragma("unroll") for (int m = 0; m < 4; ++m) _Pragma("unroll") for (int n = 0; n < 2; ++n) _Pragma("unroll") for (int k = 0; k < 2; ++k) \
;         acc[ai][bj][m][n] = __builtin_amdgcn_mfma_f32_16x16x32_bf16(Bt[n][k], At[m][k], acc[ai][bj][m][n], 0, 0, 0); __builtin_amdgcn_s_setprio(0); } while (0)
; #define PG8_WAIT_V(n) asm volatile("s_waitcnt vmcnt(" #n ")" ::: "memory")
; #define PG8_WAIT_L(n) asm volatile("s_waitcnt lgkmcnt(" #n ")" ::: "memory")
; #define PG8_BAR __builtin_amdgcn_s_barrier()
; #define PG8_SCHED __builtin_amdgcn_sched_barrier(0)
; template <class Epi, class Sched, bool ALIGN_EPI = false, bool SP2 = false>
; __device__ __forceinline__ void gemm_phase(PG8_LAS unsigned char* lds, const Gemm g, const Sched& S, const Epi& E) {
;     ...
;             PG8_LDA(At, 1, 1); PG8_STAGE(PG8_SB(1, 0), b3, voffB); PG8_STAGE(PG8_SB(1, 1), b3 + hstepB, voffB); PG8_STAGE(PG8_SA(1, 0), a3, voffA);
;             PG8_WAIT_V(8); PG8_WAIT_L(0); PG8_BAR; PG8_MMA(1, 0, At, B0); PG8_MMA(1, 1, At, B1); PG8_BAR; PG8_SCHED;
	s_mov_b32 m0, vcc_hi
	v_lshl_add_u64 v[130:131], v[130:131], 0, s[2:3]
	ds_read_b128 v[210:213], v159 offset:49152
	ds_read_b128 v[214:217], v159 offset:50176
	ds_read_b128 v[218:221], v159 offset:51200
	ds_read_b128 v[222:225], v159 offset:52224
	ds_read_b128 v[226:229], v159 offset:53248
	ds_read_b128 v[230:233], v159 offset:54272
	ds_read_b128 v[234:237], v159 offset:55296
	ds_read_b128 v[238:241], v159 offset:56320
	global_load_lds_dwordx4 v[130:131], off
	v_lshl_add_u64 v[130:131], v[132:133], 0, s[2:3]
	s_mov_b32 m0, vcc_lo
	s_nop 0
	global_load_lds_dwordx4 v[130:131], off
	v_lshl_add_u64 v[130:131], s[52:53], 0, v[0:1]
	s_mov_b32 m0, s11
	s_nop 0
	global_load_lds_dwordx4 v[130:131], off
	v_lshl_add_u64 v[130:131], s[52:53], 0, v[150:151]
	s_mov_b32 m0, s10
	s_nop 0
	global_load_lds_dwordx4 v[130:131], off
	v_lshl_add_u64 v[130:131], v[172:173], 0, s[2:3]
	s_mov_b32 m0, s35
	s_nop 0
	global_load_lds_dwordx4 v[130:131], off
	v_lshl_add_u64 v[130:131], v[242:243], 0, s[2:3]
	s_mov_b32 m0, s88
	s_nop 0
	global_load_lds_dwordx4 v[130:131], off
	s_waitcnt vmcnt(8)
	s_waitcnt lgkmcnt(0)
	s_barrier
	v_mfma_f32_16x16x32_bf16 v[62:65], v[160:163], v[210:213], v[62:65]
	v_mfma_f32_16x16x32_bf16 v[58:61], v[168:171], v[210:213], v[58:61]
	v_mfma_f32_16x16x32_bf16 v[54:57], v[160:163], v[218:221], v[54:57]
	v_mfma_f32_16x16x32_bf16 v[50:53], v[168:171], v[218:221], v[50:53]
	v_mfma_f32_16x16x32_bf16 v[38:41], v[160:163], v[226:229], v[38:41]
	v_mfma_f32_16x16x32_bf16 v[34:37], v[168:171], v[226:229], v[34:37]
	v_mfma_f32_16x16x32_bf16 v[22:25], v[160:163], v[234:237], v[22:25]
	v_mfma_f32_16x16x32_bf16 v[18:21], v[168:171], v[234:237], v[18:21]
	v_mfma_f32_16x16x32_bf16 v[62:65], v[164:167], v[214:217], v[62:65]
	v_mfma_f32_16x16x32_bf16 v[58:61], v[186:189], v[214:217], v[58:61]
	v_mfma_f32_16x16x32_bf16 v[54:57], v[164:167], v[222:225], v[54:57]
	v_mfma_f32_16x16x32_bf16 v[50:53], v[186:189], v[222:225], v[50:53]
	v_mfma_f32_16x16x32_bf16 v[38:41], v[164:167], v[230:233], v[38:41]
	v_mfma_f32_16x16x32_bf16 v[34:37], v[186:189], v[230:233], v[34:37]
	v_mfma_f32_16x16x32_bf16 v[22:25], v[164:167], v[238:241], v[22:25]
	v_mfma_f32_16x16x32_bf16 v[18:21], v[186:189], v[238:241], v[18:21]
	v_mfma_f32_16x16x32_bf16 v[46:49], v[190:193], v[210:213], v[46:49]
	v_mfma_f32_16x16x32_bf16 v[42:45], v[202:205], v[210:213], v[42:45]
	v_mfma_f32_16x16x32_bf16 v[30:33], v[190:193], v[218:221], v[30:33]
	v_mfma_f32_16x16x32_bf16 v[26:29], v[202:205], v[218:221], v[26:29]
	v_mfma_f32_16x16x32_bf16 v[14:17], v[190:193], v[226:229], v[14:17]
	v_mfma_f32_16x16x32_bf16 v[10:13], v[202:205], v[226:229], v[10:13]
	v_mfma_f32_16x16x32_bf16 v[6:9], v[190:193], v[234:237], v[6:9]
	v_mfma_f32_16x16x32_bf16 v[2:5], v[202:205], v[234:237], v[2:5]
	v_mfma_f32_16x16x32_bf16 v[46:49], v[198:201], v[214:217], v[46:49]
	v_mfma_f32_16x16x32_bf16 v[42:45], v[206:209], v[214:217], v[42:45]
	v_mfma_f32_16x16x32_bf16 v[30:33], v[198:201], v[222:225], v[30:33]
	v_mfma_f32_16x16x32_bf16 v[26:29], v[206:209], v[222:225], v[26:29]
	v_mfma_f32_16x16x32_bf16 v[14:17], v[198:201], v[230:233], v[14:17]
	v_mfma_f32_16x16x32_bf16 v[10:13], v[206:209], v[230:233], v[10:13]
	v_mfma_f32_16x16x32_bf16 v[6:9], v[198:201], v[238:241], v[6:9]
	v_mfma_f32_16x16x32_bf16 v[2:5], v[206:209], v[238:241], v[2:5]
	s_barrier
	s_movk_i32 s36, 0x100
	s_andn2_b64 vcc, exec, s[0:1]
	s_mov_b64 s[52:53], -1
	s_mov_b64 s[0:1], 0
	s_cbranch_vccz .LBB0_424
	s_and_b64 vcc, exec, s[40:41]
	s_cbranch_vccz .LBB0_427
	s_barrier

; #define PG8_STAGE(bufoff, gbase, voff) do { _Pragma("unroll") for (int _i = 0; _i < 2; ++_i) \
;         __builtin_amdgcn_global_load_lds((const unsigned*)((const char*)(gbase) + (voff)[_i]), (PG8_LAS unsigned*)(lds + (bufoff) + ldsw + _i * 8192), 16, 0, 0); } while (0)
; #define PG8_LDA(dst, b, h) do { _Pragma("unroll") for (int m = 0; m < 4; ++m) _Pragma("unroll") for (int k = 0; k < 2; ++k) dst[m][k] = *(const PG8_LAS bf16x8*)(lds + PG8_SA(b, h) + aoff + m * 2048 + k * 1024); } while (0)
; #define PG8_LDB(dst, b, h) do { _Pragma("unroll") for (int n = 0; n < 2; ++n) _Pragma("unroll") for (int k = 0; k < 2; ++k) dst[n][k] = *(const PG8_LAS bf16x8*)(lds + PG8_SB(b, h) + boff + n * 2048 + k * 1024); } while (0)
; #define PG8_MMA(ai, bj, At, Bt) do { __builtin_amdgcn_s_setprio(1); _Pragma("unroll") for (int m = 0; m < 4; ++m) _Pragma("unroll") for (int n = 0; n < 2; ++n) _Pragma("unroll") for (int k = 0; k < 2; ++k) \
;         acc[ai][bj][m][n] = __builtin_amdgcn_mfma_f32_16x16x32_bf16(Bt[n][k], At[m][k], acc[ai][bj][m][n], 0, 0, 0); __builtin_amdgcn_s_setprio(0); } while (0)
; #define PG8_WAIT_V(n) asm volatile("s_waitcnt vmcnt(" #n ")" ::: "memory")
; #define PG8_WAIT_L(n) asm volatile("s_waitcnt lgkmcnt(" #n ")" ::: "memory")
; #define PG8_BAR __builtin_amdgcn_s_barrier()
; #define PG8_SCHED __builtin_amdgcn_sched_barrier(0)
; template <class Epi, class Sched, bool ALIGN_EPI = false, bool SP2 = false>
; __device__ __forceinline__ void gemm_phase(PG8_LAS unsigned char* lds, const Gemm g, const Sched& S, const Epi& E) {
;     ...
;             PG8_LDB(B0, 0, 0); PG8_LDB(B1, 0, 1); PG8_SCHED; PG8_LDA(At, 0, 0); PG8_STAGE(PG8_SA(1, 1), a1 + hstepA, voffA);
;             PG8_WAIT_V(8); PG8_WAIT_L(0); PG8_BAR; PG8_MMA(0, 0, At, B0); PG8_MMA(0, 1, At, B1); PG8_BAR; PG8_SCHED;
;             PG8_LDA(At, 0, 1); PG8_STAGE(PG8_SB(0, 0), b2, voffB); PG8_STAGE(PG8_SB(0, 1), b2 + hstepB, voffB); PG8_STAGE(PG8_SA(0, 0), a2, voffA);
;             PG8_WAIT_V(8); PG8_WAIT_L(0); PG8_BAR; PG8_MMA(1, 0, At, B0); PG8_MMA(1, 1, At, B1); PG8_BAR; PG8_SCHED;
.Lgk_603:
	ds_read_b128 v[166:169], v130
	ds_read_b128 v[170:173], v130 offset:1024
	ds_read_b128 v[186:189], v130 offset:2048
	ds_read_b128 v[190:193], v130 offset:3072
	v_add_u32_e32 v130, s13, v163
	ds_read_b128 v[198:201], v130
	ds_read_b128 v[202:205], v130 offset:1024
	ds_read_b128 v[206:209], v130 offset:2048
	ds_read_b128 v[210:213], v130 offset:3072
	v_lshl_add_u64 v[130:131], s[50:51], 0, v[156:157]
	s_add_i32 m0, s31, 0xc000
	ds_read_b128 v[214:217], v165
	ds_read_b128 v[218:221], v165 offset:1024
	ds_read_b128 v[222:225], v165 offset:2048
	ds_read_b128 v[226:229], v165 offset:3072
	ds_read_b128 v[230:233], v165 offset:4096
	ds_read_b128 v[234:237], v165 offset:5120
	ds_read_b128 v[238:241], v165 offset:6144
	ds_read_b128 v[242:245], v165 offset:7168
	global_load_lds_dwordx4 v[130:131], off
	v_lshl_add_u64 v[130:131], s[50:51], 0, v[158:159]
	s_add_i32 m0, s31, 0xe000
	s_nop 0
	global_load_lds_dwordx4 v[130:131], off
	s_waitcnt vmcnt(8)
	s_waitcnt lgkmcnt(0)
	s_barrier
	v_mfma_f32_16x16x32_bf16 v[126:129], v[166:169], v[214:217], v[126:129]
	v_mfma_f32_16x16x32_bf16 v[122:125], v[186:189], v[214:217], v[122:125]
	v_mfma_f32_16x16x32_bf16 v[110:113], v[166:169], v[222:225], v[110:113]
	v_mfma_f32_16x16x32_bf16 v[106:109], v[186:189], v[222:225], v[106:109]
	v_mfma_f32_16x16x32_bf16 v[94:97], v[166:169], v[230:233], v[94:97]
	v_mfma_f32_16x16x32_bf16 v[90:93], v[186:189], v[230:233], v[90:93]
	v_mfma_f32_16x16x32_bf16 v[78:81], v[166:169], v[238:241], v[78:81]
	v_mfma_f32_16x16x32_bf16 v[74:77], v[186:189], v[238:241], v[74:77]
	v_mfma_f32_16x16x32_bf16 v[126:129], v[170:173], v[218:221], v[126:129]
	v_mfma_f32_16x16x32_bf16 v[122:125], v[190:193], v[218:221], v[122:125]
	v_mfma_f32_16x16x32_bf16 v[110:113], v[170:173], v[226:229], v[110:113]
	v_mfma_f32_16x16x32_bf16 v[106:109], v[190:193], v[226:229], v[106:109]
	v_mfma_f32_16x16x32_bf16 v[94:97], v[170:173], v[234:237], v[94:97]
	v_mfma_f32_16x16x32_bf16 v[90:93], v[190:193], v[234:237], v[90:93]
	v_mfma_f32_16x16x32_bf16 v[78:81], v[170:173], v[242:245], v[78:81]
	v_mfma_f32_16x16x32_bf16 v[74:77], v[190:193], v[242:245], v[74:77]
	v_mfma_f32_16x16x32_bf16 v[118:121], v[198:201], v[214:217], v[118:121]
	v_mfma_f32_16x16x32_bf16 v[114:117], v[206:209], v[214:217], v[114:117]
	v_mfma_f32_16x16x32_bf16 v[102:105], v[198:201], v[222:225], v[102:105]
	v_mfma_f32_16x16x32_bf16 v[98:101], v[206:209], v[222:225], v[98:101]
	v_mfma_f32_16x16x32_bf16 v[86:89], v[198:201], v[230:233], v[86:89]
	v_mfma_f32_16x16x32_bf16 v[82:85], v[206:209], v[230:233], v[82:85]
	v_mfma_f32_16x16x32_bf16 v[70:73], v[198:201], v[238:241], v[70:73]
	v_mfma_f32_16x16x32_bf16 v[66:69], v[206:209], v[238:241], v[66:69]
	v_mfma_f32_16x16x32_bf16 v[118:121], v[202:205], v[218:221], v[118:121]
	v_mfma_f32_16x16x32_bf16 v[114:117], v[210:213], v[218:221], v[114:117]
	v_mfma_f32_16x16x32_bf16 v[102:105], v[202:205], v[226:229], v[102:105]
	v_mfma_f32_16x16x32_bf16 v[98:101], v[210:213], v[226:229], v[98:101]
	v_mfma_f32_16x16x32_bf16 v[86:89], v[202:205], v[234:237], v[86:89]
	v_mfma_f32_16x16x32_bf16 v[82:85], v[210:213], v[234:237], v[82:85]
	v_mfma_f32_16x16x32_bf16 v[70:73], v[202:205], v[242:245], v[70:73]
	v_mfma_f32_16x16x32_bf16 v[66:69], v[210:213], v[242:245], v[66:69]
	s_barrier
	s_add_i32 s10, s12, s30
	v_lshl_add_u64 v[130:131], s[52:53], 0, v[0:1]
	s_mov_b32 m0, s10
	ds_read_b128 v[214:217], v165 offset:16384
	ds_read_b128 v[218:221], v165 offset:17408
	ds_read_b128 v[222:225], v165 offset:18432
	ds_read_b128 v[226:229], v165 offset:19456
	ds_read_b128 v[230:233], v165 offset:20480
	ds_read_b128 v[234:237], v165 offset:21504
	ds_read_b128 v[238:241], v165 offset:22528
	ds_read_b128 v[242:245], v165 offset:23552
	global_load_lds_dwordx4 v[130:131], off
	s_add_i32 m0, s10, 0x2000
	s_add_u32 s10, s52, 0x40000
	v_lshl_add_u64 v[132:133], s[52:53], 0, v[150:151]
	s_addc_u32 s11, s53, 0
	s_add_i32 s12, s13, s30
	global_load_lds_dwordx4 v[132:133], off
	v_lshl_add_u64 v[160:161], s[10:11], 0, v[0:1]
	s_mov_b32 m0, s12
	v_lshl_add_u64 v[246:247], s[54:55], 0, v[152:153]
	global_load_lds_dwordx4 v[160:161], off
	v_lshl_add_u64 v[160:161], s[10:11], 0, v[150:151]
	s_add_i32 m0, s12, 0x2000
	s_nop 0
	global_load_lds_dwordx4 v[160:161], off
	v_lshl_add_u64 v[160:161], s[54:55], 0, v[154:155]
	s_mov_b32 m0, s31
	s_nop 0
	global_load_lds_dwordx4 v[160:161], off
	s_mov_b32 m0, s34
	s_nop 0
	global_load_lds_dwordx4 v[246:247], off
	s_waitcnt vmcnt(8)
	s_waitcnt lgkmcnt(0)
	s_barrier
	v_mfma_f32_16x16x32_bf16 v[62:65], v[166:169], v[214:217], v[62:65]
	v_mfma_f32_16x16x32_bf16 v[58:61], v[186:189], v[214:217], v[58:61]
	v_mfma_f32_16x16x32_bf16 v[46:49], v[166:169], v[222:225], v[46:49]
	v_mfma_f32_16x16x32_bf16 v[42:45], v[186:189], v[222:225], v[42:45]
	v_mfma_f32_16x16x32_bf16 v[30:33], v[166:169], v[230:233], v[30:33]
	v_mfma_f32_16x16x32_bf16 v[26:29], v[186:189], v[230:233], v[26:29]
	v_mfma_f32_16x16x32_bf16 v[14:17], v[166:169], v[238:241], v[14:17]
	v_mfma_f32_16x16x32_bf16 v[10:13], v[186:189], v[238:241], v[10:13]
	v_mfma_f32_16x16x32_bf16 v[62:65], v[170:173], v[218:221], v[62:65]
	v_mfma_f32_16x16x32_bf16 v[58:61], v[190:193], v[218:221], v[58:61]
	v_mfma_f32_16x16x32_bf16 v[46:49], v[170:173], v[226:229], v[46:49]
	v_mfma_f32_16x16x32_bf16 v[42:45], v[190:193], v[226:229], v[42:45]
	v_mfma_f32_16x16x32_bf16 v[30:33], v[170:173], v[234:237], v[30:33]
	v_mfma_f32_16x16x32_bf16 v[26:29], v[190:193], v[234:237], v[26:29]
	v_mfma_f32_16x16x32_bf16 v[14:17], v[170:173], v[242:245], v[14:17]
	v_mfma_f32_16x16x32_bf16 v[10:13], v[190:193], v[242:245], v[10:13]
	v_mfma_f32_16x16x32_bf16 v[54:57], v[198:201], v[214:217], v[54:57]
	v_mfma_f32_16x16x32_bf16 v[50:53], v[206:209], v[214:217], v[50:53]
	v_mfma_f32_16x16x32_bf16 v[38:41], v[198:201], v[222:225], v[38:41]
	v_mfma_f32_16x16x32_bf16 v[34:37], v[206:209], v[222:225], v[34:37]
	v_mfma_f32_16x16x32_bf16 v[22:25], v[198:201], v[230:233], v[22:25]
	v_mfma_f32_16x16x32_bf16 v[18:21], v[206:209], v[230:233], v[18:21]
	v_mfma_f32_16x16x32_bf16 v[6:9], v[198:201], v[238:241], v[6:9]
	v_mfma_f32_16x16x32_bf16 v[2:5], v[206:209], v[238:241], v[2:5]
	v_mfma_f32_16x16x32_bf16 v[54:57], v[202:205], v[218:221], v[54:57]
	v_mfma_f32_16x16x32_bf16 v[50:53], v[210:213], v[218:221], v[50:53]
	v_mfma_f32_16x16x32_bf16 v[38:41], v[202:205], v[226:229], v[38:41]
	v_mfma_f32_16x16x32_bf16 v[34:37], v[210:213], v[226:229], v[34:37]
	v_mfma_f32_16x16x32_bf16 v[22:25], v[202:205], v[234:237], v[22:25]
	v_mfma_f32_16x16x32_bf16 v[18:21], v[210:213], v[234:237], v[18:21]
	v_mfma_f32_16x16x32_bf16 v[6:9], v[202:205], v[242:245], v[6:9]
	v_mfma_f32_16x16x32_bf16 v[2:5], v[210:213], v[242:245], v[2:5]
	s_barrier
; #define PG8_STAGE(bufoff, gbase, voff) do { _Pragma("unroll") for (int _i = 0; _i < 2; ++_i) \
;         __builtin_amdgcn_global_load_lds((const unsigned*)((const char*)(gbase) + (voff)[_i]), (PG8_LAS unsigned*)(lds + (bufoff) + ldsw + _i * 8192), 16, 0, 0); } while (0)
; #define PG8_LDA(dst, b, h) do { _Pragma("unroll") for (int m = 0; m < 4; ++m) _Pragma("unroll") for (int k = 0; k < 2; ++k) dst[m][k] = *(const PG8_LAS bf16x8*)(lds + PG8_SA(b, h) + aoff + m * 2048 + k * 1024); } while (0)
; #define PG8_LDB(dst, b, h) do { _Pragma("unroll") for (int n = 0; n < 2; ++n) _Pragma("unroll") for (int k = 0; k < 2; ++k) dst[n][k] = *(const PG8_LAS bf16x8*)(lds + PG8_SB(b, h) + boff + n * 2048 + k * 1024); } while (0)
; #define PG8_MMA(ai, bj, At, Bt) do { __builtin_amdgcn_s_setprio(1); _Pragma("unroll") for (int m = 0; m < 4; ++m) _Pragma("unroll") for (int n = 0; n < 2; ++n) _Pragma("unroll") for (int k = 0; k < 2; ++k) \
;         acc[ai][bj][m][n] = __builtin_amdgcn_mfma_f32_16x16x32_bf16(Bt[n][k], At[m][k], acc[ai][bj][m][n], 0, 0, 0); __builtin_amdgcn_s_setprio(0); } while (0)
; #define PG8_WAIT_V(n) asm volatile("s_waitcnt vmcnt(" #n ")" ::: "memory")
; #define PG8_WAIT_L(n) asm volatile("s_waitcnt lgkmcnt(" #n ")" ::: "memory")
; #define PG8_BAR __builtin_amdgcn_s_barrier()
; #define PG8_SCHED __builtin_amdgcn_sched_barrier(0)
; template <class Epi, class Sched, bool ALIGN_EPI = false, bool SP2 = false>
; __device__ __forceinline__ void gemm_phase(PG8_LAS unsigned char* lds, const Gemm g, const Sched& S, const Epi& E) {
;     ...
;             PG8_LDB(B0, 1, 0); PG8_LDB(B1, 1, 1); PG8_SCHED; PG8_LDA(At, 1, 0); PG8_STAGE(PG8_SA(0, 1), a2 + hstepA, voffA);
;             PG8_WAIT_V(8); PG8_WAIT_L(0); PG8_BAR; PG8_MMA(0, 0, At, B0); PG8_MMA(0, 1, At, B1); PG8_BAR; PG8_SCHED;
	s_add_i32 s12, 0, 0x18000
	s_add_i32 s13, 0, 0x1c000
	v_add_u32_e32 v190, s12, v163
	v_add_u32_e32 v210, s13, v163
	ds_read_b128 v[166:169], v190
	ds_read_b128 v[170:173], v190 offset:1024
	ds_read_b128 v[186:189], v190 offset:2048
	ds_read_b128 v[190:193], v190 offset:3072
	ds_read_b128 v[198:201], v210
	ds_read_b128 v[202:205], v210 offset:1024
	ds_read_b128 v[206:209], v210 offset:2048
	ds_read_b128 v[210:213], v210 offset:3072
	s_add_u32 s10, s54, 0x40000
	s_addc_u32 s11, s55, 0
	s_mov_b32 m0, s35
	v_lshl_add_u64 v[248:249], s[10:11], 0, v[154:155]
	ds_read_b128 v[214:217], v165 offset:32768
	ds_read_b128 v[218:221], v165 offset:33792
	ds_read_b128 v[222:225], v165 offset:34816
	ds_read_b128 v[226:229], v165 offset:35840
	ds_read_b128 v[230:233], v165 offset:36864
	ds_read_b128 v[234:237], v165 offset:37888
	ds_read_b128 v[238:241], v165 offset:38912
	ds_read_b128 v[242:245], v165 offset:39936
	global_load_lds_dwordx4 v[248:249], off
	v_lshl_add_u64 v[248:249], s[10:11], 0, v[152:153]
	s_mov_b32 m0, s56
	s_nop 0
	global_load_lds_dwordx4 v[248:249], off
	s_waitcnt vmcnt(8)
	s_waitcnt lgkmcnt(0)
	s_barrier
	v_mfma_f32_16x16x32_bf16 v[126:129], v[166:169], v[214:217], v[126:129]
	v_mfma_f32_16x16x32_bf16 v[122:125], v[186:189], v[214:217], v[122:125]
	v_mfma_f32_16x16x32_bf16 v[110:113], v[166:169], v[222:225], v[110:113]
	v_mfma_f32_16x16x32_bf16 v[106:109], v[186:189], v[222:225], v[106:109]
	v_mfma_f32_16x16x32_bf16 v[94:97], v[166:169], v[230:233], v[94:97]
	v_mfma_f32_16x16x32_bf16 v[90:93], v[186:189], v[230:233], v[90:93]
	v_mfma_f32_16x16x32_bf16 v[78:81], v[166:169], v[238:241], v[78:81]
	v_mfma_f32_16x16x32_bf16 v[74:77], v[186:189], v[238:241], v[74:77]
	v_mfma_f32_16x16x32_bf16 v[126:129], v[170:173], v[218:221], v[126:129]
	v_mfma_f32_16x16x32_bf16 v[122:125], v[190:193], v[218:221], v[122:125]
	v_mfma_f32_16x16x32_bf16 v[110:113], v[170:173], v[226:229], v[110:113]
	v_mfma_f32_16x16x32_bf16 v[106:109], v[190:193], v[226:229], v[106:109]
	v_mfma_f32_16x16x32_bf16 v[94:97], v[170:173], v[234:237], v[94:97]
	v_mfma_f32_16x16x32_bf16 v[90:93], v[190:193], v[234:237], v[90:93]
	v_mfma_f32_16x16x32_bf16 v[78:81], v[170:173], v[242:245], v[78:81]
	v_mfma_f32_16x16x32_bf16 v[74:77], v[190:193], v[242:245], v[74:77]
	v_mfma_f32_16x16x32_bf16 v[118:121], v[198:201], v[214:217], v[118:121]
	v_mfma_f32_16x16x32_bf16 v[114:117], v[206:209], v[214:217], v[114:117]
	v_mfma_f32_16x16x32_bf16 v[102:105], v[198:201], v[222:225], v[102:105]
	v_mfma_f32_16x16x32_bf16 v[98:101], v[206:209], v[222:225], v[98:101]
	v_mfma_f32_16x16x32_bf16 v[86:89], v[198:201], v[230:233], v[86:89]
	v_mfma_f32_16x16x32_bf16 v[82:85], v[206:209], v[230:233], v[82:85]
	v_mfma_f32_16x16x32_bf16 v[70:73], v[198:201], v[238:241], v[70:73]
	v_mfma_f32_16x16x32_bf16 v[66:69], v[206:209], v[238:241], v[66:69]
	v_mfma_f32_16x16x32_bf16 v[118:121], v[202:205], v[218:221], v[118:121]
	v_mfma_f32_16x16x32_bf16 v[114:117], v[210:213], v[218:221], v[114:117]
	v_mfma_f32_16x16x32_bf16 v[102:105], v[202:205], v[226:229], v[102:105]
	v_mfma_f32_16x16x32_bf16 v[98:101], v[210:213], v[226:229], v[98:101]
	v_mfma_f32_16x16x32_bf16 v[86:89], v[202:205], v[234:237], v[86:89]
	v_mfma_f32_16x16x32_bf16 v[82:85], v[210:213], v[234:237], v[82:85]
	v_mfma_f32_16x16x32_bf16 v[70:73], v[202:205], v[242:245], v[70:73]
	v_mfma_f32_16x16x32_bf16 v[66:69], v[210:213], v[242:245], v[66:69]
	s_barrier
; #define PG8_STAGE(bufoff, gbase, voff) do { _Pragma("unroll") for (int _i = 0; _i < 2; ++_i) \
;         __builtin_amdgcn_global_load_lds((const unsigned*)((const char*)(gbase) + (voff)[_i]), (PG8_LAS unsigned*)(lds + (bufoff) + ldsw + _i * 8192), 16, 0, 0); } while (0)
; #define PG8_LDA(dst, b, h) do { _Pragma("unroll") for (int m = 0; m < 4; ++m) _Pragma("unroll") for (int k = 0; k < 2; ++k) dst[m][k] = *(const PG8_LAS bf16x8*)(lds + PG8_SA(b, h) + aoff + m * 2048 + k * 1024); } while (0)
; #define PG8_MMA(ai, bj, At, Bt) do { __builtin_amdgcn_s_setprio(1); _Pragma("unroll") for (int m = 0; m < 4; ++m) _Pragma("unroll") for (int n = 0; n < 2; ++n) _Pragma("unroll") for (int k = 0; k < 2; ++k) \
;         acc[ai][bj][m][n] = __builtin_amdgcn_mfma_f32_16x16x32_bf16(Bt[n][k], At[m][k], acc[ai][bj][m][n], 0, 0, 0); __builtin_amdgcn_s_setprio(0); } while (0)
; #define PG8_WAIT_V(n) asm volatile("s_waitcnt vmcnt(" #n ")" ::: "memory")
; #define PG8_WAIT_L(n) asm volatile("s_waitcnt lgkmcnt(" #n ")" ::: "memory")
; #define PG8_BAR __builtin_amdgcn_s_barrier()
; #define PG8_SCHED __builtin_amdgcn_sched_barrier(0)
; template <class Epi, class Sched, bool ALIGN_EPI = false, bool SP2 = false>
; __device__ __forceinline__ void gemm_phase(PG8_LAS unsigned char* lds, const Gemm g, const Sched& S, const Epi& E) {
;     ...
;         for (int t = 0; t < nt; t += 2) {
;             const bool last = (t == nt - 2);
;             const char* a1 = cA + (size_t)(t + 1) * kstep;
;             const char* a2 = last ? nA : cA + (size_t)(t + 2) * kstep; const char* b2 = last ? nB : cB + (size_t)(t + 2) * kstep;
;     ...
;             PG8_LDA(At, 1, 1); PG8_STAGE(PG8_SB(1, 0), b3, voffB); PG8_STAGE(PG8_SB(1, 1), b3 + hstepB, voffB); PG8_STAGE(PG8_SA(1, 0), a3, voffA);
;             PG8_WAIT_V(8); PG8_WAIT_L(0); PG8_BAR; PG8_MMA(1, 0, At, B0); PG8_MMA(1, 1, At, B1); PG8_BAR; PG8_SCHED;
	s_add_i32 s10, s12, s30
	v_lshl_add_u64 v[130:131], v[130:131], 0, s[2:3]
	s_mov_b32 m0, s10
	ds_read_b128 v[214:217], v165 offset:49152
	ds_read_b128 v[218:221], v165 offset:50176
	ds_read_b128 v[222:225], v165 offset:51200
	ds_read_b128 v[226:229], v165 offset:52224
	ds_read_b128 v[230:233], v165 offset:53248
	ds_read_b128 v[234:237], v165 offset:54272
	ds_read_b128 v[238:241], v165 offset:55296
	ds_read_b128 v[242:245], v165 offset:56320
	global_load_lds_dwordx4 v[130:131], off
	s_add_i32 m0, s10, 0x2000
	s_add_u32 s10, s52, 0x40080
	v_lshl_add_u64 v[130:131], v[132:133], 0, s[2:3]
	s_addc_u32 s11, s53, 0
	s_add_i32 s12, s13, s30
	global_load_lds_dwordx4 v[130:131], off
	v_lshl_add_u64 v[130:131], s[10:11], 0, v[0:1]
	s_mov_b32 m0, s12
	s_nop 0
	global_load_lds_dwordx4 v[130:131], off
	v_lshl_add_u64 v[130:131], s[10:11], 0, v[150:151]
	s_add_i32 m0, s12, 0x2000
	s_nop 0
	global_load_lds_dwordx4 v[130:131], off
	v_lshl_add_u64 v[130:131], v[160:161], 0, s[2:3]
	s_mov_b32 m0, s57
	s_nop 0
	global_load_lds_dwordx4 v[130:131], off
	v_lshl_add_u64 v[130:131], v[246:247], 0, s[2:3]
	s_mov_b32 m0, s62
	s_nop 0
	global_load_lds_dwordx4 v[130:131], off
	s_waitcnt vmcnt(8)
	s_waitcnt lgkmcnt(0)
	s_barrier
	v_mfma_f32_16x16x32_bf16 v[62:65], v[166:169], v[214:217], v[62:65]
	v_mfma_f32_16x16x32_bf16 v[58:61], v[186:189], v[214:217], v[58:61]
	s_add_i32 s95, s95, 2
	v_mfma_f32_16x16x32_bf16 v[46:49], v[166:169], v[222:225], v[46:49]
	s_add_u32 s50, s50, 0x100
	v_mfma_f32_16x16x32_bf16 v[42:45], v[186:189], v[222:225], v[42:45]
	s_addc_u32 s51, s51, 0
	v_mfma_f32_16x16x32_bf16 v[30:33], v[166:169], v[230:233], v[30:33]
	s_add_u32 s91, s91, 0x100
	v_mfma_f32_16x16x32_bf16 v[26:29], v[186:189], v[230:233], v[26:29]
	s_addc_u32 s94, s94, 0
	v_mfma_f32_16x16x32_bf16 v[14:17], v[166:169], v[238:241], v[14:17]
	s_add_u32 s10, s50, 0xfffc0080
	v_mfma_f32_16x16x32_bf16 v[10:13], v[186:189], v[238:241], v[10:13]
	s_addc_u32 s11, s51, -1
	v_mfma_f32_16x16x32_bf16 v[62:65], v[170:173], v[218:221], v[62:65]
	s_add_i32 s12, 0, 0x10000
	v_mfma_f32_16x16x32_bf16 v[58:61], v[190:193], v[218:221], v[58:61]
	s_cmp_eq_u32 s95, 12
	v_mfma_f32_16x16x32_bf16 v[46:49], v[170:173], v[226:229], v[46:49]
	s_cselect_b32 s55, s45, s11
	v_mfma_f32_16x16x32_bf16 v[42:45], v[190:193], v[226:229], v[42:45]
	s_cselect_b32 s54, s90, s10
	v_mfma_f32_16x16x32_bf16 v[30:33], v[170:173], v[234:237], v[30:33]
	v_add_u32_e32 v130, s12, v163
	v_mfma_f32_16x16x32_bf16 v[26:29], v[190:193], v[234:237], v[26:29]
	s_cselect_b32 s53, s4, s94
	v_mfma_f32_16x16x32_bf16 v[14:17], v[170:173], v[242:245], v[14:17]
	s_cselect_b32 s52, s43, s91
	v_mfma_f32_16x16x32_bf16 v[10:13], v[190:193], v[242:245], v[10:13]
	s_add_i32 s13, 0, 0x14000
	v_mfma_f32_16x16x32_bf16 v[54:57], v[198:201], v[214:217], v[54:57]
	s_cmp_gt_u32 s95, 13
	v_mfma_f32_16x16x32_bf16 v[50:53], v[206:209], v[214:217], v[50:53]
	v_mfma_f32_16x16x32_bf16 v[38:41], v[198:201], v[222:225], v[38:41]
	v_mfma_f32_16x16x32_bf16 v[34:37], v[206:209], v[222:225], v[34:37]
	v_mfma_f32_16x16x32_bf16 v[22:25], v[198:201], v[230:233], v[22:25]
	v_mfma_f32_16x16x32_bf16 v[18:21], v[206:209], v[230:233], v[18:21]
	v_mfma_f32_16x16x32_bf16 v[6:9], v[198:201], v[238:241], v[6:9]
	v_mfma_f32_16x16x32_bf16 v[2:5], v[206:209], v[238:241], v[2:5]
	v_mfma_f32_16x16x32_bf16 v[54:57], v[202:205], v[218:221], v[54:57]
	v_mfma_f32_16x16x32_bf16 v[50:53], v[210:213], v[218:221], v[50:53]
	v_mfma_f32_16x16x32_bf16 v[38:41], v[202:205], v[226:229], v[38:41]
	v_mfma_f32_16x16x32_bf16 v[34:37], v[210:213], v[226:229], v[34:37]
	v_mfma_f32_16x16x32_bf16 v[22:25], v[202:205], v[234:237], v[22:25]
	v_mfma_f32_16x16x32_bf16 v[18:21], v[210:213], v[234:237], v[18:21]
	v_mfma_f32_16x16x32_bf16 v[6:9], v[202:205], v[242:245], v[6:9]
	v_mfma_f32_16x16x32_bf16 v[2:5], v[210:213], v[242:245], v[2:5]
	s_barrier
	s_cbranch_scc0 .Lgk_603
	s_and_b64 vcc, exec, s[40:41]
	s_cbranch_vccz .LBB0_606
	s_barrier

; #define PG8_STAGE(bufoff, gbase, voff) do { _Pragma("unroll") for (int _i = 0; _i < 2; ++_i) \
;         __builtin_amdgcn_global_load_lds((const unsigned*)((const char*)(gbase) + (voff)[_i]), (PG8_LAS unsigned*)(lds + (bufoff) + ldsw + _i * 8192), 16, 0, 0); } while (0)
; #define PG8_LDA(dst, b, h) do { _Pragma("unroll") for (int m = 0; m < 4; ++m) _Pragma("unroll") for (int k = 0; k < 2; ++k) dst[m][k] = *(const PG8_LAS bf16x8*)(lds + PG8_SA(b, h) + aoff + m * 2048 + k * 1024); } while (0)
; #define PG8_LDB(dst, b, h) do { _Pragma("unroll") for (int n = 0; n < 2; ++n) _Pragma("unroll") for (int k = 0; k < 2; ++k) dst[n][k] = *(const PG8_LAS bf16x8*)(lds + PG8_SB(b, h) + boff + n * 2048 + k * 1024); } while (0)
; #define PG8_MMA(ai, bj, At, Bt) do { __builtin_amdgcn_s_setprio(1); _Pragma("unroll") for (int m = 0; m < 4; ++m) _Pragma("unroll") for (int n = 0; n < 2; ++n) _Pragma("unroll") for (int k = 0; k < 2; ++k) \
;         acc[ai][bj][m][n] = __builtin_amdgcn_mfma_f32_16x16x32_bf16(Bt[n][k], At[m][k], acc[ai][bj][m][n], 0, 0, 0); __builtin_amdgcn_s_setprio(0); } while (0)
; #define PG8_WAIT_V(n) asm volatile("s_waitcnt vmcnt(" #n ")" ::: "memory")
; #define PG8_WAIT_L(n) asm volatile("s_waitcnt lgkmcnt(" #n ")" ::: "memory")
; #define PG8_BAR __builtin_amdgcn_s_barrier()
; #define PG8_SCHED __builtin_amdgcn_sched_barrier(0)
; template <class Epi, class Sched, bool ALIGN_EPI = false, bool SP2 = false>
; __device__ __forceinline__ void gemm_phase(PG8_LAS unsigned char* lds, const Gemm g, const Sched& S, const Epi& E) {
;     ...
;             PG8_LDB(B0, 0, 0); PG8_LDB(B1, 0, 1); PG8_SCHED; PG8_LDA(At, 0, 0); PG8_STAGE(PG8_SA(1, 1), a1 + hstepA, voffA);
;             PG8_WAIT_V(8); PG8_WAIT_L(0); PG8_BAR; PG8_MMA(0, 0, At, B0); PG8_MMA(0, 1, At, B1); PG8_BAR; PG8_SCHED;
;             PG8_LDA(At, 0, 1); PG8_STAGE(PG8_SB(0, 0), b2, voffB); PG8_STAGE(PG8_SB(0, 1), b2 + hstepB, voffB); PG8_STAGE(PG8_SA(0, 0), a2, voffA);
;             PG8_WAIT_V(8); PG8_WAIT_L(0); PG8_BAR; PG8_MMA(1, 0, At, B0); PG8_MMA(1, 1, At, B1); PG8_BAR; PG8_SCHED;
.Lgk_623:
	ds_read_b128 v[160:163], v130
	ds_read_b128 v[164:167], v130 offset:1024
	ds_read_b128 v[186:189], v130 offset:2048
	ds_read_b128 v[190:193], v130 offset:3072
	v_add_u32_e32 v130, s13, v169
	ds_read_b128 v[198:201], v130
	ds_read_b128 v[202:205], v130 offset:1024
	ds_read_b128 v[206:209], v130 offset:2048
	ds_read_b128 v[210:213], v130 offset:3072
	v_lshl_add_u64 v[130:131], s[54:55], 0, v[156:157]
	s_add_i32 m0, s53, 0xc000
	ds_read_b128 v[214:217], v171
	ds_read_b128 v[218:221], v171 offset:1024
	ds_read_b128 v[222:225], v171 offset:2048
	ds_read_b128 v[226:229], v171 offset:3072
	ds_read_b128 v[230:233], v171 offset:4096
	ds_read_b128 v[234:237], v171 offset:5120
	ds_read_b128 v[238:241], v171 offset:6144
	ds_read_b128 v[242:245], v171 offset:7168
	global_load_lds_dwordx4 v[130:131], off
	v_lshl_add_u64 v[130:131], s[54:55], 0, v[158:159]
	s_add_i32 m0, s53, 0xe000
	s_nop 0
	global_load_lds_dwordx4 v[130:131], off
	s_waitcnt vmcnt(8)
	s_waitcnt lgkmcnt(0)
	s_barrier
	v_mfma_f32_16x16x32_bf16 v[126:129], v[160:163], v[214:217], v[126:129]
	v_mfma_f32_16x16x32_bf16 v[122:125], v[186:189], v[214:217], v[122:125]
	v_mfma_f32_16x16x32_bf16 v[110:113], v[160:163], v[222:225], v[110:113]
	v_mfma_f32_16x16x32_bf16 v[106:109], v[186:189], v[222:225], v[106:109]
	v_mfma_f32_16x16x32_bf16 v[94:97], v[160:163], v[230:233], v[94:97]
	v_mfma_f32_16x16x32_bf16 v[90:93], v[186:189], v[230:233], v[90:93]
	v_mfma_f32_16x16x32_bf16 v[78:81], v[160:163], v[238:241], v[78:81]
	v_mfma_f32_16x16x32_bf16 v[74:77], v[186:189], v[238:241], v[74:77]
	v_mfma_f32_16x16x32_bf16 v[126:129], v[164:167], v[218:221], v[126:129]
	v_mfma_f32_16x16x32_bf16 v[122:125], v[190:193], v[218:221], v[122:125]
	v_mfma_f32_16x16x32_bf16 v[110:113], v[164:167], v[226:229], v[110:113]
	v_mfma_f32_16x16x32_bf16 v[106:109], v[190:193], v[226:229], v[106:109]
	v_mfma_f32_16x16x32_bf16 v[94:97], v[164:167], v[234:237], v[94:97]
	v_mfma_f32_16x16x32_bf16 v[90:93], v[190:193], v[234:237], v[90:93]
	v_mfma_f32_16x16x32_bf16 v[78:81], v[164:167], v[242:245], v[78:81]
	v_mfma_f32_16x16x32_bf16 v[74:77], v[190:193], v[242:245], v[74:77]
	v_mfma_f32_16x16x32_bf16 v[118:121], v[198:201], v[214:217], v[118:121]
	v_mfma_f32_16x16x32_bf16 v[114:117], v[206:209], v[214:217], v[114:117]
	v_mfma_f32_16x16x32_bf16 v[102:105], v[198:201], v[222:225], v[102:105]
	v_mfma_f32_16x16x32_bf16 v[98:101], v[206:209], v[222:225], v[98:101]
	v_mfma_f32_16x16x32_bf16 v[86:89], v[198:201], v[230:233], v[86:89]
	v_mfma_f32_16x16x32_bf16 v[82:85], v[206:209], v[230:233], v[82:85]
	v_mfma_f32_16x16x32_bf16 v[70:73], v[198:201], v[238:241], v[70:73]
	v_mfma_f32_16x16x32_bf16 v[66:69], v[206:209], v[238:241], v[66:69]
	v_mfma_f32_16x16x32_bf16 v[118:121], v[202:205], v[218:221], v[118:121]
	v_mfma_f32_16x16x32_bf16 v[114:117], v[210:213], v[218:221], v[114:117]
	v_mfma_f32_16x16x32_bf16 v[102:105], v[202:205], v[226:229], v[102:105]
	v_mfma_f32_16x16x32_bf16 v[98:101], v[210:213], v[226:229], v[98:101]
	v_mfma_f32_16x16x32_bf16 v[86:89], v[202:205], v[234:237], v[86:89]
	v_mfma_f32_16x16x32_bf16 v[82:85], v[210:213], v[234:237], v[82:85]
	v_mfma_f32_16x16x32_bf16 v[70:73], v[202:205], v[242:245], v[70:73]
	v_mfma_f32_16x16x32_bf16 v[66:69], v[210:213], v[242:245], v[66:69]
	s_barrier
	s_add_i32 s10, s12, s68
	v_lshl_add_u64 v[130:131], s[56:57], 0, v[0:1]
	s_mov_b32 m0, s10
	ds_read_b128 v[214:217], v171 offset:16384
	ds_read_b128 v[218:221], v171 offset:17408
	ds_read_b128 v[222:225], v171 offset:18432
	ds_read_b128 v[226:229], v171 offset:19456
	ds_read_b128 v[230:233], v171 offset:20480
	ds_read_b128 v[234:237], v171 offset:21504
	ds_read_b128 v[238:241], v171 offset:22528
	ds_read_b128 v[242:245], v171 offset:23552
	global_load_lds_dwordx4 v[130:131], off
	s_add_i32 m0, s10, 0x2000
	s_add_u32 s10, s56, 0x20000
	v_lshl_add_u64 v[132:133], s[56:57], 0, v[150:151]
	s_addc_u32 s11, s57, 0
	s_add_i32 s12, s13, s68
	global_load_lds_dwordx4 v[132:133], off
	v_lshl_add_u64 v[172:173], s[10:11], 0, v[0:1]
	s_mov_b32 m0, s12
	v_lshl_add_u64 v[246:247], s[62:63], 0, v[152:153]
	global_load_lds_dwordx4 v[172:173], off
	v_lshl_add_u64 v[172:173], s[10:11], 0, v[150:151]
	s_add_i32 m0, s12, 0x2000
	s_nop 0
	global_load_lds_dwordx4 v[172:173], off
	v_lshl_add_u64 v[172:173], s[62:63], 0, v[154:155]
	s_mov_b32 m0, s53
	s_nop 0
	global_load_lds_dwordx4 v[172:173], off
	s_mov_b32 m0, s69
	s_nop 0
	global_load_lds_dwordx4 v[246:247], off
	s_waitcnt vmcnt(8)
	s_waitcnt lgkmcnt(0)
	s_barrier
	v_mfma_f32_16x16x32_bf16 v[62:65], v[160:163], v[214:217], v[62:65]
	v_mfma_f32_16x16x32_bf16 v[58:61], v[186:189], v[214:217], v[58:61]
	v_mfma_f32_16x16x32_bf16 v[46:49], v[160:163], v[222:225], v[46:49]
	v_mfma_f32_16x16x32_bf16 v[42:45], v[186:189], v[222:225], v[42:45]
	v_mfma_f32_16x16x32_bf16 v[30:33], v[160:163], v[230:233], v[30:33]
	v_mfma_f32_16x16x32_bf16 v[26:29], v[186:189], v[230:233], v[26:29]
	v_mfma_f32_16x16x32_bf16 v[14:17], v[160:163], v[238:241], v[14:17]
	v_mfma_f32_16x16x32_bf16 v[10:13], v[186:189], v[238:241], v[10:13]
	v_mfma_f32_16x16x32_bf16 v[62:65], v[164:167], v[218:221], v[62:65]
	v_mfma_f32_16x16x32_bf16 v[58:61], v[190:193], v[218:221], v[58:61]
	v_mfma_f32_16x16x32_bf16 v[46:49], v[164:167], v[226:229], v[46:49]
	v_mfma_f32_16x16x32_bf16 v[42:45], v[190:193], v[226:229], v[42:45]
	v_mfma_f32_16x16x32_bf16 v[30:33], v[164:167], v[234:237], v[30:33]
	v_mfma_f32_16x16x32_bf16 v[26:29], v[190:193], v[234:237], v[26:29]
	v_mfma_f32_16x16x32_bf16 v[14:17], v[164:167], v[242:245], v[14:17]
	v_mfma_f32_16x16x32_bf16 v[10:13], v[190:193], v[242:245], v[10:13]
	v_mfma_f32_16x16x32_bf16 v[54:57], v[198:201], v[214:217], v[54:57]
	v_mfma_f32_16x16x32_bf16 v[50:53], v[206:209], v[214:217], v[50:53]
	v_mfma_f32_16x16x32_bf16 v[38:41], v[198:201], v[222:225], v[38:41]
	v_mfma_f32_16x16x32_bf16 v[34:37], v[206:209], v[222:225], v[34:37]
	v_mfma_f32_16x16x32_bf16 v[22:25], v[198:201], v[230:233], v[22:25]
	v_mfma_f32_16x16x32_bf16 v[18:21], v[206:209], v[230:233], v[18:21]
	v_mfma_f32_16x16x32_bf16 v[6:9], v[198:201], v[238:241], v[6:9]
	v_mfma_f32_16x16x32_bf16 v[2:5], v[206:209], v[238:241], v[2:5]
	v_mfma_f32_16x16x32_bf16 v[54:57], v[202:205], v[218:221], v[54:57]
	v_mfma_f32_16x16x32_bf16 v[50:53], v[210:213], v[218:221], v[50:53]
	v_mfma_f32_16x16x32_bf16 v[38:41], v[202:205], v[226:229], v[38:41]
	v_mfma_f32_16x16x32_bf16 v[34:37], v[210:213], v[226:229], v[34:37]
	v_mfma_f32_16x16x32_bf16 v[22:25], v[202:205], v[234:237], v[22:25]
	v_mfma_f32_16x16x32_bf16 v[18:21], v[210:213], v[234:237], v[18:21]
	v_mfma_f32_16x16x32_bf16 v[6:9], v[202:205], v[242:245], v[6:9]
	v_mfma_f32_16x16x32_bf16 v[2:5], v[210:213], v[242:245], v[2:5]
	s_barrier
; #define PG8_STAGE(bufoff, gbase, voff) do { _Pragma("unroll") for (int _i = 0; _i < 2; ++_i) \
;         __builtin_amdgcn_global_load_lds((const unsigned*)((const char*)(gbase) + (voff)[_i]), (PG8_LAS unsigned*)(lds + (bufoff) + ldsw + _i * 8192), 16, 0, 0); } while (0)
; #define PG8_LDA(dst, b, h) do { _Pragma("unroll") for (int m = 0; m < 4; ++m) _Pragma("unroll") for (int k = 0; k < 2; ++k) dst[m][k] = *(const PG8_LAS bf16x8*)(lds + PG8_SA(b, h) + aoff + m * 2048 + k * 1024); } while (0)
; #define PG8_LDB(dst, b, h) do { _Pragma("unroll") for (int n = 0; n < 2; ++n) _Pragma("unroll") for (int k = 0; k < 2; ++k) dst[n][k] = *(const PG8_LAS bf16x8*)(lds + PG8_SB(b, h) + boff + n * 2048 + k * 1024); } while (0)
; #define PG8_MMA(ai, bj, At, Bt) do { __builtin_amdgcn_s_setprio(1); _Pragma("unroll") for (int m = 0; m < 4; ++m) _Pragma("unroll") for (int n = 0; n < 2; ++n) _Pragma("unroll") for (int k = 0; k < 2; ++k) \
;         acc[ai][bj][m][n] = __builtin_amdgcn_mfma_f32_16x16x32_bf16(Bt[n][k], At[m][k], acc[ai][bj][m][n], 0, 0, 0); __builtin_amdgcn_s_setprio(0); } while (0)
; #define PG8_WAIT_V(n) asm volatile("s_waitcnt vmcnt(" #n ")" ::: "memory")
; #define PG8_WAIT_L(n) asm volatile("s_waitcnt lgkmcnt(" #n ")" ::: "memory")
; #define PG8_BAR __builtin_amdgcn_s_barrier()
; #define PG8_SCHED __builtin_amdgcn_sched_barrier(0)
; template <class Epi, class Sched, bool ALIGN_EPI = false, bool SP2 = false>
; __device__ __forceinline__ void gemm_phase(PG8_LAS unsigned char* lds, const Gemm g, const Sched& S, const Epi& E) {
;     ...
;             PG8_LDB(B0, 1, 0); PG8_LDB(B1, 1, 1); PG8_SCHED; PG8_LDA(At, 1, 0); PG8_STAGE(PG8_SA(0, 1), a2 + hstepA, voffA);
;             PG8_WAIT_V(8); PG8_WAIT_L(0); PG8_BAR; PG8_MMA(0, 0, At, B0); PG8_MMA(0, 1, At, B1); PG8_BAR; PG8_SCHED;
	s_add_i32 s12, 0, 0x18000
	s_add_i32 s13, 0, 0x1c000
	v_add_u32_e32 v190, s12, v169
	v_add_u32_e32 v210, s13, v169
	ds_read_b128 v[160:163], v190
	ds_read_b128 v[164:167], v190 offset:1024
	ds_read_b128 v[186:189], v190 offset:2048
	ds_read_b128 v[190:193], v190 offset:3072
	ds_read_b128 v[198:201], v210
	ds_read_b128 v[202:205], v210 offset:1024
	ds_read_b128 v[206:209], v210 offset:2048
	ds_read_b128 v[210:213], v210 offset:3072
	s_add_u32 s10, s62, 0x20000
	s_addc_u32 s11, s63, 0
	s_mov_b32 m0, s94
	v_lshl_add_u64 v[248:249], s[10:11], 0, v[154:155]
	ds_read_b128 v[214:217], v171 offset:32768
	ds_read_b128 v[218:221], v171 offset:33792
	ds_read_b128 v[222:225], v171 offset:34816
	ds_read_b128 v[226:229], v171 offset:35840
	ds_read_b128 v[230:233], v171 offset:36864
	ds_read_b128 v[234:237], v171 offset:37888
	ds_read_b128 v[238:241], v171 offset:38912
	ds_read_b128 v[242:245], v171 offset:39936
	global_load_lds_dwordx4 v[248:249], off
	v_lshl_add_u64 v[248:249], s[10:11], 0, v[152:153]
	s_mov_b32 m0, s95
	s_nop 0
	global_load_lds_dwordx4 v[248:249], off
	s_waitcnt vmcnt(8)
	s_waitcnt lgkmcnt(0)
	s_barrier
	v_mfma_f32_16x16x32_bf16 v[126:129], v[160:163], v[214:217], v[126:129]
	v_mfma_f32_16x16x32_bf16 v[122:125], v[186:189], v[214:217], v[122:125]
	v_mfma_f32_16x16x32_bf16 v[110:113], v[160:163], v[222:225], v[110:113]
	v_mfma_f32_16x16x32_bf16 v[106:109], v[186:189], v[222:225], v[106:109]
	v_mfma_f32_16x16x32_bf16 v[94:97], v[160:163], v[230:233], v[94:97]
	v_mfma_f32_16x16x32_bf16 v[90:93], v[186:189], v[230:233], v[90:93]
	v_mfma_f32_16x16x32_bf16 v[78:81], v[160:163], v[238:241], v[78:81]
	v_mfma_f32_16x16x32_bf16 v[74:77], v[186:189], v[238:241], v[74:77]
	v_mfma_f32_16x16x32_bf16 v[126:129], v[164:167], v[218:221], v[126:129]
	v_mfma_f32_16x16x32_bf16 v[122:125], v[190:193], v[218:221], v[122:125]
	v_mfma_f32_16x16x32_bf16 v[110:113], v[164:167], v[226:229], v[110:113]
	v_mfma_f32_16x16x32_bf16 v[106:109], v[190:193], v[226:229], v[106:109]
	v_mfma_f32_16x16x32_bf16 v[94:97], v[164:167], v[234:237], v[94:97]
	v_mfma_f32_16x16x32_bf16 v[90:93], v[190:193], v[234:237], v[90:93]
	v_mfma_f32_16x16x32_bf16 v[78:81], v[164:167], v[242:245], v[78:81]
	v_mfma_f32_16x16x32_bf16 v[74:77], v[190:193], v[242:245], v[74:77]
	v_mfma_f32_16x16x32_bf16 v[118:121], v[198:201], v[214:217], v[118:121]
	v_mfma_f32_16x16x32_bf16 v[114:117], v[206:209], v[214:217], v[114:117]
	v_mfma_f32_16x16x32_bf16 v[102:105], v[198:201], v[222:225], v[102:105]
	v_mfma_f32_16x16x32_bf16 v[98:101], v[206:209], v[222:225], v[98:101]
	v_mfma_f32_16x16x32_bf16 v[86:89], v[198:201], v[230:233], v[86:89]
	v_mfma_f32_16x16x32_bf16 v[82:85], v[206:209], v[230:233], v[82:85]
	v_mfma_f32_16x16x32_bf16 v[70:73], v[198:201], v[238:241], v[70:73]
	v_mfma_f32_16x16x32_bf16 v[66:69], v[206:209], v[238:241], v[66:69]
	v_mfma_f32_16x16x32_bf16 v[118:121], v[202:205], v[218:221], v[118:121]
	v_mfma_f32_16x16x32_bf16 v[114:117], v[210:213], v[218:221], v[114:117]
	v_mfma_f32_16x16x32_bf16 v[102:105], v[202:205], v[226:229], v[102:105]
	v_mfma_f32_16x16x32_bf16 v[98:101], v[210:213], v[226:229], v[98:101]
	v_mfma_f32_16x16x32_bf16 v[86:89], v[202:205], v[234:237], v[86:89]
	v_mfma_f32_16x16x32_bf16 v[82:85], v[210:213], v[234:237], v[82:85]
	v_mfma_f32_16x16x32_bf16 v[70:73], v[202:205], v[242:245], v[70:73]
	v_mfma_f32_16x16x32_bf16 v[66:69], v[210:213], v[242:245], v[66:69]
	s_barrier
; #define PG8_STAGE(bufoff, gbase, voff) do { _Pragma("unroll") for (int _i = 0; _i < 2; ++_i) \
;         __builtin_amdgcn_global_load_lds((const unsigned*)((const char*)(gbase) + (voff)[_i]), (PG8_LAS unsigned*)(lds + (bufoff) + ldsw + _i * 8192), 16, 0, 0); } while (0)
; #define PG8_LDA(dst, b, h) do { _Pragma("unroll") for (int m = 0; m < 4; ++m) _Pragma("unroll") for (int k = 0; k < 2; ++k) dst[m][k] = *(const PG8_LAS bf16x8*)(lds + PG8_SA(b, h) + aoff + m * 2048 + k * 1024); } while (0)
; #define PG8_MMA(ai, bj, At, Bt) do { __builtin_amdgcn_s_setprio(1); _Pragma("unroll") for (int m = 0; m < 4; ++m) _Pragma("unroll") for (int n = 0; n < 2; ++n) _Pragma("unroll") for (int k = 0; k < 2; ++k) \
;         acc[ai][bj][m][n] = __builtin_amdgcn_mfma_f32_16x16x32_bf16(Bt[n][k], At[m][k], acc[ai][bj][m][n], 0, 0, 0); __builtin_amdgcn_s_setprio(0); } while (0)
; #define PG8_WAIT_V(n) asm volatile("s_waitcnt vmcnt(" #n ")" ::: "memory")
; #define PG8_WAIT_L(n) asm volatile("s_waitcnt lgkmcnt(" #n ")" ::: "memory")
; #define PG8_BAR __builtin_amdgcn_s_barrier()
; #define PG8_SCHED __builtin_amdgcn_sched_barrier(0)
; template <class Epi, class Sched, bool ALIGN_EPI = false, bool SP2 = false>
; __device__ __forceinline__ void gemm_phase(PG8_LAS unsigned char* lds, const Gemm g, const Sched& S, const Epi& E) {
;     ...
;         for (int t = 0; t < nt; t += 2) {
;             const bool last = (t == nt - 2);
;             const char* a1 = cA + (size_t)(t + 1) * kstep;
;             const char* a2 = last ? nA : cA + (size_t)(t + 2) * kstep; const char* b2 = last ? nB : cB + (size_t)(t + 2) * kstep;
;     ...
;             PG8_LDA(At, 1, 1); PG8_STAGE(PG8_SB(1, 0), b3, voffB); PG8_STAGE(PG8_SB(1, 1), b3 + hstepB, voffB); PG8_STAGE(PG8_SA(1, 0), a3, voffA);
;             PG8_WAIT_V(8); PG8_WAIT_L(0); PG8_BAR; PG8_MMA(1, 0, At, B0); PG8_MMA(1, 1, At, B1); PG8_BAR; PG8_SCHED;
	s_add_i32 s10, s12, s68
	v_lshl_add_u64 v[130:131], v[130:131], 0, s[2:3]
	s_mov_b32 m0, s10
	ds_read_b128 v[214:217], v171 offset:49152
	ds_read_b128 v[218:221], v171 offset:50176
	ds_read_b128 v[222:225], v171 offset:51200
	ds_read_b128 v[226:229], v171 offset:52224
	ds_read_b128 v[230:233], v171 offset:53248
	ds_read_b128 v[234:237], v171 offset:54272
	ds_read_b128 v[238:241], v171 offset:55296
	ds_read_b128 v[242:245], v171 offset:56320
	global_load_lds_dwordx4 v[130:131], off
	s_add_i32 m0, s10, 0x2000
	s_add_u32 s10, s56, 0x20080
	v_lshl_add_u64 v[130:131], v[132:133], 0, s[2:3]
	s_addc_u32 s11, s57, 0
	s_add_i32 s12, s13, s68
	global_load_lds_dwordx4 v[130:131], off
	v_lshl_add_u64 v[130:131], s[10:11], 0, v[0:1]
	s_mov_b32 m0, s12
	s_nop 0
	global_load_lds_dwordx4 v[130:131], off
	v_lshl_add_u64 v[130:131], s[10:11], 0, v[150:151]
	s_add_i32 m0, s12, 0x2000
	s_nop 0
	global_load_lds_dwordx4 v[130:131], off
	v_lshl_add_u64 v[130:131], v[172:173], 0, s[2:3]
	s_mov_b32 m0, s8
	s_nop 0
	global_load_lds_dwordx4 v[130:131], off
	v_lshl_add_u64 v[130:131], v[246:247], 0, s[2:3]
	s_mov_b32 m0, s9
	s_nop 0
	global_load_lds_dwordx4 v[130:131], off
	s_waitcnt vmcnt(8)
	s_waitcnt lgkmcnt(0)
	s_barrier
	v_mfma_f32_16x16x32_bf16 v[62:65], v[160:163], v[214:217], v[62:65]
	v_mfma_f32_16x16x32_bf16 v[58:61], v[186:189], v[214:217], v[58:61]
	s_add_i32 vcc_hi, vcc_hi, 2
	v_mfma_f32_16x16x32_bf16 v[46:49], v[160:163], v[222:225], v[46:49]
	s_add_u32 s54, s54, 0x100
	v_mfma_f32_16x16x32_bf16 v[42:45], v[186:189], v[222:225], v[42:45]
	s_addc_u32 s55, s55, 0
	v_mfma_f32_16x16x32_bf16 v[30:33], v[160:163], v[230:233], v[30:33]
	s_add_u32 s91, s91, 0x100
	v_mfma_f32_16x16x32_bf16 v[26:29], v[186:189], v[230:233], v[26:29]
	s_addc_u32 vcc_lo, vcc_lo, 0
	v_mfma_f32_16x16x32_bf16 v[14:17], v[160:163], v[238:241], v[14:17]
	s_add_u32 s10, s54, 0xfffe0080
	v_mfma_f32_16x16x32_bf16 v[10:13], v[186:189], v[238:241], v[10:13]
	s_addc_u32 s11, s55, -1
	v_mfma_f32_16x16x32_bf16 v[62:65], v[164:167], v[218:221], v[62:65]
	s_add_i32 s12, 0, 0x10000
	v_mfma_f32_16x16x32_bf16 v[58:61], v[190:193], v[218:221], v[58:61]
	s_cmp_eq_u32 vcc_hi, 4
	v_mfma_f32_16x16x32_bf16 v[46:49], v[164:167], v[226:229], v[46:49]
	s_cselect_b32 s63, s41, s11
	v_mfma_f32_16x16x32_bf16 v[42:45], v[190:193], v[226:229], v[42:45]
	s_cselect_b32 s62, s47, s10
	v_mfma_f32_16x16x32_bf16 v[30:33], v[164:167], v[234:237], v[30:33]
	v_add_u32_e32 v130, s12, v169
	v_mfma_f32_16x16x32_bf16 v[26:29], v[190:193], v[234:237], v[26:29]
	s_cselect_b32 s57, s4, vcc_lo
	v_mfma_f32_16x16x32_bf16 v[14:17], v[164:167], v[242:245], v[14:17]
	s_cselect_b32 s56, s45, s91
	v_mfma_f32_16x16x32_bf16 v[10:13], v[190:193], v[242:245], v[10:13]
	s_add_i32 s13, 0, 0x14000
	v_mfma_f32_16x16x32_bf16 v[54:57], v[198:201], v[214:217], v[54:57]
	s_cmp_gt_u32 vcc_hi, 5
	v_mfma_f32_16x16x32_bf16 v[50:53], v[206:209], v[214:217], v[50:53]
	v_mfma_f32_16x16x32_bf16 v[38:41], v[198:201], v[222:225], v[38:41]
	v_mfma_f32_16x16x32_bf16 v[34:37], v[206:209], v[222:225], v[34:37]
	v_mfma_f32_16x16x32_bf16 v[22:25], v[198:201], v[230:233], v[22:25]
	v_mfma_f32_16x16x32_bf16 v[18:21], v[206:209], v[230:233], v[18:21]
	v_mfma_f32_16x16x32_bf16 v[6:9], v[198:201], v[238:241], v[6:9]
	v_mfma_f32_16x16x32_bf16 v[2:5], v[206:209], v[238:241], v[2:5]
	v_mfma_f32_16x16x32_bf16 v[54:57], v[202:205], v[218:221], v[54:57]
	v_mfma_f32_16x16x32_bf16 v[50:53], v[210:213], v[218:221], v[50:53]
	v_mfma_f32_16x16x32_bf16 v[38:41], v[202:205], v[226:229], v[38:41]
	v_mfma_f32_16x16x32_bf16 v[34:37], v[210:213], v[226:229], v[34:37]
	v_mfma_f32_16x16x32_bf16 v[22:25], v[202:205], v[234:237], v[22:25]
	v_mfma_f32_16x16x32_bf16 v[18:21], v[210:213], v[234:237], v[18:21]
	v_mfma_f32_16x16x32_bf16 v[6:9], v[202:205], v[242:245], v[6:9]
	v_mfma_f32_16x16x32_bf16 v[2:5], v[210:213], v[242:245], v[2:5]
	s_barrier
	s_cbranch_scc0 .Lgk_623
	s_and_b64 vcc, exec, s[42:43]
	s_cbranch_vccz .LBB0_626
	s_barrier

; #define PG8_STAGE(bufoff, gbase, voff) do { _Pragma("unroll") for (int _i = 0; _i < 2; ++_i) \
;         __builtin_amdgcn_global_load_lds((const unsigned*)((const char*)(gbase) + (voff)[_i]), (PG8_LAS unsigned*)(lds + (bufoff) + ldsw + _i * 8192), 16, 0, 0); } while (0)
; #define PG8_LDA(dst, b, h) do { _Pragma("unroll") for (int m = 0; m < 4; ++m) _Pragma("unroll") for (int k = 0; k < 2; ++k) dst[m][k] = *(const PG8_LAS bf16x8*)(lds + PG8_SA(b, h) + aoff + m * 2048 + k * 1024); } while (0)
; #define PG8_LDB(dst, b, h) do { _Pragma("unroll") for (int n = 0; n < 2; ++n) _Pragma("unroll") for (int k = 0; k < 2; ++k) dst[n][k] = *(const PG8_LAS bf16x8*)(lds + PG8_SB(b, h) + boff + n * 2048 + k * 1024); } while (0)
; #define PG8_MMA(ai, bj, At, Bt) do { __builtin_amdgcn_s_setprio(1); _Pragma("unroll") for (int m = 0; m < 4; ++m) _Pragma("unroll") for (int n = 0; n < 2; ++n) _Pragma("unroll") for (int k = 0; k < 2; ++k) \
;         acc[ai][bj][m][n] = __builtin_amdgcn_mfma_f32_16x16x32_bf16(Bt[n][k], At[m][k], acc[ai][bj][m][n], 0, 0, 0); __builtin_amdgcn_s_setprio(0); } while (0)
; #define PG8_WAIT_V(n) asm volatile("s_waitcnt vmcnt(" #n ")" ::: "memory")
; #define PG8_WAIT_L(n) asm volatile("s_waitcnt lgkmcnt(" #n ")" ::: "memory")
; #define PG8_BAR __builtin_amdgcn_s_barrier()
; #define PG8_SCHED __builtin_amdgcn_sched_barrier(0)
; template <class Epi, class Sched, bool ALIGN_EPI = false, bool SP2 = false>
; __device__ __forceinline__ void gemm_phase(PG8_LAS unsigned char* lds, const Gemm g, const Sched& S, const Epi& E) {
;     ...
;             const bool last = (t == nt - 2);
;             const char* a1 = cA + (size_t)(t + 1) * kstep;
;             const char* a2 = last ? nA : cA + (size_t)(t + 2) * kstep; const char* b2 = last ? nB : cB + (size_t)(t + 2) * kstep;
;             const char* a3 = a2 + kstep; const char* b3 = b2 + kstep;
;     ...
;             PG8_LDB(B0, 0, 0); PG8_LDB(B1, 0, 1); PG8_SCHED; PG8_LDA(At, 0, 0); PG8_STAGE(PG8_SA(1, 1), a1 + hstepA, voffA);
;             PG8_WAIT_V(8); PG8_WAIT_L(0); PG8_BAR; PG8_MMA(0, 0, At, B0); PG8_MMA(0, 1, At, B1); PG8_BAR; PG8_SCHED;
;             PG8_LDA(At, 0, 1); PG8_STAGE(PG8_SB(0, 0), b2, voffB); PG8_STAGE(PG8_SB(0, 1), b2 + hstepB, voffB); PG8_STAGE(PG8_SA(0, 0), a2, voffA);
;             PG8_WAIT_V(8); PG8_WAIT_L(0); PG8_BAR; PG8_MMA(1, 0, At, B0); PG8_MMA(1, 1, At, B1); PG8_BAR; PG8_SCHED;
.LBB0_726:
	s_add_u32 s10, s48, 0xfffc0080
	s_addc_u32 s11, s49, -1
	s_add_i32 s12, 0, 0x10000
	s_cmp_eq_u32 s69, 12
	s_cselect_b32 s53, s43, s11
	s_cselect_b32 s52, s62, s10
	v_add_u32_e32 v130, s12, v167
	s_cselect_b32 s51, s4, s68
	s_cselect_b32 s50, s41, s63
	s_add_i32 s13, 0, 0x14000
	ds_read_b128 v[160:163], v130
	ds_read_b128 v[170:173], v130 offset:1024
	ds_read_b128 v[186:189], v130 offset:2048
	ds_read_b128 v[190:193], v130 offset:3072
	v_add_u32_e32 v130, s13, v167
	ds_read_b128 v[198:201], v130
	ds_read_b128 v[202:205], v130 offset:1024
	ds_read_b128 v[206:209], v130 offset:2048
	ds_read_b128 v[210:213], v130 offset:3072
	v_lshl_add_u64 v[130:131], s[48:49], 0, v[156:157]
	s_add_i32 m0, s9, 0xc000
	ds_read_b128 v[214:217], v169
	ds_read_b128 v[218:221], v169 offset:1024
	ds_read_b128 v[222:225], v169 offset:2048
	ds_read_b128 v[226:229], v169 offset:3072
	ds_read_b128 v[230:233], v169 offset:4096
	ds_read_b128 v[234:237], v169 offset:5120
	ds_read_b128 v[238:241], v169 offset:6144
	ds_read_b128 v[242:245], v169 offset:7168
	global_load_lds_dwordx4 v[130:131], off
	v_lshl_add_u64 v[130:131], s[48:49], 0, v[158:159]
	s_add_i32 m0, s9, 0xe000
	s_nop 0
	global_load_lds_dwordx4 v[130:131], off
	s_waitcnt vmcnt(8)
	s_waitcnt lgkmcnt(0)
	s_barrier
	v_mfma_f32_16x16x32_bf16 v[126:129], v[160:163], v[214:217], v[126:129]
	v_mfma_f32_16x16x32_bf16 v[122:125], v[186:189], v[214:217], v[122:125]
	v_mfma_f32_16x16x32_bf16 v[110:113], v[160:163], v[222:225], v[110:113]
	v_mfma_f32_16x16x32_bf16 v[106:109], v[186:189], v[222:225], v[106:109]
	v_mfma_f32_16x16x32_bf16 v[94:97], v[160:163], v[230:233], v[94:97]
	v_mfma_f32_16x16x32_bf16 v[90:93], v[186:189], v[230:233], v[90:93]
	v_mfma_f32_16x16x32_bf16 v[78:81], v[160:163], v[238:241], v[78:81]
	v_mfma_f32_16x16x32_bf16 v[74:77], v[186:189], v[238:241], v[74:77]
	v_mfma_f32_16x16x32_bf16 v[126:129], v[170:173], v[218:221], v[126:129]
	v_mfma_f32_16x16x32_bf16 v[122:125], v[190:193], v[218:221], v[122:125]
	v_mfma_f32_16x16x32_bf16 v[110:113], v[170:173], v[226:229], v[110:113]
	v_mfma_f32_16x16x32_bf16 v[106:109], v[190:193], v[226:229], v[106:109]
	v_mfma_f32_16x16x32_bf16 v[94:97], v[170:173], v[234:237], v[94:97]
	v_mfma_f32_16x16x32_bf16 v[90:93], v[190:193], v[234:237], v[90:93]
	v_mfma_f32_16x16x32_bf16 v[78:81], v[170:173], v[242:245], v[78:81]
	v_mfma_f32_16x16x32_bf16 v[74:77], v[190:193], v[242:245], v[74:77]
	v_mfma_f32_16x16x32_bf16 v[118:121], v[198:201], v[214:217], v[118:121]
	v_mfma_f32_16x16x32_bf16 v[114:117], v[206:209], v[214:217], v[114:117]
	v_mfma_f32_16x16x32_bf16 v[102:105], v[198:201], v[222:225], v[102:105]
	v_mfma_f32_16x16x32_bf16 v[98:101], v[206:209], v[222:225], v[98:101]
	v_mfma_f32_16x16x32_bf16 v[86:89], v[198:201], v[230:233], v[86:89]
	v_mfma_f32_16x16x32_bf16 v[82:85], v[206:209], v[230:233], v[82:85]
	v_mfma_f32_16x16x32_bf16 v[70:73], v[198:201], v[238:241], v[70:73]
	v_mfma_f32_16x16x32_bf16 v[66:69], v[206:209], v[238:241], v[66:69]
	v_mfma_f32_16x16x32_bf16 v[118:121], v[202:205], v[218:221], v[118:121]
	v_mfma_f32_16x16x32_bf16 v[114:117], v[210:213], v[218:221], v[114:117]
	v_mfma_f32_16x16x32_bf16 v[102:105], v[202:205], v[226:229], v[102:105]
	v_mfma_f32_16x16x32_bf16 v[98:101], v[210:213], v[226:229], v[98:101]
	v_mfma_f32_16x16x32_bf16 v[86:89], v[202:205], v[234:237], v[86:89]
	v_mfma_f32_16x16x32_bf16 v[82:85], v[210:213], v[234:237], v[82:85]
	v_mfma_f32_16x16x32_bf16 v[70:73], v[202:205], v[242:245], v[70:73]
	v_mfma_f32_16x16x32_bf16 v[66:69], v[210:213], v[242:245], v[66:69]
	s_barrier
	s_add_i32 s10, s12, s8
	v_lshl_add_u64 v[130:131], s[50:51], 0, v[0:1]
	s_mov_b32 m0, s10
	ds_read_b128 v[214:217], v169 offset:16384
	ds_read_b128 v[218:221], v169 offset:17408
	ds_read_b128 v[222:225], v169 offset:18432
	ds_read_b128 v[226:229], v169 offset:19456
	ds_read_b128 v[230:233], v169 offset:20480
	ds_read_b128 v[234:237], v169 offset:21504
	ds_read_b128 v[238:241], v169 offset:22528
	ds_read_b128 v[242:245], v169 offset:23552
	global_load_lds_dwordx4 v[130:131], off
	s_add_i32 m0, s10, 0x2000
	s_add_u32 s10, s50, 0x40000
	v_lshl_add_u64 v[132:133], s[50:51], 0, v[150:151]
	s_addc_u32 s11, s51, 0
	s_add_i32 s12, s13, s8
	global_load_lds_dwordx4 v[132:133], off
	v_lshl_add_u64 v[164:165], s[10:11], 0, v[0:1]
	s_mov_b32 m0, s12
	v_lshl_add_u64 v[246:247], s[52:53], 0, v[152:153]
	global_load_lds_dwordx4 v[164:165], off
	v_lshl_add_u64 v[164:165], s[10:11], 0, v[150:151]
	s_add_i32 m0, s12, 0x2000
	s_nop 0
	global_load_lds_dwordx4 v[164:165], off
	v_lshl_add_u64 v[164:165], s[52:53], 0, v[154:155]
	s_mov_b32 m0, s9
	s_nop 0
	global_load_lds_dwordx4 v[164:165], off
	s_mov_b32 m0, s30
	s_nop 0
	global_load_lds_dwordx4 v[246:247], off
	s_waitcnt vmcnt(8)
	s_waitcnt lgkmcnt(0)
	s_barrier
; #define PG8_STAGE(bufoff, gbase, voff) do { _Pragma("unroll") for (int _i = 0; _i < 2; ++_i) \
;         __builtin_amdgcn_global_load_lds((const unsigned*)((const char*)(gbase) + (voff)[_i]), (PG8_LAS unsigned*)(lds + (bufoff) + ldsw + _i * 8192), 16, 0, 0); } while (0)
; #define PG8_LDA(dst, b, h) do { _Pragma("unroll") for (int m = 0; m < 4; ++m) _Pragma("unroll") for (int k = 0; k < 2; ++k) dst[m][k] = *(const PG8_LAS bf16x8*)(lds + PG8_SA(b, h) + aoff + m * 2048 + k * 1024); } while (0)
; #define PG8_LDB(dst, b, h) do { _Pragma("unroll") for (int n = 0; n < 2; ++n) _Pragma("unroll") for (int k = 0; k < 2; ++k) dst[n][k] = *(const PG8_LAS bf16x8*)(lds + PG8_SB(b, h) + boff + n * 2048 + k * 1024); } while (0)
; #define PG8_MMA(ai, bj, At, Bt) do { __builtin_amdgcn_s_setprio(1); _Pragma("unroll") for (int m = 0; m < 4; ++m) _Pragma("unroll") for (int n = 0; n < 2; ++n) _Pragma("unroll") for (int k = 0; k < 2; ++k) \
;         acc[ai][bj][m][n] = __builtin_amdgcn_mfma_f32_16x16x32_bf16(Bt[n][k], At[m][k], acc[ai][bj][m][n], 0, 0, 0); __builtin_amdgcn_s_setprio(0); } while (0)
; #define PG8_WAIT_V(n) asm volatile("s_waitcnt vmcnt(" #n ")" ::: "memory")
; #define PG8_WAIT_L(n) asm volatile("s_waitcnt lgkmcnt(" #n ")" ::: "memory")
; #define PG8_BAR __builtin_amdgcn_s_barrier()
; #define PG8_SCHED __builtin_amdgcn_sched_barrier(0)
; template <class Epi, class Sched, bool ALIGN_EPI = false, bool SP2 = false>
; __device__ __forceinline__ void gemm_phase(PG8_LAS unsigned char* lds, const Gemm g, const Sched& S, const Epi& E) {
;     ...
;             PG8_WAIT_V(8); PG8_WAIT_L(0); PG8_BAR; PG8_MMA(1, 0, At, B0); PG8_MMA(1, 1, At, B1); PG8_BAR; PG8_SCHED;
;             PG8_LDB(B0, 1, 0); PG8_LDB(B1, 1, 1); PG8_SCHED; PG8_LDA(At, 1, 0); PG8_STAGE(PG8_SA(0, 1), a2 + hstepA, voffA);
;             PG8_WAIT_V(8); PG8_WAIT_L(0); PG8_BAR; PG8_MMA(0, 0, At, B0); PG8_MMA(0, 1, At, B1); PG8_BAR; PG8_SCHED;
	v_mfma_f32_16x16x32_bf16 v[62:65], v[160:163], v[214:217], v[62:65]
	v_mfma_f32_16x16x32_bf16 v[58:61], v[186:189], v[214:217], v[58:61]
	v_mfma_f32_16x16x32_bf16 v[46:49], v[160:163], v[222:225], v[46:49]
	v_mfma_f32_16x16x32_bf16 v[42:45], v[186:189], v[222:225], v[42:45]
	v_mfma_f32_16x16x32_bf16 v[30:33], v[160:163], v[230:233], v[30:33]
	v_mfma_f32_16x16x32_bf16 v[26:29], v[186:189], v[230:233], v[26:29]
	v_mfma_f32_16x16x32_bf16 v[14:17], v[160:163], v[238:241], v[14:17]
	v_mfma_f32_16x16x32_bf16 v[10:13], v[186:189], v[238:241], v[10:13]
	v_mfma_f32_16x16x32_bf16 v[62:65], v[170:173], v[218:221], v[62:65]
	v_mfma_f32_16x16x32_bf16 v[58:61], v[190:193], v[218:221], v[58:61]
	v_mfma_f32_16x16x32_bf16 v[46:49], v[170:173], v[226:229], v[46:49]
	v_mfma_f32_16x16x32_bf16 v[42:45], v[190:193], v[226:229], v[42:45]
	v_mfma_f32_16x16x32_bf16 v[30:33], v[170:173], v[234:237], v[30:33]
	v_mfma_f32_16x16x32_bf16 v[26:29], v[190:193], v[234:237], v[26:29]
	v_mfma_f32_16x16x32_bf16 v[14:17], v[170:173], v[242:245], v[14:17]
	v_mfma_f32_16x16x32_bf16 v[10:13], v[190:193], v[242:245], v[10:13]
	v_mfma_f32_16x16x32_bf16 v[54:57], v[198:201], v[214:217], v[54:57]
	v_mfma_f32_16x16x32_bf16 v[50:53], v[206:209], v[214:217], v[50:53]
	v_mfma_f32_16x16x32_bf16 v[38:41], v[198:201], v[222:225], v[38:41]
	v_mfma_f32_16x16x32_bf16 v[34:37], v[206:209], v[222:225], v[34:37]
	v_mfma_f32_16x16x32_bf16 v[22:25], v[198:201], v[230:233], v[22:25]
	v_mfma_f32_16x16x32_bf16 v[18:21], v[206:209], v[230:233], v[18:21]
	v_mfma_f32_16x16x32_bf16 v[6:9], v[198:201], v[238:241], v[6:9]
	v_mfma_f32_16x16x32_bf16 v[2:5], v[206:209], v[238:241], v[2:5]
	v_mfma_f32_16x16x32_bf16 v[54:57], v[202:205], v[218:221], v[54:57]
	v_mfma_f32_16x16x32_bf16 v[50:53], v[210:213], v[218:221], v[50:53]
	v_mfma_f32_16x16x32_bf16 v[38:41], v[202:205], v[226:229], v[38:41]
	v_mfma_f32_16x16x32_bf16 v[34:37], v[210:213], v[226:229], v[34:37]
	v_mfma_f32_16x16x32_bf16 v[22:25], v[202:205], v[234:237], v[22:25]
	v_mfma_f32_16x16x32_bf16 v[18:21], v[210:213], v[234:237], v[18:21]
	v_mfma_f32_16x16x32_bf16 v[6:9], v[202:205], v[242:245], v[6:9]
	v_mfma_f32_16x16x32_bf16 v[2:5], v[210:213], v[242:245], v[2:5]
	s_barrier
	s_add_i32 s12, 0, 0x18000
	s_add_i32 s13, 0, 0x1c000
	v_add_u32_e32 v190, s12, v167
	v_add_u32_e32 v210, s13, v167
	ds_read_b128 v[160:163], v190
	ds_read_b128 v[170:173], v190 offset:1024
	ds_read_b128 v[186:189], v190 offset:2048
	ds_read_b128 v[190:193], v190 offset:3072
	ds_read_b128 v[198:201], v210
	ds_read_b128 v[202:205], v210 offset:1024
	ds_read_b128 v[206:209], v210 offset:2048
	ds_read_b128 v[210:213], v210 offset:3072
	s_add_u32 s10, s52, 0x40000
	s_addc_u32 s11, s53, 0
	s_mov_b32 m0, s31
	v_lshl_add_u64 v[248:249], s[10:11], 0, v[154:155]
	ds_read_b128 v[214:217], v169 offset:32768
	ds_read_b128 v[218:221], v169 offset:33792
	ds_read_b128 v[222:225], v169 offset:34816
	ds_read_b128 v[226:229], v169 offset:35840
	ds_read_b128 v[230:233], v169 offset:36864
	ds_read_b128 v[234:237], v169 offset:37888
	ds_read_b128 v[238:241], v169 offset:38912
	ds_read_b128 v[242:245], v169 offset:39936
	global_load_lds_dwordx4 v[248:249], off
	v_lshl_add_u64 v[248:249], s[10:11], 0, v[152:153]
	s_mov_b32 m0, s34
	s_nop 0
	global_load_lds_dwordx4 v[248:249], off
	s_waitcnt vmcnt(8)
	s_waitcnt lgkmcnt(0)
	s_barrier
	v_mfma_f32_16x16x32_bf16 v[126:129], v[160:163], v[214:217], v[126:129]
	v_mfma_f32_16x16x32_bf16 v[122:125], v[186:189], v[214:217], v[122:125]
	v_mfma_f32_16x16x32_bf16 v[110:113], v[160:163], v[222:225], v[110:113]
	v_mfma_f32_16x16x32_bf16 v[106:109], v[186:189], v[222:225], v[106:109]
	v_mfma_f32_16x16x32_bf16 v[94:97], v[160:163], v[230:233], v[94:97]
	v_mfma_f32_16x16x32_bf16 v[90:93], v[186:189], v[230:233], v[90:93]
	v_mfma_f32_16x16x32_bf16 v[78:81], v[160:163], v[238:241], v[78:81]
	v_mfma_f32_16x16x32_bf16 v[74:77], v[186:189], v[238:241], v[74:77]
	v_mfma_f32_16x16x32_bf16 v[126:129], v[170:173], v[218:221], v[126:129]
	v_mfma_f32_16x16x32_bf16 v[122:125], v[190:193], v[218:221], v[122:125]
	v_mfma_f32_16x16x32_bf16 v[110:113], v[170:173], v[226:229], v[110:113]
	v_mfma_f32_16x16x32_bf16 v[106:109], v[190:193], v[226:229], v[106:109]
	v_mfma_f32_16x16x32_bf16 v[94:97], v[170:173], v[234:237], v[94:97]
	v_mfma_f32_16x16x32_bf16 v[90:93], v[190:193], v[234:237], v[90:93]
	v_mfma_f32_16x16x32_bf16 v[78:81], v[170:173], v[242:245], v[78:81]
	v_mfma_f32_16x16x32_bf16 v[74:77], v[190:193], v[242:245], v[74:77]
	v_mfma_f32_16x16x32_bf16 v[118:121], v[198:201], v[214:217], v[118:121]
	v_mfma_f32_16x16x32_bf16 v[114:117], v[206:209], v[214:217], v[114:117]
	v_mfma_f32_16x16x32_bf16 v[102:105], v[198:201], v[222:225], v[102:105]
	v_mfma_f32_16x16x32_bf16 v[98:101], v[206:209], v[222:225], v[98:101]
	v_mfma_f32_16x16x32_bf16 v[86:89], v[198:201], v[230:233], v[86:89]
	v_mfma_f32_16x16x32_bf16 v[82:85], v[206:209], v[230:233], v[82:85]
	v_mfma_f32_16x16x32_bf16 v[70:73], v[198:201], v[238:241], v[70:73]
	v_mfma_f32_16x16x32_bf16 v[66:69], v[206:209], v[238:241], v[66:69]
	v_mfma_f32_16x16x32_bf16 v[118:121], v[202:205], v[218:221], v[118:121]
	v_mfma_f32_16x16x32_bf16 v[114:117], v[210:213], v[218:221], v[114:117]
	v_mfma_f32_16x16x32_bf16 v[102:105], v[202:205], v[226:229], v[102:105]
	v_mfma_f32_16x16x32_bf16 v[98:101], v[210:213], v[226:229], v[98:101]
	v_mfma_f32_16x16x32_bf16 v[86:89], v[202:205], v[234:237], v[86:89]
	v_mfma_f32_16x16x32_bf16 v[82:85], v[210:213], v[234:237], v[82:85]
	v_mfma_f32_16x16x32_bf16 v[70:73], v[202:205], v[242:245], v[70:73]
	v_mfma_f32_16x16x32_bf16 v[66:69], v[210:213], v[242:245], v[66:69]
	s_barrier
; #define PG8_STAGE(bufoff, gbase, voff) do { _Pragma("unroll") for (int _i = 0; _i < 2; ++_i) \
;         __builtin_amdgcn_global_load_lds((const unsigned*)((const char*)(gbase) + (voff)[_i]), (PG8_LAS unsigned*)(lds + (bufoff) + ldsw + _i * 8192), 16, 0, 0); } while (0)
; #define PG8_LDA(dst, b, h) do { _Pragma("unroll") for (int m = 0; m < 4; ++m) _Pragma("unroll") for (int k = 0; k < 2; ++k) dst[m][k] = *(const PG8_LAS bf16x8*)(lds + PG8_SA(b, h) + aoff + m * 2048 + k * 1024); } while (0)
; #define PG8_MMA(ai, bj, At, Bt) do { __builtin_amdgcn_s_setprio(1); _Pragma("unroll") for (int m = 0; m < 4; ++m) _Pragma("unroll") for (int n = 0; n < 2; ++n) _Pragma("unroll") for (int k = 0; k < 2; ++k) \
;         acc[ai][bj][m][n] = __builtin_amdgcn_mfma_f32_16x16x32_bf16(Bt[n][k], At[m][k], acc[ai][bj][m][n], 0, 0, 0); __builtin_amdgcn_s_setprio(0); } while (0)
; #define PG8_WAIT_V(n) asm volatile("s_waitcnt vmcnt(" #n ")" ::: "memory")
; #define PG8_WAIT_L(n) asm volatile("s_waitcnt lgkmcnt(" #n ")" ::: "memory")
; #define PG8_BAR __builtin_amdgcn_s_barrier()
; #define PG8_SCHED __builtin_amdgcn_sched_barrier(0)
; template <class Epi, class Sched, bool ALIGN_EPI = false, bool SP2 = false>
; __device__ __forceinline__ void gemm_phase(PG8_LAS unsigned char* lds, const Gemm g, const Sched& S, const Epi& E) {
;     ...
;             PG8_LDA(At, 1, 1); PG8_STAGE(PG8_SB(1, 0), b3, voffB); PG8_STAGE(PG8_SB(1, 1), b3 + hstepB, voffB); PG8_STAGE(PG8_SA(1, 0), a3, voffA);
;             PG8_WAIT_V(8); PG8_WAIT_L(0); PG8_BAR; PG8_MMA(1, 0, At, B0); PG8_MMA(1, 1, At, B1); PG8_BAR; PG8_SCHED;
;     ...
;         if constexpr (ALIGN_EPI) { if (wr == 0) PG8_BAR; }
	s_add_i32 s10, s12, s8
	v_lshl_add_u64 v[130:131], v[130:131], 0, s[2:3]
	s_mov_b32 m0, s10
	ds_read_b128 v[214:217], v169 offset:49152
	ds_read_b128 v[218:221], v169 offset:50176
	ds_read_b128 v[222:225], v169 offset:51200
	ds_read_b128 v[226:229], v169 offset:52224
	ds_read_b128 v[230:233], v169 offset:53248
	ds_read_b128 v[234:237], v169 offset:54272
	ds_read_b128 v[238:241], v169 offset:55296
	ds_read_b128 v[242:245], v169 offset:56320
	global_load_lds_dwordx4 v[130:131], off
	s_add_i32 m0, s10, 0x2000
	s_add_u32 s10, s50, 0x40080
	v_lshl_add_u64 v[130:131], v[132:133], 0, s[2:3]
	s_addc_u32 s11, s51, 0
	s_add_i32 s12, s13, s8
	global_load_lds_dwordx4 v[130:131], off
	v_lshl_add_u64 v[130:131], s[10:11], 0, v[0:1]
	s_mov_b32 m0, s12
	s_nop 0
	global_load_lds_dwordx4 v[130:131], off
	v_lshl_add_u64 v[130:131], s[10:11], 0, v[150:151]
	s_add_i32 m0, s12, 0x2000
	s_nop 0
	global_load_lds_dwordx4 v[130:131], off
	v_lshl_add_u64 v[130:131], v[164:165], 0, s[2:3]
	s_mov_b32 m0, s35
	s_nop 0
	global_load_lds_dwordx4 v[130:131], off
	v_lshl_add_u64 v[130:131], v[246:247], 0, s[2:3]
	s_mov_b32 m0, s54
	s_nop 0
	global_load_lds_dwordx4 v[130:131], off
	s_waitcnt vmcnt(8)
	s_waitcnt lgkmcnt(0)
	s_barrier
	v_mfma_f32_16x16x32_bf16 v[62:65], v[160:163], v[214:217], v[62:65]
	v_mfma_f32_16x16x32_bf16 v[58:61], v[186:189], v[214:217], v[58:61]
	v_mfma_f32_16x16x32_bf16 v[46:49], v[160:163], v[222:225], v[46:49]
	v_mfma_f32_16x16x32_bf16 v[42:45], v[186:189], v[222:225], v[42:45]
	v_mfma_f32_16x16x32_bf16 v[30:33], v[160:163], v[230:233], v[30:33]
	v_mfma_f32_16x16x32_bf16 v[26:29], v[186:189], v[230:233], v[26:29]
	v_mfma_f32_16x16x32_bf16 v[14:17], v[160:163], v[238:241], v[14:17]
	v_mfma_f32_16x16x32_bf16 v[10:13], v[186:189], v[238:241], v[10:13]
	v_mfma_f32_16x16x32_bf16 v[62:65], v[170:173], v[218:221], v[62:65]
	v_mfma_f32_16x16x32_bf16 v[58:61], v[190:193], v[218:221], v[58:61]
	v_mfma_f32_16x16x32_bf16 v[46:49], v[170:173], v[226:229], v[46:49]
	v_mfma_f32_16x16x32_bf16 v[42:45], v[190:193], v[226:229], v[42:45]
	v_mfma_f32_16x16x32_bf16 v[30:33], v[170:173], v[234:237], v[30:33]
	v_mfma_f32_16x16x32_bf16 v[26:29], v[190:193], v[234:237], v[26:29]
	v_mfma_f32_16x16x32_bf16 v[14:17], v[170:173], v[242:245], v[14:17]
	v_mfma_f32_16x16x32_bf16 v[10:13], v[190:193], v[242:245], v[10:13]
	v_mfma_f32_16x16x32_bf16 v[54:57], v[198:201], v[214:217], v[54:57]
	v_mfma_f32_16x16x32_bf16 v[50:53], v[206:209], v[214:217], v[50:53]
	v_mfma_f32_16x16x32_bf16 v[38:41], v[198:201], v[222:225], v[38:41]
	v_mfma_f32_16x16x32_bf16 v[34:37], v[206:209], v[222:225], v[34:37]
	v_mfma_f32_16x16x32_bf16 v[22:25], v[198:201], v[230:233], v[22:25]
	v_mfma_f32_16x16x32_bf16 v[18:21], v[206:209], v[230:233], v[18:21]
	v_mfma_f32_16x16x32_bf16 v[6:9], v[198:201], v[238:241], v[6:9]
	v_mfma_f32_16x16x32_bf16 v[2:5], v[206:209], v[238:241], v[2:5]
	v_mfma_f32_16x16x32_bf16 v[54:57], v[202:205], v[218:221], v[54:57]
	v_mfma_f32_16x16x32_bf16 v[50:53], v[210:213], v[218:221], v[50:53]
	v_mfma_f32_16x16x32_bf16 v[38:41], v[202:205], v[226:229], v[38:41]
	v_mfma_f32_16x16x32_bf16 v[34:37], v[210:213], v[226:229], v[34:37]
	v_mfma_f32_16x16x32_bf16 v[22:25], v[202:205], v[234:237], v[22:25]
	v_mfma_f32_16x16x32_bf16 v[18:21], v[210:213], v[234:237], v[18:21]
	v_mfma_f32_16x16x32_bf16 v[6:9], v[202:205], v[242:245], v[6:9]
	v_mfma_f32_16x16x32_bf16 v[2:5], v[210:213], v[242:245], v[2:5]
	s_barrier
	s_add_i32 s69, s69, 2
	s_add_u32 s48, s48, 0x100
	s_addc_u32 s49, s49, 0
	s_add_u32 s63, s63, 0x100
	s_addc_u32 s68, s68, 0
	s_cmp_gt_u32 s69, 13
	s_cbranch_scc0 .LBB0_726
	s_and_b64 vcc, exec, s[20:21]
	s_mov_b64 s[62:63], s[14:15]
	s_cbranch_vccz .LBB0_729
	s_barrier

; #define PG8_STAGE(bufoff, gbase, voff) do { _Pragma("unroll") for (int _i = 0; _i < 2; ++_i) \
;         __builtin_amdgcn_global_load_lds((const unsigned*)((const char*)(gbase) + (voff)[_i]), (PG8_LAS unsigned*)(lds + (bufoff) + ldsw + _i * 8192), 16, 0, 0); } while (0)
; #define PG8_LDA(dst, b, h) do { _Pragma("unroll") for (int m = 0; m < 4; ++m) _Pragma("unroll") for (int k = 0; k < 2; ++k) dst[m][k] = *(const PG8_LAS bf16x8*)(lds + PG8_SA(b, h) + aoff + m * 2048 + k * 1024); } while (0)
; #define PG8_LDB(dst, b, h) do { _Pragma("unroll") for (int n = 0; n < 2; ++n) _Pragma("unroll") for (int k = 0; k < 2; ++k) dst[n][k] = *(const PG8_LAS bf16x8*)(lds + PG8_SB(b, h) + boff + n * 2048 + k * 1024); } while (0)
; #define PG8_MMA(ai, bj, At, Bt) do { __builtin_amdgcn_s_setprio(1); _Pragma("unroll") for (int m = 0; m < 4; ++m) _Pragma("unroll") for (int n = 0; n < 2; ++n) _Pragma("unroll") for (int k = 0; k < 2; ++k) \
;         acc[ai][bj][m][n] = __builtin_amdgcn_mfma_f32_16x16x32_bf16(Bt[n][k], At[m][k], acc[ai][bj][m][n], 0, 0, 0); __builtin_amdgcn_s_setprio(0); } while (0)
; #define PG8_WAIT_V(n) asm volatile("s_waitcnt vmcnt(" #n ")" ::: "memory")
; #define PG8_WAIT_L(n) asm volatile("s_waitcnt lgkmcnt(" #n ")" ::: "memory")
; #define PG8_BAR __builtin_amdgcn_s_barrier()
; #define PG8_SCHED __builtin_amdgcn_sched_barrier(0)
; template <class Epi, class Sched, bool ALIGN_EPI = false, bool SP2 = false>
; __device__ __forceinline__ void gemm_phase(PG8_LAS unsigned char* lds, const Gemm g, const Sched& S, const Epi& E) {
;     ...
;             const bool last = (t == nt - 2);
;             const char* a1 = cA + (size_t)(t + 1) * kstep;
;             const char* a2 = last ? nA : cA + (size_t)(t + 2) * kstep; const char* b2 = last ? nB : cB + (size_t)(t + 2) * kstep;
;             const char* a3 = a2 + kstep; const char* b3 = b2 + kstep;
;     ...
;             PG8_LDB(B0, 0, 0); PG8_LDB(B1, 0, 1); PG8_SCHED; PG8_LDA(At, 0, 0); PG8_STAGE(PG8_SA(1, 1), a1 + hstepA, voffA);
;             PG8_WAIT_V(8); PG8_WAIT_L(0); PG8_BAR; PG8_MMA(0, 0, At, B0); PG8_MMA(0, 1, At, B1); PG8_BAR; PG8_SCHED;
;             PG8_LDA(At, 0, 1); PG8_STAGE(PG8_SB(0, 0), b2, voffB); PG8_STAGE(PG8_SB(0, 1), b2 + hstepB, voffB); PG8_STAGE(PG8_SA(0, 0), a2, voffA);
;             PG8_WAIT_V(8); PG8_WAIT_L(0); PG8_BAR; PG8_MMA(1, 0, At, B0); PG8_MMA(1, 1, At, B1); PG8_BAR; PG8_SCHED;
.LBB0_856:
	s_add_u32 s10, s48, 0xfffc0080
	s_addc_u32 s11, s49, -1
	s_add_i32 s12, 0, 0x10000
	s_cmp_eq_u32 s69, 12
	s_cselect_b32 s53, s43, s11
	s_cselect_b32 s52, s62, s10
	v_add_u32_e32 v130, s12, v161
	s_cselect_b32 s51, s4, s68
	s_cselect_b32 s50, s41, s63
	s_add_i32 s13, 0, 0x14000
	ds_read_b128 v[164:167], v130
	ds_read_b128 v[168:171], v130 offset:1024
	ds_read_b128 v[186:189], v130 offset:2048
	ds_read_b128 v[190:193], v130 offset:3072
	v_add_u32_e32 v130, s13, v161
	ds_read_b128 v[198:201], v130
	ds_read_b128 v[202:205], v130 offset:1024
	ds_read_b128 v[206:209], v130 offset:2048
	ds_read_b128 v[210:213], v130 offset:3072
	v_lshl_add_u64 v[130:131], s[48:49], 0, v[156:157]
	s_add_i32 m0, s9, 0xc000
	ds_read_b128 v[214:217], v163
	ds_read_b128 v[218:221], v163 offset:1024
	ds_read_b128 v[222:225], v163 offset:2048
	ds_read_b128 v[226:229], v163 offset:3072
	ds_read_b128 v[230:233], v163 offset:4096
	ds_read_b128 v[234:237], v163 offset:5120
	ds_read_b128 v[238:241], v163 offset:6144
	ds_read_b128 v[242:245], v163 offset:7168
	global_load_lds_dwordx4 v[130:131], off
	v_lshl_add_u64 v[130:131], s[48:49], 0, v[158:159]
	s_add_i32 m0, s9, 0xe000
	s_nop 0
	global_load_lds_dwordx4 v[130:131], off
	s_waitcnt vmcnt(8)
	s_waitcnt lgkmcnt(0)
	s_barrier
	v_mfma_f32_16x16x32_bf16 v[126:129], v[164:167], v[214:217], v[126:129]
	v_mfma_f32_16x16x32_bf16 v[122:125], v[186:189], v[214:217], v[122:125]
	v_mfma_f32_16x16x32_bf16 v[110:113], v[164:167], v[222:225], v[110:113]
	v_mfma_f32_16x16x32_bf16 v[106:109], v[186:189], v[222:225], v[106:109]
	v_mfma_f32_16x16x32_bf16 v[94:97], v[164:167], v[230:233], v[94:97]
	v_mfma_f32_16x16x32_bf16 v[90:93], v[186:189], v[230:233], v[90:93]
	v_mfma_f32_16x16x32_bf16 v[78:81], v[164:167], v[238:241], v[78:81]
	v_mfma_f32_16x16x32_bf16 v[74:77], v[186:189], v[238:241], v[74:77]
	v_mfma_f32_16x16x32_bf16 v[126:129], v[168:171], v[218:221], v[126:129]
	v_mfma_f32_16x16x32_bf16 v[122:125], v[190:193], v[218:221], v[122:125]
	v_mfma_f32_16x16x32_bf16 v[110:113], v[168:171], v[226:229], v[110:113]
	v_mfma_f32_16x16x32_bf16 v[106:109], v[190:193], v[226:229], v[106:109]
	v_mfma_f32_16x16x32_bf16 v[94:97], v[168:171], v[234:237], v[94:97]
	v_mfma_f32_16x16x32_bf16 v[90:93], v[190:193], v[234:237], v[90:93]
	v_mfma_f32_16x16x32_bf16 v[78:81], v[168:171], v[242:245], v[78:81]
	v_mfma_f32_16x16x32_bf16 v[74:77], v[190:193], v[242:245], v[74:77]
	v_mfma_f32_16x16x32_bf16 v[118:121], v[198:201], v[214:217], v[118:121]
	v_mfma_f32_16x16x32_bf16 v[114:117], v[206:209], v[214:217], v[114:117]
	v_mfma_f32_16x16x32_bf16 v[102:105], v[198:201], v[222:225], v[102:105]
	v_mfma_f32_16x16x32_bf16 v[98:101], v[206:209], v[222:225], v[98:101]
	v_mfma_f32_16x16x32_bf16 v[86:89], v[198:201], v[230:233], v[86:89]
	v_mfma_f32_16x16x32_bf16 v[82:85], v[206:209], v[230:233], v[82:85]
	v_mfma_f32_16x16x32_bf16 v[70:73], v[198:201], v[238:241], v[70:73]
	v_mfma_f32_16x16x32_bf16 v[66:69], v[206:209], v[238:241], v[66:69]
	v_mfma_f32_16x16x32_bf16 v[118:121], v[202:205], v[218:221], v[118:121]
	v_mfma_f32_16x16x32_bf16 v[114:117], v[210:213], v[218:221], v[114:117]
	v_mfma_f32_16x16x32_bf16 v[102:105], v[202:205], v[226:229], v[102:105]
	v_mfma_f32_16x16x32_bf16 v[98:101], v[210:213], v[226:229], v[98:101]
	v_mfma_f32_16x16x32_bf16 v[86:89], v[202:205], v[234:237], v[86:89]
	v_mfma_f32_16x16x32_bf16 v[82:85], v[210:213], v[234:237], v[82:85]
	v_mfma_f32_16x16x32_bf16 v[70:73], v[202:205], v[242:245], v[70:73]
	v_mfma_f32_16x16x32_bf16 v[66:69], v[210:213], v[242:245], v[66:69]
	s_barrier
	s_add_i32 s10, s12, s8
	v_lshl_add_u64 v[130:131], s[50:51], 0, v[0:1]
	s_mov_b32 m0, s10
	ds_read_b128 v[214:217], v163 offset:16384
	ds_read_b128 v[218:221], v163 offset:17408
	ds_read_b128 v[222:225], v163 offset:18432
	ds_read_b128 v[226:229], v163 offset:19456
	ds_read_b128 v[230:233], v163 offset:20480
	ds_read_b128 v[234:237], v163 offset:21504
	ds_read_b128 v[238:241], v163 offset:22528
	ds_read_b128 v[242:245], v163 offset:23552
	global_load_lds_dwordx4 v[130:131], off
	s_add_i32 m0, s10, 0x2000
	s_add_u32 s10, s50, 0x40000
	v_lshl_add_u64 v[132:133], s[50:51], 0, v[150:151]
	s_addc_u32 s11, s51, 0
	s_add_i32 s12, s13, s8
	global_load_lds_dwordx4 v[132:133], off
	v_lshl_add_u64 v[172:173], s[10:11], 0, v[0:1]
	s_mov_b32 m0, s12
	v_lshl_add_u64 v[246:247], s[52:53], 0, v[152:153]
	global_load_lds_dwordx4 v[172:173], off
	v_lshl_add_u64 v[172:173], s[10:11], 0, v[150:151]
	s_add_i32 m0, s12, 0x2000
	s_nop 0
	global_load_lds_dwordx4 v[172:173], off
	v_lshl_add_u64 v[172:173], s[52:53], 0, v[154:155]
	s_mov_b32 m0, s9
	s_nop 0
	global_load_lds_dwordx4 v[172:173], off
	s_mov_b32 m0, s30
	s_nop 0
	global_load_lds_dwordx4 v[246:247], off
	s_waitcnt vmcnt(8)
	s_waitcnt lgkmcnt(0)
	s_barrier
; #define PG8_STAGE(bufoff, gbase, voff) do { _Pragma("unroll") for (int _i = 0; _i < 2; ++_i) \
;         __builtin_amdgcn_global_load_lds((const unsigned*)((const char*)(gbase) + (voff)[_i]), (PG8_LAS unsigned*)(lds + (bufoff) + ldsw + _i * 8192), 16, 0, 0); } while (0)
; #define PG8_LDA(dst, b, h) do { _Pragma("unroll") for (int m = 0; m < 4; ++m) _Pragma("unroll") for (int k = 0; k < 2; ++k) dst[m][k] = *(const PG8_LAS bf16x8*)(lds + PG8_SA(b, h) + aoff + m * 2048 + k * 1024); } while (0)
; #define PG8_LDB(dst, b, h) do { _Pragma("unroll") for (int n = 0; n < 2; ++n) _Pragma("unroll") for (int k = 0; k < 2; ++k) dst[n][k] = *(const PG8_LAS bf16x8*)(lds + PG8_SB(b, h) + boff + n * 2048 + k * 1024); } while (0)
; #define PG8_MMA(ai, bj, At, Bt) do { __builtin_amdgcn_s_setprio(1); _Pragma("unroll") for (int m = 0; m < 4; ++m) _Pragma("unroll") for (int n = 0; n < 2; ++n) _Pragma("unroll") for (int k = 0; k < 2; ++k) \
;         acc[ai][bj][m][n] = __builtin_amdgcn_mfma_f32_16x16x32_bf16(Bt[n][k], At[m][k], acc[ai][bj][m][n], 0, 0, 0); __builtin_amdgcn_s_setprio(0); } while (0)
; #define PG8_WAIT_V(n) asm volatile("s_waitcnt vmcnt(" #n ")" ::: "memory")
; #define PG8_WAIT_L(n) asm volatile("s_waitcnt lgkmcnt(" #n ")" ::: "memory")
; #define PG8_BAR __builtin_amdgcn_s_barrier()
; #define PG8_SCHED __builtin_amdgcn_sched_barrier(0)
; template <class Epi, class Sched, bool ALIGN_EPI = false, bool SP2 = false>
; __device__ __forceinline__ void gemm_phase(PG8_LAS unsigned char* lds, const Gemm g, const Sched& S, const Epi& E) {
;     ...
;             PG8_WAIT_V(8); PG8_WAIT_L(0); PG8_BAR; PG8_MMA(1, 0, At, B0); PG8_MMA(1, 1, At, B1); PG8_BAR; PG8_SCHED;
;             PG8_LDB(B0, 1, 0); PG8_LDB(B1, 1, 1); PG8_SCHED; PG8_LDA(At, 1, 0); PG8_STAGE(PG8_SA(0, 1), a2 + hstepA, voffA);
;             PG8_WAIT_V(8); PG8_WAIT_L(0); PG8_BAR; PG8_MMA(0, 0, At, B0); PG8_MMA(0, 1, At, B1); PG8_BAR; PG8_SCHED;
	v_mfma_f32_16x16x32_bf16 v[62:65], v[164:167], v[214:217], v[62:65]
	v_mfma_f32_16x16x32_bf16 v[58:61], v[186:189], v[214:217], v[58:61]
	v_mfma_f32_16x16x32_bf16 v[46:49], v[164:167], v[222:225], v[46:49]
	v_mfma_f32_16x16x32_bf16 v[42:45], v[186:189], v[222:225], v[42:45]
	v_mfma_f32_16x16x32_bf16 v[30:33], v[164:167], v[230:233], v[30:33]
	v_mfma_f32_16x16x32_bf16 v[26:29], v[186:189], v[230:233], v[26:29]
	v_mfma_f32_16x16x32_bf16 v[14:17], v[164:167], v[238:241], v[14:17]
	v_mfma_f32_16x16x32_bf16 v[10:13], v[186:189], v[238:241], v[10:13]
	v_mfma_f32_16x16x32_bf16 v[62:65], v[168:171], v[218:221], v[62:65]
	v_mfma_f32_16x16x32_bf16 v[58:61], v[190:193], v[218:221], v[58:61]
	v_mfma_f32_16x16x32_bf16 v[46:49], v[168:171], v[226:229], v[46:49]
	v_mfma_f32_16x16x32_bf16 v[42:45], v[190:193], v[226:229], v[42:45]
	v_mfma_f32_16x16x32_bf16 v[30:33], v[168:171], v[234:237], v[30:33]
	v_mfma_f32_16x16x32_bf16 v[26:29], v[190:193], v[234:237], v[26:29]
	v_mfma_f32_16x16x32_bf16 v[14:17], v[168:171], v[242:245], v[14:17]
	v_mfma_f32_16x16x32_bf16 v[10:13], v[190:193], v[242:245], v[10:13]
	v_mfma_f32_16x16x32_bf16 v[54:57], v[198:201], v[214:217], v[54:57]
	v_mfma_f32_16x16x32_bf16 v[50:53], v[206:209], v[214:217], v[50:53]
	v_mfma_f32_16x16x32_bf16 v[38:41], v[198:201], v[222:225], v[38:41]
	v_mfma_f32_16x16x32_bf16 v[34:37], v[206:209], v[222:225], v[34:37]
	v_mfma_f32_16x16x32_bf16 v[22:25], v[198:201], v[230:233], v[22:25]
	v_mfma_f32_16x16x32_bf16 v[18:21], v[206:209], v[230:233], v[18:21]
	v_mfma_f32_16x16x32_bf16 v[6:9], v[198:201], v[238:241], v[6:9]
	v_mfma_f32_16x16x32_bf16 v[2:5], v[206:209], v[238:241], v[2:5]
	v_mfma_f32_16x16x32_bf16 v[54:57], v[202:205], v[218:221], v[54:57]
	v_mfma_f32_16x16x32_bf16 v[50:53], v[210:213], v[218:221], v[50:53]
	v_mfma_f32_16x16x32_bf16 v[38:41], v[202:205], v[226:229], v[38:41]
	v_mfma_f32_16x16x32_bf16 v[34:37], v[210:213], v[226:229], v[34:37]
	v_mfma_f32_16x16x32_bf16 v[22:25], v[202:205], v[234:237], v[22:25]
	v_mfma_f32_16x16x32_bf16 v[18:21], v[210:213], v[234:237], v[18:21]
	v_mfma_f32_16x16x32_bf16 v[6:9], v[202:205], v[242:245], v[6:9]
	v_mfma_f32_16x16x32_bf16 v[2:5], v[210:213], v[242:245], v[2:5]
	s_barrier
	s_add_i32 s12, 0, 0x18000
	s_add_i32 s13, 0, 0x1c000
	v_add_u32_e32 v190, s12, v161
	v_add_u32_e32 v210, s13, v161
	ds_read_b128 v[164:167], v190
	ds_read_b128 v[168:171], v190 offset:1024
	ds_read_b128 v[186:189], v190 offset:2048
	ds_read_b128 v[190:193], v190 offset:3072
	ds_read_b128 v[198:201], v210
	ds_read_b128 v[202:205], v210 offset:1024
	ds_read_b128 v[206:209], v210 offset:2048
	ds_read_b128 v[210:213], v210 offset:3072
	s_add_u32 s10, s52, 0x40000
	s_addc_u32 s11, s53, 0
	s_mov_b32 m0, s31
	v_lshl_add_u64 v[248:249], s[10:11], 0, v[154:155]
	ds_read_b128 v[214:217], v163 offset:32768
	ds_read_b128 v[218:221], v163 offset:33792
	ds_read_b128 v[222:225], v163 offset:34816
	ds_read_b128 v[226:229], v163 offset:35840
	ds_read_b128 v[230:233], v163 offset:36864
	ds_read_b128 v[234:237], v163 offset:37888
	ds_read_b128 v[238:241], v163 offset:38912
	ds_read_b128 v[242:245], v163 offset:39936
	global_load_lds_dwordx4 v[248:249], off
	v_lshl_add_u64 v[248:249], s[10:11], 0, v[152:153]
	s_mov_b32 m0, s34
	s_nop 0
	global_load_lds_dwordx4 v[248:249], off
	s_waitcnt vmcnt(8)
	s_waitcnt lgkmcnt(0)
	s_barrier
	v_mfma_f32_16x16x32_bf16 v[126:129], v[164:167], v[214:217], v[126:129]
	v_mfma_f32_16x16x32_bf16 v[122:125], v[186:189], v[214:217], v[122:125]
	v_mfma_f32_16x16x32_bf16 v[110:113], v[164:167], v[222:225], v[110:113]
	v_mfma_f32_16x16x32_bf16 v[106:109], v[186:189], v[222:225], v[106:109]
	v_mfma_f32_16x16x32_bf16 v[94:97], v[164:167], v[230:233], v[94:97]
	v_mfma_f32_16x16x32_bf16 v[90:93], v[186:189], v[230:233], v[90:93]
	v_mfma_f32_16x16x32_bf16 v[78:81], v[164:167], v[238:241], v[78:81]
	v_mfma_f32_16x16x32_bf16 v[74:77], v[186:189], v[238:241], v[74:77]
	v_mfma_f32_16x16x32_bf16 v[126:129], v[168:171], v[218:221], v[126:129]
	v_mfma_f32_16x16x32_bf16 v[122:125], v[190:193], v[218:221], v[122:125]
	v_mfma_f32_16x16x32_bf16 v[110:113], v[168:171], v[226:229], v[110:113]
	v_mfma_f32_16x16x32_bf16 v[106:109], v[190:193], v[226:229], v[106:109]
	v_mfma_f32_16x16x32_bf16 v[94:97], v[168:171], v[234:237], v[94:97]
	v_mfma_f32_16x16x32_bf16 v[90:93], v[190:193], v[234:237], v[90:93]
	v_mfma_f32_16x16x32_bf16 v[78:81], v[168:171], v[242:245], v[78:81]
	v_mfma_f32_16x16x32_bf16 v[74:77], v[190:193], v[242:245], v[74:77]
	v_mfma_f32_16x16x32_bf16 v[118:121], v[198:201], v[214:217], v[118:121]
	v_mfma_f32_16x16x32_bf16 v[114:117], v[206:209], v[214:217], v[114:117]
	v_mfma_f32_16x16x32_bf16 v[102:105], v[198:201], v[222:225], v[102:105]
	v_mfma_f32_16x16x32_bf16 v[98:101], v[206:209], v[222:225], v[98:101]
	v_mfma_f32_16x16x32_bf16 v[86:89], v[198:201], v[230:233], v[86:89]
	v_mfma_f32_16x16x32_bf16 v[82:85], v[206:209], v[230:233], v[82:85]
	v_mfma_f32_16x16x32_bf16 v[70:73], v[198:201], v[238:241], v[70:73]
	v_mfma_f32_16x16x32_bf16 v[66:69], v[206:209], v[238:241], v[66:69]
	v_mfma_f32_16x16x32_bf16 v[118:121], v[202:205], v[218:221], v[118:121]
	v_mfma_f32_16x16x32_bf16 v[114:117], v[210:213], v[218:221], v[114:117]
	v_mfma_f32_16x16x32_bf16 v[102:105], v[202:205], v[226:229], v[102:105]
	v_mfma_f32_16x16x32_bf16 v[98:101], v[210:213], v[226:229], v[98:101]
	v_mfma_f32_16x16x32_bf16 v[86:89], v[202:205], v[234:237], v[86:89]
	v_mfma_f32_16x16x32_bf16 v[82:85], v[210:213], v[234:237], v[82:85]
	v_mfma_f32_16x16x32_bf16 v[70:73], v[202:205], v[242:245], v[70:73]
	v_mfma_f32_16x16x32_bf16 v[66:69], v[210:213], v[242:245], v[66:69]
	s_barrier
; #define PG8_STAGE(bufoff, gbase, voff) do { _Pragma("unroll") for (int _i = 0; _i < 2; ++_i) \
;         __builtin_amdgcn_global_load_lds((const unsigned*)((const char*)(gbase) + (voff)[_i]), (PG8_LAS unsigned*)(lds + (bufoff) + ldsw + _i * 8192), 16, 0, 0); } while (0)
; #define PG8_LDA(dst, b, h) do { _Pragma("unroll") for (int m = 0; m < 4; ++m) _Pragma("unroll") for (int k = 0; k < 2; ++k) dst[m][k] = *(const PG8_LAS bf16x8*)(lds + PG8_SA(b, h) + aoff + m * 2048 + k * 1024); } while (0)
; #define PG8_MMA(ai, bj, At, Bt) do { __builtin_amdgcn_s_setprio(1); _Pragma("unroll") for (int m = 0; m < 4; ++m) _Pragma("unroll") for (int n = 0; n < 2; ++n) _Pragma("unroll") for (int k = 0; k < 2; ++k) \
;         acc[ai][bj][m][n] = __builtin_amdgcn_mfma_f32_16x16x32_bf16(Bt[n][k], At[m][k], acc[ai][bj][m][n], 0, 0, 0); __builtin_amdgcn_s_setprio(0); } while (0)
; #define PG8_WAIT_V(n) asm volatile("s_waitcnt vmcnt(" #n ")" ::: "memory")
; #define PG8_WAIT_L(n) asm volatile("s_waitcnt lgkmcnt(" #n ")" ::: "memory")
; #define PG8_BAR __builtin_amdgcn_s_barrier()
; #define PG8_SCHED __builtin_amdgcn_sched_barrier(0)
; template <class Epi, class Sched, bool ALIGN_EPI = false, bool SP2 = false>
; __device__ __forceinline__ void gemm_phase(PG8_LAS unsigned char* lds, const Gemm g, const Sched& S, const Epi& E) {
;     ...
;             PG8_LDA(At, 1, 1); PG8_STAGE(PG8_SB(1, 0), b3, voffB); PG8_STAGE(PG8_SB(1, 1), b3 + hstepB, voffB); PG8_STAGE(PG8_SA(1, 0), a3, voffA);
;             PG8_WAIT_V(8); PG8_WAIT_L(0); PG8_BAR; PG8_MMA(1, 0, At, B0); PG8_MMA(1, 1, At, B1); PG8_BAR; PG8_SCHED;
;     ...
;         if constexpr (ALIGN_EPI) { if (wr == 0) PG8_BAR; }
	s_add_i32 s10, s12, s8
	v_lshl_add_u64 v[130:131], v[130:131], 0, s[2:3]
	s_mov_b32 m0, s10
	ds_read_b128 v[214:217], v163 offset:49152
	ds_read_b128 v[218:221], v163 offset:50176
	ds_read_b128 v[222:225], v163 offset:51200
	ds_read_b128 v[226:229], v163 offset:52224
	ds_read_b128 v[230:233], v163 offset:53248
	ds_read_b128 v[234:237], v163 offset:54272
	ds_read_b128 v[238:241], v163 offset:55296
	ds_read_b128 v[242:245], v163 offset:56320
	global_load_lds_dwordx4 v[130:131], off
	s_add_i32 m0, s10, 0x2000
	s_add_u32 s10, s50, 0x40080
	v_lshl_add_u64 v[130:131], v[132:133], 0, s[2:3]
	s_addc_u32 s11, s51, 0
	s_add_i32 s12, s13, s8
	global_load_lds_dwordx4 v[130:131], off
	v_lshl_add_u64 v[130:131], s[10:11], 0, v[0:1]
	s_mov_b32 m0, s12
	s_nop 0
	global_load_lds_dwordx4 v[130:131], off
	v_lshl_add_u64 v[130:131], s[10:11], 0, v[150:151]
	s_add_i32 m0, s12, 0x2000
	s_nop 0
	global_load_lds_dwordx4 v[130:131], off
	v_lshl_add_u64 v[130:131], v[172:173], 0, s[2:3]
	s_mov_b32 m0, s35
	s_nop 0
	global_load_lds_dwordx4 v[130:131], off
	v_lshl_add_u64 v[130:131], v[246:247], 0, s[2:3]
	s_mov_b32 m0, s54
	s_nop 0
	global_load_lds_dwordx4 v[130:131], off
	s_waitcnt vmcnt(8)
	s_waitcnt lgkmcnt(0)
	s_barrier
	v_mfma_f32_16x16x32_bf16 v[62:65], v[164:167], v[214:217], v[62:65]
	v_mfma_f32_16x16x32_bf16 v[58:61], v[186:189], v[214:217], v[58:61]
	v_mfma_f32_16x16x32_bf16 v[46:49], v[164:167], v[222:225], v[46:49]
	v_mfma_f32_16x16x32_bf16 v[42:45], v[186:189], v[222:225], v[42:45]
	v_mfma_f32_16x16x32_bf16 v[30:33], v[164:167], v[230:233], v[30:33]
	v_mfma_f32_16x16x32_bf16 v[26:29], v[186:189], v[230:233], v[26:29]
	v_mfma_f32_16x16x32_bf16 v[14:17], v[164:167], v[238:241], v[14:17]
	v_mfma_f32_16x16x32_bf16 v[10:13], v[186:189], v[238:241], v[10:13]
	v_mfma_f32_16x16x32_bf16 v[62:65], v[168:171], v[218:221], v[62:65]
	v_mfma_f32_16x16x32_bf16 v[58:61], v[190:193], v[218:221], v[58:61]
	v_mfma_f32_16x16x32_bf16 v[46:49], v[168:171], v[226:229], v[46:49]
	v_mfma_f32_16x16x32_bf16 v[42:45], v[190:193], v[226:229], v[42:45]
	v_mfma_f32_16x16x32_bf16 v[30:33], v[168:171], v[234:237], v[30:33]
	v_mfma_f32_16x16x32_bf16 v[26:29], v[190:193], v[234:237], v[26:29]
	v_mfma_f32_16x16x32_bf16 v[14:17], v[168:171], v[242:245], v[14:17]
	v_mfma_f32_16x16x32_bf16 v[10:13], v[190:193], v[242:245], v[10:13]
	v_mfma_f32_16x16x32_bf16 v[54:57], v[198:201], v[214:217], v[54:57]
	v_mfma_f32_16x16x32_bf16 v[50:53], v[206:209], v[214:217], v[50:53]
	v_mfma_f32_16x16x32_bf16 v[38:41], v[198:201], v[222:225], v[38:41]
	v_mfma_f32_16x16x32_bf16 v[34:37], v[206:209], v[222:225], v[34:37]
	v_mfma_f32_16x16x32_bf16 v[22:25], v[198:201], v[230:233], v[22:25]
	v_mfma_f32_16x16x32_bf16 v[18:21], v[206:209], v[230:233], v[18:21]
	v_mfma_f32_16x16x32_bf16 v[6:9], v[198:201], v[238:241], v[6:9]
	v_mfma_f32_16x16x32_bf16 v[2:5], v[206:209], v[238:241], v[2:5]
	v_mfma_f32_16x16x32_bf16 v[54:57], v[202:205], v[218:221], v[54:57]
	v_mfma_f32_16x16x32_bf16 v[50:53], v[210:213], v[218:221], v[50:53]
	v_mfma_f32_16x16x32_bf16 v[38:41], v[202:205], v[226:229], v[38:41]
	v_mfma_f32_16x16x32_bf16 v[34:37], v[210:213], v[226:229], v[34:37]
	v_mfma_f32_16x16x32_bf16 v[22:25], v[202:205], v[234:237], v[22:25]
	v_mfma_f32_16x16x32_bf16 v[18:21], v[210:213], v[234:237], v[18:21]
	v_mfma_f32_16x16x32_bf16 v[6:9], v[202:205], v[242:245], v[6:9]
	v_mfma_f32_16x16x32_bf16 v[2:5], v[210:213], v[242:245], v[2:5]
	s_barrier
	s_add_i32 s69, s69, 2
	s_add_u32 s48, s48, 0x100
	s_addc_u32 s49, s49, 0
	s_add_u32 s63, s63, 0x100
	s_addc_u32 s68, s68, 0
	s_cmp_gt_u32 s69, 13
	s_cbranch_scc0 .LBB0_856
	s_and_b64 vcc, exec, s[20:21]
	s_mov_b64 s[62:63], s[14:15]
	s_cbranch_vccz .LBB0_859
	s_barrier

; #define PG8_STAGE(bufoff, gbase, voff) do { _Pragma("unroll") for (int _i = 0; _i < 2; ++_i) \
;         __builtin_amdgcn_global_load_lds((const unsigned*)((const char*)(gbase) + (voff)[_i]), (PG8_LAS unsigned*)(lds + (bufoff) + ldsw + _i * 8192), 16, 0, 0); } while (0)
; #define PG8_LDA(dst, b, h) do { _Pragma("unroll") for (int m = 0; m < 4; ++m) _Pragma("unroll") for (int k = 0; k < 2; ++k) dst[m][k] = *(const PG8_LAS bf16x8*)(lds + PG8_SA(b, h) + aoff + m * 2048 + k * 1024); } while (0)
; #define PG8_LDB(dst, b, h) do { _Pragma("unroll") for (int n = 0; n < 2; ++n) _Pragma("unroll") for (int k = 0; k < 2; ++k) dst[n][k] = *(const PG8_LAS bf16x8*)(lds + PG8_SB(b, h) + boff + n * 2048 + k * 1024); } while (0)
; #define PG8_MMA(ai, bj, At, Bt) do { __builtin_amdgcn_s_setprio(1); _Pragma("unroll") for (int m = 0; m < 4; ++m) _Pragma("unroll") for (int n = 0; n < 2; ++n) _Pragma("unroll") for (int k = 0; k < 2; ++k) \
;         acc[ai][bj][m][n] = __builtin_amdgcn_mfma_f32_16x16x32_bf16(Bt[n][k], At[m][k], acc[ai][bj][m][n], 0, 0, 0); __builtin_amdgcn_s_setprio(0); } while (0)
; #define PG8_WAIT_V(n) asm volatile("s_waitcnt vmcnt(" #n ")" ::: "memory")
; #define PG8_WAIT_L(n) asm volatile("s_waitcnt lgkmcnt(" #n ")" ::: "memory")
; #define PG8_BAR __builtin_amdgcn_s_barrier()
; #define PG8_SCHED __builtin_amdgcn_sched_barrier(0)
; template <class Epi, class Sched, bool ALIGN_EPI = false, bool SP2 = false>
; __device__ __forceinline__ void gemm_phase(PG8_LAS unsigned char* lds, const Gemm g, const Sched& S, const Epi& E) {
;     ...
;             PG8_LDB(B0, 0, 0); PG8_LDB(B1, 0, 1); PG8_SCHED; PG8_LDA(At, 0, 0); PG8_STAGE(PG8_SA(1, 1), a1 + hstepA, voffA);
;             PG8_WAIT_V(8); PG8_WAIT_L(0); PG8_BAR; PG8_MMA(0, 0, At, B0); PG8_MMA(0, 1, At, B1); PG8_BAR; PG8_SCHED;
;             PG8_LDA(At, 0, 1); PG8_STAGE(PG8_SB(0, 0), b2, voffB); PG8_STAGE(PG8_SB(0, 1), b2 + hstepB, voffB); PG8_STAGE(PG8_SA(0, 0), a2, voffA);
;             PG8_WAIT_V(8); PG8_WAIT_L(0); PG8_BAR; PG8_MMA(1, 0, At, B0); PG8_MMA(1, 1, At, B1); PG8_BAR; PG8_SCHED;
.Lgk_929:
	ds_read_b128 v[160:163], v130
	ds_read_b128 v[170:173], v130 offset:1024
	ds_read_b128 v[186:189], v130 offset:2048
	ds_read_b128 v[190:193], v130 offset:3072
	v_add_u32_e32 v130, s13, v167
	ds_read_b128 v[198:201], v130
	ds_read_b128 v[202:205], v130 offset:1024
	ds_read_b128 v[206:209], v130 offset:2048
	ds_read_b128 v[210:213], v130 offset:3072
	v_lshl_add_u64 v[130:131], s[46:47], 0, v[156:157]
	s_add_i32 m0, s9, 0xc000
	ds_read_b128 v[214:217], v169
	ds_read_b128 v[218:221], v169 offset:1024
	ds_read_b128 v[222:225], v169 offset:2048
	ds_read_b128 v[226:229], v169 offset:3072
	ds_read_b128 v[230:233], v169 offset:4096
	ds_read_b128 v[234:237], v169 offset:5120
	ds_read_b128 v[238:241], v169 offset:6144
	ds_read_b128 v[242:245], v169 offset:7168
	global_load_lds_dwordx4 v[130:131], off
	v_lshl_add_u64 v[130:131], s[46:47], 0, v[158:159]
	s_add_i32 m0, s9, 0xe000
	s_nop 0
	global_load_lds_dwordx4 v[130:131], off
	s_waitcnt vmcnt(8)
	s_waitcnt lgkmcnt(0)
	s_barrier
	v_mfma_f32_16x16x32_bf16 v[126:129], v[160:163], v[214:217], v[126:129]
	v_mfma_f32_16x16x32_bf16 v[122:125], v[186:189], v[214:217], v[122:125]
	v_mfma_f32_16x16x32_bf16 v[110:113], v[160:163], v[222:225], v[110:113]
	v_mfma_f32_16x16x32_bf16 v[106:109], v[186:189], v[222:225], v[106:109]
	v_mfma_f32_16x16x32_bf16 v[94:97], v[160:163], v[230:233], v[94:97]
	v_mfma_f32_16x16x32_bf16 v[90:93], v[186:189], v[230:233], v[90:93]
	v_mfma_f32_16x16x32_bf16 v[78:81], v[160:163], v[238:241], v[78:81]
	v_mfma_f32_16x16x32_bf16 v[74:77], v[186:189], v[238:241], v[74:77]
	v_mfma_f32_16x16x32_bf16 v[126:129], v[170:173], v[218:221], v[126:129]
	v_mfma_f32_16x16x32_bf16 v[122:125], v[190:193], v[218:221], v[122:125]
	v_mfma_f32_16x16x32_bf16 v[110:113], v[170:173], v[226:229], v[110:113]
	v_mfma_f32_16x16x32_bf16 v[106:109], v[190:193], v[226:229], v[106:109]
	v_mfma_f32_16x16x32_bf16 v[94:97], v[170:173], v[234:237], v[94:97]
	v_mfma_f32_16x16x32_bf16 v[90:93], v[190:193], v[234:237], v[90:93]
	v_mfma_f32_16x16x32_bf16 v[78:81], v[170:173], v[242:245], v[78:81]
	v_mfma_f32_16x16x32_bf16 v[74:77], v[190:193], v[242:245], v[74:77]
	v_mfma_f32_16x16x32_bf16 v[118:121], v[198:201], v[214:217], v[118:121]
	v_mfma_f32_16x16x32_bf16 v[114:117], v[206:209], v[214:217], v[114:117]
	v_mfma_f32_16x16x32_bf16 v[102:105], v[198:201], v[222:225], v[102:105]
	v_mfma_f32_16x16x32_bf16 v[98:101], v[206:209], v[222:225], v[98:101]
	v_mfma_f32_16x16x32_bf16 v[86:89], v[198:201], v[230:233], v[86:89]
	v_mfma_f32_16x16x32_bf16 v[82:85], v[206:209], v[230:233], v[82:85]
	v_mfma_f32_16x16x32_bf16 v[70:73], v[198:201], v[238:241], v[70:73]
	v_mfma_f32_16x16x32_bf16 v[66:69], v[206:209], v[238:241], v[66:69]
	v_mfma_f32_16x16x32_bf16 v[118:121], v[202:205], v[218:221], v[118:121]
	v_mfma_f32_16x16x32_bf16 v[114:117], v[210:213], v[218:221], v[114:117]
	v_mfma_f32_16x16x32_bf16 v[102:105], v[202:205], v[226:229], v[102:105]
	v_mfma_f32_16x16x32_bf16 v[98:101], v[210:213], v[226:229], v[98:101]
	v_mfma_f32_16x16x32_bf16 v[86:89], v[202:205], v[234:237], v[86:89]
	v_mfma_f32_16x16x32_bf16 v[82:85], v[210:213], v[234:237], v[82:85]
	v_mfma_f32_16x16x32_bf16 v[70:73], v[202:205], v[242:245], v[70:73]
	v_mfma_f32_16x16x32_bf16 v[66:69], v[210:213], v[242:245], v[66:69]
	s_barrier
	s_add_i32 s10, s12, s8
	v_lshl_add_u64 v[130:131], s[48:49], 0, v[0:1]
	s_mov_b32 m0, s10
	ds_read_b128 v[214:217], v169 offset:16384
	ds_read_b128 v[218:221], v169 offset:17408
	ds_read_b128 v[222:225], v169 offset:18432
	ds_read_b128 v[226:229], v169 offset:19456
	ds_read_b128 v[230:233], v169 offset:20480
	ds_read_b128 v[234:237], v169 offset:21504
	ds_read_b128 v[238:241], v169 offset:22528
	ds_read_b128 v[242:245], v169 offset:23552
	global_load_lds_dwordx4 v[130:131], off
	s_add_i32 m0, s10, 0x2000
	s_add_u32 s10, s48, 0x100000
	v_lshl_add_u64 v[132:133], s[48:49], 0, v[150:151]
	s_addc_u32 s11, s49, 0
	s_add_i32 s12, s13, s8
	global_load_lds_dwordx4 v[132:133], off
	v_lshl_add_u64 v[164:165], s[10:11], 0, v[0:1]
	s_mov_b32 m0, s12
	v_lshl_add_u64 v[246:247], s[50:51], 0, v[152:153]
	global_load_lds_dwordx4 v[164:165], off
	v_lshl_add_u64 v[164:165], s[10:11], 0, v[150:151]
	s_add_i32 m0, s12, 0x2000
	s_nop 0
	global_load_lds_dwordx4 v[164:165], off
	v_lshl_add_u64 v[164:165], s[50:51], 0, v[154:155]
	s_mov_b32 m0, s9
	s_nop 0
	global_load_lds_dwordx4 v[164:165], off
	s_mov_b32 m0, s30
	s_nop 0
	global_load_lds_dwordx4 v[246:247], off
	s_waitcnt vmcnt(8)
	s_waitcnt lgkmcnt(0)
	s_barrier
	v_mfma_f32_16x16x32_bf16 v[62:65], v[160:163], v[214:217], v[62:65]
	v_mfma_f32_16x16x32_bf16 v[58:61], v[186:189], v[214:217], v[58:61]
	v_mfma_f32_16x16x32_bf16 v[46:49], v[160:163], v[222:225], v[46:49]
	v_mfma_f32_16x16x32_bf16 v[42:45], v[186:189], v[222:225], v[42:45]
	v_mfma_f32_16x16x32_bf16 v[30:33], v[160:163], v[230:233], v[30:33]
	v_mfma_f32_16x16x32_bf16 v[26:29], v[186:189], v[230:233], v[26:29]
	v_mfma_f32_16x16x32_bf16 v[14:17], v[160:163], v[238:241], v[14:17]
	v_mfma_f32_16x16x32_bf16 v[10:13], v[186:189], v[238:241], v[10:13]
	v_mfma_f32_16x16x32_bf16 v[62:65], v[170:173], v[218:221], v[62:65]
	v_mfma_f32_16x16x32_bf16 v[58:61], v[190:193], v[218:221], v[58:61]
	v_mfma_f32_16x16x32_bf16 v[46:49], v[170:173], v[226:229], v[46:49]
	v_mfma_f32_16x16x32_bf16 v[42:45], v[190:193], v[226:229], v[42:45]
	v_mfma_f32_16x16x32_bf16 v[30:33], v[170:173], v[234:237], v[30:33]
	v_mfma_f32_16x16x32_bf16 v[26:29], v[190:193], v[234:237], v[26:29]
	v_mfma_f32_16x16x32_bf16 v[14:17], v[170:173], v[242:245], v[14:17]
	v_mfma_f32_16x16x32_bf16 v[10:13], v[190:193], v[242:245], v[10:13]
	v_mfma_f32_16x16x32_bf16 v[54:57], v[198:201], v[214:217], v[54:57]
	v_mfma_f32_16x16x32_bf16 v[50:53], v[206:209], v[214:217], v[50:53]
	v_mfma_f32_16x16x32_bf16 v[38:41], v[198:201], v[222:225], v[38:41]
	v_mfma_f32_16x16x32_bf16 v[34:37], v[206:209], v[222:225], v[34:37]
	v_mfma_f32_16x16x32_bf16 v[22:25], v[198:201], v[230:233], v[22:25]
	v_mfma_f32_16x16x32_bf16 v[18:21], v[206:209], v[230:233], v[18:21]
	v_mfma_f32_16x16x32_bf16 v[6:9], v[198:201], v[238:241], v[6:9]
	v_mfma_f32_16x16x32_bf16 v[2:5], v[206:209], v[238:241], v[2:5]
	v_mfma_f32_16x16x32_bf16 v[54:57], v[202:205], v[218:221], v[54:57]
	v_mfma_f32_16x16x32_bf16 v[50:53], v[210:213], v[218:221], v[50:53]
	v_mfma_f32_16x16x32_bf16 v[38:41], v[202:205], v[226:229], v[38:41]
	v_mfma_f32_16x16x32_bf16 v[34:37], v[210:213], v[226:229], v[34:37]
	v_mfma_f32_16x16x32_bf16 v[22:25], v[202:205], v[234:237], v[22:25]
	v_mfma_f32_16x16x32_bf16 v[18:21], v[210:213], v[234:237], v[18:21]
	v_mfma_f32_16x16x32_bf16 v[6:9], v[202:205], v[242:245], v[6:9]
	v_mfma_f32_16x16x32_bf16 v[2:5], v[210:213], v[242:245], v[2:5]
	s_barrier
; #define PG8_STAGE(bufoff, gbase, voff) do { _Pragma("unroll") for (int _i = 0; _i < 2; ++_i) \
;         __builtin_amdgcn_global_load_lds((const unsigned*)((const char*)(gbase) + (voff)[_i]), (PG8_LAS unsigned*)(lds + (bufoff) + ldsw + _i * 8192), 16, 0, 0); } while (0)
; #define PG8_LDA(dst, b, h) do { _Pragma("unroll") for (int m = 0; m < 4; ++m) _Pragma("unroll") for (int k = 0; k < 2; ++k) dst[m][k] = *(const PG8_LAS bf16x8*)(lds + PG8_SA(b, h) + aoff + m * 2048 + k * 1024); } while (0)
; #define PG8_LDB(dst, b, h) do { _Pragma("unroll") for (int n = 0; n < 2; ++n) _Pragma("unroll") for (int k = 0; k < 2; ++k) dst[n][k] = *(const PG8_LAS bf16x8*)(lds + PG8_SB(b, h) + boff + n * 2048 + k * 1024); } while (0)
; #define PG8_MMA(ai, bj, At, Bt) do { __builtin_amdgcn_s_setprio(1); _Pragma("unroll") for (int m = 0; m < 4; ++m) _Pragma("unroll") for (int n = 0; n < 2; ++n) _Pragma("unroll") for (int k = 0; k < 2; ++k) \
;         acc[ai][bj][m][n] = __builtin_amdgcn_mfma_f32_16x16x32_bf16(Bt[n][k], At[m][k], acc[ai][bj][m][n], 0, 0, 0); __builtin_amdgcn_s_setprio(0); } while (0)
; #define PG8_WAIT_V(n) asm volatile("s_waitcnt vmcnt(" #n ")" ::: "memory")
; #define PG8_WAIT_L(n) asm volatile("s_waitcnt lgkmcnt(" #n ")" ::: "memory")
; #define PG8_BAR __builtin_amdgcn_s_barrier()
; #define PG8_SCHED __builtin_amdgcn_sched_barrier(0)
; template <class Epi, class Sched, bool ALIGN_EPI = false, bool SP2 = false>
; __device__ __forceinline__ void gemm_phase(PG8_LAS unsigned char* lds, const Gemm g, const Sched& S, const Epi& E) {
;     ...
;             PG8_LDB(B0, 1, 0); PG8_LDB(B1, 1, 1); PG8_SCHED; PG8_LDA(At, 1, 0); PG8_STAGE(PG8_SA(0, 1), a2 + hstepA, voffA);
;             PG8_WAIT_V(8); PG8_WAIT_L(0); PG8_BAR; PG8_MMA(0, 0, At, B0); PG8_MMA(0, 1, At, B1); PG8_BAR; PG8_SCHED;
	s_add_i32 s12, 0, 0x18000
	s_add_i32 s13, 0, 0x1c000
	v_add_u32_e32 v190, s12, v167
	v_add_u32_e32 v210, s13, v167
	ds_read_b128 v[160:163], v190
	ds_read_b128 v[170:173], v190 offset:1024
	ds_read_b128 v[186:189], v190 offset:2048
	ds_read_b128 v[190:193], v190 offset:3072
	ds_read_b128 v[198:201], v210
	ds_read_b128 v[202:205], v210 offset:1024
	ds_read_b128 v[206:209], v210 offset:2048
	ds_read_b128 v[210:213], v210 offset:3072
	s_add_u32 s10, s50, 0x100000
	s_addc_u32 s11, s51, 0
	s_mov_b32 m0, s31
	v_lshl_add_u64 v[248:249], s[10:11], 0, v[154:155]
	ds_read_b128 v[214:217], v169 offset:32768
	ds_read_b128 v[218:221], v169 offset:33792
	ds_read_b128 v[222:225], v169 offset:34816
	ds_read_b128 v[226:229], v169 offset:35840
	ds_read_b128 v[230:233], v169 offset:36864
	ds_read_b128 v[234:237], v169 offset:37888
	ds_read_b128 v[238:241], v169 offset:38912
	ds_read_b128 v[242:245], v169 offset:39936
	global_load_lds_dwordx4 v[248:249], off
	v_lshl_add_u64 v[248:249], s[10:11], 0, v[152:153]
	s_mov_b32 m0, s34
	s_nop 0
	global_load_lds_dwordx4 v[248:249], off
	s_waitcnt vmcnt(8)
	s_waitcnt lgkmcnt(0)
	s_barrier
	v_mfma_f32_16x16x32_bf16 v[126:129], v[160:163], v[214:217], v[126:129]
	v_mfma_f32_16x16x32_bf16 v[122:125], v[186:189], v[214:217], v[122:125]
	v_mfma_f32_16x16x32_bf16 v[110:113], v[160:163], v[222:225], v[110:113]
	v_mfma_f32_16x16x32_bf16 v[106:109], v[186:189], v[222:225], v[106:109]
	v_mfma_f32_16x16x32_bf16 v[94:97], v[160:163], v[230:233], v[94:97]
	v_mfma_f32_16x16x32_bf16 v[90:93], v[186:189], v[230:233], v[90:93]
	v_mfma_f32_16x16x32_bf16 v[78:81], v[160:163], v[238:241], v[78:81]
	v_mfma_f32_16x16x32_bf16 v[74:77], v[186:189], v[238:241], v[74:77]
	v_mfma_f32_16x16x32_bf16 v[126:129], v[170:173], v[218:221], v[126:129]
	v_mfma_f32_16x16x32_bf16 v[122:125], v[190:193], v[218:221], v[122:125]
	v_mfma_f32_16x16x32_bf16 v[110:113], v[170:173], v[226:229], v[110:113]
	v_mfma_f32_16x16x32_bf16 v[106:109], v[190:193], v[226:229], v[106:109]
	v_mfma_f32_16x16x32_bf16 v[94:97], v[170:173], v[234:237], v[94:97]
	v_mfma_f32_16x16x32_bf16 v[90:93], v[190:193], v[234:237], v[90:93]
	v_mfma_f32_16x16x32_bf16 v[78:81], v[170:173], v[242:245], v[78:81]
	v_mfma_f32_16x16x32_bf16 v[74:77], v[190:193], v[242:245], v[74:77]
	v_mfma_f32_16x16x32_bf16 v[118:121], v[198:201], v[214:217], v[118:121]
	v_mfma_f32_16x16x32_bf16 v[114:117], v[206:209], v[214:217], v[114:117]
	v_mfma_f32_16x16x32_bf16 v[102:105], v[198:201], v[222:225], v[102:105]
	v_mfma_f32_16x16x32_bf16 v[98:101], v[206:209], v[222:225], v[98:101]
	v_mfma_f32_16x16x32_bf16 v[86:89], v[198:201], v[230:233], v[86:89]
	v_mfma_f32_16x16x32_bf16 v[82:85], v[206:209], v[230:233], v[82:85]
	v_mfma_f32_16x16x32_bf16 v[70:73], v[198:201], v[238:241], v[70:73]
	v_mfma_f32_16x16x32_bf16 v[66:69], v[206:209], v[238:241], v[66:69]
	v_mfma_f32_16x16x32_bf16 v[118:121], v[202:205], v[218:221], v[118:121]
	v_mfma_f32_16x16x32_bf16 v[114:117], v[210:213], v[218:221], v[114:117]
	v_mfma_f32_16x16x32_bf16 v[102:105], v[202:205], v[226:229], v[102:105]
	v_mfma_f32_16x16x32_bf16 v[98:101], v[210:213], v[226:229], v[98:101]
	v_mfma_f32_16x16x32_bf16 v[86:89], v[202:205], v[234:237], v[86:89]
	v_mfma_f32_16x16x32_bf16 v[82:85], v[210:213], v[234:237], v[82:85]
	v_mfma_f32_16x16x32_bf16 v[70:73], v[202:205], v[242:245], v[70:73]
	v_mfma_f32_16x16x32_bf16 v[66:69], v[210:213], v[242:245], v[66:69]
	s_barrier
; #define PG8_STAGE(bufoff, gbase, voff) do { _Pragma("unroll") for (int _i = 0; _i < 2; ++_i) \
;         __builtin_amdgcn_global_load_lds((const unsigned*)((const char*)(gbase) + (voff)[_i]), (PG8_LAS unsigned*)(lds + (bufoff) + ldsw + _i * 8192), 16, 0, 0); } while (0)
; #define PG8_LDA(dst, b, h) do { _Pragma("unroll") for (int m = 0; m < 4; ++m) _Pragma("unroll") for (int k = 0; k < 2; ++k) dst[m][k] = *(const PG8_LAS bf16x8*)(lds + PG8_SA(b, h) + aoff + m * 2048 + k * 1024); } while (0)
; #define PG8_MMA(ai, bj, At, Bt) do { __builtin_amdgcn_s_setprio(1); _Pragma("unroll") for (int m = 0; m < 4; ++m) _Pragma("unroll") for (int n = 0; n < 2; ++n) _Pragma("unroll") for (int k = 0; k < 2; ++k) \
;         acc[ai][bj][m][n] = __builtin_amdgcn_mfma_f32_16x16x32_bf16(Bt[n][k], At[m][k], acc[ai][bj][m][n], 0, 0, 0); __builtin_amdgcn_s_setprio(0); } while (0)
; #define PG8_WAIT_V(n) asm volatile("s_waitcnt vmcnt(" #n ")" ::: "memory")
; #define PG8_WAIT_L(n) asm volatile("s_waitcnt lgkmcnt(" #n ")" ::: "memory")
; #define PG8_BAR __builtin_amdgcn_s_barrier()
; #define PG8_SCHED __builtin_amdgcn_sched_barrier(0)
; template <class Epi, class Sched, bool ALIGN_EPI = false, bool SP2 = false>
; __device__ __forceinline__ void gemm_phase(PG8_LAS unsigned char* lds, const Gemm g, const Sched& S, const Epi& E) {
;     ...
;         for (int t = 0; t < nt; t += 2) {
;             const bool last = (t == nt - 2);
;             const char* a1 = cA + (size_t)(t + 1) * kstep;
;             const char* a2 = last ? nA : cA + (size_t)(t + 2) * kstep; const char* b2 = last ? nB : cB + (size_t)(t + 2) * kstep;
;     ...
;             PG8_LDA(At, 1, 1); PG8_STAGE(PG8_SB(1, 0), b3, voffB); PG8_STAGE(PG8_SB(1, 1), b3 + hstepB, voffB); PG8_STAGE(PG8_SA(1, 0), a3, voffA);
;             PG8_WAIT_V(8); PG8_WAIT_L(0); PG8_BAR; PG8_MMA(1, 0, At, B0); PG8_MMA(1, 1, At, B1); PG8_BAR; PG8_SCHED;
	s_add_i32 s10, s12, s8
	v_lshl_add_u64 v[130:131], v[130:131], 0, s[2:3]
	s_mov_b32 m0, s10
	ds_read_b128 v[214:217], v169 offset:49152
	ds_read_b128 v[218:221], v169 offset:50176
	ds_read_b128 v[222:225], v169 offset:51200
	ds_read_b128 v[226:229], v169 offset:52224
	ds_read_b128 v[230:233], v169 offset:53248
	ds_read_b128 v[234:237], v169 offset:54272
	ds_read_b128 v[238:241], v169 offset:55296
	ds_read_b128 v[242:245], v169 offset:56320
	global_load_lds_dwordx4 v[130:131], off
	s_add_i32 m0, s10, 0x2000
	s_add_u32 s10, s48, 0x100080
	v_lshl_add_u64 v[130:131], v[132:133], 0, s[2:3]
	s_addc_u32 s11, s49, 0
	s_add_i32 s12, s13, s8
	global_load_lds_dwordx4 v[130:131], off
	v_lshl_add_u64 v[130:131], s[10:11], 0, v[0:1]
	s_mov_b32 m0, s12
	s_nop 0
	global_load_lds_dwordx4 v[130:131], off
	v_lshl_add_u64 v[130:131], s[10:11], 0, v[150:151]
	s_add_i32 m0, s12, 0x2000
	s_nop 0
	global_load_lds_dwordx4 v[130:131], off
	v_lshl_add_u64 v[130:131], v[164:165], 0, s[2:3]
	s_mov_b32 m0, s35
	s_nop 0
	global_load_lds_dwordx4 v[130:131], off
	v_lshl_add_u64 v[130:131], v[246:247], 0, s[2:3]
	s_mov_b32 m0, s52
	s_nop 0
	global_load_lds_dwordx4 v[130:131], off
	s_waitcnt vmcnt(8)
	s_waitcnt lgkmcnt(0)
	s_barrier
	v_mfma_f32_16x16x32_bf16 v[62:65], v[160:163], v[214:217], v[62:65]
	v_mfma_f32_16x16x32_bf16 v[58:61], v[186:189], v[214:217], v[58:61]
	s_add_i32 s63, s63, 2
	v_mfma_f32_16x16x32_bf16 v[46:49], v[160:163], v[222:225], v[46:49]
	s_add_u32 s46, s46, 0x100
	v_mfma_f32_16x16x32_bf16 v[42:45], v[186:189], v[222:225], v[42:45]
	s_addc_u32 s47, s47, 0
	v_mfma_f32_16x16x32_bf16 v[30:33], v[160:163], v[230:233], v[30:33]
	s_add_u32 s57, s57, 0x100
	v_mfma_f32_16x16x32_bf16 v[26:29], v[186:189], v[230:233], v[26:29]
	s_addc_u32 s62, s62, 0
	v_mfma_f32_16x16x32_bf16 v[14:17], v[160:163], v[238:241], v[14:17]
	s_add_u32 s10, s46, 0xfff00080
	v_mfma_f32_16x16x32_bf16 v[10:13], v[186:189], v[238:241], v[10:13]
	s_addc_u32 s11, s47, -1
	v_mfma_f32_16x16x32_bf16 v[62:65], v[170:173], v[218:221], v[62:65]
	s_add_i32 s12, 0, 0x10000
	v_mfma_f32_16x16x32_bf16 v[58:61], v[190:193], v[218:221], v[58:61]
	s_cmp_eq_u32 s63, 60
	v_mfma_f32_16x16x32_bf16 v[46:49], v[170:173], v[226:229], v[46:49]
	s_cselect_b32 s51, s41, s11
	v_mfma_f32_16x16x32_bf16 v[42:45], v[190:193], v[226:229], v[42:45]
	s_cselect_b32 s50, s56, s10
	v_mfma_f32_16x16x32_bf16 v[30:33], v[170:173], v[234:237], v[30:33]
	v_add_u32_e32 v130, s12, v167
	v_mfma_f32_16x16x32_bf16 v[26:29], v[190:193], v[234:237], v[26:29]
	s_cselect_b32 s49, s4, s62
	v_mfma_f32_16x16x32_bf16 v[14:17], v[170:173], v[242:245], v[14:17]
	s_cselect_b32 s48, s39, s57
	v_mfma_f32_16x16x32_bf16 v[10:13], v[190:193], v[242:245], v[10:13]
	s_add_i32 s13, 0, 0x14000
	v_mfma_f32_16x16x32_bf16 v[54:57], v[198:201], v[214:217], v[54:57]
	s_cmp_gt_u32 s63, 61
	v_mfma_f32_16x16x32_bf16 v[50:53], v[206:209], v[214:217], v[50:53]
	v_mfma_f32_16x16x32_bf16 v[38:41], v[198:201], v[222:225], v[38:41]
	v_mfma_f32_16x16x32_bf16 v[34:37], v[206:209], v[222:225], v[34:37]
	v_mfma_f32_16x16x32_bf16 v[22:25], v[198:201], v[230:233], v[22:25]
	v_mfma_f32_16x16x32_bf16 v[18:21], v[206:209], v[230:233], v[18:21]
	v_mfma_f32_16x16x32_bf16 v[6:9], v[198:201], v[238:241], v[6:9]
	v_mfma_f32_16x16x32_bf16 v[2:5], v[206:209], v[238:241], v[2:5]
	v_mfma_f32_16x16x32_bf16 v[54:57], v[202:205], v[218:221], v[54:57]
	v_mfma_f32_16x16x32_bf16 v[50:53], v[210:213], v[218:221], v[50:53]
	v_mfma_f32_16x16x32_bf16 v[38:41], v[202:205], v[226:229], v[38:41]
	v_mfma_f32_16x16x32_bf16 v[34:37], v[210:213], v[226:229], v[34:37]
	v_mfma_f32_16x16x32_bf16 v[22:25], v[202:205], v[234:237], v[22:25]
	v_mfma_f32_16x16x32_bf16 v[18:21], v[210:213], v[234:237], v[18:21]
	v_mfma_f32_16x16x32_bf16 v[6:9], v[202:205], v[242:245], v[6:9]
	v_mfma_f32_16x16x32_bf16 v[2:5], v[210:213], v[242:245], v[2:5]
	s_barrier
	s_cbranch_scc0 .Lgk_929
	s_and_b64 vcc, exec, s[20:21]
	s_mov_b64 s[62:63], s[14:15]
	s_cbranch_vccz .LBB0_932
	s_barrier
